# all hipcc v_pk_mul/add/fma_f32 in the slab loop split into scalar f32 ops (bit-identical), on top of previous version
# baseline (speedup 1.0000x reference)
; #define P (*launderP(lp))
; __device__ __forceinline__ void phase_peer_gather(PREF P, int slab, int tbeg, int tend) {
;     ...
;     {
;       const float corr = 128.f * csum;
;       float hv[16], pv[16];
; #pragma unroll
;       for (int hf = 0; hf < 2; ++hf) {
;         ld16bf(hrow + hf * 1024, hv);
;         ld16bf(P.peb + (size_t)t * 2048 + lane * 16 + hf * 1024, pv);
; #pragma unroll
;         for (int e = 0; e < 16; ++e) acc[hf * 16 + e] = acc[hf * 16 + e] - corr + DN_ALPHA * hv[e] + pv[e];
;       }
;     }
;     float s = 0.f;
; #pragma unroll
;     for (int e = 0; e < 32; ++e) s += acc[e];
.LBB0_153:
	ds_read_b64 v[2:3], v53 offset:360
	v_mul_f32_e32 v18, 0x43000000, v55
	v_sub_f32_e32 v20, v134, v18
	v_sub_f32_e32 v21, v135, v18
	v_sub_f32_e32 v22, v132, v18
	v_sub_f32_e32 v23, v133, v18
	v_sub_f32_e32 v24, v130, v18
	v_sub_f32_e32 v25, v131, v18
	s_waitcnt lgkmcnt(0)
	v_lshl_add_u64 v[2:3], v[0:1], 1, v[2:3]
	v_lshl_add_u64 v[14:15], v[2:3], 0, v[180:181]
	flat_load_dwordx4 v[2:5], v[14:15]
	flat_load_dwordx4 v[6:9], v[14:15] offset:16
	flat_load_dwordx4 v[10:13], v[14:15] offset:2048
	s_nop 0
	flat_load_dwordx4 v[14:17], v[14:15] offset:2064
	v_sub_f32_e32 v26, v128, v18
	v_sub_f32_e32 v27, v129, v18
	v_sub_f32_e32 v28, v126, v18
	v_sub_f32_e32 v29, v127, v18
	v_sub_f32_e32 v30, v124, v18
	v_sub_f32_e32 v31, v125, v18
	v_sub_f32_e32 v32, v122, v18
	v_sub_f32_e32 v33, v123, v18
	v_sub_f32_e32 v34, v120, v18
	v_sub_f32_e32 v35, v121, v18
	v_sub_f32_e32 v36, v118, v18
	v_sub_f32_e32 v37, v119, v18
	v_sub_f32_e32 v38, v116, v18
	v_sub_f32_e32 v39, v117, v18
	v_sub_f32_e32 v40, v114, v18
	v_sub_f32_e32 v41, v115, v18
	v_sub_f32_e32 v42, v112, v18
	v_sub_f32_e32 v43, v113, v18
	v_sub_f32_e32 v44, v110, v18
	v_sub_f32_e32 v45, v111, v18
	v_sub_f32_e32 v46, v108, v18
	v_sub_f32_e32 v47, v109, v18
	v_sub_f32_e32 v100, v106, v18
	v_sub_f32_e32 v101, v107, v18
	v_sub_f32_e32 v19, v137, v18
	v_sub_f32_e32 v18, v136, v18
	v_fmac_f32_e32 v20, s28, v68
	v_fmac_f32_e32 v21, s28, v69
	v_fma_f32 v68, v76, s28, v28
	v_fma_f32 v69, v77, s28, v29
	v_fma_f32 v76, v98, s28, v18
	v_fma_f32 v77, v99, s28, v19
	v_fmac_f32_e32 v24, s28, v72
	v_fmac_f32_e32 v25, s28, v73
	v_fma_f32 v72, v80, s28, v32
	v_fma_f32 v73, v81, s28, v33
	v_fmac_f32_e32 v34, s28, v82
	v_fmac_f32_e32 v35, s28, v83
	v_fmac_f32_e32 v22, s28, v70
	v_fmac_f32_e32 v23, s28, v71
	v_fma_f32 v70, v78, s28, v30
	v_fma_f32 v71, v79, s28, v31
	v_fmac_f32_e32 v26, s28, v74
	v_fmac_f32_e32 v27, s28, v75
	v_fmac_f32_e32 v36, s28, v84
	v_fmac_f32_e32 v37, s28, v85
	v_fmac_f32_e32 v44, s28, v92
	v_fmac_f32_e32 v45, s28, v93
	v_fmac_f32_e32 v46, s28, v94
	v_fmac_f32_e32 v47, s28, v95
	v_fmac_f32_e32 v38, s28, v86
	v_fmac_f32_e32 v39, s28, v87
	v_fmac_f32_e32 v40, s28, v88
	v_fmac_f32_e32 v41, s28, v89
	v_fmac_f32_e32 v42, s28, v90
	v_fmac_f32_e32 v43, s28, v91
	v_fma_f32 v74, v96, s28, v100
	v_fma_f32 v75, v97, s28, v101
	s_mov_b32 s6, 0x800000
	v_mov_b32_e32 v61, v181
	v_mov_b32_e32 v63, v181
	v_mov_b32_e32 v65, v181
	v_mov_b32_e32 v67, v181
	v_readlane_b32 s14, v251, 6
	v_readlane_b32 s15, v251, 7
	s_waitcnt vmcnt(0) lgkmcnt(0)
	v_lshlrev_b32_e32 v18, 16, v2
	v_and_b32_e32 v19, 0xffff0000, v2
	v_lshlrev_b32_e32 v80, 16, v8
	v_and_b32_e32 v81, 0xffff0000, v8
	v_lshlrev_b32_e32 v8, 16, v9
	v_and_b32_e32 v9, 0xffff0000, v9
	v_add_f32_e32 v32, v20, v18
	v_add_f32_e32 v33, v21, v19
	v_lshlrev_b32_e32 v2, 16, v3
	v_and_b32_e32 v3, 0xffff0000, v3
	v_add_f32_e32 v18, v34, v8
	v_add_f32_e32 v19, v35, v9
	v_add_f32_e32 v34, 0, v32
	v_add_f32_e32 v30, v22, v2
	v_add_f32_e32 v31, v23, v3
	v_add_f32_e32 v34, v33, v34
	v_lshlrev_b32_e32 v28, 16, v4
	v_and_b32_e32 v29, 0xffff0000, v4
	v_add_f32_e32 v34, v30, v34
	v_add_f32_e32 v28, v24, v28
	v_add_f32_e32 v29, v25, v29
	v_add_f32_e32 v34, v31, v34
	v_lshlrev_b32_e32 v4, 16, v5
	v_and_b32_e32 v5, 0xffff0000, v5
	v_add_f32_e32 v34, v28, v34
	v_add_f32_e32 v26, v26, v4
	v_add_f32_e32 v27, v27, v5
	v_add_f32_e32 v34, v29, v34
	v_lshlrev_b32_e32 v78, 16, v6
	v_and_b32_e32 v79, 0xffff0000, v6
	v_add_f32_e32 v34, v26, v34
	v_add_f32_e32 v24, v68, v78
	v_add_f32_e32 v25, v69, v79
	v_add_f32_e32 v34, v27, v34
	v_lshlrev_b32_e32 v6, 16, v7
	v_and_b32_e32 v7, 0xffff0000, v7
	v_add_f32_e32 v34, v24, v34
	v_add_f32_e32 v22, v70, v6
	v_add_f32_e32 v23, v71, v7
	v_add_f32_e32 v34, v25, v34
	v_add_f32_e32 v34, v22, v34
	v_add_f32_e32 v20, v72, v80
	v_add_f32_e32 v21, v73, v81
	v_add_f32_e32 v34, v23, v34
	v_add_f32_e32 v34, v20, v34
	v_add_f32_e32 v34, v21, v34
	v_lshlrev_b32_e32 v82, 16, v10
	v_and_b32_e32 v83, 0xffff0000, v10
	v_add_f32_e32 v34, v18, v34
	v_lshlrev_b32_e32 v92, 16, v16
	v_and_b32_e32 v93, 0xffff0000, v16
	v_lshlrev_b32_e32 v94, 16, v17
	v_and_b32_e32 v95, 0xffff0000, v17
	v_add_f32_e32 v16, v36, v82
	v_add_f32_e32 v17, v37, v83
	v_add_f32_e32 v34, v19, v34
	v_lshlrev_b32_e32 v10, 16, v11
	v_and_b32_e32 v11, 0xffff0000, v11
	v_add_f32_e32 v34, v16, v34
	v_lshlrev_b32_e32 v88, 16, v14
	v_and_b32_e32 v89, 0xffff0000, v14
	v_lshlrev_b32_e32 v90, 16, v15
	v_and_b32_e32 v91, 0xffff0000, v15
	v_add_f32_e32 v14, v38, v10
	v_add_f32_e32 v15, v39, v11
	v_add_f32_e32 v34, v17, v34
	v_lshlrev_b32_e32 v84, 16, v12
	v_and_b32_e32 v85, 0xffff0000, v12
	v_add_f32_e32 v34, v14, v34
	v_lshlrev_b32_e32 v86, 16, v13
	v_and_b32_e32 v87, 0xffff0000, v13
	v_add_f32_e32 v12, v40, v84
	v_add_f32_e32 v13, v41, v85
	v_add_f32_e32 v34, v15, v34
	v_add_f32_e32 v34, v12, v34
	v_add_f32_e32 v10, v42, v86
	v_add_f32_e32 v11, v43, v87
	v_add_f32_e32 v34, v13, v34
	v_add_f32_e32 v34, v10, v34
	v_add_f32_e32 v8, v44, v88
	v_add_f32_e32 v9, v45, v89
	v_add_f32_e32 v34, v11, v34
	v_add_f32_e32 v34, v8, v34
	v_add_f32_e32 v6, v46, v90
	v_add_f32_e32 v7, v47, v91
	v_add_f32_e32 v34, v9, v34
	v_add_f32_e32 v34, v6, v34
	v_add_f32_e32 v4, v74, v92
	v_add_f32_e32 v5, v75, v93
	v_add_f32_e32 v34, v7, v34
	v_add_f32_e32 v34, v4, v34
	v_add_f32_e32 v2, v76, v94
	v_add_f32_e32 v3, v77, v95
	v_add_f32_e32 v34, v5, v34
	v_add_f32_e32 v34, v2, v34
	v_add_f32_e32 v34, v3, v34
	ds_bpermute_b32 v35, v138, v34
	v_lshlrev_b32_e32 v42, 2, v54
	v_mov_b32_e32 v43, v181
	s_waitcnt lgkmcnt(0)
	v_add_f32_e32 v34, v34, v35
	ds_bpermute_b32 v35, v139, v34
	s_waitcnt lgkmcnt(0)
; __device__ __forceinline__ void phase_peer_gather(PREF P, int slab, int tbeg, int tend) {
;     ...
;     for (int e = 0; e < 32; ++e) s += acc[e];
;     const float mu = wsum(s) * (1.f / 2048.f);
;     float vs = 0.f;
; #pragma unroll
;     for (int e = 0; e < 32; ++e) { float d = acc[e] - mu; vs += d * d; }
;     const float rs = rsqrtf(wsum(vs) * (1.f / 2048.f) + LN_EPS);
	v_add_f32_e32 v34, v34, v35
	ds_bpermute_b32 v35, v140, v34
	s_waitcnt lgkmcnt(0)
	v_add_f32_e32 v34, v34, v35
	ds_bpermute_b32 v35, v141, v34
	s_waitcnt lgkmcnt(0)
	v_add_f32_e32 v38, v34, v35
	ds_bpermute_b32 v39, v142, v38
	ds_read2_b64 v[34:37], v53 offset0:18 offset1:19
	s_waitcnt lgkmcnt(1)
	v_add_f32_e32 v44, v38, v39
	ds_bpermute_b32 v45, v143, v44
	s_waitcnt lgkmcnt(1)
	v_lshl_add_u64 v[34:35], v[34:35], 0, v[42:43]
	v_lshl_add_u64 v[38:39], v[36:37], 0, v[42:43]
	flat_load_dwordx4 v[34:37], v[34:35]
	s_nop 0
	flat_load_dwordx4 v[38:41], v[38:39]
	s_waitcnt lgkmcnt(0)
	v_add_f32_e32 v44, v44, v45
	v_mul_f32_e32 v44, 0x3a000000, v44
	v_sub_f32_e32 v32, v32, v44
	v_sub_f32_e32 v33, v33, v44
	v_sub_f32_e32 v30, v30, v44
	v_sub_f32_e32 v31, v31, v44
	v_mul_f32_e32 v46, v32, v32
	v_mul_f32_e32 v47, v33, v33
	v_mul_f32_e32 v68, v30, v30
	v_mul_f32_e32 v69, v31, v31
	v_add_f32_e32 v46, v46, v47
	v_sub_f32_e32 v28, v28, v44
	v_sub_f32_e32 v29, v29, v44
	v_add_f32_e32 v46, v68, v46
	v_mul_f32_e32 v70, v28, v28
	v_mul_f32_e32 v71, v29, v29
	v_add_f32_e32 v46, v69, v46
	v_sub_f32_e32 v26, v26, v44
	v_sub_f32_e32 v27, v27, v44
	v_add_f32_e32 v46, v70, v46
	v_mul_f32_e32 v72, v26, v26
	v_mul_f32_e32 v73, v27, v27
	v_add_f32_e32 v46, v71, v46
	v_sub_f32_e32 v24, v24, v44
	v_sub_f32_e32 v25, v25, v44
	v_add_f32_e32 v46, v72, v46
	v_mul_f32_e32 v74, v24, v24
	v_mul_f32_e32 v75, v25, v25
	v_add_f32_e32 v46, v73, v46
	v_sub_f32_e32 v22, v22, v44
	v_sub_f32_e32 v23, v23, v44
	v_add_f32_e32 v46, v74, v46
	v_mul_f32_e32 v76, v22, v22
	v_mul_f32_e32 v77, v23, v23
	v_add_f32_e32 v46, v75, v46
	v_sub_f32_e32 v20, v20, v44
	v_sub_f32_e32 v21, v21, v44
	v_add_f32_e32 v46, v76, v46
	v_mul_f32_e32 v78, v20, v20
	v_mul_f32_e32 v79, v21, v21
	v_add_f32_e32 v46, v77, v46
	v_sub_f32_e32 v18, v18, v44
	v_sub_f32_e32 v19, v19, v44
	v_add_f32_e32 v46, v78, v46
	v_mul_f32_e32 v80, v18, v18
	v_mul_f32_e32 v81, v19, v19
	v_add_f32_e32 v46, v79, v46
	v_sub_f32_e32 v16, v16, v44
	v_sub_f32_e32 v17, v17, v44
	v_add_f32_e32 v46, v80, v46
	v_mul_f32_e32 v82, v16, v16
	v_mul_f32_e32 v83, v17, v17
	v_add_f32_e32 v46, v81, v46
	v_sub_f32_e32 v14, v14, v44
	v_sub_f32_e32 v15, v15, v44
	v_add_f32_e32 v46, v82, v46
	v_mul_f32_e32 v84, v14, v14
	v_mul_f32_e32 v85, v15, v15
	v_add_f32_e32 v46, v83, v46
	v_sub_f32_e32 v12, v12, v44
	v_sub_f32_e32 v13, v13, v44
	v_add_f32_e32 v46, v84, v46
	v_mul_f32_e32 v86, v12, v12
	v_mul_f32_e32 v87, v13, v13
	v_add_f32_e32 v46, v85, v46
	v_sub_f32_e32 v10, v10, v44
	v_sub_f32_e32 v11, v11, v44
	v_add_f32_e32 v46, v86, v46
	v_mul_f32_e32 v88, v10, v10
	v_mul_f32_e32 v89, v11, v11
	v_add_f32_e32 v46, v87, v46
	v_sub_f32_e32 v8, v8, v44
	v_sub_f32_e32 v9, v9, v44
	v_add_f32_e32 v46, v88, v46
	v_mul_f32_e32 v90, v8, v8
	v_mul_f32_e32 v91, v9, v9
	v_add_f32_e32 v46, v89, v46
	v_sub_f32_e32 v92, v6, v44
	v_sub_f32_e32 v93, v7, v44
	v_add_f32_e32 v46, v90, v46
	v_mul_f32_e32 v6, v92, v92
	v_mul_f32_e32 v7, v93, v93
	v_add_f32_e32 v46, v91, v46
	v_sub_f32_e32 v94, v4, v44
	v_sub_f32_e32 v95, v5, v44
	v_add_f32_e32 v6, v6, v46
	v_mul_f32_e32 v4, v94, v94
	v_mul_f32_e32 v5, v95, v95
	v_add_f32_e32 v6, v7, v6
	v_sub_f32_e32 v45, v3, v44
	v_sub_f32_e32 v44, v2, v44
	v_add_f32_e32 v4, v4, v6
	v_mul_f32_e32 v2, v44, v44
	v_mul_f32_e32 v3, v45, v45
	v_add_f32_e32 v4, v5, v4
	v_add_f32_e32 v2, v2, v4
	v_add_f32_e32 v2, v3, v2
	ds_bpermute_b32 v3, v138, v2
	v_lshl_add_u64 v[46:47], v[0:1], 2, v[50:51]
	v_lshl_add_u64 v[68:69], v[46:47], 0, v[42:43]
	s_waitcnt lgkmcnt(0)
	v_add_f32_e32 v2, v2, v3
	ds_bpermute_b32 v3, v139, v2
	s_waitcnt lgkmcnt(0)
	v_add_f32_e32 v2, v2, v3
	ds_bpermute_b32 v3, v140, v2
	s_waitcnt lgkmcnt(0)
	v_add_f32_e32 v2, v2, v3
	ds_bpermute_b32 v3, v141, v2
	s_waitcnt lgkmcnt(0)
	v_add_f32_e32 v2, v2, v3
	ds_bpermute_b32 v3, v142, v2
	s_waitcnt lgkmcnt(0)
	v_add_f32_e32 v2, v2, v3
	ds_bpermute_b32 v3, v143, v2
	s_waitcnt lgkmcnt(0)
	v_add_f32_e32 v2, v2, v3
	v_fmamk_f32 v2, v2, 0x3a000000, v191
	v_mul_f32_e32 v3, 0x4b800000, v2
	v_cmp_gt_f32_e32 vcc, s6, v2
	s_mov_b32 s6, s14
	s_nop 0
	v_cndmask_b32_e32 v2, v2, v3, vcc
	v_rsq_f32_e32 v2, v2
	s_nop 0
	v_mul_f32_e32 v0, 0x45800000, v2
	v_cndmask_b32_e32 v70, v2, v0, vcc
	v_mul_f32_e32 v0, v32, v70
	v_mul_f32_e32 v1, v33, v70
	v_mul_f32_e32 v2, v30, v70
	v_mul_f32_e32 v3, v31, v70
	s_waitcnt vmcnt(0)
; #define P (*launderP(lp))
; __device__ __forceinline__ void phase_peer_gather(PREF P, int slab, int tbeg, int tend) {
;     ...
;     float* orow = outs + (size_t)t * 2048;
; #pragma unroll
;     for (int hf = 0; hf < 2; ++hf)
; #pragma unroll
;       for (int c4 = 0; c4 < 4; ++c4) {
;         const int c = hf * 1024 + lane * 16 + c4 * 4;
;         float4 g = *(const float4*)(P.ln2_g + c), b = *(const float4*)(P.ln2_b + c);
;         float4 o;
;         o.x = (acc[hf * 16 + c4 * 4 + 0] - mu) * rs * g.x + b.x;
;         o.y = (acc[hf * 16 + c4 * 4 + 1] - mu) * rs * g.y + b.y;
;         o.z = (acc[hf * 16 + c4 * 4 + 2] - mu) * rs * g.z + b.z;
;         o.w = (acc[hf * 16 + c4 * 4 + 3] - mu) * rs * g.w + b.w;
;         *(float4*)(orow + c) = o;
;       }
;   }
	v_fma_f32 v0, v34, v0, v38
	v_fma_f32 v1, v35, v1, v39
	v_fma_f32 v2, v36, v2, v40
	v_fma_f32 v3, v37, v3, v41
	flat_store_dwordx4 v[68:69], v[0:3]
	ds_read2_b64 v[0:3], v53 offset0:18 offset1:19
	v_mul_f32_e32 v28, v28, v70
	v_mul_f32_e32 v29, v29, v70
	v_mul_f32_e32 v26, v26, v70
	v_mul_f32_e32 v27, v27, v70
	v_mul_f32_e32 v24, v24, v70
	v_mul_f32_e32 v25, v25, v70
	v_mul_f32_e32 v22, v22, v70
	v_mul_f32_e32 v23, v23, v70
	s_waitcnt lgkmcnt(0)
	v_lshl_add_u64 v[0:1], v[0:1], 0, v[42:43]
	v_lshl_add_u64 v[4:5], v[2:3], 0, v[42:43]
	flat_load_dwordx4 v[0:3], v[0:1] offset:16
	s_nop 0
	flat_load_dwordx4 v[4:7], v[4:5] offset:16
	v_mul_f32_e32 v20, v20, v70
	v_mul_f32_e32 v21, v21, v70
	v_mul_f32_e32 v18, v18, v70
	v_mul_f32_e32 v19, v19, v70
	v_mul_f32_e32 v16, v16, v70
	v_mul_f32_e32 v17, v17, v70
	v_mul_f32_e32 v14, v14, v70
	v_mul_f32_e32 v15, v15, v70
	v_mul_f32_e32 v12, v12, v70
	v_mul_f32_e32 v13, v13, v70
	v_mul_f32_e32 v10, v10, v70
	v_mul_f32_e32 v11, v11, v70
	v_mul_f32_e32 v8, v8, v70
	v_mul_f32_e32 v9, v9, v70
	s_waitcnt vmcnt(0) lgkmcnt(0)
	v_fma_f32 v0, v0, v28, v4
	v_fma_f32 v1, v1, v29, v5
	v_fma_f32 v2, v2, v26, v6
	v_fma_f32 v3, v3, v27, v7
	flat_store_dwordx4 v[68:69], v[0:3] offset:16
	ds_read2_b64 v[0:3], v53 offset0:18 offset1:19
	s_waitcnt lgkmcnt(0)
	v_lshl_add_u64 v[4:5], v[2:3], 0, v[42:43]
	v_lshl_add_u64 v[0:1], v[0:1], 0, v[42:43]
	flat_load_dwordx4 v[0:3], v[0:1] offset:32
	s_nop 0
	flat_load_dwordx4 v[4:7], v[4:5] offset:32
	s_waitcnt vmcnt(0) lgkmcnt(0)
	v_fma_f32 v0, v0, v24, v4
	v_fma_f32 v1, v1, v25, v5
	v_fma_f32 v2, v2, v22, v6
	v_fma_f32 v3, v3, v23, v7
	flat_store_dwordx4 v[68:69], v[0:3] offset:32
	ds_read2_b64 v[0:3], v53 offset0:18 offset1:19
	s_waitcnt lgkmcnt(0)
	v_lshl_add_u64 v[4:5], v[2:3], 0, v[42:43]
	v_lshl_add_u64 v[0:1], v[0:1], 0, v[42:43]
	flat_load_dwordx4 v[0:3], v[0:1] offset:48
	s_nop 0
	flat_load_dwordx4 v[4:7], v[4:5] offset:48
	s_waitcnt vmcnt(0) lgkmcnt(0)
	v_fma_f32 v0, v0, v20, v4
	v_fma_f32 v1, v1, v21, v5
	v_fma_f32 v2, v2, v18, v6
	v_fma_f32 v3, v3, v19, v7
	flat_store_dwordx4 v[68:69], v[0:3] offset:48
	ds_read2_b64 v[0:3], v53 offset0:18 offset1:19
	v_lshl_add_u64 v[18:19], v[46:47], 0, v[60:61]
	s_waitcnt lgkmcnt(0)
	v_lshl_add_u64 v[0:1], v[0:1], 0, v[60:61]
	v_lshl_add_u64 v[4:5], v[2:3], 0, v[60:61]
	flat_load_dwordx4 v[0:3], v[0:1]
	s_nop 0
	flat_load_dwordx4 v[4:7], v[4:5]
	s_waitcnt vmcnt(0) lgkmcnt(0)
	v_fma_f32 v0, v0, v16, v4
	v_fma_f32 v1, v1, v17, v5
	v_fma_f32 v2, v2, v14, v6
	v_fma_f32 v3, v3, v15, v7
	flat_store_dwordx4 v[18:19], v[0:3]
	ds_read2_b64 v[0:3], v53 offset0:18 offset1:19
	v_lshl_add_u64 v[14:15], v[46:47], 0, v[62:63]
	s_waitcnt lgkmcnt(0)
	v_lshl_add_u64 v[0:1], v[0:1], 0, v[62:63]
	v_lshl_add_u64 v[4:5], v[2:3], 0, v[62:63]
	flat_load_dwordx4 v[0:3], v[0:1]
	s_nop 0
	flat_load_dwordx4 v[4:7], v[4:5]
	s_waitcnt vmcnt(0) lgkmcnt(0)
	v_fma_f32 v0, v0, v12, v4
	v_fma_f32 v1, v1, v13, v5
	v_fma_f32 v2, v2, v10, v6
	v_fma_f32 v3, v3, v11, v7
	flat_store_dwordx4 v[14:15], v[0:3]
	ds_read2_b64 v[0:3], v53 offset0:18 offset1:19
	v_mul_f32_e32 v12, v92, v70
	v_mul_f32_e32 v13, v93, v70
	v_lshl_add_u64 v[10:11], v[46:47], 0, v[64:65]
	s_waitcnt lgkmcnt(0)
	v_lshl_add_u64 v[0:1], v[0:1], 0, v[64:65]
	v_lshl_add_u64 v[4:5], v[2:3], 0, v[64:65]
	flat_load_dwordx4 v[0:3], v[0:1]
	s_nop 0
	flat_load_dwordx4 v[4:7], v[4:5]
	s_waitcnt vmcnt(0) lgkmcnt(0)
	v_fma_f32 v0, v8, v0, v4
	v_fma_f32 v1, v9, v1, v5
	v_fma_f32 v2, v12, v2, v6
	v_fma_f32 v3, v13, v3, v7
	flat_store_dwordx4 v[10:11], v[0:3]
	ds_read2_b64 v[0:3], v53 offset0:18 offset1:19
	v_mul_f32_e32 v10, v94, v70
	v_mul_f32_e32 v11, v95, v70
	v_mul_f32_e32 v12, v44, v70
	v_mul_f32_e32 v13, v45, v70
	v_lshl_add_u64 v[8:9], v[46:47], 0, v[66:67]
	s_waitcnt lgkmcnt(0)
	v_lshl_add_u64 v[0:1], v[0:1], 0, v[66:67]
	v_lshl_add_u64 v[4:5], v[2:3], 0, v[66:67]
	flat_load_dwordx4 v[0:3], v[0:1]
	s_nop 0
	flat_load_dwordx4 v[4:7], v[4:5]
	s_waitcnt vmcnt(0) lgkmcnt(0)
	v_fma_f32 v0, v10, v0, v4
	v_fma_f32 v1, v11, v1, v5
	v_fma_f32 v2, v12, v2, v6
	v_fma_f32 v3, v13, v3, v7
	flat_store_dwordx4 v[8:9], v[0:3]
	s_nop 0
	v_lshl_add_u32 v48, s6, 2, v48
	s_movk_i32 s6, 0x1fff
	v_cmp_lt_i32_e32 vcc, s6, v48
	s_or_b64 s[36:37], vcc, s[36:37]
	s_andn2_b64 exec, exec, s[36:37]
	s_cbranch_execz .LBB0_175

; DEV int tid_() { int t = threadIdx.x; asm volatile("" : "+v"(t)); return t; }
; #define P (*launderP(lp))
; DEV float log_sigmoid(float x) { return -log1pf(expf(-x)); }
; __device__ __forceinline__ void ret_kv_item(PREF P, int w, u16* ST, char* smem) {
;   const int lane = tid_() & 63, wid = tid_() >> 6, l15 = lane & 15, q = lane >> 4;
;   const int dir = w & 1, h = (w >> 1) & 7, n = w >> 4;
;   const int tok0 = n * 128;
;   const float l2 = log_sigmoid(P.decay_logit[dir * 8 + h]) * LOG2E;
;   __syncthreads();
;   {
;     const u16* kt = P.KrT + (size_t)(h * 128) * TS + tok0;
;     dma_rows256([&](int row) { return kt + (size_t)row * TS; }, 128, smem);
.LBB0_179:
	s_mov_b64 s[60:61], 0x40000
	s_or_b64 exec, exec, s[14:15]
	s_waitcnt vmcnt(0)
	v_mul_f32_e32 v0, 0xbfb8aa3b, v5
	v_rndne_f32_e32 v1, v0
	s_waitcnt lgkmcnt(0)
	v_sub_f32_e32 v2, v0, v1
	v_fma_f32 v0, v5, s22, -v0
	v_fmac_f32_e32 v0, 0xb2a5705f, v5
	v_add_f32_e32 v0, v2, v0
	v_cvt_i32_f32_e32 v1, v1
	v_exp_f32_e32 v0, v0
	v_cmp_nlt_f32_e32 vcc, s23, v5
	s_mov_b32 s14, 0x3f2aaaab
	v_and_b32_e32 v186, 0xffffffc0, v222
	v_ldexp_f32 v0, v0, v1
	v_cndmask_b32_e32 v0, 0, v0, vcc
	v_cmp_ngt_f32_e32 vcc, s20, v5
	v_and_b32_e32 v223, 15, v221
	v_and_b32_e32 v180, 48, v221
	v_cndmask_b32_e32 v5, v205, v0, vcc
	v_add_f32_e32 v2, 1.0, v5
	v_cvt_f64_f32_e32 v[0:1], v2
	v_frexp_exp_i32_f64_e32 v0, v[0:1]
	v_frexp_mant_f32_e32 v1, v2
	v_cmp_gt_f32_e32 vcc, s14, v1
	v_add_f32_e32 v6, -1.0, v2
	v_sub_f32_e32 v7, v5, v6
	v_subbrev_co_u32_e32 v1, vcc, 0, v0, vcc
	v_cvt_f32_i32_e32 v0, v1
	v_sub_u32_e32 v1, 0, v1
	v_ldexp_f32 v3, v2, v1
	v_sub_f32_e32 v2, v6, v2
	v_add_f32_e32 v2, 1.0, v2
	v_add_f32_e32 v9, -1.0, v3
	v_add_f32_e32 v2, v7, v2
	v_ldexp_f32 v1, v2, v1
	v_add_f32_e32 v2, 1.0, v9
	v_sub_f32_e32 v2, v3, v2
	v_add_f32_e32 v10, v1, v2
	v_add_f32_e32 v2, 1.0, v3
	v_add_f32_e32 v6, -1.0, v2
	v_sub_f32_e32 v3, v3, v6
	v_add_f32_e32 v1, v1, v3
	v_add_f32_e32 v12, v2, v1
	v_rcp_f32_e32 v13, v12
	v_add_f32_e32 v3, v9, v10
	v_sub_f32_e32 v2, v2, v12
	v_add_f32_e32 v1, v1, v2
	v_mul_f32_e32 v14, v3, v13
	v_mul_f32_e32 v6, v12, v14
	v_fma_f32 v8, v14, v12, -v6
	v_fmac_f32_e32 v8, v14, v1
	v_add_f32_e32 v2, v6, v8
	v_sub_f32_e32 v7, v3, v2
	v_sub_f32_e32 v9, v9, v3
	v_add_f32_e32 v15, v10, v9
	v_sub_f32_e32 v10, v2, v6
	v_sub_f32_e32 v11, v3, v7
	v_mov_b32_e32 v9, v2
	v_sub_f32_e32 v2, v10, v8
	v_sub_f32_e32 v3, v11, v9
	s_mov_b32 s14, 0x3f317218
	v_add_f32_e32 v3, v15, v3
	v_add_f32_e32 v10, v2, v3
	v_add_f32_e32 v3, v7, v10
	v_mul_f32_e32 v2, v13, v3
	v_add_f32_e32 v15, v14, v2
	v_sub_f32_e32 v6, v15, v14
	v_mul_f32_e32 v8, v12, v2
	v_sub_f32_e32 v14, v2, v6
	v_fma_f32 v6, v2, v12, -v8
	v_fmac_f32_e32 v6, v2, v1
	v_add_f32_e32 v2, v8, v6
	v_sub_f32_e32 v9, v3, v2
	v_sub_f32_e32 v1, v7, v3
	v_add_f32_e32 v1, v10, v1
	v_sub_f32_e32 v10, v2, v8
	v_sub_f32_e32 v11, v3, v9
	v_mov_b32_e32 v7, v2
	v_sub_f32_e32 v2, v10, v6
	v_sub_f32_e32 v3, v11, v7
	s_cmp_eq_u32 s6, 0
	v_add_f32_e32 v1, v1, v3
	v_add_f32_e32 v1, v2, v1
	v_add_f32_e32 v1, v9, v1
	v_mul_f32_e32 v1, v13, v1
	v_add_f32_e32 v2, v14, v1
	v_add_f32_e32 v6, v15, v2
	v_mul_f32_e32 v7, v6, v6
	v_fmamk_f32 v8, v7, 0x3e9b6dac, v192
	v_ldexp_f32 v3, v6, 1
	v_mul_f32_e32 v1, v6, v7
	v_fmaak_f32 v183, v7, v8, 0x3f2aaada
	v_sub_f32_e32 v6, v6, v15
	v_sub_f32_e32 v2, v2, v6
	v_mul_f32_e32 v6, v0, v182
	v_mul_f32_e32 v7, v1, v183
	v_ldexp_f32 v8, v2, 1
	v_fma_f32 v2, v0, s14, -v6
	v_fmac_f32_e32 v2, 0xb102e308, v0
	v_add_f32_e32 v0, v6, v2
	v_add_f32_e32 v1, v7, v3
	s_mov_b32 s14, 0x7f800000
	v_sub_f32_e32 v3, v1, v3
	v_sub_f32_e32 v3, v7, v3
	v_add_f32_e32 v9, v8, v3
	v_mov_b32_e32 v8, v6
	v_sub_f32_e32 v6, v0, v6
	v_sub_f32_e32 v7, v1, v7
	v_add_f32_e32 v10, v0, v8
	v_add_f32_e32 v11, v1, v9
	v_mov_b32_e32 v3, v0
	v_mov_b32_e32 v7, v11
	v_sub_f32_e32 v12, v2, v6
	v_sub_f32_e32 v13, v3, v7
	v_add_f32_e32 v2, v2, v6
	v_add_f32_e32 v3, v3, v7
	v_mov_b32_e32 v8, v9
	v_sub_f32_e32 v6, v3, v0
	v_sub_f32_e32 v7, v2, v1
	v_sub_f32_e32 v14, v10, v6
	v_sub_f32_e32 v15, v11, v6
	v_mov_b32_e32 v10, v11
	v_mov_b32_e32 v11, v3
	v_pk_mov_b32 v[6:7], v[0:1], v[6:7] op_sel:[1,0]
	v_mov_b32_e32 v9, v0
	v_sub_f32_e32 v6, v10, v6
	v_sub_f32_e32 v7, v11, v7
	v_mov_b32_e32 v14, v12
	v_sub_f32_e32 v0, v8, v6
	v_sub_f32_e32 v1, v9, v7
	v_mov_b32_e32 v13, v3
	v_add_f32_e32 v6, v14, v0
	v_add_f32_e32 v7, v15, v1
	v_cmp_neq_f32_e32 vcc, s14, v5
	v_add_f32_e32 v8, v6, v7
	v_add_f32_e32 v9, v7, v6
	s_mov_b32 s14, 0x33800000
	v_pk_add_f32 v[2:3], v[2:3], v[8:9] op_sel:[1,0] op_sel_hi:[0,1]
	v_mov_b32_e32 v7, v2
	v_sub_f32_e32 v10, v6, v12
	v_sub_f32_e32 v11, v7, v13
	v_mov_b32_e32 v1, v8
	v_sub_f32_e32 v3, v6, v10
	v_sub_f32_e32 v0, v0, v10
	v_sub_f32_e32 v1, v1, v11
	v_sub_f32_e32 v3, v12, v3
	v_add_f32_e32 v0, v0, v3
	v_add_f32_e32 v0, v0, v1
	v_add_f32_e32 v0, v2, v0
	v_cndmask_b32_e32 v0, v205, v0, vcc
	v_cmp_lt_f32_e64 vcc, |v5|, s14
	v_lshl_add_u32 v2, s18, 8, v186
	v_or_b32_e32 v2, v2, v223
	v_cndmask_b32_e32 v0, v0, v5, vcc
	v_mul_f32_e32 v187, 0xbfb8aa3b, v0
	ds_read_b64 v[0:1], v4 offset:256
	v_ashrrev_i32_e32 v3, 31, v2
	v_lshlrev_b64 v[2:3], 14, v[2:3]
	v_bfe_u32 v183, v221, 4, 2
	v_lshlrev_b32_e32 v224, 3, v183
	s_waitcnt lgkmcnt(0)
; #define MFMA(a, b, c) __builtin_amdgcn_mfma_f32_16x16x32_bf16((a), (b), (c), 0, 0, 0)
; DEV float bflo(unsigned u) { return __uint_as_float(u << 16); }
; DEV float bfhi(unsigned u) { return __uint_as_float(u & 0xffff0000u); }
; #define DMA_WAIT_SYNC() do { asm volatile("s_waitcnt vmcnt(0)" ::: "memory"); __syncthreads(); } while (0)
; #define P (*launderP(lp))
; __device__ __forceinline__ void ret_kv_item(PREF P, int w, u16* ST, char* smem) {
;     ...
;   u32x4 vraw[4][4];
;   {
;     const u16* vbase = P.VrT + (size_t)(h * 256 + wid * 64 + l15) * TS + tok0 + q * 8;
; #pragma unroll
;     for (int kk = 0; kk < 4; ++kk)
; #pragma unroll
;       for (int jd = 0; jd < 4; ++jd) vraw[kk][jd] = *(const u32x4*)(vbase + (size_t)jd * 16 * TS + kk * 32);
;   }
;   f32x4 acc[8][4];
; #pragma unroll
;   for (int a = 0; a < 8; ++a)
; #pragma unroll
;     for (int b = 0; b < 4; ++b) acc[a][b] = f32x4{0.f, 0.f, 0.f, 0.f};
;   DMA_WAIT_SYNC();
; #pragma unroll
;   for (int kk = 0; kk < 4; ++kk) {
;     const int tb = kk * 32 + q * 8;
;     float z[8];
; #pragma unroll
;     for (int e = 0; e < 8; ++e) {
;       int t = tb + e;
;       z[e] = __builtin_amdgcn_exp2f(l2 * (float)(dir == 0 ? 127 - t : t));
;     }
;     bf16x8 vb[4];
; #pragma unroll
;     for (int jd = 0; jd < 4; ++jd) {
;       u32x4 raw = vraw[kk][jd];
;       u32x4 o;
;       o.x = pack2(bflo(raw.x) * z[0], bfhi(raw.x) * z[1]);
;       o.y = pack2(bflo(raw.y) * z[2], bfhi(raw.y) * z[3]);
;       o.z = pack2(bflo(raw.z) * z[4], bfhi(raw.z) * z[5]);
;       o.w = pack2(bflo(raw.w) * z[6], bfhi(raw.w) * z[7]);
;       vb[jd] = __builtin_bit_cast(bf16x8, o);
;     }
; #pragma unroll
;     for (int ik = 0; ik < 8; ++ik) {
;       bf16x8 ka = rd128(smem, ik * 16 + l15, kk * 4 + q);
; #pragma unroll
;       for (int jd = 0; jd < 4; ++jd) acc[ik][jd] = MFMA(ka, vb[jd], acc[ik][jd]);
	v_lshl_add_u64 v[0:1], v[0:1], 0, v[2:3]
	v_lshl_add_u64 v[0:1], s[0:1], 1, v[0:1]
	v_lshl_add_u64 v[0:1], v[0:1], 0, v[180:181]
	flat_load_dwordx4 v[48:51], v[0:1]
	s_mov_b32 s0, 0x40000
	v_add_co_u32_e32 v2, vcc, s0, v0
	s_mov_b32 s0, 0x80000
	s_nop 0
	v_addc_co_u32_e32 v3, vcc, 0, v1, vcc
	v_add_co_u32_e32 v4, vcc, s0, v0
	s_mov_b32 s0, 0xc0000
	s_nop 0
	v_addc_co_u32_e32 v5, vcc, 0, v1, vcc
	v_add_co_u32_e32 v64, vcc, s0, v0
	v_lshlrev_b32_e32 v180, 8, v223
	s_nop 0
	v_addc_co_u32_e32 v65, vcc, 0, v1, vcc
	flat_load_dwordx4 v[44:47], v[0:1] offset:64
	flat_load_dwordx4 v[52:55], v[2:3]
	flat_load_dwordx4 v[40:43], v[2:3] offset:64
	flat_load_dwordx4 v[56:59], v[4:5]
	flat_load_dwordx4 v[36:39], v[4:5] offset:64
	flat_load_dwordx4 v[60:63], v[64:65]
	flat_load_dwordx4 v[32:35], v[64:65] offset:64
	flat_load_dwordx4 v[28:31], v[0:1] offset:128
	flat_load_dwordx4 v[12:15], v[0:1] offset:192
	flat_load_dwordx4 v[24:27], v[2:3] offset:128
	flat_load_dwordx4 v[8:11], v[2:3] offset:192
	flat_load_dwordx4 v[20:23], v[4:5] offset:128
	s_nop 0
	flat_load_dwordx4 v[4:7], v[4:5] offset:192
	s_nop 0
	flat_load_dwordx4 v[16:19], v[64:65] offset:128
	flat_load_dwordx4 v[0:3], v[64:65] offset:192
	v_xor_b32_e32 v64, 0x7f, v224
	s_cselect_b64 vcc, -1, 0
	v_cndmask_b32_e32 v64, v224, v64, vcc
	v_cvt_f32_ubyte0_e32 v64, v64
	v_mul_f32_e32 v64, v187, v64
	v_exp_f32_e32 v68, v64
	v_or_b32_e32 v64, 1, v224
	v_xor_b32_e32 v65, 0x7e, v224
	v_cndmask_b32_e32 v64, v64, v65, vcc
	v_cvt_f32_ubyte0_e32 v64, v64
	v_mul_f32_e32 v64, v187, v64
	v_exp_f32_e32 v69, v64
	v_or_b32_e32 v64, 2, v224
	v_xor_b32_e32 v65, 0x7d, v224
	v_cndmask_b32_e32 v64, v64, v65, vcc
	v_cvt_f32_ubyte0_e32 v64, v64
	v_mul_f32_e32 v64, v187, v64
	v_exp_f32_e32 v70, v64
	v_or_b32_e32 v64, 3, v224
	v_xor_b32_e32 v65, 0x7c, v224
	v_cndmask_b32_e32 v64, v64, v65, vcc
	v_cvt_f32_ubyte0_e32 v64, v64
	v_mul_f32_e32 v64, v187, v64
	v_exp_f32_e32 v71, v64
	v_or_b32_e32 v64, 4, v224
	v_xor_b32_e32 v65, 0x7b, v224
	v_cndmask_b32_e32 v64, v64, v65, vcc
	v_cvt_f32_ubyte0_e32 v64, v64
	v_mul_f32_e32 v64, v187, v64
	v_exp_f32_e32 v72, v64
	v_or_b32_e32 v64, 5, v224
	v_xor_b32_e32 v65, 0x7a, v224
	v_cndmask_b32_e32 v64, v64, v65, vcc
	v_cvt_f32_ubyte0_e32 v64, v64
	v_mul_f32_e32 v64, v187, v64
	v_exp_f32_e32 v73, v64
	v_or_b32_e32 v64, 6, v224
	v_xor_b32_e32 v65, 0x79, v224
	v_cndmask_b32_e32 v64, v64, v65, vcc
	v_cvt_f32_ubyte0_e32 v64, v64
	v_mul_f32_e32 v64, v187, v64
	v_exp_f32_e32 v74, v64
	v_or_b32_e32 v64, 7, v224
	v_xor_b32_e32 v65, 0x78, v224
	v_cndmask_b32_e32 v64, v64, v65, vcc
	v_cvt_f32_ubyte0_e32 v64, v64
	v_mul_f32_e32 v64, v187, v64
	v_exp_f32_e32 v75, v64
	s_waitcnt vmcnt(0)
	s_waitcnt lgkmcnt(0)
	s_barrier
	s_and_b32 s0, s44, -16
	s_lshl_b32 s1, s18, 1
	s_or_b32 s0, s1, s0
	s_or_b32 s0, s0, s6
	s_ashr_i32 s1, s0, 31
	s_lshl_b64 s[0:1], s[0:1], 16
	s_waitcnt vmcnt(0)
	v_lshlrev_b32_e32 v64, 16, v48
	v_and_b32_e32 v65, 0xffff0000, v48
	v_lshlrev_b32_e32 v48, 16, v49
	v_and_b32_e32 v49, 0xffff0000, v49
	v_mul_f32_e32 v48, v70, v48
	v_mul_f32_e32 v49, v71, v49
	v_mul_f32_e32 v64, v68, v64
	v_mul_f32_e32 v65, v69, v65
	v_cvt_pk_bf16_f32 v161, v48, v49
	v_lshlrev_b32_e32 v48, 16, v50
	v_and_b32_e32 v49, 0xffff0000, v50
	v_mul_f32_e32 v48, v72, v48
	v_mul_f32_e32 v49, v73, v49
	v_bitop3_b32 v50, v183, v221, 15 bitop3:0x78
	v_cvt_pk_bf16_f32 v162, v48, v49
	v_lshlrev_b32_e32 v48, 16, v51
	v_and_b32_e32 v49, 0xffff0000, v51
	v_mul_f32_e32 v48, v74, v48
	v_mul_f32_e32 v49, v75, v49
	v_lshl_or_b32 v225, v50, 4, v180
	v_cvt_pk_bf16_f32 v163, v48, v49
	v_lshlrev_b32_e32 v48, 16, v52
	v_and_b32_e32 v49, 0xffff0000, v52
	v_mul_f32_e32 v48, v68, v48
	v_mul_f32_e32 v49, v69, v49
	v_cvt_pk_bf16_f32 v160, v64, v65
	v_cvt_pk_bf16_f32 v164, v48, v49
	v_lshlrev_b32_e32 v48, 16, v53
	v_and_b32_e32 v49, 0xffff0000, v53
	v_mul_f32_e32 v48, v70, v48
	v_mul_f32_e32 v49, v71, v49
	ds_read_b128 v[64:67], v225
	ds_read_b128 v[76:79], v225 offset:4096
	v_cvt_pk_bf16_f32 v165, v48, v49
	v_lshlrev_b32_e32 v48, 16, v54
	v_and_b32_e32 v49, 0xffff0000, v54
	v_mul_f32_e32 v48, v72, v48
	v_mul_f32_e32 v49, v73, v49
	ds_read_b128 v[92:95], v225 offset:8192
	ds_read_b128 v[108:111], v225 offset:12288
	v_cvt_pk_bf16_f32 v166, v48, v49
	v_lshlrev_b32_e32 v48, 16, v55
	v_and_b32_e32 v49, 0xffff0000, v55
	v_mul_f32_e32 v48, v74, v48
	v_mul_f32_e32 v49, v75, v49
	ds_read_b128 v[124:127], v225 offset:16384
	ds_read_b128 v[140:143], v225 offset:20480
	v_cvt_pk_bf16_f32 v167, v48, v49
	v_lshlrev_b32_e32 v48, 16, v56
	v_and_b32_e32 v49, 0xffff0000, v56
	v_mul_f32_e32 v48, v68, v48
	v_mul_f32_e32 v49, v69, v49
	ds_read_b128 v[156:159], v225 offset:24576
	ds_read_b128 v[226:229], v225 offset:28672
	v_cvt_pk_bf16_f32 v168, v48, v49
	v_lshlrev_b32_e32 v48, 16, v57
	v_and_b32_e32 v49, 0xffff0000, v57
	v_mul_f32_e32 v48, v70, v48
	v_mul_f32_e32 v49, v71, v49
	v_lshlrev_b32_e32 v56, 16, v62
	v_cvt_pk_bf16_f32 v169, v48, v49
	v_lshlrev_b32_e32 v48, 16, v58
	v_and_b32_e32 v49, 0xffff0000, v58
	v_mul_f32_e32 v48, v72, v48
	v_mul_f32_e32 v49, v73, v49
	v_and_b32_e32 v57, 0xffff0000, v62
	v_cvt_pk_bf16_f32 v170, v48, v49
	v_lshlrev_b32_e32 v48, 16, v59
	v_and_b32_e32 v49, 0xffff0000, v59
	v_mul_f32_e32 v48, v74, v48
	v_mul_f32_e32 v49, v75, v49
	v_mul_f32_e32 v56, v72, v56
	v_mul_f32_e32 v57, v73, v57
	v_cvt_pk_bf16_f32 v171, v48, v49
	v_lshlrev_b32_e32 v48, 16, v60
	v_and_b32_e32 v49, 0xffff0000, v60
	v_mul_f32_e32 v48, v68, v48
	v_mul_f32_e32 v49, v69, v49
	v_lshlrev_b32_e32 v60, 16, v63
	v_cvt_pk_bf16_f32 v172, v48, v49
	v_lshlrev_b32_e32 v48, 16, v61
	v_and_b32_e32 v49, 0xffff0000, v61
	v_and_b32_e32 v61, 0xffff0000, v63
	v_mul_f32_e32 v52, v70, v48
	v_mul_f32_e32 v53, v71, v49
	v_mul_f32_e32 v60, v74, v60
	v_mul_f32_e32 v61, v75, v61
	v_cvt_pk_bf16_f32 v173, v52, v53
	v_cvt_pk_bf16_f32 v174, v56, v57
	v_cvt_pk_bf16_f32 v175, v60, v61
	s_waitcnt lgkmcnt(7)
; #define MFMA(a, b, c) __builtin_amdgcn_mfma_f32_16x16x32_bf16((a), (b), (c), 0, 0, 0)
; DEV float bflo(unsigned u) { return __uint_as_float(u << 16); }
; DEV float bfhi(unsigned u) { return __uint_as_float(u & 0xffff0000u); }
; __device__ __forceinline__ void ret_kv_item(PREF P, int w, u16* ST, char* smem) {
;     ...
;   for (int kk = 0; kk < 4; ++kk) {
;     const int tb = kk * 32 + q * 8;
;     float z[8];
; #pragma unroll
;     for (int e = 0; e < 8; ++e) {
;       int t = tb + e;
;       z[e] = __builtin_amdgcn_exp2f(l2 * (float)(dir == 0 ? 127 - t : t));
;     }
;     bf16x8 vb[4];
; #pragma unroll
;     for (int jd = 0; jd < 4; ++jd) {
;       u32x4 raw = vraw[kk][jd];
;       u32x4 o;
;       o.x = pack2(bflo(raw.x) * z[0], bfhi(raw.x) * z[1]);
;       o.y = pack2(bflo(raw.y) * z[2], bfhi(raw.y) * z[3]);
;       o.z = pack2(bflo(raw.z) * z[4], bfhi(raw.z) * z[5]);
;       o.w = pack2(bflo(raw.w) * z[6], bfhi(raw.w) * z[7]);
;       vb[jd] = __builtin_bit_cast(bf16x8, o);
;     }
; #pragma unroll
;     for (int ik = 0; ik < 8; ++ik) {
;       bf16x8 ka = rd128(smem, ik * 16 + l15, kk * 4 + q);
; #pragma unroll
;       for (int jd = 0; jd < 4; ++jd) acc[ik][jd] = MFMA(ka, vb[jd], acc[ik][jd]);
	v_mfma_f32_16x16x32_bf16 v[48:51], v[64:67], v[160:163], 0
	v_or_b32_e32 v225, 32, v224
	v_mfma_f32_16x16x32_bf16 v[52:55], v[64:67], v[164:167], 0
	v_mfma_f32_16x16x32_bf16 v[56:59], v[64:67], v[168:171], 0
	v_mfma_f32_16x16x32_bf16 v[60:63], v[64:67], v[172:175], 0
	s_waitcnt lgkmcnt(6)
	v_mfma_f32_16x16x32_bf16 v[64:67], v[76:79], v[160:163], 0
	v_mfma_f32_16x16x32_bf16 v[68:71], v[76:79], v[164:167], 0
	v_mfma_f32_16x16x32_bf16 v[72:75], v[76:79], v[168:171], 0
	v_mfma_f32_16x16x32_bf16 v[76:79], v[76:79], v[172:175], 0
	s_waitcnt lgkmcnt(5)
	v_mfma_f32_16x16x32_bf16 v[80:83], v[92:95], v[160:163], 0
	v_mfma_f32_16x16x32_bf16 v[84:87], v[92:95], v[164:167], 0
	v_mfma_f32_16x16x32_bf16 v[88:91], v[92:95], v[168:171], 0
	v_mfma_f32_16x16x32_bf16 v[92:95], v[92:95], v[172:175], 0
	s_waitcnt lgkmcnt(4)
	v_mfma_f32_16x16x32_bf16 v[96:99], v[108:111], v[160:163], 0
	v_mfma_f32_16x16x32_bf16 v[100:103], v[108:111], v[164:167], 0
	v_mfma_f32_16x16x32_bf16 v[104:107], v[108:111], v[168:171], 0
	v_mfma_f32_16x16x32_bf16 v[108:111], v[108:111], v[172:175], 0
	s_waitcnt lgkmcnt(3)
	v_mfma_f32_16x16x32_bf16 v[112:115], v[124:127], v[160:163], 0
	v_mfma_f32_16x16x32_bf16 v[116:119], v[124:127], v[164:167], 0
	v_mfma_f32_16x16x32_bf16 v[120:123], v[124:127], v[168:171], 0
	v_mfma_f32_16x16x32_bf16 v[124:127], v[124:127], v[172:175], 0
	s_waitcnt lgkmcnt(2)
	v_mfma_f32_16x16x32_bf16 v[128:131], v[140:143], v[160:163], 0
	v_mfma_f32_16x16x32_bf16 v[132:135], v[140:143], v[164:167], 0
	v_mfma_f32_16x16x32_bf16 v[136:139], v[140:143], v[168:171], 0
	v_mfma_f32_16x16x32_bf16 v[140:143], v[140:143], v[172:175], 0
	s_waitcnt lgkmcnt(1)
	v_mfma_f32_16x16x32_bf16 v[144:147], v[156:159], v[160:163], 0
	v_mfma_f32_16x16x32_bf16 v[148:151], v[156:159], v[164:167], 0
	v_mfma_f32_16x16x32_bf16 v[152:155], v[156:159], v[168:171], 0
	v_mfma_f32_16x16x32_bf16 v[156:159], v[156:159], v[172:175], 0
	s_waitcnt lgkmcnt(0)
	v_mfma_f32_16x16x32_bf16 v[160:163], v[226:229], v[160:163], 0
	v_mfma_f32_16x16x32_bf16 v[164:167], v[226:229], v[164:167], 0
	v_mfma_f32_16x16x32_bf16 v[168:171], v[226:229], v[168:171], 0
	v_mfma_f32_16x16x32_bf16 v[172:175], v[226:229], v[172:175], 0
	v_xor_b32_e32 v226, 0x5f, v224
	v_cndmask_b32_e32 v225, v225, v226, vcc
	v_cvt_f32_ubyte0_e32 v225, v225
	v_mul_f32_e32 v225, v187, v225
	v_exp_f32_e32 v242, v225
	v_or_b32_e32 v225, 33, v224
	v_xor_b32_e32 v226, 0x5e, v224
	v_cndmask_b32_e32 v225, v225, v226, vcc
	v_cvt_f32_ubyte0_e32 v225, v225
	v_mul_f32_e32 v225, v187, v225
	v_exp_f32_e32 v243, v225
	v_or_b32_e32 v225, 34, v224
	v_xor_b32_e32 v226, 0x5d, v224
	v_cndmask_b32_e32 v225, v225, v226, vcc
	v_cvt_f32_ubyte0_e32 v225, v225
	v_mul_f32_e32 v225, v187, v225
	v_exp_f32_e32 v244, v225
	v_or_b32_e32 v225, 35, v224
	v_xor_b32_e32 v226, 0x5c, v224
	v_cndmask_b32_e32 v225, v225, v226, vcc
	v_cvt_f32_ubyte0_e32 v225, v225
	v_mul_f32_e32 v225, v187, v225
	v_exp_f32_e32 v245, v225
	v_or_b32_e32 v225, 36, v224
	v_xor_b32_e32 v226, 0x5b, v224
	v_cndmask_b32_e32 v225, v225, v226, vcc
	v_cvt_f32_ubyte0_e32 v225, v225
	v_mul_f32_e32 v225, v187, v225
	v_exp_f32_e32 v246, v225
	v_or_b32_e32 v225, 37, v224
	v_xor_b32_e32 v226, 0x5a, v224
	v_cndmask_b32_e32 v225, v225, v226, vcc
	v_cvt_f32_ubyte0_e32 v225, v225
	v_mul_f32_e32 v225, v187, v225
	v_exp_f32_e32 v247, v225
	v_or_b32_e32 v225, 38, v224
	v_xor_b32_e32 v226, 0x59, v224
	v_cndmask_b32_e32 v225, v225, v226, vcc
	v_cvt_f32_ubyte0_e32 v225, v225
	v_mul_f32_e32 v225, v187, v225
	v_exp_f32_e32 v248, v225
	v_or_b32_e32 v225, 39, v224
	v_xor_b32_e32 v226, 0x58, v224
	v_cndmask_b32_e32 v225, v225, v226, vcc
	v_cvt_f32_ubyte0_e32 v225, v225
	v_mul_f32_e32 v225, v187, v225
	v_lshlrev_b32_e32 v226, 16, v44
	v_and_b32_e32 v227, 0xffff0000, v44
	v_lshlrev_b32_e32 v44, 16, v45
	v_and_b32_e32 v45, 0xffff0000, v45
	v_exp_f32_e32 v249, v225
	v_mul_f32_e32 v226, v242, v226
	v_mul_f32_e32 v227, v243, v227
	v_mul_f32_e32 v44, v244, v44
	v_mul_f32_e32 v45, v245, v45
	v_cvt_pk_bf16_f32 v226, v226, v227
	v_cvt_pk_bf16_f32 v227, v44, v45
	v_lshlrev_b32_e32 v44, 16, v46
	v_and_b32_e32 v45, 0xffff0000, v46
	v_mul_f32_e32 v44, v246, v44
	v_mul_f32_e32 v45, v247, v45
	s_nop 0
	v_cvt_pk_bf16_f32 v228, v44, v45
	v_lshlrev_b32_e32 v44, 16, v47
	v_and_b32_e32 v45, 0xffff0000, v47
	v_mul_f32_e32 v44, v248, v44
	v_mul_f32_e32 v45, v249, v45
	s_nop 0
	v_cvt_pk_bf16_f32 v229, v44, v45
	v_lshlrev_b32_e32 v44, 16, v40
	v_and_b32_e32 v45, 0xffff0000, v40
	v_lshlrev_b32_e32 v40, 16, v41
	v_and_b32_e32 v41, 0xffff0000, v41
	v_mul_f32_e32 v40, v244, v40
	v_mul_f32_e32 v41, v245, v41
	v_mul_f32_e32 v44, v242, v44
	v_mul_f32_e32 v45, v243, v45
	v_cvt_pk_bf16_f32 v231, v40, v41
	v_lshlrev_b32_e32 v40, 16, v42
	v_and_b32_e32 v41, 0xffff0000, v42
	v_mul_f32_e32 v40, v246, v40
	v_mul_f32_e32 v41, v247, v41
	v_cvt_pk_bf16_f32 v230, v44, v45
	v_cvt_pk_bf16_f32 v232, v40, v41
	v_lshlrev_b32_e32 v40, 16, v43
	v_and_b32_e32 v41, 0xffff0000, v43
	v_mul_f32_e32 v40, v248, v40
	v_mul_f32_e32 v41, v249, v41
	s_nop 0
	v_cvt_pk_bf16_f32 v233, v40, v41
	v_lshlrev_b32_e32 v40, 16, v36
	v_and_b32_e32 v41, 0xffff0000, v36
	v_lshlrev_b32_e32 v36, 16, v37
	v_and_b32_e32 v37, 0xffff0000, v37
	v_mul_f32_e32 v36, v244, v36
	v_mul_f32_e32 v37, v245, v37
	v_mul_f32_e32 v40, v242, v40
	v_mul_f32_e32 v41, v243, v41
	v_cvt_pk_bf16_f32 v235, v36, v37
	v_lshlrev_b32_e32 v36, 16, v38
	v_and_b32_e32 v37, 0xffff0000, v38
	v_bitop3_b32 v38, v183, v223, 4 bitop3:0x36
	v_mul_f32_e32 v36, v246, v36
	v_mul_f32_e32 v37, v247, v37
	v_lshl_or_b32 v225, v38, 4, v180
	v_cvt_pk_bf16_f32 v236, v36, v37
	v_lshlrev_b32_e32 v36, 16, v39
	v_and_b32_e32 v37, 0xffff0000, v39
	ds_read_b128 v[238:241], v225
	v_mul_f32_e32 v36, v248, v36
	v_mul_f32_e32 v37, v249, v37
	v_cvt_pk_bf16_f32 v234, v40, v41
	v_cvt_pk_bf16_f32 v237, v36, v37
	v_lshlrev_b32_e32 v36, 16, v32
	v_and_b32_e32 v37, 0xffff0000, v32
	v_lshlrev_b32_e32 v32, 16, v33
	v_and_b32_e32 v33, 0xffff0000, v33
	v_mul_f32_e32 v32, v244, v32
	v_mul_f32_e32 v33, v245, v33
	v_mul_f32_e32 v36, v242, v36
	v_mul_f32_e32 v37, v243, v37
	v_cvt_pk_bf16_f32 v243, v32, v33
	v_lshlrev_b32_e32 v32, 16, v34
	v_and_b32_e32 v33, 0xffff0000, v34
	v_mul_f32_e32 v32, v246, v32
	v_mul_f32_e32 v33, v247, v33
	v_cvt_pk_bf16_f32 v242, v36, v37
	v_cvt_pk_bf16_f32 v244, v32, v33
	v_lshlrev_b32_e32 v32, 16, v35
	v_and_b32_e32 v33, 0xffff0000, v35
	v_mul_f32_e32 v32, v248, v32
	v_mul_f32_e32 v33, v249, v33
	s_waitcnt lgkmcnt(0)
; #define MFMA(a, b, c) __builtin_amdgcn_mfma_f32_16x16x32_bf16((a), (b), (c), 0, 0, 0)
; DEV float bflo(unsigned u) { return __uint_as_float(u << 16); }
; DEV float bfhi(unsigned u) { return __uint_as_float(u & 0xffff0000u); }
; __device__ __forceinline__ void ret_kv_item(PREF P, int w, u16* ST, char* smem) {
;     ...
;   for (int kk = 0; kk < 4; ++kk) {
;     const int tb = kk * 32 + q * 8;
;     float z[8];
; #pragma unroll
;     for (int e = 0; e < 8; ++e) {
;       int t = tb + e;
;       z[e] = __builtin_amdgcn_exp2f(l2 * (float)(dir == 0 ? 127 - t : t));
;     }
;     bf16x8 vb[4];
; #pragma unroll
;     for (int jd = 0; jd < 4; ++jd) {
;       u32x4 raw = vraw[kk][jd];
;       u32x4 o;
;       o.x = pack2(bflo(raw.x) * z[0], bfhi(raw.x) * z[1]);
;       o.y = pack2(bflo(raw.y) * z[2], bfhi(raw.y) * z[3]);
;       o.z = pack2(bflo(raw.z) * z[4], bfhi(raw.z) * z[5]);
;       o.w = pack2(bflo(raw.w) * z[6], bfhi(raw.w) * z[7]);
;       vb[jd] = __builtin_bit_cast(bf16x8, o);
;     }
; #pragma unroll
;     for (int ik = 0; ik < 8; ++ik) {
;       bf16x8 ka = rd128(smem, ik * 16 + l15, kk * 4 + q);
; #pragma unroll
;       for (int jd = 0; jd < 4; ++jd) acc[ik][jd] = MFMA(ka, vb[jd], acc[ik][jd]);
	v_mfma_f32_16x16x32_bf16 v[36:39], v[238:241], v[226:229], v[48:51]
	v_cvt_pk_bf16_f32 v245, v32, v33
	s_nop 1
	v_mfma_f32_16x16x32_bf16 v[32:35], v[238:241], v[242:245], v[60:63]
	s_nop 2
	ds_read_b128 v[60:63], v225 offset:4096
	v_mfma_f32_16x16x32_bf16 v[40:43], v[238:241], v[230:233], v[52:55]
	v_mfma_f32_16x16x32_bf16 v[44:47], v[238:241], v[234:237], v[56:59]
	s_waitcnt lgkmcnt(0)
	v_mfma_f32_16x16x32_bf16 v[48:51], v[60:63], v[226:229], v[64:67]
	v_mfma_f32_16x16x32_bf16 v[52:55], v[60:63], v[230:233], v[68:71]
	v_mfma_f32_16x16x32_bf16 v[56:59], v[60:63], v[234:237], v[72:75]
	v_mfma_f32_16x16x32_bf16 v[60:63], v[60:63], v[242:245], v[76:79]
	s_nop 2
	ds_read_b128 v[76:79], v225 offset:8192
	s_waitcnt lgkmcnt(0)
	v_mfma_f32_16x16x32_bf16 v[64:67], v[76:79], v[226:229], v[80:83]
	v_mfma_f32_16x16x32_bf16 v[68:71], v[76:79], v[230:233], v[84:87]
	v_mfma_f32_16x16x32_bf16 v[72:75], v[76:79], v[234:237], v[88:91]
	v_mfma_f32_16x16x32_bf16 v[76:79], v[76:79], v[242:245], v[92:95]
	s_nop 2
	ds_read_b128 v[92:95], v225 offset:12288
	s_waitcnt lgkmcnt(0)
	v_mfma_f32_16x16x32_bf16 v[80:83], v[92:95], v[226:229], v[96:99]
	v_mfma_f32_16x16x32_bf16 v[84:87], v[92:95], v[230:233], v[100:103]
	v_mfma_f32_16x16x32_bf16 v[88:91], v[92:95], v[234:237], v[104:107]
	v_mfma_f32_16x16x32_bf16 v[92:95], v[92:95], v[242:245], v[108:111]
	s_nop 2
	ds_read_b128 v[108:111], v225 offset:16384
	s_waitcnt lgkmcnt(0)
	v_mfma_f32_16x16x32_bf16 v[96:99], v[108:111], v[226:229], v[112:115]
	v_mfma_f32_16x16x32_bf16 v[100:103], v[108:111], v[230:233], v[116:119]
	v_mfma_f32_16x16x32_bf16 v[104:107], v[108:111], v[234:237], v[120:123]
	v_mfma_f32_16x16x32_bf16 v[108:111], v[108:111], v[242:245], v[124:127]
	s_nop 2
	ds_read_b128 v[124:127], v225 offset:20480
	s_waitcnt lgkmcnt(0)
	v_mfma_f32_16x16x32_bf16 v[112:115], v[124:127], v[226:229], v[128:131]
	v_mfma_f32_16x16x32_bf16 v[116:119], v[124:127], v[230:233], v[132:135]
	v_mfma_f32_16x16x32_bf16 v[120:123], v[124:127], v[234:237], v[136:139]
	v_mfma_f32_16x16x32_bf16 v[124:127], v[124:127], v[242:245], v[140:143]
	s_nop 2
	ds_read_b128 v[140:143], v225 offset:24576
	s_waitcnt lgkmcnt(0)
	v_mfma_f32_16x16x32_bf16 v[128:131], v[140:143], v[226:229], v[144:147]
	v_mfma_f32_16x16x32_bf16 v[132:135], v[140:143], v[230:233], v[148:151]
	v_mfma_f32_16x16x32_bf16 v[136:139], v[140:143], v[234:237], v[152:155]
	v_mfma_f32_16x16x32_bf16 v[140:143], v[140:143], v[242:245], v[156:159]
	s_nop 2
	ds_read_b128 v[156:159], v225 offset:28672
	s_waitcnt lgkmcnt(0)
	v_mfma_f32_16x16x32_bf16 v[144:147], v[156:159], v[226:229], v[160:163]
	s_nop 2
	v_or_b32_e32 v160, 64, v224
	v_xor_b32_e32 v161, 63, v224
	v_cndmask_b32_e32 v160, v160, v161, vcc
	v_cvt_f32_ubyte0_e32 v160, v160
	v_mul_f32_e32 v160, v187, v160
	v_exp_f32_e32 v226, v160
	v_or_b32_e32 v160, 0x41, v224
	v_xor_b32_e32 v161, 62, v224
	v_cndmask_b32_e32 v160, v160, v161, vcc
	v_cvt_f32_ubyte0_e32 v160, v160
	v_mul_f32_e32 v160, v187, v160
	v_exp_f32_e32 v227, v160
	v_or_b32_e32 v160, 0x42, v224
	v_xor_b32_e32 v161, 61, v224
	v_cndmask_b32_e32 v160, v160, v161, vcc
	v_cvt_f32_ubyte0_e32 v160, v160
	v_mul_f32_e32 v160, v187, v160
	v_exp_f32_e32 v228, v160
	v_or_b32_e32 v160, 0x43, v224
	v_xor_b32_e32 v161, 60, v224
	v_cndmask_b32_e32 v160, v160, v161, vcc
	v_cvt_f32_ubyte0_e32 v160, v160
	v_mul_f32_e32 v160, v187, v160
	v_exp_f32_e32 v229, v160
	v_or_b32_e32 v160, 0x44, v224
	v_xor_b32_e32 v161, 59, v224
	v_cndmask_b32_e32 v160, v160, v161, vcc
	v_cvt_f32_ubyte0_e32 v160, v160
	v_mul_f32_e32 v160, v187, v160
	v_mfma_f32_16x16x32_bf16 v[148:151], v[156:159], v[230:233], v[164:167]
	v_exp_f32_e32 v230, v160
	v_or_b32_e32 v160, 0x45, v224
	v_xor_b32_e32 v161, 58, v224
	v_cndmask_b32_e32 v160, v160, v161, vcc
	v_cvt_f32_ubyte0_e32 v160, v160
	v_mul_f32_e32 v160, v187, v160
	v_exp_f32_e32 v231, v160
	v_or_b32_e32 v160, 0x46, v224
	v_xor_b32_e32 v161, 57, v224
	v_cndmask_b32_e32 v160, v160, v161, vcc
	v_cvt_f32_ubyte0_e32 v160, v160
	v_mul_f32_e32 v160, v187, v160
	v_exp_f32_e32 v232, v160
	v_or_b32_e32 v160, 0x47, v224
	v_xor_b32_e32 v161, 56, v224
	v_cndmask_b32_e32 v160, v160, v161, vcc
	v_cvt_f32_ubyte0_e32 v160, v160
	v_mul_f32_e32 v160, v187, v160
	v_exp_f32_e32 v233, v160
	v_lshlrev_b32_e32 v160, 16, v28
	v_and_b32_e32 v161, 0xffff0000, v28
	v_lshlrev_b32_e32 v28, 16, v29
	v_and_b32_e32 v29, 0xffff0000, v29
	v_mul_f32_e32 v160, v226, v160
	v_mul_f32_e32 v161, v227, v161
	v_mul_f32_e32 v28, v228, v28
	v_mul_f32_e32 v29, v229, v29
	v_cvt_pk_bf16_f32 v160, v160, v161
	v_cvt_pk_bf16_f32 v161, v28, v29
	v_lshlrev_b32_e32 v28, 16, v30
	v_and_b32_e32 v29, 0xffff0000, v30
	v_mul_f32_e32 v28, v230, v28
	v_mul_f32_e32 v29, v231, v29
	v_mfma_f32_16x16x32_bf16 v[152:155], v[156:159], v[234:237], v[168:171]
	v_cvt_pk_bf16_f32 v162, v28, v29
	v_lshlrev_b32_e32 v28, 16, v31
	v_and_b32_e32 v29, 0xffff0000, v31
	v_mul_f32_e32 v28, v232, v28
	v_mul_f32_e32 v29, v233, v29
	v_mfma_f32_16x16x32_bf16 v[156:159], v[156:159], v[242:245], v[172:175]
	v_cvt_pk_bf16_f32 v163, v28, v29
	v_lshlrev_b32_e32 v28, 16, v24
	v_and_b32_e32 v29, 0xffff0000, v24
	v_lshlrev_b32_e32 v24, 16, v25
	v_and_b32_e32 v25, 0xffff0000, v25
	v_mul_f32_e32 v24, v228, v24
	v_mul_f32_e32 v25, v229, v25
	v_mul_f32_e32 v28, v226, v28
	v_mul_f32_e32 v29, v227, v29
	v_cvt_pk_bf16_f32 v165, v24, v25
	v_lshlrev_b32_e32 v24, 16, v26
	v_and_b32_e32 v25, 0xffff0000, v26
	v_mul_f32_e32 v24, v230, v24
	v_mul_f32_e32 v25, v231, v25
	v_cvt_pk_bf16_f32 v164, v28, v29
	v_cvt_pk_bf16_f32 v166, v24, v25
	v_lshlrev_b32_e32 v24, 16, v27
	v_and_b32_e32 v25, 0xffff0000, v27
	v_mul_f32_e32 v24, v232, v24
	v_mul_f32_e32 v25, v233, v25
	v_lshlrev_b32_e32 v28, 16, v18
	v_cvt_pk_bf16_f32 v167, v24, v25
	v_lshlrev_b32_e32 v24, 16, v20
	v_and_b32_e32 v25, 0xffff0000, v20
	v_lshlrev_b32_e32 v20, 16, v21
	v_and_b32_e32 v21, 0xffff0000, v21
	v_mul_f32_e32 v20, v228, v20
	v_mul_f32_e32 v21, v229, v21
	v_mul_f32_e32 v24, v226, v24
	v_mul_f32_e32 v25, v227, v25
	v_cvt_pk_bf16_f32 v169, v20, v21
	v_lshlrev_b32_e32 v20, 16, v22
	v_and_b32_e32 v21, 0xffff0000, v22
	v_bitop3_b32 v22, v183, v223, 8 bitop3:0x36
	v_lshl_or_b32 v225, v22, 4, v180
	ds_read_b128 v[172:175], v225
	v_mul_f32_e32 v20, v230, v20
	v_mul_f32_e32 v21, v231, v21
	v_cvt_pk_bf16_f32 v168, v24, v25
	v_cvt_pk_bf16_f32 v170, v20, v21
	v_lshlrev_b32_e32 v20, 16, v23
	v_and_b32_e32 v21, 0xffff0000, v23
	v_mul_f32_e32 v20, v232, v20
	v_mul_f32_e32 v21, v233, v21
	v_and_b32_e32 v29, 0xffff0000, v18
	v_cvt_pk_bf16_f32 v171, v20, v21
	v_lshlrev_b32_e32 v20, 16, v16
	v_and_b32_e32 v21, 0xffff0000, v16
	v_mul_f32_e32 v20, v226, v20
	v_mul_f32_e32 v21, v227, v21
	v_mul_f32_e32 v28, v230, v28
	v_mul_f32_e32 v29, v231, v29
	v_cvt_pk_bf16_f32 v16, v20, v21
	v_lshlrev_b32_e32 v20, 16, v17
	v_and_b32_e32 v21, 0xffff0000, v17
	v_mul_f32_e32 v24, v228, v20
	v_mul_f32_e32 v25, v229, v21
	s_waitcnt lgkmcnt(0)
; #define MFMA(a, b, c) __builtin_amdgcn_mfma_f32_16x16x32_bf16((a), (b), (c), 0, 0, 0)
; DEV float bflo(unsigned u) { return __uint_as_float(u << 16); }
; DEV float bfhi(unsigned u) { return __uint_as_float(u & 0xffff0000u); }
; __device__ __forceinline__ void ret_kv_item(PREF P, int w, u16* ST, char* smem) {
;     ...
;   for (int kk = 0; kk < 4; ++kk) {
;     const int tb = kk * 32 + q * 8;
;     float z[8];
; #pragma unroll
;     for (int e = 0; e < 8; ++e) {
;       int t = tb + e;
;       z[e] = __builtin_amdgcn_exp2f(l2 * (float)(dir == 0 ? 127 - t : t));
;     }
;     bf16x8 vb[4];
; #pragma unroll
;     for (int jd = 0; jd < 4; ++jd) {
;       u32x4 raw = vraw[kk][jd];
;       u32x4 o;
;       o.x = pack2(bflo(raw.x) * z[0], bfhi(raw.x) * z[1]);
;       o.y = pack2(bflo(raw.y) * z[2], bfhi(raw.y) * z[3]);
;       o.z = pack2(bflo(raw.z) * z[4], bfhi(raw.z) * z[5]);
;       o.w = pack2(bflo(raw.w) * z[6], bfhi(raw.w) * z[7]);
;       vb[jd] = __builtin_bit_cast(bf16x8, o);
;     }
; #pragma unroll
;     for (int ik = 0; ik < 8; ++ik) {
;       bf16x8 ka = rd128(smem, ik * 16 + l15, kk * 4 + q);
; #pragma unroll
;       for (int jd = 0; jd < 4; ++jd) acc[ik][jd] = MFMA(ka, vb[jd], acc[ik][jd]);
	v_mfma_f32_16x16x32_bf16 v[20:23], v[172:175], v[160:163], v[36:39]
	v_cvt_pk_bf16_f32 v17, v24, v25
	v_cvt_pk_bf16_f32 v18, v28, v29
	s_nop 0
	v_lshlrev_b32_e32 v36, 16, v19
	v_and_b32_e32 v37, 0xffff0000, v19
	v_mul_f32_e32 v36, v232, v36
	v_mul_f32_e32 v37, v233, v37
	v_mfma_f32_16x16x32_bf16 v[24:27], v[172:175], v[164:167], v[40:43]
	v_cvt_pk_bf16_f32 v19, v36, v37
	v_mfma_f32_16x16x32_bf16 v[28:31], v[172:175], v[168:171], v[44:47]
	s_nop 0
	v_mfma_f32_16x16x32_bf16 v[32:35], v[172:175], v[16:19], v[32:35]
	ds_read_b128 v[172:175], v225 offset:4096
	s_waitcnt lgkmcnt(0)
	v_mfma_f32_16x16x32_bf16 v[36:39], v[172:175], v[160:163], v[48:51]
	v_mfma_f32_16x16x32_bf16 v[40:43], v[172:175], v[164:167], v[52:55]
	v_mfma_f32_16x16x32_bf16 v[44:47], v[172:175], v[168:171], v[56:59]
	v_mfma_f32_16x16x32_bf16 v[48:51], v[172:175], v[16:19], v[60:63]
	ds_read_b128 v[172:175], v225 offset:8192
	s_waitcnt lgkmcnt(0)
	v_mfma_f32_16x16x32_bf16 v[52:55], v[172:175], v[160:163], v[64:67]
	v_mfma_f32_16x16x32_bf16 v[56:59], v[172:175], v[164:167], v[68:71]
	v_mfma_f32_16x16x32_bf16 v[60:63], v[172:175], v[168:171], v[72:75]
	v_mfma_f32_16x16x32_bf16 v[64:67], v[172:175], v[16:19], v[76:79]
	ds_read_b128 v[172:175], v225 offset:12288
	s_waitcnt lgkmcnt(0)
	v_mfma_f32_16x16x32_bf16 v[68:71], v[172:175], v[160:163], v[80:83]
	v_mfma_f32_16x16x32_bf16 v[72:75], v[172:175], v[164:167], v[84:87]
	v_mfma_f32_16x16x32_bf16 v[76:79], v[172:175], v[168:171], v[88:91]
	v_mfma_f32_16x16x32_bf16 v[80:83], v[172:175], v[16:19], v[92:95]
	ds_read_b128 v[172:175], v225 offset:16384
	s_waitcnt lgkmcnt(0)
	v_mfma_f32_16x16x32_bf16 v[84:87], v[172:175], v[160:163], v[96:99]
	v_mfma_f32_16x16x32_bf16 v[88:91], v[172:175], v[164:167], v[100:103]
	v_mfma_f32_16x16x32_bf16 v[92:95], v[172:175], v[168:171], v[104:107]
	v_mfma_f32_16x16x32_bf16 v[96:99], v[172:175], v[16:19], v[108:111]
	ds_read_b128 v[172:175], v225 offset:20480
	s_waitcnt lgkmcnt(0)
	v_mfma_f32_16x16x32_bf16 v[100:103], v[172:175], v[160:163], v[112:115]
	v_mfma_f32_16x16x32_bf16 v[104:107], v[172:175], v[164:167], v[116:119]
	v_mfma_f32_16x16x32_bf16 v[108:111], v[172:175], v[168:171], v[120:123]
	v_mfma_f32_16x16x32_bf16 v[112:115], v[172:175], v[16:19], v[124:127]
	ds_read_b128 v[172:175], v225 offset:24576
	s_waitcnt lgkmcnt(0)
	v_mfma_f32_16x16x32_bf16 v[116:119], v[172:175], v[160:163], v[128:131]
	v_mfma_f32_16x16x32_bf16 v[120:123], v[172:175], v[164:167], v[132:135]
	v_mfma_f32_16x16x32_bf16 v[124:127], v[172:175], v[168:171], v[136:139]
	v_mfma_f32_16x16x32_bf16 v[128:131], v[172:175], v[16:19], v[140:143]
	ds_read_b128 v[172:175], v225 offset:28672
	s_waitcnt lgkmcnt(0)
	v_mfma_f32_16x16x32_bf16 v[132:135], v[172:175], v[160:163], v[144:147]
	s_nop 2
	v_or_b32_e32 v144, 0x60, v224
	v_xor_b32_e32 v145, 31, v224
	v_cndmask_b32_e32 v144, v144, v145, vcc
	v_cvt_f32_ubyte0_e32 v144, v144
	v_mul_f32_e32 v144, v187, v144
	v_mfma_f32_16x16x32_bf16 v[136:139], v[172:175], v[164:167], v[148:151]
	v_xor_b32_e32 v145, 30, v224
	s_nop 1
	v_exp_f32_e32 v148, v144
	v_or_b32_e32 v144, 0x61, v224
	v_cndmask_b32_e32 v144, v144, v145, vcc
	v_cvt_f32_ubyte0_e32 v144, v144
	v_mul_f32_e32 v144, v187, v144
	v_exp_f32_e32 v149, v144
	v_or_b32_e32 v144, 0x62, v224
	v_xor_b32_e32 v145, 29, v224
	v_cndmask_b32_e32 v144, v144, v145, vcc
	v_cvt_f32_ubyte0_e32 v144, v144
	v_mul_f32_e32 v144, v187, v144
	v_exp_f32_e32 v150, v144
	v_or_b32_e32 v144, 0x63, v224
	v_xor_b32_e32 v145, 28, v224
	v_cndmask_b32_e32 v144, v144, v145, vcc
	v_cvt_f32_ubyte0_e32 v144, v144
	v_mul_f32_e32 v144, v187, v144
	v_exp_f32_e32 v151, v144
	v_or_b32_e32 v144, 0x64, v224
	v_xor_b32_e32 v145, 27, v224
	v_cndmask_b32_e32 v144, v144, v145, vcc
	v_cvt_f32_ubyte0_e32 v144, v144
	v_mul_f32_e32 v144, v187, v144
	v_mfma_f32_16x16x32_bf16 v[140:143], v[172:175], v[168:171], v[152:155]
	v_xor_b32_e32 v145, 26, v224
	s_nop 1
	v_exp_f32_e32 v152, v144
	v_or_b32_e32 v144, 0x65, v224
	v_cndmask_b32_e32 v144, v144, v145, vcc
	v_cvt_f32_ubyte0_e32 v144, v144
	v_mul_f32_e32 v144, v187, v144
	v_exp_f32_e32 v153, v144
	v_or_b32_e32 v144, 0x66, v224
	v_xor_b32_e32 v145, 25, v224
	v_cndmask_b32_e32 v144, v144, v145, vcc
	v_cvt_f32_ubyte0_e32 v144, v144
	v_mul_f32_e32 v144, v187, v144
	v_exp_f32_e32 v154, v144
	v_or_b32_e32 v144, 0x67, v224
	v_xor_b32_e32 v145, 24, v224
	v_cndmask_b32_e32 v144, v144, v145, vcc
	v_cvt_f32_ubyte0_e32 v144, v144
	v_mul_f32_e32 v144, v187, v144
	v_exp_f32_e32 v155, v144
	v_lshlrev_b32_e32 v144, 16, v12
	v_and_b32_e32 v145, 0xffff0000, v12
	v_mul_f32_e32 v144, v148, v144
	v_mul_f32_e32 v145, v149, v145
	v_mfma_f32_16x16x32_bf16 v[16:19], v[172:175], v[16:19], v[156:159]
	v_cvt_pk_bf16_f32 v12, v144, v145
	v_lshlrev_b32_e32 v144, 16, v13
	v_and_b32_e32 v145, 0xffff0000, v13
	v_mul_f32_e32 v144, v150, v144
	v_mul_f32_e32 v145, v151, v145
	v_ashrrev_i32_e32 v187, 31, v186
	v_cvt_pk_bf16_f32 v13, v144, v145
	v_lshlrev_b32_e32 v144, 16, v14
	v_and_b32_e32 v145, 0xffff0000, v14
	v_mul_f32_e32 v144, v152, v144
	v_mul_f32_e32 v145, v153, v145
	s_nop 0
	v_cvt_pk_bf16_f32 v14, v144, v145
	v_lshlrev_b32_e32 v144, 16, v15
	v_and_b32_e32 v145, 0xffff0000, v15
	v_mul_f32_e32 v144, v154, v144
	v_mul_f32_e32 v145, v155, v145
	s_nop 0
	v_cvt_pk_bf16_f32 v15, v144, v145
	v_lshlrev_b32_e32 v144, 16, v8
	v_and_b32_e32 v145, 0xffff0000, v8
	v_mul_f32_e32 v144, v148, v144
	v_mul_f32_e32 v145, v149, v145
	s_nop 0
	v_cvt_pk_bf16_f32 v8, v144, v145
	v_lshlrev_b32_e32 v144, 16, v9
	v_and_b32_e32 v145, 0xffff0000, v9
	v_mul_f32_e32 v144, v150, v144
	v_mul_f32_e32 v145, v151, v145
	s_nop 0
	v_cvt_pk_bf16_f32 v9, v144, v145
	v_lshlrev_b32_e32 v144, 16, v10
	v_and_b32_e32 v145, 0xffff0000, v10
	v_mul_f32_e32 v144, v152, v144
	v_mul_f32_e32 v145, v153, v145
	s_nop 0
	v_cvt_pk_bf16_f32 v10, v144, v145
	v_lshlrev_b32_e32 v144, 16, v11
	v_and_b32_e32 v145, 0xffff0000, v11
	v_mul_f32_e32 v144, v154, v144
	v_mul_f32_e32 v145, v155, v145
	s_nop 0
	v_cvt_pk_bf16_f32 v11, v144, v145
	v_lshlrev_b32_e32 v144, 16, v4
	v_and_b32_e32 v145, 0xffff0000, v4
	v_mul_f32_e32 v144, v148, v144
	v_mul_f32_e32 v145, v149, v145
	s_nop 0
	v_cvt_pk_bf16_f32 v4, v144, v145
	v_lshlrev_b32_e32 v144, 16, v5
	v_and_b32_e32 v145, 0xffff0000, v5
	v_mul_f32_e32 v144, v150, v144
	v_mul_f32_e32 v145, v151, v145
	s_nop 0
	v_cvt_pk_bf16_f32 v5, v144, v145
	v_lshlrev_b32_e32 v144, 16, v6
	v_and_b32_e32 v145, 0xffff0000, v6
	v_mul_f32_e32 v144, v152, v144
	v_mul_f32_e32 v145, v153, v145
	s_nop 0
	v_cvt_pk_bf16_f32 v6, v144, v145
	v_lshlrev_b32_e32 v144, 16, v7
	v_and_b32_e32 v145, 0xffff0000, v7
	v_bitop3_b32 v7, v183, v223, 12 bitop3:0x36
	v_mul_f32_e32 v156, v154, v144
	v_mul_f32_e32 v157, v155, v145
	v_lshl_or_b32 v158, v7, 4, v180
	ds_read_b128 v[144:147], v158
	v_cvt_pk_bf16_f32 v7, v156, v157
	v_lshlrev_b32_e32 v156, 16, v0
	v_and_b32_e32 v157, 0xffff0000, v0
	v_mul_f32_e32 v148, v148, v156
	v_mul_f32_e32 v149, v149, v157
	s_waitcnt lgkmcnt(0)
; #define MFMA(a, b, c) __builtin_amdgcn_mfma_f32_16x16x32_bf16((a), (b), (c), 0, 0, 0)
; __device__ __forceinline__ void ret_kv_item(PREF P, int w, u16* ST, char* smem) {
;     ...
; #pragma unroll
;     for (int ik = 0; ik < 8; ++ik) {
;       bf16x8 ka = rd128(smem, ik * 16 + l15, kk * 4 + q);
; #pragma unroll
;       for (int jd = 0; jd < 4; ++jd) acc[ik][jd] = MFMA(ka, vb[jd], acc[ik][jd]);
;     }
;   }
;   u16* dst = ST + ((size_t)((n * 8 + h) * 2 + dir)) * 32768 + (size_t)(wid * 64) * 128;
;   __syncthreads();
;   char* wst = smem + wid * 16384;
; #pragma unroll
;   for (int ik = 0; ik < 8; ++ik)
; #pragma unroll
;     for (int jd = 0; jd < 4; ++jd) {
;       const int r = jd * 16 + l15, c = ik * 2 + (q >> 1);
;       u32x2 o; o.x = pack2(acc[ik][jd][0], acc[ik][jd][1]); o.y = pack2(acc[ik][jd][2], acc[ik][jd][3]);
;       *(u32x2*)(wst + r * 256 + ((c ^ (r & 15)) << 4) + (q & 1) * 8) = o;
;     }
	v_mfma_f32_16x16x32_bf16 v[20:23], v[144:147], v[12:15], v[20:23]
	v_cvt_pk_bf16_f32 v0, v148, v149
	v_lshlrev_b32_e32 v148, 16, v1
	v_and_b32_e32 v149, 0xffff0000, v1
	v_mul_f32_e32 v148, v150, v148
	v_mul_f32_e32 v149, v151, v149
	v_mfma_f32_16x16x32_bf16 v[24:27], v[144:147], v[8:11], v[24:27]
	v_cvt_pk_bf16_f32 v1, v148, v149
	v_lshlrev_b32_e32 v148, 16, v2
	v_and_b32_e32 v149, 0xffff0000, v2
	v_mul_f32_e32 v148, v152, v148
	v_mul_f32_e32 v149, v153, v149
	v_mfma_f32_16x16x32_bf16 v[28:31], v[144:147], v[4:7], v[28:31]
	v_cvt_pk_bf16_f32 v2, v148, v149
	v_lshlrev_b32_e32 v148, 16, v3
	v_and_b32_e32 v149, 0xffff0000, v3
	v_mul_f32_e32 v148, v154, v148
	v_mul_f32_e32 v149, v155, v149
	s_nop 0
	v_cvt_pk_bf16_f32 v3, v148, v149
	s_nop 1
	v_mfma_f32_16x16x32_bf16 v[32:35], v[144:147], v[0:3], v[32:35]
	ds_read_b128 v[144:147], v158 offset:4096
	s_waitcnt lgkmcnt(0)
	v_mfma_f32_16x16x32_bf16 v[36:39], v[144:147], v[12:15], v[36:39]
	v_mfma_f32_16x16x32_bf16 v[40:43], v[144:147], v[8:11], v[40:43]
	v_mfma_f32_16x16x32_bf16 v[44:47], v[144:147], v[4:7], v[44:47]
	v_mfma_f32_16x16x32_bf16 v[48:51], v[144:147], v[0:3], v[48:51]
	ds_read_b128 v[144:147], v158 offset:8192
	s_waitcnt lgkmcnt(0)
	v_mfma_f32_16x16x32_bf16 v[52:55], v[144:147], v[12:15], v[52:55]
	v_mfma_f32_16x16x32_bf16 v[56:59], v[144:147], v[8:11], v[56:59]
	v_mfma_f32_16x16x32_bf16 v[60:63], v[144:147], v[4:7], v[60:63]
	v_mfma_f32_16x16x32_bf16 v[64:67], v[144:147], v[0:3], v[64:67]
	ds_read_b128 v[144:147], v158 offset:12288
	s_waitcnt lgkmcnt(0)
	v_mfma_f32_16x16x32_bf16 v[68:71], v[144:147], v[12:15], v[68:71]
	v_mfma_f32_16x16x32_bf16 v[72:75], v[144:147], v[8:11], v[72:75]
	v_mfma_f32_16x16x32_bf16 v[76:79], v[144:147], v[4:7], v[76:79]
	v_mfma_f32_16x16x32_bf16 v[80:83], v[144:147], v[0:3], v[80:83]
	ds_read_b128 v[144:147], v158 offset:16384
	s_waitcnt lgkmcnt(0)
	v_mfma_f32_16x16x32_bf16 v[84:87], v[144:147], v[12:15], v[84:87]
	v_mfma_f32_16x16x32_bf16 v[88:91], v[144:147], v[8:11], v[88:91]
	v_mfma_f32_16x16x32_bf16 v[92:95], v[144:147], v[4:7], v[92:95]
	v_mfma_f32_16x16x32_bf16 v[96:99], v[144:147], v[0:3], v[96:99]
	ds_read_b128 v[144:147], v158 offset:20480
	s_waitcnt lgkmcnt(0)
	v_mfma_f32_16x16x32_bf16 v[100:103], v[144:147], v[12:15], v[100:103]
	v_mfma_f32_16x16x32_bf16 v[104:107], v[144:147], v[8:11], v[104:107]
	v_mfma_f32_16x16x32_bf16 v[108:111], v[144:147], v[4:7], v[108:111]
	v_mfma_f32_16x16x32_bf16 v[112:115], v[144:147], v[0:3], v[112:115]
	ds_read_b128 v[144:147], v158 offset:24576
	s_waitcnt lgkmcnt(0)
	v_mfma_f32_16x16x32_bf16 v[116:119], v[144:147], v[12:15], v[116:119]
	v_mfma_f32_16x16x32_bf16 v[120:123], v[144:147], v[8:11], v[120:123]
	v_mfma_f32_16x16x32_bf16 v[124:127], v[144:147], v[4:7], v[124:127]
	v_mfma_f32_16x16x32_bf16 v[128:131], v[144:147], v[0:3], v[128:131]
	ds_read_b128 v[144:147], v158 offset:28672
	s_waitcnt lgkmcnt(0)
	s_barrier
	v_mfma_f32_16x16x32_bf16 v[0:3], v[144:147], v[0:3], v[16:19]
	s_nop 2
	v_lshlrev_b32_e32 v18, 8, v222
	v_cvt_pk_bf16_f32 v19, v22, v23
	v_mfma_f32_16x16x32_bf16 v[12:15], v[144:147], v[12:15], v[132:135]
	s_nop 1
	v_cvt_pk_bf16_f32 v0, v0, v1
	v_cvt_pk_bf16_f32 v1, v2, v3
	v_lshlrev_b64 v[16:17], 8, v[186:187]
	v_mfma_f32_16x16x32_bf16 v[8:11], v[144:147], v[8:11], v[136:139]
	v_and_b32_e32 v135, 0xffffc000, v18
	v_and_b32_e32 v18, 8, v224
	v_cvt_pk_bf16_f32 v12, v12, v13
	v_bfe_u32 v136, v221, 5, 1
	v_or3_b32 v137, v135, v180, v18
	v_bitop3_b32 v18, v136, v221, 15 bitop3:0x78
	v_lshl_or_b32 v138, v18, 4, v137
	v_cvt_pk_bf16_f32 v18, v20, v21
	v_cvt_pk_bf16_f32 v20, v24, v25
	v_cvt_pk_bf16_f32 v21, v26, v27
	ds_write2st64_b64 v138, v[18:19], v[20:21] offset1:8
	v_cvt_pk_bf16_f32 v18, v28, v29
	v_cvt_pk_bf16_f32 v19, v30, v31
	v_cvt_pk_bf16_f32 v20, v32, v33
	v_cvt_pk_bf16_f32 v21, v34, v35
	ds_write2st64_b64 v138, v[18:19], v[20:21] offset0:16 offset1:24
	v_bitop3_b32 v18, v136, v223, 2 bitop3:0x36
	v_lshl_or_b32 v22, v18, 4, v137
	v_cvt_pk_bf16_f32 v18, v36, v37
	v_cvt_pk_bf16_f32 v19, v38, v39
	v_cvt_pk_bf16_f32 v20, v40, v41
	v_cvt_pk_bf16_f32 v21, v42, v43
	ds_write2st64_b64 v22, v[18:19], v[20:21] offset1:8
	v_cvt_pk_bf16_f32 v18, v44, v45
	v_cvt_pk_bf16_f32 v19, v46, v47
	v_cvt_pk_bf16_f32 v20, v48, v49
	v_cvt_pk_bf16_f32 v21, v50, v51
	ds_write2st64_b64 v22, v[18:19], v[20:21] offset0:16 offset1:24
	v_bitop3_b32 v18, v136, v223, 4 bitop3:0x36
	v_lshl_or_b32 v22, v18, 4, v137
	v_cvt_pk_bf16_f32 v18, v52, v53
	v_cvt_pk_bf16_f32 v19, v54, v55
	v_cvt_pk_bf16_f32 v20, v56, v57
	v_cvt_pk_bf16_f32 v21, v58, v59
	ds_write2st64_b64 v22, v[18:19], v[20:21] offset1:8
	v_cvt_pk_bf16_f32 v18, v60, v61
	v_cvt_pk_bf16_f32 v19, v62, v63
	v_cvt_pk_bf16_f32 v20, v64, v65
	v_cvt_pk_bf16_f32 v21, v66, v67
	ds_write2st64_b64 v22, v[18:19], v[20:21] offset0:16 offset1:24
	v_bitop3_b32 v18, v136, v223, 6 bitop3:0x36
	v_lshl_or_b32 v22, v18, 4, v137
	v_cvt_pk_bf16_f32 v18, v68, v69
	v_cvt_pk_bf16_f32 v19, v70, v71
	v_cvt_pk_bf16_f32 v20, v72, v73
	v_cvt_pk_bf16_f32 v21, v74, v75
	ds_write2st64_b64 v22, v[18:19], v[20:21] offset1:8
	v_cvt_pk_bf16_f32 v18, v76, v77
	v_cvt_pk_bf16_f32 v19, v78, v79
	v_cvt_pk_bf16_f32 v20, v80, v81
	v_cvt_pk_bf16_f32 v21, v82, v83
	ds_write2st64_b64 v22, v[18:19], v[20:21] offset0:16 offset1:24
	v_bitop3_b32 v18, v136, v223, 8 bitop3:0x36
	v_lshl_or_b32 v22, v18, 4, v137
	v_cvt_pk_bf16_f32 v18, v84, v85
	v_cvt_pk_bf16_f32 v19, v86, v87
	v_cvt_pk_bf16_f32 v20, v88, v89
	v_cvt_pk_bf16_f32 v21, v90, v91
	ds_write2st64_b64 v22, v[18:19], v[20:21] offset1:8
	v_cvt_pk_bf16_f32 v18, v92, v93
	v_cvt_pk_bf16_f32 v19, v94, v95
	v_cvt_pk_bf16_f32 v20, v96, v97
	v_cvt_pk_bf16_f32 v21, v98, v99
; __device__ __forceinline__ void ret_kv_item(PREF P, int w, u16* ST, char* smem) {
;     ...
;   u16* dst = ST + ((size_t)((n * 8 + h) * 2 + dir)) * 32768 + (size_t)(wid * 64) * 128;
;   __syncthreads();
;   char* wst = smem + wid * 16384;
; #pragma unroll
;   for (int ik = 0; ik < 8; ++ik)
; #pragma unroll
;     for (int jd = 0; jd < 4; ++jd) {
;       const int r = jd * 16 + l15, c = ik * 2 + (q >> 1);
;       u32x2 o; o.x = pack2(acc[ik][jd][0], acc[ik][jd][1]); o.y = pack2(acc[ik][jd][2], acc[ik][jd][3]);
;       *(u32x2*)(wst + r * 256 + ((c ^ (r & 15)) << 4) + (q & 1) * 8) = o;
;     }
; #pragma unroll
;   for (int k = 0; k < 16; ++k) {
;     const int chunk = k * 64 + lane, r = chunk >> 4, p = chunk & 15;
;     u32x4 d = *(const u32x4*)(wst + r * 256 + (p << 4));
;     __builtin_nontemporal_store(d, (u32x4*)(dst + (size_t)r * 128 + ((p ^ (r & 15)) << 3)));
;   }
	ds_write2st64_b64 v22, v[18:19], v[20:21] offset0:16 offset1:24
	v_bitop3_b32 v18, v136, v223, 10 bitop3:0x36
	v_lshl_or_b32 v22, v18, 4, v137
	v_cvt_pk_bf16_f32 v18, v100, v101
	v_cvt_pk_bf16_f32 v19, v102, v103
	v_cvt_pk_bf16_f32 v20, v104, v105
	v_cvt_pk_bf16_f32 v21, v106, v107
	ds_write2st64_b64 v22, v[18:19], v[20:21] offset1:8
	v_cvt_pk_bf16_f32 v18, v108, v109
	v_cvt_pk_bf16_f32 v19, v110, v111
	v_cvt_pk_bf16_f32 v20, v112, v113
	v_cvt_pk_bf16_f32 v21, v114, v115
	v_mfma_f32_16x16x32_bf16 v[4:7], v[144:147], v[4:7], v[140:143]
	ds_write2st64_b64 v22, v[18:19], v[20:21] offset0:16 offset1:24
	v_bitop3_b32 v18, v136, v223, 12 bitop3:0x36
	v_lshl_or_b32 v22, v18, 4, v137
	v_cvt_pk_bf16_f32 v18, v116, v117
	v_cvt_pk_bf16_f32 v19, v118, v119
	v_cvt_pk_bf16_f32 v20, v120, v121
	v_cvt_pk_bf16_f32 v21, v122, v123
	ds_write2st64_b64 v22, v[18:19], v[20:21] offset1:8
	v_cvt_pk_bf16_f32 v18, v124, v125
	v_cvt_pk_bf16_f32 v19, v126, v127
	v_cvt_pk_bf16_f32 v20, v128, v129
	v_cvt_pk_bf16_f32 v21, v130, v131
	ds_write2st64_b64 v22, v[18:19], v[20:21] offset0:16 offset1:24
	v_bitop3_b32 v18, v136, v223, 14 bitop3:0x36
	v_lshl_or_b32 v18, v18, 4, v137
	v_cvt_pk_bf16_f32 v4, v4, v5
	v_cvt_pk_bf16_f32 v5, v6, v7
	ds_write2st64_b64 v18, v[4:5], v[0:1] offset0:16 offset1:24
	v_lshl_add_u64 v[0:1], v[184:185], 0, s[0:1]
	v_cvt_pk_bf16_f32 v13, v14, v15
	v_cvt_pk_bf16_f32 v8, v8, v9
	v_cvt_pk_bf16_f32 v9, v10, v11
	v_lshl_add_u64 v[4:5], v[0:1], 0, v[16:17]
	v_lshlrev_b32_e32 v0, 4, v221
	s_movk_i32 s0, 0xf0
	ds_write2st64_b64 v18, v[12:13], v[8:9] offset1:8
	v_and_or_b32 v12, v0, s0, v135
	v_lshlrev_b32_e32 v180, 8, v183
	v_or_b32_e32 v0, v12, v180
	ds_read_b128 v[0:3], v0
	v_xor_b32_e32 v8, v183, v221
	v_lshlrev_b32_e32 v8, 4, v8
	v_lshl_add_u64 v[6:7], v[4:5], 0, v[180:181]
	v_and_b32_e32 v8, 0xf0, v8
	v_mov_b32_e32 v9, v181
	v_or_b32_e32 v132, 4, v183
	v_lshl_add_u64 v[6:7], v[6:7], 0, v[8:9]
	s_waitcnt lgkmcnt(0)
	flat_store_dwordx4 v[6:7], v[0:3] nt
	v_lshlrev_b32_e32 v6, 8, v132
	v_bitop3_b32 v10, v183, v221, 4 bitop3:0x36
	v_or_b32_e32 v0, v12, v6
	ds_read_b128 v[0:3], v0
	v_mov_b32_e32 v7, v181
	v_lshlrev_b32_e32 v10, 4, v10
	v_lshl_add_u64 v[6:7], v[4:5], 0, v[6:7]
	v_and_b32_e32 v10, 0xf0, v10
	v_mov_b32_e32 v11, v181
	v_or_b32_e32 v133, 8, v183
	v_lshl_add_u64 v[6:7], v[6:7], 0, v[10:11]
	s_waitcnt lgkmcnt(0)
	flat_store_dwordx4 v[6:7], v[0:3] nt
	v_lshlrev_b32_e32 v6, 8, v133
	v_bitop3_b32 v10, v183, v221, 8 bitop3:0x36
	v_or_b32_e32 v0, v12, v6
	ds_read_b128 v[0:3], v0
	v_mov_b32_e32 v7, v181
	v_lshlrev_b32_e32 v10, 4, v10
	v_lshl_add_u64 v[6:7], v[4:5], 0, v[6:7]
	v_and_b32_e32 v10, 0xf0, v10
	v_or_b32_e32 v134, 12, v183
	v_lshl_add_u64 v[6:7], v[6:7], 0, v[10:11]
	s_waitcnt lgkmcnt(0)
	flat_store_dwordx4 v[6:7], v[0:3] nt
	v_lshlrev_b32_e32 v6, 8, v134
	v_bitop3_b32 v10, v183, v221, 12 bitop3:0x36
	v_or_b32_e32 v0, v12, v6
	ds_read_b128 v[0:3], v0
	v_mov_b32_e32 v7, v181
	v_lshlrev_b32_e32 v10, 4, v10
	v_lshl_add_u64 v[6:7], v[4:5], 0, v[6:7]
	v_and_b32_e32 v10, 0xf0, v10
	v_lshl_add_u64 v[6:7], v[6:7], 0, v[10:11]
	s_waitcnt lgkmcnt(0)
	flat_store_dwordx4 v[6:7], v[0:3] nt
	v_or_b32_e32 v6, 0x1000, v180
	v_mov_b32_e32 v7, v181
	v_or_b32_e32 v0, v12, v6
	ds_read_b128 v[0:3], v0
	v_lshl_add_u64 v[6:7], v[4:5], 0, v[6:7]
	v_lshl_add_u64 v[6:7], v[6:7], 0, v[8:9]
	v_bitop3_b32 v10, v183, v221, 20 bitop3:0x36
	v_lshlrev_b32_e32 v10, 4, v10
	s_waitcnt lgkmcnt(0)
	flat_store_dwordx4 v[6:7], v[0:3] nt
	v_mov_b32_e32 v7, v181
	v_and_b32_e32 v10, 0xf0, v10
	v_or_b32_e32 v0, 20, v183
	v_lshlrev_b32_e32 v6, 8, v0
	v_or_b32_e32 v0, v12, v6
	ds_read_b128 v[0:3], v0
	v_lshl_add_u64 v[6:7], v[4:5], 0, v[6:7]
	v_lshl_add_u64 v[6:7], v[6:7], 0, v[10:11]
	v_bitop3_b32 v10, v183, v221, 24 bitop3:0x36
	v_lshlrev_b32_e32 v10, 4, v10
	s_waitcnt lgkmcnt(0)
; __device__ __forceinline__ void ret_kv_item(PREF P, int w, u16* ST, char* smem) {
;     ...
; #pragma unroll
;   for (int k = 0; k < 16; ++k) {
;     const int chunk = k * 64 + lane, r = chunk >> 4, p = chunk & 15;
;     u32x4 d = *(const u32x4*)(wst + r * 256 + (p << 4));
;     __builtin_nontemporal_store(d, (u32x4*)(dst + (size_t)r * 128 + ((p ^ (r & 15)) << 3)));
;   }
	flat_store_dwordx4 v[6:7], v[0:3] nt
	v_mov_b32_e32 v7, v181
	v_and_b32_e32 v10, 0xf0, v10
	v_or_b32_e32 v0, 24, v183
	v_lshlrev_b32_e32 v6, 8, v0
	v_or_b32_e32 v0, v12, v6
	ds_read_b128 v[0:3], v0
	v_lshl_add_u64 v[6:7], v[4:5], 0, v[6:7]
	v_lshl_add_u64 v[6:7], v[6:7], 0, v[10:11]
	v_bitop3_b32 v10, v183, v221, 28 bitop3:0x36
	v_lshlrev_b32_e32 v10, 4, v10
	s_waitcnt lgkmcnt(0)
	flat_store_dwordx4 v[6:7], v[0:3] nt
	v_mov_b32_e32 v7, v181
	v_and_b32_e32 v10, 0xf0, v10
	v_or_b32_e32 v0, 28, v183
	v_lshlrev_b32_e32 v6, 8, v0
	v_or_b32_e32 v0, v12, v6
	ds_read_b128 v[0:3], v0
	v_lshl_add_u64 v[6:7], v[4:5], 0, v[6:7]
	v_lshl_add_u64 v[6:7], v[6:7], 0, v[10:11]
	v_bitop3_b32 v10, v183, v221, 36 bitop3:0x36
	v_lshlrev_b32_e32 v10, 4, v10
	s_waitcnt lgkmcnt(0)
	flat_store_dwordx4 v[6:7], v[0:3] nt
	v_or_b32_e32 v6, 0x2000, v180
	v_mov_b32_e32 v7, v181
	v_or_b32_e32 v0, v12, v6
	ds_read_b128 v[0:3], v0
	v_lshl_add_u64 v[6:7], v[4:5], 0, v[6:7]
	v_lshl_add_u64 v[6:7], v[6:7], 0, v[8:9]
	v_and_b32_e32 v10, 0xf0, v10
	v_or_b32_e32 v180, 0x3000, v180
	s_waitcnt lgkmcnt(0)
	flat_store_dwordx4 v[6:7], v[0:3] nt
	v_mov_b32_e32 v7, v181
	s_nop 0
	v_or_b32_e32 v0, 36, v183
	v_lshlrev_b32_e32 v6, 8, v0
	v_or_b32_e32 v0, v12, v6
	ds_read_b128 v[0:3], v0
	v_lshl_add_u64 v[6:7], v[4:5], 0, v[6:7]
	v_lshl_add_u64 v[6:7], v[6:7], 0, v[10:11]
	v_bitop3_b32 v10, v183, v221, 40 bitop3:0x36
	v_lshlrev_b32_e32 v10, 4, v10
	s_waitcnt lgkmcnt(0)
	flat_store_dwordx4 v[6:7], v[0:3] nt
	v_mov_b32_e32 v7, v181
	v_and_b32_e32 v10, 0xf0, v10
	v_or_b32_e32 v0, 40, v183
	v_lshlrev_b32_e32 v6, 8, v0
	v_or_b32_e32 v0, v12, v6
	ds_read_b128 v[0:3], v0
	v_lshl_add_u64 v[6:7], v[4:5], 0, v[6:7]
	v_lshl_add_u64 v[6:7], v[6:7], 0, v[10:11]
	v_bitop3_b32 v10, v183, v221, 44 bitop3:0x36
	v_lshlrev_b32_e32 v10, 4, v10
	s_waitcnt lgkmcnt(0)
	flat_store_dwordx4 v[6:7], v[0:3] nt
	v_mov_b32_e32 v7, v181
	v_and_b32_e32 v10, 0xf0, v10
	v_or_b32_e32 v0, 44, v183
	v_lshlrev_b32_e32 v6, 8, v0
	v_or_b32_e32 v0, v12, v6
	ds_read_b128 v[0:3], v0
	v_lshl_add_u64 v[6:7], v[4:5], 0, v[6:7]
	v_lshl_add_u64 v[6:7], v[6:7], 0, v[10:11]
	s_waitcnt lgkmcnt(0)
	flat_store_dwordx4 v[6:7], v[0:3] nt
	s_nop 1
	v_or_b32_e32 v0, v12, v180
	ds_read_b128 v[0:3], v0
	v_lshl_add_u64 v[6:7], v[4:5], 0, v[180:181]
	v_lshl_add_u64 v[6:7], v[6:7], 0, v[8:9]
	v_bitop3_b32 v8, v183, v221, 52 bitop3:0x36
	v_lshlrev_b32_e32 v8, 4, v8
	s_waitcnt lgkmcnt(0)
	flat_store_dwordx4 v[6:7], v[0:3] nt
	s_nop 1
	v_or_b32_e32 v0, 52, v183
	v_lshlrev_b32_e32 v180, 8, v0
	v_or_b32_e32 v0, v12, v180
	ds_read_b128 v[0:3], v0
	v_lshl_add_u64 v[6:7], v[4:5], 0, v[180:181]
	v_and_b32_e32 v180, 0xf0, v8
	v_lshl_add_u64 v[6:7], v[6:7], 0, v[180:181]
	v_bitop3_b32 v8, v183, v221, 56 bitop3:0x36
	s_waitcnt lgkmcnt(0)
	flat_store_dwordx4 v[6:7], v[0:3] nt
	v_lshlrev_b32_e32 v8, 4, v8
	s_nop 0
	v_or_b32_e32 v0, 56, v183
	v_lshlrev_b32_e32 v180, 8, v0
	v_or_b32_e32 v0, v12, v180
	ds_read_b128 v[0:3], v0
	v_lshl_add_u64 v[6:7], v[4:5], 0, v[180:181]
	v_and_b32_e32 v180, 0xf0, v8
	v_lshl_add_u64 v[6:7], v[6:7], 0, v[180:181]
	s_waitcnt lgkmcnt(0)
	flat_store_dwordx4 v[6:7], v[0:3] nt
	v_bitop3_b32 v6, v183, v221, 60 bitop3:0x36
	s_nop 0
	v_or_b32_e32 v0, 60, v183
	v_lshlrev_b32_e32 v180, 8, v0
	v_or_b32_e32 v0, v12, v180
	ds_read_b128 v[0:3], v0
	v_lshlrev_b32_e32 v6, 4, v6
	v_lshl_add_u64 v[4:5], v[4:5], 0, v[180:181]
	v_and_b32_e32 v180, 0xf0, v6
	v_lshl_add_u64 v[4:5], v[4:5], 0, v[180:181]
	s_waitcnt lgkmcnt(0)
	flat_store_dwordx4 v[4:5], v[0:3] nt

; #define MFMA(a, b, c) __builtin_amdgcn_mfma_f32_16x16x32_bf16((a), (b), (c), 0, 0, 0)
; #define DMA_WAIT_SYNC() do { asm volatile("s_waitcnt vmcnt(0)" ::: "memory"); __syncthreads(); } while (0)
; __device__ __forceinline__ void attn_item(PREF P, int w, int Sshift, char* smem) {
;     ...
; #pragma unroll 1
;   for (int half = 0; half < 2; ++half) {
;     const char* vb = half == 0 ? VH : KW;
;     if (half == 1) DMA_WAIT_SYNC();
;     f32x4 oT[4];
; #pragma unroll
;     for (int d = 0; d < 4; ++d) oT[d] = f32x4{0.f, 0.f, 0.f, 0.f};
; #pragma unroll
;     for (int j2 = 0; j2 < 5; ++j2) {
;       int ia = wid * 16 + j2 * 32 + q * 4;
;       int ib = ia + 16;
;       if (ia >= 192) ia = 0;
;       if (ib >= 192) ib = 0;
; #pragma unroll
;       for (int dvt = 0; dvt < 4; ++dvt) {
;         const char* vrow = vb + (dvt * 16 + l15) * 400;
;         u32x2 a0 = *(const u32x2*)(vrow + ia * 2), a1 = *(const u32x2*)(vrow + ib * 2);
;         u32x4 vv = {a0.x, a0.y, a1.x, a1.y};
;         oT[dvt] = MFMA(__builtin_bit_cast(bf16x8, vv), pf[j2], oT[dvt]);
;       }
;     }
; #pragma unroll
;     for (int dvt = 0; dvt < 4; ++dvt) {
;       uint2 o;
;       o.x = pack2(oT[dvt][0] * inv, oT[dvt][1] * inv);
;       o.y = pack2(oT[dvt][2] * inv, oT[dvt][3] * inv);
;       *(uint2*)(orow + half * 64 + dvt * 16) = o;
;     }
.LBB0_193:
	s_xor_b64 s[0:1], s[16:17], -1
	s_and_b64 s[16:17], s[16:17], exec
	s_cselect_b32 s6, 0xc000, 0
	v_or_b32_e32 v39, s6, v28
	v_add_u32_e32 v52, v39, v29
	v_add_u32_e32 v54, v39, v30
	ds_read_b64 v[40:41], v52
	ds_read_b64 v[42:43], v54
	v_add_u32_e32 v60, v39, v31
	v_add_u32_e32 v61, v39, v32
	ds_read_b64 v[44:45], v52 offset:6400
	ds_read_b64 v[46:47], v54 offset:6400
	ds_read_b64 v[48:49], v52 offset:12800
	ds_read_b64 v[50:51], v54 offset:12800
	ds_read_b64 v[52:53], v52 offset:19200
	ds_read_b64 v[54:55], v54 offset:19200
	ds_read_b64 v[56:57], v60
	ds_read_b64 v[58:59], v61
	s_waitcnt lgkmcnt(0)
	v_mfma_f32_16x16x32_bf16 v[40:43], v[40:43], v[0:3], 0
	s_mov_b64 s[18:19], -1
	s_mov_b64 s[16:17], 0
	s_and_b64 vcc, exec, s[0:1]
	s_waitcnt lgkmcnt(0)
	v_mfma_f32_16x16x32_bf16 v[40:43], v[56:59], v[4:7], v[40:43]
	ds_read_b64 v[56:57], v60 offset:6400
	ds_read_b64 v[58:59], v61 offset:6400
	v_mfma_f32_16x16x32_bf16 v[44:47], v[44:47], v[0:3], 0
	s_waitcnt lgkmcnt(0)
	v_mfma_f32_16x16x32_bf16 v[44:47], v[56:59], v[4:7], v[44:47]
	ds_read_b64 v[56:57], v60 offset:12800
	ds_read_b64 v[58:59], v61 offset:12800
	v_mfma_f32_16x16x32_bf16 v[48:51], v[48:51], v[0:3], 0
	s_waitcnt lgkmcnt(0)
	v_mfma_f32_16x16x32_bf16 v[48:51], v[56:59], v[4:7], v[48:51]
	ds_read_b64 v[56:57], v60 offset:19200
	ds_read_b64 v[58:59], v61 offset:19200
	v_add_u32_e32 v60, v39, v33
	v_add_u32_e32 v61, v39, v34
	v_mfma_f32_16x16x32_bf16 v[52:55], v[52:55], v[0:3], 0
	s_waitcnt lgkmcnt(0)
	v_mfma_f32_16x16x32_bf16 v[52:55], v[56:59], v[4:7], v[52:55]
	ds_read_b64 v[56:57], v60
	ds_read_b64 v[58:59], v61
	s_waitcnt lgkmcnt(0)
	v_mfma_f32_16x16x32_bf16 v[40:43], v[56:59], v[8:11], v[40:43]
	ds_read_b64 v[56:57], v60 offset:6400
	ds_read_b64 v[58:59], v61 offset:6400
	s_waitcnt lgkmcnt(0)
	v_mfma_f32_16x16x32_bf16 v[44:47], v[56:59], v[8:11], v[44:47]
	ds_read_b64 v[56:57], v60 offset:12800
	ds_read_b64 v[58:59], v61 offset:12800
	s_waitcnt lgkmcnt(0)
	v_mfma_f32_16x16x32_bf16 v[48:51], v[56:59], v[8:11], v[48:51]
	ds_read_b64 v[56:57], v60 offset:19200
	ds_read_b64 v[58:59], v61 offset:19200
	v_add_u32_e32 v60, v39, v35
	v_add_u32_e32 v61, v39, v36
	s_waitcnt lgkmcnt(0)
	v_mfma_f32_16x16x32_bf16 v[52:55], v[56:59], v[8:11], v[52:55]
	ds_read_b64 v[56:57], v60
	ds_read_b64 v[58:59], v61
	s_waitcnt lgkmcnt(0)
	v_mfma_f32_16x16x32_bf16 v[40:43], v[56:59], v[12:15], v[40:43]
	ds_read_b64 v[56:57], v60 offset:6400
	ds_read_b64 v[58:59], v61 offset:6400
	s_waitcnt lgkmcnt(0)
	v_mfma_f32_16x16x32_bf16 v[44:47], v[56:59], v[12:15], v[44:47]
	ds_read_b64 v[56:57], v60 offset:12800
	ds_read_b64 v[58:59], v61 offset:12800
	s_waitcnt lgkmcnt(0)
	v_mfma_f32_16x16x32_bf16 v[48:51], v[56:59], v[12:15], v[48:51]
	ds_read_b64 v[56:57], v60 offset:19200
	ds_read_b64 v[58:59], v61 offset:19200
	v_add_u32_e32 v60, v39, v37
	v_add_u32_e32 v39, v39, v38
	s_waitcnt lgkmcnt(0)
	v_mfma_f32_16x16x32_bf16 v[52:55], v[56:59], v[12:15], v[52:55]
	ds_read_b64 v[56:57], v60
	ds_read_b64 v[58:59], v39
	s_waitcnt lgkmcnt(0)
	v_mfma_f32_16x16x32_bf16 v[40:43], v[56:59], v[16:19], v[40:43]
	ds_read_b64 v[56:57], v60 offset:6400
	ds_read_b64 v[58:59], v39 offset:6400
	s_nop 5
	v_mul_f32_e32 v40, v22, v40
	v_mul_f32_e32 v41, v23, v41
	s_waitcnt lgkmcnt(0)
	v_mfma_f32_16x16x32_bf16 v[44:47], v[56:59], v[16:19], v[44:47]
	ds_read_b64 v[56:57], v60 offset:12800
	ds_read_b64 v[58:59], v39 offset:12800
	v_mul_f32_e32 v42, v22, v42
	v_mul_f32_e32 v43, v23, v43
	v_cvt_pk_bf16_f32 v40, v40, v41
	s_waitcnt lgkmcnt(0)
	v_mfma_f32_16x16x32_bf16 v[48:51], v[56:59], v[16:19], v[48:51]
	ds_read_b64 v[56:57], v60 offset:19200
	ds_read_b64 v[58:59], v39 offset:19200
	v_cvt_pk_bf16_f32 v41, v42, v43
	v_mul_f32_e32 v42, v22, v46
	v_mul_f32_e32 v43, v23, v47
	s_waitcnt lgkmcnt(0)
	v_mfma_f32_16x16x32_bf16 v[52:55], v[56:59], v[16:19], v[52:55]
	v_lshl_add_u64 v[56:57], s[14:15], 1, v[24:25]
	flat_store_dwordx2 v[56:57], v[40:41]
	v_mul_f32_e32 v40, v22, v44
	v_mul_f32_e32 v41, v23, v45
	s_mov_b64 s[14:15], 64
	v_cvt_pk_bf16_f32 v40, v40, v41
	v_cvt_pk_bf16_f32 v41, v42, v43
	flat_store_dwordx2 v[56:57], v[40:41] offset:32
	v_mul_f32_e32 v40, v22, v48
	v_mul_f32_e32 v41, v23, v49
	v_mul_f32_e32 v42, v22, v50
	v_mul_f32_e32 v43, v23, v51
	v_cvt_pk_bf16_f32 v40, v40, v41
	v_cvt_pk_bf16_f32 v41, v42, v43
	flat_store_dwordx2 v[56:57], v[40:41] offset:64
	v_mul_f32_e32 v40, v22, v52
	v_mul_f32_e32 v41, v23, v53
	v_mul_f32_e32 v42, v22, v54
	v_mul_f32_e32 v43, v23, v55
	v_cvt_pk_bf16_f32 v40, v40, v41
	v_cvt_pk_bf16_f32 v41, v42, v43
	flat_store_dwordx2 v[56:57], v[40:41] offset:96
	s_cbranch_vccnz .LBB0_196

; DEV float bflo(unsigned u) { return __uint_as_float(u << 16); }
; DEV float bfhi(unsigned u) { return __uint_as_float(u & 0xffff0000u); }
; __device__ __forceinline__ void phase_scan(PREF P, int slab, u16* ST) {
;     ...
;     for (int cc = 0; cc < nC; cc += 4) {
;       uint4 v[4];
; #pragma unroll
;       for (int u = 0; u < 4; ++u) {
;         int c = dir == 0 ? (cc + u) : (nC - 1 - cc - u);
;         v[u] = *(const uint4*)(base + (size_t)(seq * nC + c) * (16 * 32768));
;       }
; #pragma unroll
;       for (int u = 0; u < 4; ++u) {
;         int c = dir == 0 ? (cc + u) : (nC - 1 - cc - u);
;         uint4 o;
;         o.x = pack2(R[0], R[1]); o.y = pack2(R[2], R[3]); o.z = pack2(R[4], R[5]); o.w = pack2(R[6], R[7]);
;         *(uint4*)(base + (size_t)(seq * nC + c) * (16 * 32768)) = o;
;         R[0] = R[0] * dec + bflo(v[u].x); R[1] = R[1] * dec + bfhi(v[u].x);
;         R[2] = R[2] * dec + bflo(v[u].y); R[3] = R[3] * dec + bfhi(v[u].y);
;         R[4] = R[4] * dec + bflo(v[u].z); R[5] = R[5] * dec + bfhi(v[u].z);
;         R[6] = R[6] * dec + bflo(v[u].w); R[7] = R[7] * dec + bfhi(v[u].w);
;       }
;     }
.LBB0_254:
	s_add_i32 s36, s24, 3
	v_mov_b32_e32 v23, s36
	v_mov_b32_e32 v24, s19
	v_cndmask_b32_e32 v23, v23, v24, vcc
	v_add_u32_e32 v24, v23, v22
	v_ashrrev_i32_e32 v25, 31, v24
	v_lshlrev_b64 v[24:25], 20, v[24:25]
	s_add_i32 s36, s24, 2
	s_add_i32 s37, s19, 1
	v_lshl_add_u64 v[44:45], v[4:5], 0, v[24:25]
	v_mov_b32_e32 v23, s36
	v_mov_b32_e32 v28, s37
	flat_load_dwordx4 v[24:27], v[44:45]
	v_cndmask_b32_e32 v23, v23, v28, vcc
	v_add_u32_e32 v28, v23, v22
	v_ashrrev_i32_e32 v29, 31, v28
	v_lshlrev_b64 v[28:29], 20, v[28:29]
	v_lshl_add_u64 v[46:47], v[4:5], 0, v[28:29]
	s_add_i32 s36, s24, 1
	s_add_i32 s37, s19, 2
	flat_load_dwordx4 v[28:31], v[46:47]
	v_mov_b32_e32 v23, s36
	v_mov_b32_e32 v32, s37
	v_cndmask_b32_e32 v23, v23, v32, vcc
	v_add_u32_e32 v32, v23, v22
	v_ashrrev_i32_e32 v33, 31, v32
	v_lshlrev_b64 v[32:33], 20, v[32:33]
	v_lshl_add_u64 v[48:49], v[4:5], 0, v[32:33]
	s_add_i32 s36, s19, 3
	flat_load_dwordx4 v[32:35], v[48:49]
	v_mov_b32_e32 v23, s24
	v_mov_b32_e32 v36, s36
	v_cndmask_b32_e32 v23, v23, v36, vcc
	v_add_u32_e32 v36, v23, v22
	v_ashrrev_i32_e32 v37, 31, v36
	v_lshlrev_b64 v[36:37], 20, v[36:37]
	v_lshl_add_u64 v[50:51], v[4:5], 0, v[36:37]
	flat_load_dwordx4 v[36:39], v[50:51]
	v_cvt_pk_bf16_f32 v40, v0, v1
	v_cvt_pk_bf16_f32 v41, v16, v17
	v_cvt_pk_bf16_f32 v42, v14, v15
	v_cvt_pk_bf16_f32 v43, v18, v19
	flat_store_dwordx4 v[44:45], v[40:43]
	s_add_i32 s24, s24, -4
	s_add_i32 s19, s19, 4
	s_cmp_ge_u32 s19, s17
	s_waitcnt vmcnt(0) lgkmcnt(0)
	v_lshlrev_b32_e32 v40, 16, v24
	v_and_b32_e32 v41, 0xffff0000, v24
	v_lshlrev_b32_e32 v24, 16, v25
	v_and_b32_e32 v25, 0xffff0000, v25
	v_fmac_f32_e32 v24, v2, v16
	v_fmac_f32_e32 v25, v3, v17
	v_lshlrev_b32_e32 v16, 16, v26
	v_and_b32_e32 v17, 0xffff0000, v26
	v_fma_f32 v0, v2, v0, v40
	v_fma_f32 v1, v3, v1, v41
	v_fma_f32 v40, v2, v14, v16
	v_fma_f32 v41, v3, v15, v17
	v_lshlrev_b32_e32 v14, 16, v27
	v_and_b32_e32 v15, 0xffff0000, v27
	v_fma_f32 v18, v2, v18, v14
	v_fma_f32 v19, v3, v19, v15
	v_cvt_pk_bf16_f32 v14, v0, v1
	v_cvt_pk_bf16_f32 v15, v24, v25
	v_cvt_pk_bf16_f32 v16, v40, v41
	v_cvt_pk_bf16_f32 v17, v18, v19
	flat_store_dwordx4 v[46:47], v[14:17]
	s_nop 1
	v_lshlrev_b32_e32 v14, 16, v28
	v_and_b32_e32 v15, 0xffff0000, v28
	v_fma_f32 v0, v2, v0, v14
	v_fma_f32 v1, v3, v1, v15
	v_lshlrev_b32_e32 v14, 16, v29
	v_and_b32_e32 v15, 0xffff0000, v29
	v_fma_f32 v24, v2, v24, v14
	v_fma_f32 v25, v3, v25, v15
	v_lshlrev_b32_e32 v14, 16, v30
	v_and_b32_e32 v15, 0xffff0000, v30
	v_fma_f32 v26, v2, v40, v14
	v_fma_f32 v27, v3, v41, v15
	v_lshlrev_b32_e32 v14, 16, v31
	v_and_b32_e32 v15, 0xffff0000, v31
	v_fma_f32 v18, v2, v18, v14
	v_fma_f32 v19, v3, v19, v15
	v_cvt_pk_bf16_f32 v14, v0, v1
	v_cvt_pk_bf16_f32 v15, v24, v25
	v_cvt_pk_bf16_f32 v16, v26, v27
	v_cvt_pk_bf16_f32 v17, v18, v19
	flat_store_dwordx4 v[48:49], v[14:17]
	v_lshlrev_b32_e32 v28, 16, v36
	v_and_b32_e32 v29, 0xffff0000, v36
	v_lshlrev_b32_e32 v14, 16, v32
	v_and_b32_e32 v15, 0xffff0000, v32
	v_fma_f32 v0, v2, v0, v14
	v_fma_f32 v1, v3, v1, v15
	v_lshlrev_b32_e32 v14, 16, v33
	v_and_b32_e32 v15, 0xffff0000, v33
	v_fma_f32 v24, v2, v24, v14
	v_fma_f32 v25, v3, v25, v15
	v_lshlrev_b32_e32 v14, 16, v34
	v_and_b32_e32 v15, 0xffff0000, v34
	v_fma_f32 v26, v2, v26, v14
	v_fma_f32 v27, v3, v27, v15
	v_lshlrev_b32_e32 v14, 16, v35
	v_and_b32_e32 v15, 0xffff0000, v35
	v_fma_f32 v18, v2, v18, v14
	v_fma_f32 v19, v3, v19, v15
	v_cvt_pk_bf16_f32 v14, v0, v1
	v_cvt_pk_bf16_f32 v15, v24, v25
	v_cvt_pk_bf16_f32 v16, v26, v27
	v_cvt_pk_bf16_f32 v17, v18, v19
	flat_store_dwordx4 v[50:51], v[14:17]
	v_lshlrev_b32_e32 v30, 16, v39
	v_and_b32_e32 v31, 0xffff0000, v39
	v_lshlrev_b32_e32 v16, 16, v37
	v_and_b32_e32 v17, 0xffff0000, v37
	v_lshlrev_b32_e32 v14, 16, v38
	v_and_b32_e32 v15, 0xffff0000, v38
	v_fma_f32 v18, v12, v18, v30
	v_fma_f32 v19, v13, v19, v31
	v_fmac_f32_e32 v14, v10, v26
	v_fmac_f32_e32 v15, v11, v27
	v_fmac_f32_e32 v16, v8, v24
	v_fmac_f32_e32 v17, v9, v25
	v_fma_f32 v0, v6, v0, v28
	v_fma_f32 v1, v7, v1, v29
	s_cbranch_scc0 .LBB0_254
	v_readlane_b32 s36, v251, 6
	s_mov_b32 s19, s36
	v_readlane_b32 s37, v251, 7
	v_lshl_add_u32 v21, s19, 8, v21
	v_cmp_le_i32_e32 vcc, s6, v21
	s_or_b64 s[14:15], vcc, s[14:15]
	s_andn2_b64 exec, exec, s[14:15]
	s_cbranch_execnz .LBB0_253

; DEV int tid_() { int t = threadIdx.x; asm volatile("" : "+v"(t)); return t; }
; DEV int bid_() { int t = blockIdx.x; asm volatile("" : "+s"(t)); return t; }
; DEV int gdim_() { int t = gridDim.x; asm volatile("" : "+s"(t)); return t; }
; DEV float bflo(unsigned u) { return __uint_as_float(u << 16); }
; DEV float bfhi(unsigned u) { return __uint_as_float(u & 0xffff0000u); }
; #define P (*launderP(lp))
; __device__ __forceinline__ void phase_att_merge(PREF P, int slab) {
;     ...
;   for (int idx = bid_() * NTHR + tid_(); idx < nitems; idx += gdim_() * NTHR) {
;     const int d8 = idx & 15, hs = (idx >> 4) & 7, m = idx >> 7;
;     int pg[3];
;     float ls[3];
; #pragma unroll
;     for (int g = 0; g < 3; ++g) {
;       pg[g] = posmap(m, Sshift, 2 * g);
;       ls[g] = P.lse[((size_t)g * TS + pg[g]) * 8 + hs];
;     }
;     float mx = fmaxf(ls[0], fmaxf(ls[1], ls[2]));
;     float e0 = __expf(ls[0] - mx), e1 = __expf(ls[1] - mx), e2 = __expf(ls[2] - mx);
;     float inv = 1.f / (e0 + e1 + e2);
;     float wg[3] = {e0 * inv, e1 * inv, e2 * inv};
;     float a[8];
; #pragma unroll
;     for (int e = 0; e < 8; ++e) a[e] = 0.f;
; #pragma unroll
;     for (int g = 0; g < 3; ++g) {
;       uint4 v = *(const uint4*)(P.og + ((size_t)g * TS + pg[g]) * 1024 + hs * 128 + d8 * 8);
;       a[0] += wg[g] * bflo(v.x); a[1] += wg[g] * bfhi(v.x);
;       a[2] += wg[g] * bflo(v.y); a[3] += wg[g] * bfhi(v.y);
;       a[4] += wg[g] * bflo(v.z); a[5] += wg[g] * bfhi(v.z);
;       a[6] += wg[g] * bflo(v.w); a[7] += wg[g] * bfhi(v.w);
;     }
;     uint4 o;
;     o.x = pack2(a[0], a[1]); o.y = pack2(a[2], a[3]); o.z = pack2(a[4], a[5]); o.w = pack2(a[6], a[7]);
;     *(uint4*)(P.att + (size_t)m * 1024 + hs * 128 + d8 * 8) = o;
.LBB0_275:
	v_ashrrev_i32_e32 v6, 7, v5
	s_waitcnt lgkmcnt(0)
	ds_read2_b64 v[0:3], v4 offset0:39 offset1:41
	ds_read_b64 v[8:9], v4 offset:368
	v_and_b32_e32 v12, s14, v6
	v_lshlrev_b32_e32 v10, 4, v5
	v_and_b32_e32 v13, s6, v6
	v_ashrrev_i32_e32 v7, 31, v6
	v_lshrrev_b32_e32 v16, 2, v12
	v_and_b32_e32 v14, 3, v6
	v_and_b32_e32 v15, 15, v6
	v_and_b32_e32 v18, 0xf0, v10
	v_lshlrev_b64 v[10:11], 5, v[6:7]
	v_lshrrev_b32_e32 v12, 4, v12
	v_lshlrev_b64 v[20:21], 11, v[6:7]
	v_or_b32_e32 v6, v16, v13
	v_bfe_u32 v24, v5, 4, 3
	v_or_b32_e32 v7, v12, v13
	v_lshl_add_u32 v6, v14, s15, v6
	v_lshlrev_b32_e32 v180, 2, v24
	v_lshl_add_u32 v12, v15, s31, v7
	s_waitcnt lgkmcnt(0)
	v_lshl_add_u64 v[10:11], v[8:9], 0, v[10:11]
	v_ashrrev_i32_e32 v7, 31, v6
	v_lshl_add_u64 v[10:11], v[10:11], 0, v[180:181]
	v_lshlrev_b64 v[16:17], 5, v[6:7]
	v_ashrrev_i32_e32 v13, 31, v12
	flat_load_dword v25, v[10:11]
	v_lshl_add_u64 v[10:11], v[8:9], 0, v[16:17]
	v_lshlrev_b64 v[22:23], 5, v[12:13]
	v_lshl_add_u64 v[10:11], v[10:11], 0, v[180:181]
	v_lshl_add_u64 v[8:9], v[8:9], 0, v[22:23]
	v_add_co_u32_e32 v10, vcc, s19, v10
	v_lshl_add_u64 v[8:9], v[8:9], 0, v[180:181]
	s_nop 0
	v_addc_co_u32_e32 v11, vcc, 0, v11, vcc
	v_add_co_u32_e32 v8, vcc, s36, v8
	v_lshlrev_b64 v[6:7], 11, v[6:7]
	s_nop 0
	v_addc_co_u32_e32 v9, vcc, 0, v9, vcc
	flat_load_dword v22, v[10:11]
	flat_load_dword v23, v[8:9]
	v_lshl_add_u64 v[6:7], v[0:1], 0, v[6:7]
	v_lshlrev_b32_e32 v180, 8, v24
	v_mov_b32_e32 v19, v181
	v_lshl_add_u64 v[14:15], v[0:1], 0, v[20:21]
	v_lshlrev_b64 v[12:13], 11, v[12:13]
	v_lshl_add_u64 v[6:7], v[6:7], 0, v[180:181]
	v_lshl_add_u64 v[0:1], v[0:1], 0, v[12:13]
	v_lshl_add_u64 v[12:13], v[14:15], 0, v[180:181]
	v_lshl_add_u64 v[10:11], v[6:7], 0, v[18:19]
	s_mov_b32 s16, 0x1000000
	v_lshl_add_u64 v[0:1], v[0:1], 0, v[180:181]
	v_lshl_add_u64 v[8:9], v[12:13], 0, v[18:19]
	v_add_co_u32_e32 v10, vcc, s16, v10
	v_lshl_add_u64 v[0:1], v[0:1], 0, v[18:19]
	flat_load_dwordx4 v[6:9], v[8:9]
	v_addc_co_u32_e32 v11, vcc, 0, v11, vcc
	s_brev_b32 s16, 64
	v_add_co_u32_e32 v0, vcc, s16, v0
	s_mov_b32 s18, s24
	s_nop 0
	v_addc_co_u32_e32 v1, vcc, 0, v1, vcc
	flat_load_dwordx4 v[10:13], v[10:11]
	s_nop 0
	flat_load_dwordx4 v[14:17], v[0:1]
	v_lshl_add_u64 v[0:1], v[2:3], 0, v[20:21]
	v_lshl_add_u64 v[0:1], v[0:1], 0, v[180:181]
	v_lshl_add_u64 v[18:19], v[0:1], 0, v[18:19]
	s_waitcnt vmcnt(0) lgkmcnt(0)
	v_max3_f32 v0, v25, v22, v23
	v_sub_f32_e32 v20, v25, v0
	v_sub_f32_e32 v21, v22, v0
	v_sub_f32_e32 v22, v23, v0
	v_mul_f32_e32 v28, 0x3fb8aa3b, v20
	v_mul_f32_e32 v29, 0x3fb8aa3b, v21
	v_mul_f32_e32 v30, 0x3fb8aa3b, v22
	v_exp_f32_e32 v28, v28
	v_exp_f32_e32 v29, v29
	v_exp_f32_e32 v31, v30
	v_add_f32_e32 v30, v28, v29
	v_add_f32_e32 v30, v31, v30
	v_div_scale_f32 v32, s[16:17], v30, v30, 1.0
	v_rcp_f32_e32 v34, v32
	v_div_scale_f32 v33, vcc, 1.0, v30, 1.0
	v_lshlrev_b32_e32 v0, 16, v6
	v_fma_f32 v35, -v32, v34, 1.0
	v_fmac_f32_e32 v34, v35, v34
	v_mul_f32_e32 v35, v33, v34
	v_fma_f32 v36, -v32, v35, v33
	v_fmac_f32_e32 v35, v36, v34
	v_fma_f32 v32, -v32, v35, v33
	v_div_fmas_f32 v32, v32, v34, v35
	v_div_fixup_f32 v32, v32, v30, 1.0
	v_and_b32_e32 v1, 0xffff0000, v6
	v_lshlrev_b32_e32 v2, 16, v7
	v_and_b32_e32 v3, 0xffff0000, v7
	v_lshlrev_b32_e32 v6, 16, v8
	v_and_b32_e32 v7, 0xffff0000, v8
	v_lshlrev_b32_e32 v8, 16, v9
	v_and_b32_e32 v9, 0xffff0000, v9
	v_mul_f32_e32 v28, v28, v32
	v_lshlrev_b32_e32 v20, 16, v10
	v_and_b32_e32 v21, 0xffff0000, v10
	v_lshlrev_b32_e32 v10, 16, v11
	v_and_b32_e32 v11, 0xffff0000, v11
	v_lshlrev_b32_e32 v22, 16, v12
	v_and_b32_e32 v23, 0xffff0000, v12
	v_lshlrev_b32_e32 v12, 16, v13
	v_and_b32_e32 v13, 0xffff0000, v13
	v_mul_f32_e32 v30, v29, v32
	v_pk_fma_f32 v[0:1], v[28:29], v[0:1], 0 op_sel_hi:[0,1,0]
	v_pk_fma_f32 v[2:3], v[28:29], v[2:3], 0 op_sel_hi:[0,1,0]
	v_pk_fma_f32 v[6:7], v[28:29], v[6:7], 0 op_sel_hi:[0,1,0]
	v_pk_fma_f32 v[8:9], v[28:29], v[8:9], 0 op_sel_hi:[0,1,0]
	v_lshlrev_b32_e32 v24, 16, v14
	v_and_b32_e32 v25, 0xffff0000, v14
	v_lshlrev_b32_e32 v14, 16, v15
	v_and_b32_e32 v15, 0xffff0000, v15
	v_lshlrev_b32_e32 v26, 16, v16
	v_and_b32_e32 v27, 0xffff0000, v16
	v_lshlrev_b32_e32 v16, 16, v17
	v_and_b32_e32 v17, 0xffff0000, v17
	v_mul_f32_e32 v32, v31, v32
	v_fmac_f32_e32 v0, v30, v20
	v_fmac_f32_e32 v1, v30, v21
	v_fmac_f32_e32 v2, v30, v10
	v_fmac_f32_e32 v3, v30, v11
	v_fmac_f32_e32 v6, v30, v22
	v_fmac_f32_e32 v7, v30, v23
	v_fmac_f32_e32 v8, v30, v12
	v_fmac_f32_e32 v9, v30, v13
	v_fmac_f32_e32 v0, v32, v24
	v_fmac_f32_e32 v1, v32, v25
	v_fmac_f32_e32 v2, v32, v14
	v_fmac_f32_e32 v3, v32, v15
	v_fmac_f32_e32 v6, v32, v26
	v_fmac_f32_e32 v7, v32, v27
	v_fmac_f32_e32 v8, v32, v16
	v_fmac_f32_e32 v9, v32, v17
	v_cvt_pk_bf16_f32 v0, v0, v1
	v_cvt_pk_bf16_f32 v1, v2, v3
	v_cvt_pk_bf16_f32 v2, v6, v7
	v_cvt_pk_bf16_f32 v3, v8, v9
	flat_store_dwordx4 v[18:19], v[0:3]
	s_mov_b32 s16, 0xfffff
	v_lshl_add_u32 v5, s18, 8, v5
	v_cmp_lt_i32_e32 vcc, s16, v5
	s_or_b64 s[4:5], vcc, s[4:5]
	s_andn2_b64 exec, exec, s[4:5]
	s_cbranch_execnz .LBB0_275

; #define RO_WAIT_SYNC() do { asm volatile("s_waitcnt vmcnt(0)" : "+v"(oT[0]), "+v"(oT[1]), "+v"(oT[2]), "+v"(oT[3]), \
;     "+v"(oT[4]), "+v"(oT[5]), "+v"(oT[6]), "+v"(oT[7]) : : "memory"); __syncthreads(); } while (0)
; #define RO_DMA_V(d, hf) dma_rows256([&](int row) { return vbase + (size_t)((hf) * 128 + row) * TS; }, 128, d)
; __device__ __forceinline__ void ret_out_item(PREF P, int w, const u16* ST, char* smem) {
;     ...
;   ro_cross(X, xif, qf, oT, l15, q);
;   RO_WAIT_SYNC();
;   RO_DMA_V(X, 1);
;   ro_cross(Y, xib, qf, oT, l15, q);
; #pragma unroll
;   for (int d = 0; d < 8; ++d) {
; #pragma unroll
;     for (int r = 0; r < 4; ++r) { float v = oT[d][r]; ssum += v; ssq += v * v; }
;     park[d].x = pack2(oT[d][0], oT[d][1]);
;     park[d].y = pack2(oT[d][2], oT[d][3]);
;   }
;   RO_WAIT_SYNC();
.LBB0_327:
	s_or_b64 exec, exec, s[0:1]
	v_mul_f32_e32 v103, v65, v65
	v_add_f32_e32 v104, 0, v64
	v_fmac_f32_e32 v103, v64, v64
	v_add_f32_e32 v104, v65, v104
	v_fmac_f32_e32 v103, v66, v66
	v_add_f32_e32 v104, v66, v104
	v_fmac_f32_e32 v103, v67, v67
	v_add_f32_e32 v104, v67, v104
	v_fmac_f32_e32 v103, v68, v68
	v_add_f32_e32 v104, v68, v104
	v_fmac_f32_e32 v103, v69, v69
	v_add_f32_e32 v104, v69, v104
	v_fmac_f32_e32 v103, v70, v70
	v_add_f32_e32 v104, v70, v104
	v_fmac_f32_e32 v103, v71, v71
	v_add_f32_e32 v104, v71, v104
	v_fmac_f32_e32 v103, v72, v72
	v_add_f32_e32 v104, v72, v104
	v_fmac_f32_e32 v103, v73, v73
	v_add_f32_e32 v104, v73, v104
	v_fmac_f32_e32 v103, v74, v74
	v_add_f32_e32 v104, v74, v104
	v_fmac_f32_e32 v103, v75, v75
	v_add_f32_e32 v104, v75, v104
	v_fmac_f32_e32 v103, v76, v76
	v_add_f32_e32 v104, v76, v104
	v_fmac_f32_e32 v103, v77, v77
	v_add_f32_e32 v104, v77, v104
	v_fmac_f32_e32 v103, v78, v78
	v_add_f32_e32 v104, v78, v104
	v_fmac_f32_e32 v103, v79, v79
	v_add_f32_e32 v104, v79, v104
	v_fmac_f32_e32 v103, v80, v80
	v_add_f32_e32 v104, v80, v104
	v_fmac_f32_e32 v103, v81, v81
	v_add_f32_e32 v104, v81, v104
	v_fmac_f32_e32 v103, v82, v82
	v_add_f32_e32 v104, v82, v104
	v_fmac_f32_e32 v103, v83, v83
	v_add_f32_e32 v104, v83, v104
	v_fmac_f32_e32 v103, v84, v84
	v_add_f32_e32 v104, v84, v104
	v_fmac_f32_e32 v103, v85, v85
	v_add_f32_e32 v104, v85, v104
	v_fmac_f32_e32 v103, v86, v86
	v_add_f32_e32 v104, v86, v104
	v_fmac_f32_e32 v103, v87, v87
	v_add_f32_e32 v104, v87, v104
	v_fmac_f32_e32 v103, v92, v92
	v_add_f32_e32 v104, v92, v104
	v_fmac_f32_e32 v103, v93, v93
	v_add_f32_e32 v104, v93, v104
	v_fmac_f32_e32 v103, v94, v94
	v_add_f32_e32 v104, v94, v104
	v_fmac_f32_e32 v103, v95, v95
	v_add_f32_e32 v104, v95, v104
	v_cvt_pk_bf16_f32 v101, v88, v89
	v_fmac_f32_e32 v103, v88, v88
	v_add_f32_e32 v88, v88, v104
	v_add_f32_e32 v88, v89, v88
	v_fmac_f32_e32 v103, v89, v89
	v_add_f32_e32 v88, v90, v88
	v_cvt_pk_bf16_f32 v100, v90, v91
	v_fmac_f32_e32 v103, v90, v90
	v_add_f32_e32 v90, v91, v88
	v_cvt_pk_bf16_f32 v88, v94, v95
	v_cvt_pk_bf16_f32 v89, v92, v93
	ds_read_b128 v[92:95], v113
	ds_read_b128 v[104:107], v113 offset:4096
	ds_read_b128 v[118:121], v113 offset:8192
	ds_read_b128 v[122:125], v113 offset:12288
	ds_read_b128 v[126:129], v113 offset:16384
	ds_read_b128 v[130:133], v113 offset:20480
	ds_read_b128 v[134:137], v113 offset:24576
	ds_read_b128 v[138:141], v113 offset:28672
	s_waitcnt lgkmcnt(0)
	v_fmac_f32_e32 v103, v91, v91
	v_mfma_f32_16x16x32_bf16 v[20:23], v[92:95], v[12:15], v[20:23]
	v_cmp_lt_i32_e32 vcc, v199, v198
	s_lshl_b32 s24, s24, 1
	v_lshlrev_b32_e32 v180, 1, v109
	v_mfma_f32_16x16x32_bf16 v[24:27], v[104:107], v[12:15], v[24:27]
	s_mov_b32 s0, 0x3b800000
	v_cvt_pk_bf16_f32 v64, v64, v65
	v_cvt_pk_bf16_f32 v66, v66, v67
	v_mfma_f32_16x16x32_bf16 v[40:43], v[118:121], v[12:15], v[40:43]
	v_cvt_pk_bf16_f32 v68, v68, v69
	v_cvt_pk_bf16_f32 v70, v70, v71
	v_cvt_pk_bf16_f32 v72, v72, v73
	v_mfma_f32_16x16x32_bf16 v[48:51], v[122:125], v[12:15], v[48:51]
	v_cvt_pk_bf16_f32 v74, v74, v75
	v_cvt_pk_bf16_f32 v76, v76, v77
	v_cvt_pk_bf16_f32 v78, v78, v79
	v_mfma_f32_16x16x32_bf16 v[52:55], v[126:129], v[12:15], v[52:55]
	v_cvt_pk_bf16_f32 v80, v80, v81
	v_cvt_pk_bf16_f32 v82, v82, v83
	v_cvt_pk_bf16_f32 v84, v84, v85
	v_mfma_f32_16x16x32_bf16 v[56:59], v[130:133], v[12:15], v[56:59]
	v_cvt_pk_bf16_f32 v86, v86, v87
	v_mfma_f32_16x16x32_bf16 v[60:63], v[134:137], v[12:15], v[60:63]
	v_mfma_f32_16x16x32_bf16 v[12:15], v[138:141], v[12:15], v[16:19]
	ds_read_b128 v[16:19], v111
	ds_read_b128 v[92:95], v111 offset:4096
	ds_read_b128 v[104:107], v111 offset:8192
	ds_read_b128 v[118:121], v111 offset:12288
	ds_read_b128 v[122:125], v111 offset:16384
	ds_read_b128 v[126:129], v111 offset:20480
	ds_read_b128 v[130:133], v111 offset:24576
	ds_read_b128 v[134:137], v111 offset:28672
	s_waitcnt lgkmcnt(0)
	s_nop 0
	v_mfma_f32_16x16x32_bf16 v[16:19], v[16:19], v[44:47], v[20:23]
	v_mfma_f32_16x16x32_bf16 v[20:23], v[92:95], v[44:47], v[24:27]
	v_mfma_f32_16x16x32_bf16 v[24:27], v[104:107], v[44:47], v[40:43]
	v_mfma_f32_16x16x32_bf16 v[40:43], v[118:121], v[44:47], v[48:51]
	v_mfma_f32_16x16x32_bf16 v[48:51], v[122:125], v[44:47], v[52:55]
	v_mfma_f32_16x16x32_bf16 v[52:55], v[126:129], v[44:47], v[56:59]
	v_mfma_f32_16x16x32_bf16 v[56:59], v[130:133], v[44:47], v[60:63]
	v_mfma_f32_16x16x32_bf16 v[12:15], v[134:137], v[44:47], v[12:15]
	ds_read_b128 v[44:47], v112
	ds_read_b128 v[60:63], v112 offset:4096
	ds_read_b128 v[92:95], v112 offset:8192
	ds_read_b128 v[104:107], v112 offset:12288
	ds_read_b128 v[118:121], v112 offset:16384
	ds_read_b128 v[122:125], v112 offset:20480
	ds_read_b128 v[126:129], v112 offset:24576
	ds_read_b128 v[130:133], v112 offset:28672
	s_waitcnt lgkmcnt(0)
	s_nop 0
	v_mfma_f32_16x16x32_bf16 v[16:19], v[44:47], v[4:7], v[16:19]
	v_mfma_f32_16x16x32_bf16 v[20:23], v[60:63], v[4:7], v[20:23]
	v_mfma_f32_16x16x32_bf16 v[24:27], v[92:95], v[4:7], v[24:27]
	v_mfma_f32_16x16x32_bf16 v[40:43], v[104:107], v[4:7], v[40:43]
	v_mfma_f32_16x16x32_bf16 v[44:47], v[118:121], v[4:7], v[48:51]
	v_mfma_f32_16x16x32_bf16 v[48:51], v[122:125], v[4:7], v[52:55]
	v_mfma_f32_16x16x32_bf16 v[52:55], v[126:129], v[4:7], v[56:59]
	v_mfma_f32_16x16x32_bf16 v[4:7], v[130:133], v[4:7], v[12:15]
	ds_read_b128 v[12:15], v102
	ds_read_b128 v[56:59], v102 offset:4096
	ds_read_b128 v[60:63], v102 offset:8192
	ds_read_b128 v[92:95], v102 offset:12288
	ds_read_b128 v[104:107], v102 offset:16384
	ds_read_b128 v[110:113], v102 offset:20480
	ds_read_b128 v[118:121], v102 offset:24576
	ds_read_b128 v[122:125], v102 offset:28672
	s_waitcnt lgkmcnt(0)
	s_nop 0
	v_mfma_f32_16x16x32_bf16 v[12:15], v[12:15], v[0:3], v[16:19]
	v_mfma_f32_16x16x32_bf16 v[16:19], v[56:59], v[0:3], v[20:23]
	v_mfma_f32_16x16x32_bf16 v[20:23], v[60:63], v[0:3], v[24:27]
	v_mfma_f32_16x16x32_bf16 v[24:27], v[92:95], v[0:3], v[40:43]
	v_mfma_f32_16x16x32_bf16 v[40:43], v[104:107], v[0:3], v[44:47]
	v_mfma_f32_16x16x32_bf16 v[44:47], v[110:113], v[0:3], v[48:51]
	v_mfma_f32_16x16x32_bf16 v[48:51], v[118:121], v[0:3], v[52:55]
	v_mfma_f32_16x16x32_bf16 v[0:3], v[122:125], v[0:3], v[4:7]
	s_waitcnt vmcnt(0)
	s_waitcnt vmcnt(0) lgkmcnt(0)
	s_barrier
; #define MFMA(a, b, c) __builtin_amdgcn_mfma_f32_16x16x32_bf16((a), (b), (c), 0, 0, 0)
; DEV float bflo(unsigned u) { return __uint_as_float(u << 16); }
; DEV float bfhi(unsigned u) { return __uint_as_float(u & 0xffff0000u); }
; DEV unsigned lds_off(const char* p) { return (unsigned)(unsigned long)((__attribute__((address_space(3))) const char*)p); }
; DEV void ro_cross(const char* buf, float xi, const bf16x8 (&qf)[4], f32x4 (&oT)[8], int l15, int q) {
;   const unsigned base = lds_off(buf) + (unsigned)(l15 * 256);
; #pragma unroll
;   for (int kd = 0; kd < 4; ++kd) {
;     u32x4 raw = __builtin_bit_cast(u32x4, qf[kd]);
;     u32x4 o;
;     o.x = pack2(bflo(raw.x) * xi, bfhi(raw.x) * xi);
;     o.y = pack2(bflo(raw.y) * xi, bfhi(raw.y) * xi);
;     o.z = pack2(bflo(raw.z) * xi, bfhi(raw.z) * xi);
;     o.w = pack2(bflo(raw.w) * xi, bfhi(raw.w) * xi);
;     bf16x8 qs = __builtin_bit_cast(bf16x8, o);
;     const unsigned a0 = base + (unsigned)((((kd * 4 + q) ^ l15) & 15) << 4);
;     bf16x8 ra[8];
;     asm volatile(
;         "ds_read_b128 %0, %8\n\t"
;         "ds_read_b128 %1, %8 offset:4096\n\t"
;         "ds_read_b128 %2, %8 offset:8192\n\t"
;         "ds_read_b128 %3, %8 offset:12288\n\t"
;         "ds_read_b128 %4, %8 offset:16384\n\t"
;         "ds_read_b128 %5, %8 offset:20480\n\t"
;         "ds_read_b128 %6, %8 offset:24576\n\t"
;         "ds_read_b128 %7, %8 offset:28672\n\t"
;         "s_waitcnt lgkmcnt(0)"
;         : "=&v"(ra[0]), "=&v"(ra[1]), "=&v"(ra[2]), "=&v"(ra[3]), "=&v"(ra[4]), "=&v"(ra[5]), "=&v"(ra[6]), "=&v"(ra[7])
;         : "v"(a0)
;         : "memory");
; #pragma unroll
;     for (int dvt = 0; dvt < 8; ++dvt) oT[dvt] = MFMA(ra[dvt], qs, oT[dvt]);
;   }
; __device__ __forceinline__ void ret_out_item(PREF P, int w, const u16* ST, char* smem) {
;     ...
;   ro_cross(X, xib, qf, oT, l15, q);
; #pragma unroll
;   for (int d = 0; d < 8; ++d)
; #pragma unroll
;     for (int r = 0; r < 4; ++r) { float v = oT[d][r]; ssum += v; ssq += v * v; }
;     ...
;   ssum += __shfl_xor(ssum, 16); ssum += __shfl_xor(ssum, 32);
;   ssq += __shfl_xor(ssq, 16); ssq += __shfl_xor(ssq, 32);
;   const float mu = ssum * (1.f / 256.f);
;   const float var = fmaxf(ssq * (1.f / 256.f) - mu * mu, 0.f);
	ds_read_b128 v[4:7], v117
	ds_read_b128 v[52:55], v117 offset:4096
	ds_read_b128 v[56:59], v117 offset:8192
	ds_read_b128 v[60:63], v117 offset:12288
	ds_read_b128 v[92:95], v117 offset:16384
	ds_read_b128 v[104:107], v117 offset:20480
	ds_read_b128 v[110:113], v117 offset:24576
	ds_read_b128 v[118:121], v117 offset:28672
	s_waitcnt lgkmcnt(0)
	s_nop 0
	v_mfma_f32_16x16x32_bf16 v[4:7], v[4:7], v[36:39], v[12:15]
	v_mfma_f32_16x16x32_bf16 v[12:15], v[52:55], v[36:39], v[16:19]
	v_mfma_f32_16x16x32_bf16 v[16:19], v[56:59], v[36:39], v[20:23]
	v_mfma_f32_16x16x32_bf16 v[20:23], v[60:63], v[36:39], v[24:27]
	v_mfma_f32_16x16x32_bf16 v[24:27], v[92:95], v[36:39], v[40:43]
	v_mfma_f32_16x16x32_bf16 v[40:43], v[104:107], v[36:39], v[44:47]
	v_mfma_f32_16x16x32_bf16 v[44:47], v[110:113], v[36:39], v[48:51]
	v_mfma_f32_16x16x32_bf16 v[0:3], v[118:121], v[36:39], v[0:3]
	ds_read_b128 v[36:39], v115
	ds_read_b128 v[48:51], v115 offset:4096
	ds_read_b128 v[52:55], v115 offset:8192
	ds_read_b128 v[56:59], v115 offset:12288
	ds_read_b128 v[60:63], v115 offset:16384
	ds_read_b128 v[92:95], v115 offset:20480
	ds_read_b128 v[104:107], v115 offset:24576
	ds_read_b128 v[110:113], v115 offset:28672
	s_waitcnt lgkmcnt(0)
	s_nop 0
	v_mfma_f32_16x16x32_bf16 v[4:7], v[36:39], v[32:35], v[4:7]
	v_mfma_f32_16x16x32_bf16 v[12:15], v[48:51], v[32:35], v[12:15]
	v_mfma_f32_16x16x32_bf16 v[16:19], v[52:55], v[32:35], v[16:19]
	v_mfma_f32_16x16x32_bf16 v[20:23], v[56:59], v[32:35], v[20:23]
	v_mfma_f32_16x16x32_bf16 v[24:27], v[60:63], v[32:35], v[24:27]
	v_mfma_f32_16x16x32_bf16 v[36:39], v[92:95], v[32:35], v[40:43]
	v_mfma_f32_16x16x32_bf16 v[40:43], v[104:107], v[32:35], v[44:47]
	v_mfma_f32_16x16x32_bf16 v[0:3], v[110:113], v[32:35], v[0:3]
	ds_read_b128 v[32:35], v114
	ds_read_b128 v[44:47], v114 offset:4096
	ds_read_b128 v[48:51], v114 offset:8192
	ds_read_b128 v[52:55], v114 offset:12288
	ds_read_b128 v[56:59], v114 offset:16384
	ds_read_b128 v[60:63], v114 offset:20480
	ds_read_b128 v[92:95], v114 offset:24576
	ds_read_b128 v[104:107], v114 offset:28672
	s_waitcnt lgkmcnt(0)
	s_nop 0
	v_mfma_f32_16x16x32_bf16 v[4:7], v[32:35], v[8:11], v[4:7]
	v_mfma_f32_16x16x32_bf16 v[12:15], v[44:47], v[8:11], v[12:15]
	v_mfma_f32_16x16x32_bf16 v[16:19], v[48:51], v[8:11], v[16:19]
	v_mfma_f32_16x16x32_bf16 v[44:47], v[52:55], v[8:11], v[20:23]
	v_mfma_f32_16x16x32_bf16 v[48:51], v[56:59], v[8:11], v[24:27]
	v_mfma_f32_16x16x32_bf16 v[36:39], v[60:63], v[8:11], v[36:39]
	v_mfma_f32_16x16x32_bf16 v[40:43], v[92:95], v[8:11], v[40:43]
	v_mfma_f32_16x16x32_bf16 v[0:3], v[104:107], v[8:11], v[0:3]
	ds_read_b128 v[8:11], v116
	ds_read_b128 v[20:23], v116 offset:4096
	ds_read_b128 v[52:55], v116 offset:8192
	ds_read_b128 v[56:59], v116 offset:12288
	ds_read_b128 v[60:63], v116 offset:16384
	ds_read_b128 v[92:95], v116 offset:20480
	ds_read_b128 v[104:107], v116 offset:24576
	ds_read_b128 v[110:113], v116 offset:28672
	s_waitcnt lgkmcnt(0)
	s_nop 0
	v_mfma_f32_16x16x32_bf16 v[32:35], v[8:11], v[28:31], v[4:7]
	v_mfma_f32_16x16x32_bf16 v[24:27], v[20:23], v[28:31], v[12:15]
	v_mfma_f32_16x16x32_bf16 v[20:23], v[52:55], v[28:31], v[16:19]
	s_nop 5
	v_fmac_f32_e32 v103, v32, v32
	v_fmac_f32_e32 v103, v33, v33
	v_fmac_f32_e32 v103, v34, v34
	v_mfma_f32_16x16x32_bf16 v[16:19], v[56:59], v[28:31], v[44:47]
	v_fmac_f32_e32 v103, v35, v35
	v_fmac_f32_e32 v103, v24, v24
	v_fmac_f32_e32 v103, v25, v25
	v_mfma_f32_16x16x32_bf16 v[12:15], v[60:63], v[28:31], v[48:51]
	v_fmac_f32_e32 v103, v26, v26
	v_fmac_f32_e32 v103, v27, v27
	v_fmac_f32_e32 v103, v20, v20
	v_mfma_f32_16x16x32_bf16 v[8:11], v[92:95], v[28:31], v[36:39]
	v_fmac_f32_e32 v103, v21, v21
	v_fmac_f32_e32 v103, v22, v22
	v_fmac_f32_e32 v103, v23, v23
	v_mfma_f32_16x16x32_bf16 v[4:7], v[104:107], v[28:31], v[40:43]
	v_fmac_f32_e32 v103, v16, v16
	v_fmac_f32_e32 v103, v17, v17
	v_fmac_f32_e32 v103, v18, v18
	v_mfma_f32_16x16x32_bf16 v[0:3], v[110:113], v[28:31], v[0:3]
	v_add_f32_e32 v28, v90, v32
	v_add_f32_e32 v28, v33, v28
	v_add_f32_e32 v28, v34, v28
	v_add_f32_e32 v28, v35, v28
	v_add_f32_e32 v28, v24, v28
	v_add_f32_e32 v28, v25, v28
	v_add_f32_e32 v28, v26, v28
	v_add_f32_e32 v28, v27, v28
	v_add_f32_e32 v28, v20, v28
	v_add_f32_e32 v28, v21, v28
	v_add_f32_e32 v28, v22, v28
	v_add_f32_e32 v28, v23, v28
	v_add_f32_e32 v28, v16, v28
	v_add_f32_e32 v28, v17, v28
	v_add_f32_e32 v28, v18, v28
	v_add_f32_e32 v28, v19, v28
	v_add_f32_e32 v28, v12, v28
	v_add_f32_e32 v28, v13, v28
	v_fmac_f32_e32 v103, v19, v19
	v_add_f32_e32 v28, v14, v28
	v_fmac_f32_e32 v103, v12, v12
	v_add_f32_e32 v28, v15, v28
	v_fmac_f32_e32 v103, v13, v13
	v_add_f32_e32 v30, v8, v28
	v_mov_b32_e32 v28, v8
	v_mov_b32_e32 v29, v15
	v_fmac_f32_e32 v103, v14, v14
	v_mul_f32_e32 v28, v28, v28
	v_mul_f32_e32 v29, v29, v29
	ds_read2_b64 v[38:41], v108 offset0:33 offset1:40
	v_add_f32_e32 v29, v29, v103
	v_add_f32_e32 v36, v28, v29
	v_add_f32_e32 v28, v9, v30
	v_add_f32_e32 v37, v10, v28
	v_mul_f32_e32 v28, v10, v10
	v_mul_f32_e32 v29, v11, v11
	v_mul_f32_e32 v30, v8, v8
	v_mul_f32_e32 v31, v9, v9
	v_lshlrev_b32_e32 v44, 16, v64
	v_add_f32_e32 v29, v31, v36
	v_add_f32_e32 v30, v28, v29
	v_add_f32_e32 v28, v11, v37
	v_add_f32_e32 v31, v4, v28
	v_mov_b32_e32 v28, v4
	v_mov_b32_e32 v29, v11
	v_mul_f32_e32 v28, v28, v28
	v_mul_f32_e32 v29, v29, v29
	v_and_b32_e32 v45, 0xffff0000, v64
	v_add_f32_e32 v29, v29, v30
	v_add_f32_e32 v36, v28, v29
	v_add_f32_e32 v28, v5, v31
	v_add_f32_e32 v37, v6, v28
	v_mul_f32_e32 v28, v6, v6
	v_mul_f32_e32 v29, v7, v7
	v_mul_f32_e32 v30, v4, v4
	v_mul_f32_e32 v31, v5, v5
	s_nop 0
	v_add_f32_e32 v29, v31, v36
	v_add_f32_e32 v30, v28, v29
	v_add_f32_e32 v28, v7, v37
	v_add_f32_e32 v31, v0, v28
	v_mov_b32_e32 v28, v0
	v_mov_b32_e32 v29, v7
	v_mul_f32_e32 v28, v28, v28
	v_mul_f32_e32 v29, v29, v29
	v_mul_f32_e32 v36, v0, v0
	v_mul_f32_e32 v37, v1, v1
	v_add_f32_e32 v29, v29, v30
	v_add_f32_e32 v28, v28, v29
	v_add_f32_e32 v29, v1, v31
	v_mul_f32_e32 v30, v2, v2
	v_mul_f32_e32 v31, v3, v3
	v_add_f32_e32 v28, v37, v28
	v_cndmask_b32_e32 v31, v196, v199, vcc
	v_cmp_lt_i32_e32 vcc, v197, v198
	v_lshlrev_b32_e32 v36, 2, v31
	v_add_f32_e32 v29, v2, v29
	v_cndmask_b32_e32 v31, v196, v197, vcc
	v_add_f32_e32 v30, v30, v28
	v_mul_f32_e32 v28, v3, v3
	v_lshlrev_b32_e32 v37, 2, v31
	v_mov_b32_e32 v31, v3
	v_add_f32_e32 v28, v30, v28
	v_add_f32_e32 v29, v31, v29
	ds_bpermute_b32 v31, v36, v29
	ds_bpermute_b32 v30, v36, v28
	s_waitcnt lgkmcnt(0)
; DEV float bflo(unsigned u) { return __uint_as_float(u << 16); }
; DEV float bfhi(unsigned u) { return __uint_as_float(u & 0xffff0000u); }
; DEV float sigm(float x) { return 1.f / (1.f + __expf(-x)); }
; #define P (*launderP(lp))
; __device__ __forceinline__ void ret_out_item(PREF P, int w, const u16* ST, char* smem) {
;     ...
;   ssum += __shfl_xor(ssum, 16); ssum += __shfl_xor(ssum, 32);
;   ssq += __shfl_xor(ssq, 16); ssq += __shfl_xor(ssq, 32);
;   const float mu = ssum * (1.f / 256.f);
;   const float var = fmaxf(ssq * (1.f / 256.f) - mu * mu, 0.f);
;   const float rs = rsqrtf(var + LN_EPS);
;   const int tok = tok0 + i;
;   const u16* grow = P.Rg + (size_t)tok * 2048 + h * 256 + q * 4;
;   u16* orow = P.ret + (size_t)tok * 2048 + h * 256 + q * 4;
; #pragma unroll
;   for (int d = 0; d < 8; ++d) {
;     {
;       u32x2 pvv = park[d];
;       uint2 g = *(const uint2*)(grow + d * 16);
;       float g0 = bflo(g.x), g1 = bfhi(g.x), g2 = bflo(g.y), g3 = bfhi(g.y);
;       uint2 o;
;       o.x = pack2((bflo(pvv.x) - mu) * rs * g0 * sigm(g0), (bfhi(pvv.x) - mu) * rs * g1 * sigm(g1));
;       o.y = pack2((bflo(pvv.y) - mu) * rs * g2 * sigm(g2), (bfhi(pvv.y) - mu) * rs * g3 * sigm(g3));
;       *(uint2*)(orow + d * 16) = o;
	v_add_f32_e32 v28, v28, v30
	v_add_f32_e32 v29, v29, v31
	ds_bpermute_b32 v31, v37, v29
	ds_bpermute_b32 v30, v37, v28
	v_lshlrev_b64 v[36:37], 1, v[98:99]
	v_lshl_add_u64 v[38:39], v[38:39], 0, v[36:37]
	v_lshl_add_u64 v[38:39], v[38:39], 0, s[24:25]
	v_lshl_add_u64 v[38:39], v[38:39], 0, v[180:181]
	v_lshl_add_u64 v[36:37], v[40:41], 0, v[36:37]
	flat_load_dwordx2 v[40:41], v[38:39]
	s_waitcnt lgkmcnt(0)
	v_add_f32_e32 v28, v28, v30
	v_add_f32_e32 v29, v29, v31
	v_lshl_add_u64 v[36:37], v[36:37], 0, s[24:25]
	v_mul_f32_e32 v28, s0, v28
	v_mul_f32_e32 v29, s0, v29
	s_mov_b32 s0, 0x800000
	v_fma_f32 v30, -v29, v29, v28
	v_max_f32_e32 v30, 0, v30
	v_add_f32_e32 v30, 0x3727c5ac, v30
	v_cmp_gt_f32_e32 vcc, s0, v30
	v_mul_f32_e32 v31, 0x4b800000, v30
	v_sub_f32_e32 v44, v44, v29
	v_sub_f32_e32 v45, v45, v29
	v_cndmask_b32_e32 v30, v30, v31, vcc
	v_rsq_f32_e32 v30, v30
	v_lshl_add_u64 v[36:37], v[36:37], 0, v[180:181]
	v_sub_f32_e32 v32, v32, v29
	v_sub_f32_e32 v33, v33, v29
	v_sub_f32_e32 v34, v34, v29
	v_sub_f32_e32 v35, v35, v29
	v_mul_f32_e32 v31, 0x45800000, v30
	v_cndmask_b32_e32 v30, v30, v31, vcc
	v_sub_f32_e32 v24, v24, v29
	v_sub_f32_e32 v25, v25, v29
	v_sub_f32_e32 v26, v26, v29
	v_sub_f32_e32 v27, v27, v29
	v_sub_f32_e32 v20, v20, v29
	v_sub_f32_e32 v21, v21, v29
	v_sub_f32_e32 v22, v22, v29
	v_sub_f32_e32 v23, v23, v29
	v_sub_f32_e32 v16, v16, v29
	v_sub_f32_e32 v17, v17, v29
	v_sub_f32_e32 v18, v18, v29
	v_sub_f32_e32 v19, v19, v29
	v_sub_f32_e32 v12, v12, v29
	v_sub_f32_e32 v13, v13, v29
	v_sub_f32_e32 v14, v14, v29
	v_sub_f32_e32 v15, v15, v29
	v_sub_f32_e32 v8, v8, v29
	v_sub_f32_e32 v9, v9, v29
	v_sub_f32_e32 v10, v10, v29
	v_sub_f32_e32 v11, v11, v29
	v_sub_f32_e32 v4, v4, v29
	v_sub_f32_e32 v5, v5, v29
	v_sub_f32_e32 v6, v6, v29
	v_sub_f32_e32 v7, v7, v29
	v_sub_f32_e32 v0, v0, v29
	v_sub_f32_e32 v1, v1, v29
	v_sub_f32_e32 v2, v2, v29
	v_sub_f32_e32 v3, v3, v29
	s_waitcnt vmcnt(0)
	v_lshlrev_b32_e32 v42, 16, v40
	v_and_b32_e32 v43, 0xffff0000, v40
	v_mul_f32_e32 v31, 0xbfb8aa3b, v42
	v_exp_f32_e32 v46, v31
	v_mul_f32_e32 v44, v44, v30
	v_mul_f32_e32 v45, v45, v30
	v_mul_f32_e32 v31, 0xbfb8aa3b, v43
	v_exp_f32_e32 v47, v31
	v_mul_f32_e32 v44, v44, v42
	v_mul_f32_e32 v45, v45, v43
	v_lshlrev_b32_e32 v40, 16, v41
	v_and_b32_e32 v41, 0xffff0000, v41
	v_pk_add_f32 v[42:43], v[46:47], 1.0 op_sel_hi:[1,0]
	s_nop 0
	v_div_scale_f32 v31, s[0:1], v43, v43, 1.0
	v_rcp_f32_e32 v46, v31
	s_nop 0
	v_fma_f32 v47, -v31, v46, 1.0
	v_fmac_f32_e32 v46, v47, v46
	v_div_scale_f32 v47, vcc, 1.0, v43, 1.0
	v_mul_f32_e32 v48, v47, v46
	v_fma_f32 v49, -v31, v48, v47
	v_fmac_f32_e32 v48, v49, v46
	v_fma_f32 v31, -v31, v48, v47
	v_div_fmas_f32 v31, v31, v46, v48
	v_div_fixup_f32 v43, v31, v43, 1.0
	v_div_scale_f32 v31, s[0:1], v42, v42, 1.0
	v_rcp_f32_e32 v46, v31
	s_nop 0
	v_fma_f32 v47, -v31, v46, 1.0
	v_fmac_f32_e32 v46, v47, v46
	v_div_scale_f32 v47, vcc, 1.0, v42, 1.0
	v_mul_f32_e32 v48, v47, v46
	v_fma_f32 v49, -v31, v48, v47
	v_fmac_f32_e32 v48, v49, v46
	v_fma_f32 v31, -v31, v48, v47
	v_div_fmas_f32 v31, v31, v46, v48
	v_div_fixup_f32 v42, v31, v42, 1.0
	v_mul_f32_e32 v42, v42, v44
	v_mul_f32_e32 v43, v43, v45
	v_lshlrev_b32_e32 v44, 16, v66
	v_and_b32_e32 v45, 0xffff0000, v66
	v_mul_f32_e32 v31, 0xbfb8aa3b, v40
	v_sub_f32_e32 v44, v44, v29
	v_sub_f32_e32 v45, v45, v29
	v_exp_f32_e32 v46, v31
	v_mul_f32_e32 v44, v44, v30
	v_mul_f32_e32 v45, v45, v30
	v_mul_f32_e32 v31, 0xbfb8aa3b, v41
	v_exp_f32_e32 v47, v31
	v_mul_f32_e32 v44, v44, v40
	v_mul_f32_e32 v45, v45, v41
	v_cvt_pk_bf16_f32 v42, v42, v43
	v_pk_add_f32 v[40:41], v[46:47], 1.0 op_sel_hi:[1,0]
	s_nop 0
	v_div_scale_f32 v31, s[0:1], v41, v41, 1.0
	v_rcp_f32_e32 v43, v31
	s_nop 0
	v_fma_f32 v46, -v31, v43, 1.0
	v_fmac_f32_e32 v43, v46, v43
	v_div_scale_f32 v46, vcc, 1.0, v41, 1.0
	v_mul_f32_e32 v47, v46, v43
	v_fma_f32 v48, -v31, v47, v46
	v_fmac_f32_e32 v47, v48, v43
	v_fma_f32 v31, -v31, v47, v46
	v_div_fmas_f32 v31, v31, v43, v47
	v_div_fixup_f32 v41, v31, v41, 1.0
	v_div_scale_f32 v31, s[0:1], v40, v40, 1.0
	v_rcp_f32_e32 v43, v31
	s_nop 0
	v_fma_f32 v46, -v31, v43, 1.0
	v_fmac_f32_e32 v43, v46, v43
	v_div_scale_f32 v46, vcc, 1.0, v40, 1.0
	v_mul_f32_e32 v47, v46, v43
	v_fma_f32 v48, -v31, v47, v46
	v_fmac_f32_e32 v47, v48, v43
	v_fma_f32 v31, -v31, v47, v46
	v_div_fmas_f32 v31, v31, v43, v47
	v_div_fixup_f32 v40, v31, v40, 1.0
	v_mul_f32_e32 v40, v40, v44
	v_mul_f32_e32 v41, v41, v45
	s_nop 0
	v_cvt_pk_bf16_f32 v43, v40, v41
	flat_store_dwordx2 v[36:37], v[42:43]
	flat_load_dwordx2 v[40:41], v[38:39] offset:256
	s_waitcnt vmcnt(0) lgkmcnt(0)
; DEV float bflo(unsigned u) { return __uint_as_float(u << 16); }
; DEV float bfhi(unsigned u) { return __uint_as_float(u & 0xffff0000u); }
; DEV float sigm(float x) { return 1.f / (1.f + __expf(-x)); }
; __device__ __forceinline__ void ret_out_item(PREF P, int w, const u16* ST, char* smem) {
;     ...
; #pragma unroll
;   for (int d = 0; d < 8; ++d) {
;     {
;       u32x2 pvv = park[d];
;       uint2 g = *(const uint2*)(grow + d * 16);
;       float g0 = bflo(g.x), g1 = bfhi(g.x), g2 = bflo(g.y), g3 = bfhi(g.y);
;       uint2 o;
;       o.x = pack2((bflo(pvv.x) - mu) * rs * g0 * sigm(g0), (bfhi(pvv.x) - mu) * rs * g1 * sigm(g1));
;       o.y = pack2((bflo(pvv.y) - mu) * rs * g2 * sigm(g2), (bfhi(pvv.y) - mu) * rs * g3 * sigm(g3));
;       *(uint2*)(orow + d * 16) = o;
;     }
;     {
;       uint2 g = *(const uint2*)(grow + 128 + d * 16);
;       float g0 = bflo(g.x), g1 = bfhi(g.x), g2 = bflo(g.y), g3 = bfhi(g.y);
;       uint2 o;
;       o.x = pack2((oT[d][0] - mu) * rs * g0 * sigm(g0), (oT[d][1] - mu) * rs * g1 * sigm(g1));
;       o.y = pack2((oT[d][2] - mu) * rs * g2 * sigm(g2), (oT[d][3] - mu) * rs * g3 * sigm(g3));
;       *(uint2*)(orow + 128 + d * 16) = o;
;     }
;   }
	v_lshlrev_b32_e32 v42, 16, v40
	v_and_b32_e32 v43, 0xffff0000, v40
	v_mul_f32_e32 v31, 0xbfb8aa3b, v42
	v_exp_f32_e32 v44, v31
	v_mul_f32_e32 v32, v32, v30
	v_mul_f32_e32 v33, v33, v30
	v_mul_f32_e32 v31, 0xbfb8aa3b, v43
	v_exp_f32_e32 v45, v31
	v_mul_f32_e32 v32, v32, v42
	v_mul_f32_e32 v33, v33, v43
	v_lshlrev_b32_e32 v40, 16, v41
	v_and_b32_e32 v41, 0xffff0000, v41
	v_pk_add_f32 v[42:43], v[44:45], 1.0 op_sel_hi:[1,0]
	s_nop 0
	v_div_scale_f32 v31, s[0:1], v43, v43, 1.0
	v_rcp_f32_e32 v44, v31
	s_nop 0
	v_fma_f32 v45, -v31, v44, 1.0
	v_fmac_f32_e32 v44, v45, v44
	v_div_scale_f32 v45, vcc, 1.0, v43, 1.0
	v_mul_f32_e32 v46, v45, v44
	v_fma_f32 v47, -v31, v46, v45
	v_fmac_f32_e32 v46, v47, v44
	v_fma_f32 v31, -v31, v46, v45
	v_div_fmas_f32 v31, v31, v44, v46
	v_div_fixup_f32 v43, v31, v43, 1.0
	v_div_scale_f32 v31, s[0:1], v42, v42, 1.0
	v_rcp_f32_e32 v44, v31
	s_nop 0
	v_fma_f32 v45, -v31, v44, 1.0
	v_fmac_f32_e32 v44, v45, v44
	v_div_scale_f32 v45, vcc, 1.0, v42, 1.0
	v_mul_f32_e32 v46, v45, v44
	v_fma_f32 v47, -v31, v46, v45
	v_fmac_f32_e32 v46, v47, v44
	v_fma_f32 v31, -v31, v46, v45
	v_div_fmas_f32 v31, v31, v44, v46
	v_div_fixup_f32 v42, v31, v42, 1.0
	v_mul_f32_e32 v31, 0xbfb8aa3b, v40
	v_mul_f32_e32 v32, v42, v32
	v_mul_f32_e32 v33, v43, v33
	v_exp_f32_e32 v42, v31
	v_mul_f32_e32 v34, v34, v30
	v_mul_f32_e32 v35, v35, v30
	v_mul_f32_e32 v31, 0xbfb8aa3b, v41
	v_exp_f32_e32 v43, v31
	v_mul_f32_e32 v34, v34, v40
	v_mul_f32_e32 v35, v35, v41
	v_cvt_pk_bf16_f32 v32, v32, v33
	v_pk_add_f32 v[40:41], v[42:43], 1.0 op_sel_hi:[1,0]
	s_nop 0
	v_div_scale_f32 v31, s[0:1], v41, v41, 1.0
	v_rcp_f32_e32 v33, v31
	s_nop 0
	v_fma_f32 v42, -v31, v33, 1.0
	v_fmac_f32_e32 v33, v42, v33
	v_div_scale_f32 v42, vcc, 1.0, v41, 1.0
	v_mul_f32_e32 v43, v42, v33
	v_fma_f32 v44, -v31, v43, v42
	v_fmac_f32_e32 v43, v44, v33
	v_fma_f32 v31, -v31, v43, v42
	v_div_fmas_f32 v31, v31, v33, v43
	v_div_fixup_f32 v41, v31, v41, 1.0
	v_div_scale_f32 v31, s[0:1], v40, v40, 1.0
	v_rcp_f32_e32 v33, v31
	s_nop 0
	v_fma_f32 v42, -v31, v33, 1.0
	v_fmac_f32_e32 v33, v42, v33
	v_div_scale_f32 v42, vcc, 1.0, v40, 1.0
	v_mul_f32_e32 v43, v42, v33
	v_fma_f32 v44, -v31, v43, v42
	v_fmac_f32_e32 v43, v44, v33
	v_fma_f32 v31, -v31, v43, v42
	v_div_fmas_f32 v31, v31, v33, v43
	v_div_fixup_f32 v40, v31, v40, 1.0
	v_mul_f32_e32 v34, v40, v34
	v_mul_f32_e32 v35, v41, v35
	v_lshlrev_b32_e32 v40, 16, v68
	v_cvt_pk_bf16_f32 v33, v34, v35
	flat_store_dwordx2 v[36:37], v[32:33] offset:256
	flat_load_dwordx2 v[32:33], v[38:39] offset:32
	v_and_b32_e32 v41, 0xffff0000, v68
	v_sub_f32_e32 v40, v40, v29
	v_sub_f32_e32 v41, v41, v29
	s_waitcnt vmcnt(0) lgkmcnt(0)
	v_lshlrev_b32_e32 v34, 16, v32
	v_and_b32_e32 v35, 0xffff0000, v32
	v_mul_f32_e32 v31, 0xbfb8aa3b, v34
	v_exp_f32_e32 v42, v31
	v_mul_f32_e32 v40, v40, v30
	v_mul_f32_e32 v41, v41, v30
	v_mul_f32_e32 v31, 0xbfb8aa3b, v35
	v_exp_f32_e32 v43, v31
	v_mul_f32_e32 v40, v40, v34
	v_mul_f32_e32 v41, v41, v35
	v_lshlrev_b32_e32 v32, 16, v33
	v_and_b32_e32 v33, 0xffff0000, v33
	v_pk_add_f32 v[34:35], v[42:43], 1.0 op_sel_hi:[1,0]
	s_nop 0
	v_div_scale_f32 v31, s[0:1], v35, v35, 1.0
	v_rcp_f32_e32 v42, v31
	s_nop 0
	v_fma_f32 v43, -v31, v42, 1.0
	v_fmac_f32_e32 v42, v43, v42
	v_div_scale_f32 v43, vcc, 1.0, v35, 1.0
	v_mul_f32_e32 v44, v43, v42
	v_fma_f32 v45, -v31, v44, v43
	v_fmac_f32_e32 v44, v45, v42
	v_fma_f32 v31, -v31, v44, v43
	v_div_fmas_f32 v31, v31, v42, v44
	v_div_fixup_f32 v35, v31, v35, 1.0
	v_div_scale_f32 v31, s[0:1], v34, v34, 1.0
	v_rcp_f32_e32 v42, v31
	s_nop 0
	v_fma_f32 v43, -v31, v42, 1.0
	v_fmac_f32_e32 v42, v43, v42
	v_div_scale_f32 v43, vcc, 1.0, v34, 1.0
	v_mul_f32_e32 v44, v43, v42
	v_fma_f32 v45, -v31, v44, v43
	v_fmac_f32_e32 v44, v45, v42
	v_fma_f32 v31, -v31, v44, v43
	v_div_fmas_f32 v31, v31, v42, v44
	v_div_fixup_f32 v34, v31, v34, 1.0
	v_mul_f32_e32 v34, v34, v40
	v_mul_f32_e32 v35, v35, v41
	v_lshlrev_b32_e32 v40, 16, v70
	v_and_b32_e32 v41, 0xffff0000, v70
	v_mul_f32_e32 v31, 0xbfb8aa3b, v32
	v_sub_f32_e32 v40, v40, v29
	v_sub_f32_e32 v41, v41, v29
	v_exp_f32_e32 v42, v31
	v_mul_f32_e32 v40, v40, v30
	v_mul_f32_e32 v41, v41, v30
	v_mul_f32_e32 v31, 0xbfb8aa3b, v33
	v_exp_f32_e32 v43, v31
	v_mul_f32_e32 v40, v40, v32
	v_mul_f32_e32 v41, v41, v33
	v_cvt_pk_bf16_f32 v34, v34, v35
	v_pk_add_f32 v[32:33], v[42:43], 1.0 op_sel_hi:[1,0]
	s_nop 0
	v_div_scale_f32 v31, s[0:1], v33, v33, 1.0
	v_rcp_f32_e32 v35, v31
	s_nop 0
	v_fma_f32 v42, -v31, v35, 1.0
	v_fmac_f32_e32 v35, v42, v35
	v_div_scale_f32 v42, vcc, 1.0, v33, 1.0
	v_mul_f32_e32 v43, v42, v35
	v_fma_f32 v44, -v31, v43, v42
	v_fmac_f32_e32 v43, v44, v35
	v_fma_f32 v31, -v31, v43, v42
	v_div_fmas_f32 v31, v31, v35, v43
	v_div_fixup_f32 v33, v31, v33, 1.0
	v_div_scale_f32 v31, s[0:1], v32, v32, 1.0
	v_rcp_f32_e32 v35, v31
	s_nop 0
	v_fma_f32 v42, -v31, v35, 1.0
	v_fmac_f32_e32 v35, v42, v35
	v_div_scale_f32 v42, vcc, 1.0, v32, 1.0
	v_mul_f32_e32 v43, v42, v35
	v_fma_f32 v44, -v31, v43, v42
	v_fmac_f32_e32 v43, v44, v35
	v_fma_f32 v31, -v31, v43, v42
	v_div_fmas_f32 v31, v31, v35, v43
	v_div_fixup_f32 v32, v31, v32, 1.0
	v_mul_f32_e32 v32, v32, v40
	v_mul_f32_e32 v33, v33, v41
	s_nop 0
	v_cvt_pk_bf16_f32 v35, v32, v33
	flat_store_dwordx2 v[36:37], v[34:35] offset:32
	flat_load_dwordx2 v[32:33], v[38:39] offset:288
	s_waitcnt vmcnt(0) lgkmcnt(0)
; DEV float bflo(unsigned u) { return __uint_as_float(u << 16); }
; DEV float bfhi(unsigned u) { return __uint_as_float(u & 0xffff0000u); }
; DEV float sigm(float x) { return 1.f / (1.f + __expf(-x)); }
; __device__ __forceinline__ void ret_out_item(PREF P, int w, const u16* ST, char* smem) {
;     ...
; #pragma unroll
;   for (int d = 0; d < 8; ++d) {
;     {
;       u32x2 pvv = park[d];
;       uint2 g = *(const uint2*)(grow + d * 16);
;       float g0 = bflo(g.x), g1 = bfhi(g.x), g2 = bflo(g.y), g3 = bfhi(g.y);
;       uint2 o;
;       o.x = pack2((bflo(pvv.x) - mu) * rs * g0 * sigm(g0), (bfhi(pvv.x) - mu) * rs * g1 * sigm(g1));
;       o.y = pack2((bflo(pvv.y) - mu) * rs * g2 * sigm(g2), (bfhi(pvv.y) - mu) * rs * g3 * sigm(g3));
;       *(uint2*)(orow + d * 16) = o;
;     }
;     {
;       uint2 g = *(const uint2*)(grow + 128 + d * 16);
;       float g0 = bflo(g.x), g1 = bfhi(g.x), g2 = bflo(g.y), g3 = bfhi(g.y);
;       uint2 o;
;       o.x = pack2((oT[d][0] - mu) * rs * g0 * sigm(g0), (oT[d][1] - mu) * rs * g1 * sigm(g1));
;       o.y = pack2((oT[d][2] - mu) * rs * g2 * sigm(g2), (oT[d][3] - mu) * rs * g3 * sigm(g3));
;       *(uint2*)(orow + 128 + d * 16) = o;
;     }
;   }
	v_lshlrev_b32_e32 v34, 16, v32
	v_and_b32_e32 v35, 0xffff0000, v32
	v_mul_f32_e32 v31, 0xbfb8aa3b, v34
	v_exp_f32_e32 v40, v31
	v_mul_f32_e32 v24, v24, v30
	v_mul_f32_e32 v25, v25, v30
	v_mul_f32_e32 v31, 0xbfb8aa3b, v35
	v_exp_f32_e32 v41, v31
	v_mul_f32_e32 v24, v24, v34
	v_mul_f32_e32 v25, v25, v35
	v_lshlrev_b32_e32 v32, 16, v33
	v_and_b32_e32 v33, 0xffff0000, v33
	v_pk_add_f32 v[34:35], v[40:41], 1.0 op_sel_hi:[1,0]
	s_nop 0
	v_div_scale_f32 v31, s[0:1], v35, v35, 1.0
	v_rcp_f32_e32 v40, v31
	s_nop 0
	v_fma_f32 v41, -v31, v40, 1.0
	v_fmac_f32_e32 v40, v41, v40
	v_div_scale_f32 v41, vcc, 1.0, v35, 1.0
	v_mul_f32_e32 v42, v41, v40
	v_fma_f32 v43, -v31, v42, v41
	v_fmac_f32_e32 v42, v43, v40
	v_fma_f32 v31, -v31, v42, v41
	v_div_fmas_f32 v31, v31, v40, v42
	v_div_fixup_f32 v35, v31, v35, 1.0
	v_div_scale_f32 v31, s[0:1], v34, v34, 1.0
	v_rcp_f32_e32 v40, v31
	s_nop 0
	v_fma_f32 v41, -v31, v40, 1.0
	v_fmac_f32_e32 v40, v41, v40
	v_div_scale_f32 v41, vcc, 1.0, v34, 1.0
	v_mul_f32_e32 v42, v41, v40
	v_fma_f32 v43, -v31, v42, v41
	v_fmac_f32_e32 v42, v43, v40
	v_fma_f32 v31, -v31, v42, v41
	v_div_fmas_f32 v31, v31, v40, v42
	v_div_fixup_f32 v34, v31, v34, 1.0
	v_mul_f32_e32 v24, v34, v24
	v_mul_f32_e32 v25, v35, v25
	v_mul_f32_e32 v26, v26, v30
	v_mul_f32_e32 v27, v27, v30
	v_cvt_pk_bf16_f32 v24, v24, v25
	v_mul_f32_e32 v25, 0xbfb8aa3b, v32
	v_exp_f32_e32 v34, v25
	v_mul_f32_e32 v25, 0xbfb8aa3b, v33
	v_exp_f32_e32 v35, v25
	v_mul_f32_e32 v26, v26, v32
	v_mul_f32_e32 v27, v27, v33
	v_pk_add_f32 v[32:33], v[34:35], 1.0 op_sel_hi:[1,0]
	s_nop 0
	v_div_scale_f32 v25, s[0:1], v33, v33, 1.0
	v_rcp_f32_e32 v31, v25
	s_nop 0
	v_fma_f32 v34, -v25, v31, 1.0
	v_fmac_f32_e32 v31, v34, v31
	v_div_scale_f32 v34, vcc, 1.0, v33, 1.0
	v_mul_f32_e32 v35, v34, v31
	v_fma_f32 v40, -v25, v35, v34
	v_fmac_f32_e32 v35, v40, v31
	v_fma_f32 v25, -v25, v35, v34
	v_div_fmas_f32 v25, v25, v31, v35
	v_div_fixup_f32 v33, v25, v33, 1.0
	v_div_scale_f32 v25, s[0:1], v32, v32, 1.0
	v_rcp_f32_e32 v31, v25
	s_nop 0
	v_fma_f32 v34, -v25, v31, 1.0
	v_fmac_f32_e32 v31, v34, v31
	v_div_scale_f32 v34, vcc, 1.0, v32, 1.0
	v_mul_f32_e32 v35, v34, v31
	v_fma_f32 v40, -v25, v35, v34
	v_fmac_f32_e32 v35, v40, v31
	v_fma_f32 v25, -v25, v35, v34
	v_div_fmas_f32 v25, v25, v31, v35
	v_div_fixup_f32 v32, v25, v32, 1.0
	v_mul_f32_e32 v26, v32, v26
	v_mul_f32_e32 v27, v33, v27
	v_lshlrev_b32_e32 v32, 16, v72
	v_cvt_pk_bf16_f32 v25, v26, v27
	flat_store_dwordx2 v[36:37], v[24:25] offset:288
	flat_load_dwordx2 v[24:25], v[38:39] offset:64
	v_and_b32_e32 v33, 0xffff0000, v72
	v_sub_f32_e32 v32, v32, v29
	v_sub_f32_e32 v33, v33, v29
	s_waitcnt vmcnt(0) lgkmcnt(0)
	v_lshlrev_b32_e32 v26, 16, v24
	v_mul_f32_e32 v31, 0xbfb8aa3b, v26
	v_and_b32_e32 v27, 0xffff0000, v24
	v_mul_f32_e32 v32, v32, v30
	v_mul_f32_e32 v33, v33, v30
	v_exp_f32_e32 v34, v31
	v_mul_f32_e32 v32, v32, v26
	v_mul_f32_e32 v33, v33, v27
	v_mul_f32_e32 v26, 0xbfb8aa3b, v27
	v_exp_f32_e32 v35, v26
	v_lshlrev_b32_e32 v24, 16, v25
	v_and_b32_e32 v25, 0xffff0000, v25
	v_pk_add_f32 v[26:27], v[34:35], 1.0 op_sel_hi:[1,0]
	s_nop 0
	v_div_scale_f32 v31, s[0:1], v27, v27, 1.0
	v_rcp_f32_e32 v34, v31
	s_nop 0
	v_fma_f32 v35, -v31, v34, 1.0
	v_fmac_f32_e32 v34, v35, v34
	v_div_scale_f32 v35, vcc, 1.0, v27, 1.0
	v_mul_f32_e32 v40, v35, v34
	v_fma_f32 v41, -v31, v40, v35
	v_fmac_f32_e32 v40, v41, v34
	v_fma_f32 v31, -v31, v40, v35
	v_div_fmas_f32 v31, v31, v34, v40
	v_div_fixup_f32 v27, v31, v27, 1.0
	v_div_scale_f32 v31, s[0:1], v26, v26, 1.0
	v_rcp_f32_e32 v34, v31
	s_nop 0
	v_fma_f32 v35, -v31, v34, 1.0
	v_fmac_f32_e32 v34, v35, v34
	v_div_scale_f32 v35, vcc, 1.0, v26, 1.0
	v_mul_f32_e32 v40, v35, v34
	v_fma_f32 v41, -v31, v40, v35
	v_fmac_f32_e32 v40, v41, v34
	v_fma_f32 v31, -v31, v40, v35
	v_div_fmas_f32 v31, v31, v34, v40
	v_div_fixup_f32 v26, v31, v26, 1.0
	v_mul_f32_e32 v26, v26, v32
	v_mul_f32_e32 v27, v27, v33
	v_lshlrev_b32_e32 v32, 16, v74
	v_and_b32_e32 v33, 0xffff0000, v74
	v_sub_f32_e32 v32, v32, v29
	v_sub_f32_e32 v33, v33, v29
	v_cvt_pk_bf16_f32 v26, v26, v27
	v_mul_f32_e32 v32, v32, v30
	v_mul_f32_e32 v33, v33, v30
	v_mul_f32_e32 v27, 0xbfb8aa3b, v24
	v_mul_f32_e32 v32, v32, v24
	v_mul_f32_e32 v33, v33, v25
	v_mul_f32_e32 v24, 0xbfb8aa3b, v25
	v_exp_f32_e32 v34, v27
	v_exp_f32_e32 v35, v24
	s_nop 0
	v_pk_add_f32 v[24:25], v[34:35], 1.0 op_sel_hi:[1,0]
	s_nop 0
	v_div_scale_f32 v27, s[0:1], v25, v25, 1.0
	v_rcp_f32_e32 v31, v27
	s_nop 0
	v_fma_f32 v34, -v27, v31, 1.0
	v_fmac_f32_e32 v31, v34, v31
	v_div_scale_f32 v34, vcc, 1.0, v25, 1.0
	v_mul_f32_e32 v35, v34, v31
	v_fma_f32 v40, -v27, v35, v34
	v_fmac_f32_e32 v35, v40, v31
	v_fma_f32 v27, -v27, v35, v34
	v_div_fmas_f32 v27, v27, v31, v35
	v_div_fixup_f32 v25, v27, v25, 1.0
	v_div_scale_f32 v27, s[0:1], v24, v24, 1.0
	v_rcp_f32_e32 v31, v27
	s_nop 0
	v_fma_f32 v34, -v27, v31, 1.0
	v_fmac_f32_e32 v31, v34, v31
	v_div_scale_f32 v34, vcc, 1.0, v24, 1.0
	v_mul_f32_e32 v35, v34, v31
	v_fma_f32 v40, -v27, v35, v34
	v_fmac_f32_e32 v35, v40, v31
	v_fma_f32 v27, -v27, v35, v34
	v_div_fmas_f32 v27, v27, v31, v35
	v_div_fixup_f32 v24, v27, v24, 1.0
	v_mul_f32_e32 v24, v24, v32
	v_mul_f32_e32 v25, v25, v33
	s_nop 0
	v_cvt_pk_bf16_f32 v27, v24, v25
	flat_store_dwordx2 v[36:37], v[26:27] offset:64
	flat_load_dwordx2 v[24:25], v[38:39] offset:320
	s_waitcnt vmcnt(0) lgkmcnt(0)
; DEV float bflo(unsigned u) { return __uint_as_float(u << 16); }
; DEV float bfhi(unsigned u) { return __uint_as_float(u & 0xffff0000u); }
; DEV float sigm(float x) { return 1.f / (1.f + __expf(-x)); }
; __device__ __forceinline__ void ret_out_item(PREF P, int w, const u16* ST, char* smem) {
;     ...
; #pragma unroll
;   for (int d = 0; d < 8; ++d) {
;     {
;       u32x2 pvv = park[d];
;       uint2 g = *(const uint2*)(grow + d * 16);
;       float g0 = bflo(g.x), g1 = bfhi(g.x), g2 = bflo(g.y), g3 = bfhi(g.y);
;       uint2 o;
;       o.x = pack2((bflo(pvv.x) - mu) * rs * g0 * sigm(g0), (bfhi(pvv.x) - mu) * rs * g1 * sigm(g1));
;       o.y = pack2((bflo(pvv.y) - mu) * rs * g2 * sigm(g2), (bfhi(pvv.y) - mu) * rs * g3 * sigm(g3));
;       *(uint2*)(orow + d * 16) = o;
;     }
;     {
;       uint2 g = *(const uint2*)(grow + 128 + d * 16);
;       float g0 = bflo(g.x), g1 = bfhi(g.x), g2 = bflo(g.y), g3 = bfhi(g.y);
;       uint2 o;
;       o.x = pack2((oT[d][0] - mu) * rs * g0 * sigm(g0), (oT[d][1] - mu) * rs * g1 * sigm(g1));
;       o.y = pack2((oT[d][2] - mu) * rs * g2 * sigm(g2), (oT[d][3] - mu) * rs * g3 * sigm(g3));
;       *(uint2*)(orow + 128 + d * 16) = o;
;     }
;   }
	v_lshlrev_b32_e32 v26, 16, v24
	v_mul_f32_e32 v31, 0xbfb8aa3b, v26
	v_and_b32_e32 v27, 0xffff0000, v24
	v_mul_f32_e32 v20, v20, v30
	v_mul_f32_e32 v21, v21, v30
	v_exp_f32_e32 v32, v31
	v_mul_f32_e32 v20, v20, v26
	v_mul_f32_e32 v21, v21, v27
	v_mul_f32_e32 v26, 0xbfb8aa3b, v27
	v_exp_f32_e32 v33, v26
	v_lshlrev_b32_e32 v24, 16, v25
	v_and_b32_e32 v25, 0xffff0000, v25
	v_pk_add_f32 v[26:27], v[32:33], 1.0 op_sel_hi:[1,0]
	s_nop 0
	v_div_scale_f32 v31, s[0:1], v27, v27, 1.0
	v_rcp_f32_e32 v32, v31
	s_nop 0
	v_fma_f32 v33, -v31, v32, 1.0
	v_fmac_f32_e32 v32, v33, v32
	v_div_scale_f32 v33, vcc, 1.0, v27, 1.0
	v_mul_f32_e32 v34, v33, v32
	v_fma_f32 v35, -v31, v34, v33
	v_fmac_f32_e32 v34, v35, v32
	v_fma_f32 v31, -v31, v34, v33
	v_div_fmas_f32 v31, v31, v32, v34
	v_div_fixup_f32 v27, v31, v27, 1.0
	v_div_scale_f32 v31, s[0:1], v26, v26, 1.0
	v_rcp_f32_e32 v32, v31
	s_nop 0
	v_fma_f32 v33, -v31, v32, 1.0
	v_fmac_f32_e32 v32, v33, v32
	v_div_scale_f32 v33, vcc, 1.0, v26, 1.0
	v_mul_f32_e32 v34, v33, v32
	v_fma_f32 v35, -v31, v34, v33
	v_fmac_f32_e32 v34, v35, v32
	v_fma_f32 v31, -v31, v34, v33
	v_div_fmas_f32 v31, v31, v32, v34
	v_div_fixup_f32 v26, v31, v26, 1.0
	v_mul_f32_e32 v20, v26, v20
	v_mul_f32_e32 v21, v27, v21
	v_mul_f32_e32 v22, v22, v30
	v_mul_f32_e32 v23, v23, v30
	v_cvt_pk_bf16_f32 v20, v20, v21
	v_mul_f32_e32 v21, 0xbfb8aa3b, v24
	v_exp_f32_e32 v26, v21
	v_mul_f32_e32 v21, 0xbfb8aa3b, v25
	v_exp_f32_e32 v27, v21
	v_mul_f32_e32 v22, v22, v24
	v_mul_f32_e32 v23, v23, v25
	v_pk_add_f32 v[24:25], v[26:27], 1.0 op_sel_hi:[1,0]
	s_nop 0
	v_div_scale_f32 v21, s[0:1], v25, v25, 1.0
	v_rcp_f32_e32 v26, v21
	s_nop 0
	v_fma_f32 v27, -v21, v26, 1.0
	v_fmac_f32_e32 v26, v27, v26
	v_div_scale_f32 v27, vcc, 1.0, v25, 1.0
	v_mul_f32_e32 v31, v27, v26
	v_fma_f32 v32, -v21, v31, v27
	v_fmac_f32_e32 v31, v32, v26
	v_fma_f32 v21, -v21, v31, v27
	v_div_fmas_f32 v21, v21, v26, v31
	v_div_fixup_f32 v25, v21, v25, 1.0
	v_div_scale_f32 v21, s[0:1], v24, v24, 1.0
	v_rcp_f32_e32 v26, v21
	s_nop 0
	v_fma_f32 v27, -v21, v26, 1.0
	v_fmac_f32_e32 v26, v27, v26
	v_div_scale_f32 v27, vcc, 1.0, v24, 1.0
	v_mul_f32_e32 v31, v27, v26
	v_fma_f32 v32, -v21, v31, v27
	v_fmac_f32_e32 v31, v32, v26
	v_fma_f32 v21, -v21, v31, v27
	v_div_fmas_f32 v21, v21, v26, v31
	v_div_fixup_f32 v24, v21, v24, 1.0
	v_mul_f32_e32 v22, v24, v22
	v_mul_f32_e32 v23, v25, v23
	v_lshlrev_b32_e32 v24, 16, v76
	v_cvt_pk_bf16_f32 v21, v22, v23
	flat_store_dwordx2 v[36:37], v[20:21] offset:320
	flat_load_dwordx2 v[20:21], v[38:39] offset:96
	v_and_b32_e32 v25, 0xffff0000, v76
	v_sub_f32_e32 v24, v24, v29
	v_sub_f32_e32 v25, v25, v29
	s_waitcnt vmcnt(0) lgkmcnt(0)
	v_lshlrev_b32_e32 v22, 16, v20
	v_and_b32_e32 v23, 0xffff0000, v20
	v_mul_f32_e32 v24, v24, v30
	v_mul_f32_e32 v25, v25, v30
	v_mul_f32_e32 v26, 0xbfb8aa3b, v22
	v_mul_f32_e32 v24, v24, v22
	v_mul_f32_e32 v25, v25, v23
	v_mul_f32_e32 v22, 0xbfb8aa3b, v23
	v_exp_f32_e32 v26, v26
	v_exp_f32_e32 v27, v22
	v_lshlrev_b32_e32 v20, 16, v21
	v_and_b32_e32 v21, 0xffff0000, v21
	v_pk_add_f32 v[22:23], v[26:27], 1.0 op_sel_hi:[1,0]
	s_nop 0
	v_div_scale_f32 v26, s[0:1], v23, v23, 1.0
	v_rcp_f32_e32 v27, v26
	s_nop 0
	v_fma_f32 v31, -v26, v27, 1.0
	v_fmac_f32_e32 v27, v31, v27
	v_div_scale_f32 v31, vcc, 1.0, v23, 1.0
	v_mul_f32_e32 v32, v31, v27
	v_fma_f32 v33, -v26, v32, v31
	v_fmac_f32_e32 v32, v33, v27
	v_fma_f32 v26, -v26, v32, v31
	v_div_fmas_f32 v26, v26, v27, v32
	v_div_fixup_f32 v23, v26, v23, 1.0
	v_div_scale_f32 v26, s[0:1], v22, v22, 1.0
	v_rcp_f32_e32 v27, v26
	s_nop 0
	v_fma_f32 v31, -v26, v27, 1.0
	v_fmac_f32_e32 v27, v31, v27
	v_div_scale_f32 v31, vcc, 1.0, v22, 1.0
	v_mul_f32_e32 v32, v31, v27
	v_fma_f32 v33, -v26, v32, v31
	v_fmac_f32_e32 v32, v33, v27
	v_fma_f32 v26, -v26, v32, v31
	v_div_fmas_f32 v26, v26, v27, v32
	v_div_fixup_f32 v22, v26, v22, 1.0
	v_mul_f32_e32 v22, v22, v24
	v_mul_f32_e32 v23, v23, v25
	v_lshlrev_b32_e32 v24, 16, v78
	v_and_b32_e32 v25, 0xffff0000, v78
	v_sub_f32_e32 v24, v24, v29
	v_sub_f32_e32 v25, v25, v29
	v_cvt_pk_bf16_f32 v22, v22, v23
	v_mul_f32_e32 v24, v24, v30
	v_mul_f32_e32 v25, v25, v30
	v_mul_f32_e32 v23, 0xbfb8aa3b, v20
	v_mul_f32_e32 v24, v24, v20
	v_mul_f32_e32 v25, v25, v21
	v_mul_f32_e32 v20, 0xbfb8aa3b, v21
	v_exp_f32_e32 v26, v23
	v_exp_f32_e32 v27, v20
	s_nop 0
	v_pk_add_f32 v[20:21], v[26:27], 1.0 op_sel_hi:[1,0]
	s_nop 0
	v_div_scale_f32 v23, s[0:1], v21, v21, 1.0
	v_rcp_f32_e32 v26, v23
	s_nop 0
	v_fma_f32 v27, -v23, v26, 1.0
	v_fmac_f32_e32 v26, v27, v26
	v_div_scale_f32 v27, vcc, 1.0, v21, 1.0
	v_mul_f32_e32 v31, v27, v26
	v_fma_f32 v32, -v23, v31, v27
	v_fmac_f32_e32 v31, v32, v26
	v_fma_f32 v23, -v23, v31, v27
	v_div_fmas_f32 v23, v23, v26, v31
	v_div_fixup_f32 v21, v23, v21, 1.0
	v_div_scale_f32 v23, s[0:1], v20, v20, 1.0
	v_rcp_f32_e32 v26, v23
	s_nop 0
	v_fma_f32 v27, -v23, v26, 1.0
	v_fmac_f32_e32 v26, v27, v26
	v_div_scale_f32 v27, vcc, 1.0, v20, 1.0
	v_mul_f32_e32 v31, v27, v26
	v_fma_f32 v32, -v23, v31, v27
	v_fmac_f32_e32 v31, v32, v26
	v_fma_f32 v23, -v23, v31, v27
	v_div_fmas_f32 v23, v23, v26, v31
	v_div_fixup_f32 v20, v23, v20, 1.0
	v_mul_f32_e32 v20, v20, v24
	v_mul_f32_e32 v21, v21, v25
	v_mul_f32_e32 v16, v16, v30
	v_mul_f32_e32 v17, v17, v30
	v_cvt_pk_bf16_f32 v23, v20, v21
	flat_store_dwordx2 v[36:37], v[22:23] offset:96
	flat_load_dwordx2 v[20:21], v[38:39] offset:352
	s_waitcnt vmcnt(0) lgkmcnt(0)
; DEV float bflo(unsigned u) { return __uint_as_float(u << 16); }
; DEV float bfhi(unsigned u) { return __uint_as_float(u & 0xffff0000u); }
; DEV float sigm(float x) { return 1.f / (1.f + __expf(-x)); }
; __device__ __forceinline__ void ret_out_item(PREF P, int w, const u16* ST, char* smem) {
;     ...
; #pragma unroll
;   for (int d = 0; d < 8; ++d) {
;     {
;       u32x2 pvv = park[d];
;       uint2 g = *(const uint2*)(grow + d * 16);
;       float g0 = bflo(g.x), g1 = bfhi(g.x), g2 = bflo(g.y), g3 = bfhi(g.y);
;       uint2 o;
;       o.x = pack2((bflo(pvv.x) - mu) * rs * g0 * sigm(g0), (bfhi(pvv.x) - mu) * rs * g1 * sigm(g1));
;       o.y = pack2((bflo(pvv.y) - mu) * rs * g2 * sigm(g2), (bfhi(pvv.y) - mu) * rs * g3 * sigm(g3));
;       *(uint2*)(orow + d * 16) = o;
;     }
;     {
;       uint2 g = *(const uint2*)(grow + 128 + d * 16);
;       float g0 = bflo(g.x), g1 = bfhi(g.x), g2 = bflo(g.y), g3 = bfhi(g.y);
;       uint2 o;
;       o.x = pack2((oT[d][0] - mu) * rs * g0 * sigm(g0), (oT[d][1] - mu) * rs * g1 * sigm(g1));
;       o.y = pack2((oT[d][2] - mu) * rs * g2 * sigm(g2), (oT[d][3] - mu) * rs * g3 * sigm(g3));
;       *(uint2*)(orow + 128 + d * 16) = o;
;     }
;   }
	v_lshlrev_b32_e32 v22, 16, v20
	v_and_b32_e32 v23, 0xffff0000, v20
	v_mul_f32_e32 v24, 0xbfb8aa3b, v22
	v_mul_f32_e32 v16, v16, v22
	v_mul_f32_e32 v17, v17, v23
	v_mul_f32_e32 v22, 0xbfb8aa3b, v23
	v_exp_f32_e32 v24, v24
	v_exp_f32_e32 v25, v22
	v_lshlrev_b32_e32 v20, 16, v21
	v_and_b32_e32 v21, 0xffff0000, v21
	v_pk_add_f32 v[22:23], v[24:25], 1.0 op_sel_hi:[1,0]
	s_nop 0
	v_div_scale_f32 v24, s[0:1], v23, v23, 1.0
	v_rcp_f32_e32 v25, v24
	s_nop 0
	v_fma_f32 v26, -v24, v25, 1.0
	v_fmac_f32_e32 v25, v26, v25
	v_div_scale_f32 v26, vcc, 1.0, v23, 1.0
	v_mul_f32_e32 v27, v26, v25
	v_fma_f32 v31, -v24, v27, v26
	v_fmac_f32_e32 v27, v31, v25
	v_fma_f32 v24, -v24, v27, v26
	v_div_fmas_f32 v24, v24, v25, v27
	v_div_fixup_f32 v23, v24, v23, 1.0
	v_div_scale_f32 v24, s[0:1], v22, v22, 1.0
	v_rcp_f32_e32 v25, v24
	s_nop 0
	v_fma_f32 v26, -v24, v25, 1.0
	v_fmac_f32_e32 v25, v26, v25
	v_div_scale_f32 v26, vcc, 1.0, v22, 1.0
	v_mul_f32_e32 v27, v26, v25
	v_fma_f32 v31, -v24, v27, v26
	v_fmac_f32_e32 v27, v31, v25
	v_fma_f32 v24, -v24, v27, v26
	v_div_fmas_f32 v24, v24, v25, v27
	v_div_fixup_f32 v22, v24, v22, 1.0
	v_mul_f32_e32 v16, v16, v22
	v_mul_f32_e32 v17, v17, v23
	v_mul_f32_e32 v18, v18, v30
	v_mul_f32_e32 v19, v19, v30
	v_cvt_pk_bf16_f32 v16, v16, v17
	v_mul_f32_e32 v17, 0xbfb8aa3b, v20
	v_exp_f32_e32 v22, v17
	v_mul_f32_e32 v17, 0xbfb8aa3b, v21
	v_exp_f32_e32 v23, v17
	v_mul_f32_e32 v18, v18, v20
	v_mul_f32_e32 v19, v19, v21
	v_mul_f32_e32 v12, v12, v30
	v_mul_f32_e32 v13, v13, v30
	v_mul_f32_e32 v14, v14, v30
	v_mul_f32_e32 v15, v15, v30
	v_pk_add_f32 v[20:21], v[22:23], 1.0 op_sel_hi:[1,0]
	v_mul_f32_e32 v8, v8, v30
	v_mul_f32_e32 v9, v9, v30
	v_div_scale_f32 v17, s[0:1], v21, v21, 1.0
	v_rcp_f32_e32 v22, v17
	v_mul_f32_e32 v10, v10, v30
	v_mul_f32_e32 v11, v11, v30
	v_mul_f32_e32 v4, v4, v30
	v_mul_f32_e32 v5, v5, v30
	v_mul_f32_e32 v6, v6, v30
	v_mul_f32_e32 v7, v7, v30
	v_fma_f32 v23, -v17, v22, 1.0
	v_fmac_f32_e32 v22, v23, v22
	v_div_scale_f32 v23, vcc, 1.0, v21, 1.0
	v_mul_f32_e32 v24, v23, v22
	v_fma_f32 v25, -v17, v24, v23
	v_fmac_f32_e32 v24, v25, v22
	v_fma_f32 v17, -v17, v24, v23
	v_div_fmas_f32 v17, v17, v22, v24
	v_div_fixup_f32 v21, v17, v21, 1.0
	v_div_scale_f32 v17, s[0:1], v20, v20, 1.0
	v_rcp_f32_e32 v22, v17
	v_mul_f32_e32 v0, v0, v30
	v_mul_f32_e32 v1, v1, v30
	v_mul_f32_e32 v2, v2, v30
	v_mul_f32_e32 v3, v3, v30
	v_fma_f32 v23, -v17, v22, 1.0
	v_fmac_f32_e32 v22, v23, v22
	v_div_scale_f32 v23, vcc, 1.0, v20, 1.0
	v_mul_f32_e32 v24, v23, v22
	v_fma_f32 v25, -v17, v24, v23
	v_fmac_f32_e32 v24, v25, v22
	v_fma_f32 v17, -v17, v24, v23
	v_div_fmas_f32 v17, v17, v22, v24
	v_div_fixup_f32 v20, v17, v20, 1.0
	v_mul_f32_e32 v18, v18, v20
	v_mul_f32_e32 v19, v19, v21
	s_nop 0
	v_cvt_pk_bf16_f32 v17, v18, v19
	flat_store_dwordx2 v[36:37], v[16:17] offset:352
	flat_load_dwordx2 v[16:17], v[38:39] offset:128
	s_waitcnt vmcnt(0) lgkmcnt(0)
	v_lshlrev_b32_e32 v18, 16, v16
	v_and_b32_e32 v19, 0xffff0000, v16
	v_lshlrev_b32_e32 v20, 16, v17
	v_and_b32_e32 v21, 0xffff0000, v17
	v_lshlrev_b32_e32 v16, 16, v80
	v_and_b32_e32 v17, 0xffff0000, v80
	v_sub_f32_e32 v16, v16, v29
	v_sub_f32_e32 v17, v17, v29
	v_mul_f32_e32 v22, 0xbfb8aa3b, v18
	v_mul_f32_e32 v16, v16, v30
	v_mul_f32_e32 v17, v17, v30
	v_exp_f32_e32 v22, v22
	v_mul_f32_e32 v16, v16, v18
	v_mul_f32_e32 v17, v17, v19
	v_mul_f32_e32 v18, 0xbfb8aa3b, v19
	v_exp_f32_e32 v23, v18
	s_nop 0
	v_pk_add_f32 v[18:19], v[22:23], 1.0 op_sel_hi:[1,0]
	s_nop 0
	v_div_scale_f32 v22, s[0:1], v19, v19, 1.0
	v_rcp_f32_e32 v23, v22
	s_nop 0
	v_fma_f32 v24, -v22, v23, 1.0
	v_fmac_f32_e32 v23, v24, v23
	v_div_scale_f32 v24, vcc, 1.0, v19, 1.0
	v_mul_f32_e32 v25, v24, v23
	v_fma_f32 v26, -v22, v25, v24
	v_fmac_f32_e32 v25, v26, v23
	v_fma_f32 v22, -v22, v25, v24
	v_div_fmas_f32 v22, v22, v23, v25
	v_div_fixup_f32 v19, v22, v19, 1.0
	v_div_scale_f32 v22, s[0:1], v18, v18, 1.0
	v_rcp_f32_e32 v23, v22
	s_nop 0
	v_fma_f32 v24, -v22, v23, 1.0
	v_fmac_f32_e32 v23, v24, v23
	v_div_scale_f32 v24, vcc, 1.0, v18, 1.0
	v_mul_f32_e32 v25, v24, v23
	v_fma_f32 v26, -v22, v25, v24
	v_fmac_f32_e32 v25, v26, v23
	v_fma_f32 v22, -v22, v25, v24
	v_div_fmas_f32 v22, v22, v23, v25
	v_div_fixup_f32 v18, v22, v18, 1.0
	v_mul_f32_e32 v16, v16, v18
	v_mul_f32_e32 v17, v17, v19
	v_lshlrev_b32_e32 v18, 16, v82
	v_cvt_pk_bf16_f32 v16, v16, v17
	v_mul_f32_e32 v17, 0xbfb8aa3b, v20
	v_exp_f32_e32 v22, v17
	v_mul_f32_e32 v17, 0xbfb8aa3b, v21
	v_exp_f32_e32 v23, v17
	v_and_b32_e32 v19, 0xffff0000, v82
	v_sub_f32_e32 v18, v18, v29
	v_sub_f32_e32 v19, v19, v29
	s_nop 0
	v_mul_f32_e32 v18, v18, v30
	v_mul_f32_e32 v19, v19, v30
	s_nop 0
	v_mul_f32_e32 v18, v18, v20
	v_mul_f32_e32 v19, v19, v21
	v_pk_add_f32 v[20:21], v[22:23], 1.0 op_sel_hi:[1,0]
	s_nop 0
	v_div_scale_f32 v17, s[0:1], v21, v21, 1.0
	v_rcp_f32_e32 v22, v17
	s_nop 0
	v_fma_f32 v23, -v17, v22, 1.0
	v_fmac_f32_e32 v22, v23, v22
	v_div_scale_f32 v23, vcc, 1.0, v21, 1.0
	v_mul_f32_e32 v24, v23, v22
	v_fma_f32 v25, -v17, v24, v23
	v_fmac_f32_e32 v24, v25, v22
	v_fma_f32 v17, -v17, v24, v23
	v_div_fmas_f32 v17, v17, v22, v24
	v_div_fixup_f32 v21, v17, v21, 1.0
	v_div_scale_f32 v17, s[0:1], v20, v20, 1.0
	v_rcp_f32_e32 v22, v17
	s_nop 0
	v_fma_f32 v23, -v17, v22, 1.0
	v_fmac_f32_e32 v22, v23, v22
	v_div_scale_f32 v23, vcc, 1.0, v20, 1.0
	v_mul_f32_e32 v24, v23, v22
	v_fma_f32 v25, -v17, v24, v23
	v_fmac_f32_e32 v24, v25, v22
	v_fma_f32 v17, -v17, v24, v23
	v_div_fmas_f32 v17, v17, v22, v24
	v_div_fixup_f32 v20, v17, v20, 1.0
	v_mul_f32_e32 v18, v18, v20
	v_mul_f32_e32 v19, v19, v21
	s_nop 0
	v_cvt_pk_bf16_f32 v17, v18, v19
	flat_store_dwordx2 v[36:37], v[16:17] offset:128
	flat_load_dwordx2 v[16:17], v[38:39] offset:384
	s_waitcnt vmcnt(0) lgkmcnt(0)
; DEV float bflo(unsigned u) { return __uint_as_float(u << 16); }
; DEV float bfhi(unsigned u) { return __uint_as_float(u & 0xffff0000u); }
; DEV float sigm(float x) { return 1.f / (1.f + __expf(-x)); }
; __device__ __forceinline__ void ret_out_item(PREF P, int w, const u16* ST, char* smem) {
;     ...
; #pragma unroll
;   for (int d = 0; d < 8; ++d) {
;     {
;       u32x2 pvv = park[d];
;       uint2 g = *(const uint2*)(grow + d * 16);
;       float g0 = bflo(g.x), g1 = bfhi(g.x), g2 = bflo(g.y), g3 = bfhi(g.y);
;       uint2 o;
;       o.x = pack2((bflo(pvv.x) - mu) * rs * g0 * sigm(g0), (bfhi(pvv.x) - mu) * rs * g1 * sigm(g1));
;       o.y = pack2((bflo(pvv.y) - mu) * rs * g2 * sigm(g2), (bfhi(pvv.y) - mu) * rs * g3 * sigm(g3));
;       *(uint2*)(orow + d * 16) = o;
;     }
;     {
;       uint2 g = *(const uint2*)(grow + 128 + d * 16);
;       float g0 = bflo(g.x), g1 = bfhi(g.x), g2 = bflo(g.y), g3 = bfhi(g.y);
;       uint2 o;
;       o.x = pack2((oT[d][0] - mu) * rs * g0 * sigm(g0), (oT[d][1] - mu) * rs * g1 * sigm(g1));
;       o.y = pack2((oT[d][2] - mu) * rs * g2 * sigm(g2), (oT[d][3] - mu) * rs * g3 * sigm(g3));
;       *(uint2*)(orow + 128 + d * 16) = o;
;     }
;   }
	v_lshlrev_b32_e32 v18, 16, v16
	v_and_b32_e32 v19, 0xffff0000, v16
	v_mul_f32_e32 v20, 0xbfb8aa3b, v18
	v_mul_f32_e32 v12, v12, v18
	v_mul_f32_e32 v13, v13, v19
	v_mul_f32_e32 v18, 0xbfb8aa3b, v19
	v_exp_f32_e32 v20, v20
	v_exp_f32_e32 v21, v18
	v_lshlrev_b32_e32 v16, 16, v17
	v_and_b32_e32 v17, 0xffff0000, v17
	v_mul_f32_e32 v14, v14, v16
	v_mul_f32_e32 v15, v15, v17
	v_pk_add_f32 v[18:19], v[20:21], 1.0 op_sel_hi:[1,0]
	s_nop 0
	v_div_scale_f32 v20, s[0:1], v19, v19, 1.0
	v_rcp_f32_e32 v21, v20
	s_nop 0
	v_fma_f32 v22, -v20, v21, 1.0
	v_fmac_f32_e32 v21, v22, v21
	v_div_scale_f32 v22, vcc, 1.0, v19, 1.0
	v_mul_f32_e32 v23, v22, v21
	v_fma_f32 v24, -v20, v23, v22
	v_fmac_f32_e32 v23, v24, v21
	v_fma_f32 v20, -v20, v23, v22
	v_div_fmas_f32 v20, v20, v21, v23
	v_div_fixup_f32 v19, v20, v19, 1.0
	v_div_scale_f32 v20, s[0:1], v18, v18, 1.0
	v_rcp_f32_e32 v21, v20
	s_nop 0
	v_fma_f32 v22, -v20, v21, 1.0
	v_fmac_f32_e32 v21, v22, v21
	v_div_scale_f32 v22, vcc, 1.0, v18, 1.0
	v_mul_f32_e32 v23, v22, v21
	v_fma_f32 v24, -v20, v23, v22
	v_fmac_f32_e32 v23, v24, v21
	v_fma_f32 v20, -v20, v23, v22
	v_div_fmas_f32 v20, v20, v21, v23
	v_div_fixup_f32 v18, v20, v18, 1.0
	v_mul_f32_e32 v12, v12, v18
	v_mul_f32_e32 v13, v13, v19
	s_nop 0
	v_cvt_pk_bf16_f32 v12, v12, v13
	v_mul_f32_e32 v13, 0xbfb8aa3b, v16
	v_exp_f32_e32 v18, v13
	v_mul_f32_e32 v13, 0xbfb8aa3b, v17
	v_exp_f32_e32 v19, v13
	s_nop 0
	v_pk_add_f32 v[16:17], v[18:19], 1.0 op_sel_hi:[1,0]
	s_nop 0
	v_div_scale_f32 v13, s[0:1], v17, v17, 1.0
	v_rcp_f32_e32 v18, v13
	s_nop 0
	v_fma_f32 v19, -v13, v18, 1.0
	v_fmac_f32_e32 v18, v19, v18
	v_div_scale_f32 v19, vcc, 1.0, v17, 1.0
	v_mul_f32_e32 v20, v19, v18
	v_fma_f32 v21, -v13, v20, v19
	v_fmac_f32_e32 v20, v21, v18
	v_fma_f32 v13, -v13, v20, v19
	v_div_fmas_f32 v13, v13, v18, v20
	v_div_fixup_f32 v17, v13, v17, 1.0
	v_div_scale_f32 v13, s[0:1], v16, v16, 1.0
	v_rcp_f32_e32 v18, v13
	s_nop 0
	v_fma_f32 v19, -v13, v18, 1.0
	v_fmac_f32_e32 v18, v19, v18
	v_div_scale_f32 v19, vcc, 1.0, v16, 1.0
	v_mul_f32_e32 v20, v19, v18
	v_fma_f32 v21, -v13, v20, v19
	v_fmac_f32_e32 v20, v21, v18
	v_fma_f32 v13, -v13, v20, v19
	v_div_fmas_f32 v13, v13, v18, v20
	v_div_fixup_f32 v16, v13, v16, 1.0
	v_mul_f32_e32 v14, v14, v16
	v_mul_f32_e32 v15, v15, v17
	s_nop 0
	v_cvt_pk_bf16_f32 v13, v14, v15
	flat_store_dwordx2 v[36:37], v[12:13] offset:384
	flat_load_dwordx2 v[12:13], v[38:39] offset:160
	s_waitcnt vmcnt(0) lgkmcnt(0)
	v_lshlrev_b32_e32 v14, 16, v12
	v_and_b32_e32 v15, 0xffff0000, v12
	v_lshlrev_b32_e32 v16, 16, v13
	v_and_b32_e32 v17, 0xffff0000, v13
	v_lshlrev_b32_e32 v12, 16, v84
	v_and_b32_e32 v13, 0xffff0000, v84
	v_sub_f32_e32 v12, v12, v29
	v_sub_f32_e32 v13, v13, v29
	v_mul_f32_e32 v18, 0xbfb8aa3b, v14
	v_mul_f32_e32 v12, v12, v30
	v_mul_f32_e32 v13, v13, v30
	v_exp_f32_e32 v18, v18
	v_mul_f32_e32 v12, v12, v14
	v_mul_f32_e32 v13, v13, v15
	v_mul_f32_e32 v14, 0xbfb8aa3b, v15
	v_exp_f32_e32 v19, v14
	s_nop 0
	v_pk_add_f32 v[14:15], v[18:19], 1.0 op_sel_hi:[1,0]
	s_nop 0
	v_div_scale_f32 v18, s[0:1], v15, v15, 1.0
	v_rcp_f32_e32 v19, v18
	s_nop 0
	v_fma_f32 v20, -v18, v19, 1.0
	v_fmac_f32_e32 v19, v20, v19
	v_div_scale_f32 v20, vcc, 1.0, v15, 1.0
	v_mul_f32_e32 v21, v20, v19
	v_fma_f32 v22, -v18, v21, v20
	v_fmac_f32_e32 v21, v22, v19
	v_fma_f32 v18, -v18, v21, v20
	v_div_fmas_f32 v18, v18, v19, v21
	v_div_fixup_f32 v15, v18, v15, 1.0
	v_div_scale_f32 v18, s[0:1], v14, v14, 1.0
	v_rcp_f32_e32 v19, v18
	s_nop 0
	v_fma_f32 v20, -v18, v19, 1.0
	v_fmac_f32_e32 v19, v20, v19
	v_div_scale_f32 v20, vcc, 1.0, v14, 1.0
	v_mul_f32_e32 v21, v20, v19
	v_fma_f32 v22, -v18, v21, v20
	v_fmac_f32_e32 v21, v22, v19
	v_fma_f32 v18, -v18, v21, v20
	v_div_fmas_f32 v18, v18, v19, v21
	v_div_fixup_f32 v14, v18, v14, 1.0
	v_mul_f32_e32 v12, v12, v14
	v_mul_f32_e32 v13, v13, v15
	v_lshlrev_b32_e32 v14, 16, v86
	v_cvt_pk_bf16_f32 v12, v12, v13
	v_mul_f32_e32 v13, 0xbfb8aa3b, v16
	v_exp_f32_e32 v18, v13
	v_mul_f32_e32 v13, 0xbfb8aa3b, v17
	v_exp_f32_e32 v19, v13
	v_and_b32_e32 v15, 0xffff0000, v86
	v_sub_f32_e32 v14, v14, v29
	v_sub_f32_e32 v15, v15, v29
	s_nop 0
	v_mul_f32_e32 v14, v14, v30
	v_mul_f32_e32 v15, v15, v30
	s_nop 0
	v_mul_f32_e32 v14, v14, v16
	v_mul_f32_e32 v15, v15, v17
	v_pk_add_f32 v[16:17], v[18:19], 1.0 op_sel_hi:[1,0]
	s_nop 0
	v_div_scale_f32 v13, s[0:1], v17, v17, 1.0
	v_rcp_f32_e32 v18, v13
	s_nop 0
	v_fma_f32 v19, -v13, v18, 1.0
	v_fmac_f32_e32 v18, v19, v18
	v_div_scale_f32 v19, vcc, 1.0, v17, 1.0
	v_mul_f32_e32 v20, v19, v18
	v_fma_f32 v21, -v13, v20, v19
	v_fmac_f32_e32 v20, v21, v18
	v_fma_f32 v13, -v13, v20, v19
	v_div_fmas_f32 v13, v13, v18, v20
	v_div_fixup_f32 v17, v13, v17, 1.0
	v_div_scale_f32 v13, s[0:1], v16, v16, 1.0
	v_rcp_f32_e32 v18, v13
	s_nop 0
	v_fma_f32 v19, -v13, v18, 1.0
	v_fmac_f32_e32 v18, v19, v18
	v_div_scale_f32 v19, vcc, 1.0, v16, 1.0
	v_mul_f32_e32 v20, v19, v18
	v_fma_f32 v21, -v13, v20, v19
	v_fmac_f32_e32 v20, v21, v18
	v_fma_f32 v13, -v13, v20, v19
	v_div_fmas_f32 v13, v13, v18, v20
	v_div_fixup_f32 v16, v13, v16, 1.0
	v_mul_f32_e32 v14, v14, v16
	v_mul_f32_e32 v15, v15, v17
	s_nop 0
	v_cvt_pk_bf16_f32 v13, v14, v15
	flat_store_dwordx2 v[36:37], v[12:13] offset:160
	flat_load_dwordx2 v[12:13], v[38:39] offset:416
	s_waitcnt vmcnt(0) lgkmcnt(0)
; DEV float bflo(unsigned u) { return __uint_as_float(u << 16); }
; DEV float bfhi(unsigned u) { return __uint_as_float(u & 0xffff0000u); }
; DEV float sigm(float x) { return 1.f / (1.f + __expf(-x)); }
; __device__ __forceinline__ void ret_out_item(PREF P, int w, const u16* ST, char* smem) {
;     ...
; #pragma unroll
;   for (int d = 0; d < 8; ++d) {
;     {
;       u32x2 pvv = park[d];
;       uint2 g = *(const uint2*)(grow + d * 16);
;       float g0 = bflo(g.x), g1 = bfhi(g.x), g2 = bflo(g.y), g3 = bfhi(g.y);
;       uint2 o;
;       o.x = pack2((bflo(pvv.x) - mu) * rs * g0 * sigm(g0), (bfhi(pvv.x) - mu) * rs * g1 * sigm(g1));
;       o.y = pack2((bflo(pvv.y) - mu) * rs * g2 * sigm(g2), (bfhi(pvv.y) - mu) * rs * g3 * sigm(g3));
;       *(uint2*)(orow + d * 16) = o;
;     }
;     {
;       uint2 g = *(const uint2*)(grow + 128 + d * 16);
;       float g0 = bflo(g.x), g1 = bfhi(g.x), g2 = bflo(g.y), g3 = bfhi(g.y);
;       uint2 o;
;       o.x = pack2((oT[d][0] - mu) * rs * g0 * sigm(g0), (oT[d][1] - mu) * rs * g1 * sigm(g1));
;       o.y = pack2((oT[d][2] - mu) * rs * g2 * sigm(g2), (oT[d][3] - mu) * rs * g3 * sigm(g3));
;       *(uint2*)(orow + 128 + d * 16) = o;
;     }
;   }
	v_lshlrev_b32_e32 v14, 16, v12
	v_and_b32_e32 v15, 0xffff0000, v12
	v_mul_f32_e32 v16, 0xbfb8aa3b, v14
	v_mul_f32_e32 v8, v8, v14
	v_mul_f32_e32 v9, v9, v15
	v_mul_f32_e32 v14, 0xbfb8aa3b, v15
	v_exp_f32_e32 v16, v16
	v_exp_f32_e32 v17, v14
	v_lshlrev_b32_e32 v12, 16, v13
	v_and_b32_e32 v13, 0xffff0000, v13
	v_mul_f32_e32 v10, v10, v12
	v_mul_f32_e32 v11, v11, v13
	v_pk_add_f32 v[14:15], v[16:17], 1.0 op_sel_hi:[1,0]
	s_nop 0
	v_div_scale_f32 v16, s[0:1], v15, v15, 1.0
	v_rcp_f32_e32 v17, v16
	s_nop 0
	v_fma_f32 v18, -v16, v17, 1.0
	v_fmac_f32_e32 v17, v18, v17
	v_div_scale_f32 v18, vcc, 1.0, v15, 1.0
	v_mul_f32_e32 v19, v18, v17
	v_fma_f32 v20, -v16, v19, v18
	v_fmac_f32_e32 v19, v20, v17
	v_fma_f32 v16, -v16, v19, v18
	v_div_fmas_f32 v16, v16, v17, v19
	v_div_fixup_f32 v15, v16, v15, 1.0
	v_div_scale_f32 v16, s[0:1], v14, v14, 1.0
	v_rcp_f32_e32 v17, v16
	s_nop 0
	v_fma_f32 v18, -v16, v17, 1.0
	v_fmac_f32_e32 v17, v18, v17
	v_div_scale_f32 v18, vcc, 1.0, v14, 1.0
	v_mul_f32_e32 v19, v18, v17
	v_fma_f32 v20, -v16, v19, v18
	v_fmac_f32_e32 v19, v20, v17
	v_fma_f32 v16, -v16, v19, v18
	v_div_fmas_f32 v16, v16, v17, v19
	v_div_fixup_f32 v14, v16, v14, 1.0
	v_mul_f32_e32 v8, v8, v14
	v_mul_f32_e32 v9, v9, v15
	s_nop 0
	v_cvt_pk_bf16_f32 v8, v8, v9
	v_mul_f32_e32 v9, 0xbfb8aa3b, v12
	v_exp_f32_e32 v14, v9
	v_mul_f32_e32 v9, 0xbfb8aa3b, v13
	v_exp_f32_e32 v15, v9
	s_nop 0
	v_pk_add_f32 v[12:13], v[14:15], 1.0 op_sel_hi:[1,0]
	s_nop 0
	v_div_scale_f32 v9, s[0:1], v13, v13, 1.0
	v_rcp_f32_e32 v14, v9
	s_nop 0
	v_fma_f32 v15, -v9, v14, 1.0
	v_fmac_f32_e32 v14, v15, v14
	v_div_scale_f32 v15, vcc, 1.0, v13, 1.0
	v_mul_f32_e32 v16, v15, v14
	v_fma_f32 v17, -v9, v16, v15
	v_fmac_f32_e32 v16, v17, v14
	v_fma_f32 v9, -v9, v16, v15
	v_div_fmas_f32 v9, v9, v14, v16
	v_div_fixup_f32 v13, v9, v13, 1.0
	v_div_scale_f32 v9, s[0:1], v12, v12, 1.0
	v_rcp_f32_e32 v14, v9
	s_nop 0
	v_fma_f32 v15, -v9, v14, 1.0
	v_fmac_f32_e32 v14, v15, v14
	v_div_scale_f32 v15, vcc, 1.0, v12, 1.0
	v_mul_f32_e32 v16, v15, v14
	v_fma_f32 v17, -v9, v16, v15
	v_fmac_f32_e32 v16, v17, v14
	v_fma_f32 v9, -v9, v16, v15
	v_div_fmas_f32 v9, v9, v14, v16
	v_div_fixup_f32 v12, v9, v12, 1.0
	v_mul_f32_e32 v10, v10, v12
	v_mul_f32_e32 v11, v11, v13
	s_nop 0
	v_cvt_pk_bf16_f32 v9, v10, v11
	flat_store_dwordx2 v[36:37], v[8:9] offset:416
	flat_load_dwordx2 v[8:9], v[38:39] offset:192
	s_waitcnt vmcnt(0) lgkmcnt(0)
	v_lshlrev_b32_e32 v10, 16, v8
	v_and_b32_e32 v11, 0xffff0000, v8
	v_lshlrev_b32_e32 v12, 16, v9
	v_and_b32_e32 v13, 0xffff0000, v9
	v_lshlrev_b32_e32 v8, 16, v89
	v_and_b32_e32 v9, 0xffff0000, v89
	v_sub_f32_e32 v8, v8, v29
	v_sub_f32_e32 v9, v9, v29
	v_mul_f32_e32 v14, 0xbfb8aa3b, v10
	v_mul_f32_e32 v8, v8, v30
	v_mul_f32_e32 v9, v9, v30
	v_exp_f32_e32 v14, v14
	v_mul_f32_e32 v8, v8, v10
	v_mul_f32_e32 v9, v9, v11
	v_mul_f32_e32 v10, 0xbfb8aa3b, v11
	v_exp_f32_e32 v15, v10
	s_nop 0
	v_pk_add_f32 v[10:11], v[14:15], 1.0 op_sel_hi:[1,0]
	s_nop 0
	v_div_scale_f32 v14, s[0:1], v11, v11, 1.0
	v_rcp_f32_e32 v15, v14
	s_nop 0
	v_fma_f32 v16, -v14, v15, 1.0
	v_fmac_f32_e32 v15, v16, v15
	v_div_scale_f32 v16, vcc, 1.0, v11, 1.0
	v_mul_f32_e32 v17, v16, v15
	v_fma_f32 v18, -v14, v17, v16
	v_fmac_f32_e32 v17, v18, v15
	v_fma_f32 v14, -v14, v17, v16
	v_div_fmas_f32 v14, v14, v15, v17
	v_div_fixup_f32 v11, v14, v11, 1.0
	v_div_scale_f32 v14, s[0:1], v10, v10, 1.0
	v_rcp_f32_e32 v15, v14
	s_nop 0
	v_fma_f32 v16, -v14, v15, 1.0
	v_fmac_f32_e32 v15, v16, v15
	v_div_scale_f32 v16, vcc, 1.0, v10, 1.0
	v_mul_f32_e32 v17, v16, v15
	v_fma_f32 v18, -v14, v17, v16
	v_fmac_f32_e32 v17, v18, v15
	v_fma_f32 v14, -v14, v17, v16
	v_div_fmas_f32 v14, v14, v15, v17
	v_div_fixup_f32 v10, v14, v10, 1.0
	v_mul_f32_e32 v8, v8, v10
	v_mul_f32_e32 v9, v9, v11
	v_lshlrev_b32_e32 v10, 16, v88
	v_cvt_pk_bf16_f32 v8, v8, v9
	v_mul_f32_e32 v9, 0xbfb8aa3b, v12
	v_exp_f32_e32 v14, v9
	v_mul_f32_e32 v9, 0xbfb8aa3b, v13
	v_exp_f32_e32 v15, v9
	v_and_b32_e32 v11, 0xffff0000, v88
	v_sub_f32_e32 v10, v10, v29
	v_sub_f32_e32 v11, v11, v29
	s_nop 0
	v_mul_f32_e32 v10, v10, v30
	v_mul_f32_e32 v11, v11, v30
	s_nop 0
	v_mul_f32_e32 v10, v10, v12
	v_mul_f32_e32 v11, v11, v13
	v_pk_add_f32 v[12:13], v[14:15], 1.0 op_sel_hi:[1,0]
	s_nop 0
	v_div_scale_f32 v9, s[0:1], v13, v13, 1.0
	v_rcp_f32_e32 v14, v9
	s_nop 0
	v_fma_f32 v15, -v9, v14, 1.0
	v_fmac_f32_e32 v14, v15, v14
	v_div_scale_f32 v15, vcc, 1.0, v13, 1.0
	v_mul_f32_e32 v16, v15, v14
	v_fma_f32 v17, -v9, v16, v15
	v_fmac_f32_e32 v16, v17, v14
	v_fma_f32 v9, -v9, v16, v15
	v_div_fmas_f32 v9, v9, v14, v16
	v_div_fixup_f32 v13, v9, v13, 1.0
	v_div_scale_f32 v9, s[0:1], v12, v12, 1.0
	v_rcp_f32_e32 v14, v9
	s_nop 0
	v_fma_f32 v15, -v9, v14, 1.0
	v_fmac_f32_e32 v14, v15, v14
	v_div_scale_f32 v15, vcc, 1.0, v12, 1.0
	v_mul_f32_e32 v16, v15, v14
	v_fma_f32 v17, -v9, v16, v15
	v_fmac_f32_e32 v16, v17, v14
	v_fma_f32 v9, -v9, v16, v15
	v_div_fmas_f32 v9, v9, v14, v16
	v_div_fixup_f32 v12, v9, v12, 1.0
	v_mul_f32_e32 v10, v10, v12
	v_mul_f32_e32 v11, v11, v13
	s_nop 0
	v_cvt_pk_bf16_f32 v9, v10, v11
	flat_store_dwordx2 v[36:37], v[8:9] offset:192
	flat_load_dwordx2 v[8:9], v[38:39] offset:448
	s_waitcnt vmcnt(0) lgkmcnt(0)
; DEV float bflo(unsigned u) { return __uint_as_float(u << 16); }
; DEV float bfhi(unsigned u) { return __uint_as_float(u & 0xffff0000u); }
; DEV float sigm(float x) { return 1.f / (1.f + __expf(-x)); }
; __device__ __forceinline__ void ret_out_item(PREF P, int w, const u16* ST, char* smem) {
;     ...
; #pragma unroll
;   for (int d = 0; d < 8; ++d) {
;     {
;       u32x2 pvv = park[d];
;       uint2 g = *(const uint2*)(grow + d * 16);
;       float g0 = bflo(g.x), g1 = bfhi(g.x), g2 = bflo(g.y), g3 = bfhi(g.y);
;       uint2 o;
;       o.x = pack2((bflo(pvv.x) - mu) * rs * g0 * sigm(g0), (bfhi(pvv.x) - mu) * rs * g1 * sigm(g1));
;       o.y = pack2((bflo(pvv.y) - mu) * rs * g2 * sigm(g2), (bfhi(pvv.y) - mu) * rs * g3 * sigm(g3));
;       *(uint2*)(orow + d * 16) = o;
;     }
;     {
;       uint2 g = *(const uint2*)(grow + 128 + d * 16);
;       float g0 = bflo(g.x), g1 = bfhi(g.x), g2 = bflo(g.y), g3 = bfhi(g.y);
;       uint2 o;
;       o.x = pack2((oT[d][0] - mu) * rs * g0 * sigm(g0), (oT[d][1] - mu) * rs * g1 * sigm(g1));
;       o.y = pack2((oT[d][2] - mu) * rs * g2 * sigm(g2), (oT[d][3] - mu) * rs * g3 * sigm(g3));
;       *(uint2*)(orow + 128 + d * 16) = o;
;     }
;   }
	v_lshlrev_b32_e32 v10, 16, v8
	v_and_b32_e32 v11, 0xffff0000, v8
	v_mul_f32_e32 v12, 0xbfb8aa3b, v10
	v_mul_f32_e32 v4, v4, v10
	v_mul_f32_e32 v5, v5, v11
	v_mul_f32_e32 v10, 0xbfb8aa3b, v11
	v_exp_f32_e32 v12, v12
	v_exp_f32_e32 v13, v10
	v_lshlrev_b32_e32 v8, 16, v9
	v_and_b32_e32 v9, 0xffff0000, v9
	v_mul_f32_e32 v6, v6, v8
	v_mul_f32_e32 v7, v7, v9
	v_pk_add_f32 v[10:11], v[12:13], 1.0 op_sel_hi:[1,0]
	s_nop 0
	v_div_scale_f32 v12, s[0:1], v11, v11, 1.0
	v_rcp_f32_e32 v13, v12
	s_nop 0
	v_fma_f32 v14, -v12, v13, 1.0
	v_fmac_f32_e32 v13, v14, v13
	v_div_scale_f32 v14, vcc, 1.0, v11, 1.0
	v_mul_f32_e32 v15, v14, v13
	v_fma_f32 v16, -v12, v15, v14
	v_fmac_f32_e32 v15, v16, v13
	v_fma_f32 v12, -v12, v15, v14
	v_div_fmas_f32 v12, v12, v13, v15
	v_div_fixup_f32 v11, v12, v11, 1.0
	v_div_scale_f32 v12, s[0:1], v10, v10, 1.0
	v_rcp_f32_e32 v13, v12
	s_nop 0
	v_fma_f32 v14, -v12, v13, 1.0
	v_fmac_f32_e32 v13, v14, v13
	v_div_scale_f32 v14, vcc, 1.0, v10, 1.0
	v_mul_f32_e32 v15, v14, v13
	v_fma_f32 v16, -v12, v15, v14
	v_fmac_f32_e32 v15, v16, v13
	v_fma_f32 v12, -v12, v15, v14
	v_div_fmas_f32 v12, v12, v13, v15
	v_div_fixup_f32 v10, v12, v10, 1.0
	v_mul_f32_e32 v4, v4, v10
	v_mul_f32_e32 v5, v5, v11
	s_nop 0
	v_cvt_pk_bf16_f32 v4, v4, v5
	v_mul_f32_e32 v5, 0xbfb8aa3b, v8
	v_exp_f32_e32 v10, v5
	v_mul_f32_e32 v5, 0xbfb8aa3b, v9
	v_exp_f32_e32 v11, v5
	s_nop 0
	v_pk_add_f32 v[8:9], v[10:11], 1.0 op_sel_hi:[1,0]
	s_nop 0
	v_div_scale_f32 v5, s[0:1], v9, v9, 1.0
	v_rcp_f32_e32 v10, v5
	s_nop 0
	v_fma_f32 v11, -v5, v10, 1.0
	v_fmac_f32_e32 v10, v11, v10
	v_div_scale_f32 v11, vcc, 1.0, v9, 1.0
	v_mul_f32_e32 v12, v11, v10
	v_fma_f32 v13, -v5, v12, v11
	v_fmac_f32_e32 v12, v13, v10
	v_fma_f32 v5, -v5, v12, v11
	v_div_fmas_f32 v5, v5, v10, v12
	v_div_fixup_f32 v9, v5, v9, 1.0
	v_div_scale_f32 v5, s[0:1], v8, v8, 1.0
	v_rcp_f32_e32 v10, v5
	s_nop 0
	v_fma_f32 v11, -v5, v10, 1.0
	v_fmac_f32_e32 v10, v11, v10
	v_div_scale_f32 v11, vcc, 1.0, v8, 1.0
	v_mul_f32_e32 v12, v11, v10
	v_fma_f32 v13, -v5, v12, v11
	v_fmac_f32_e32 v12, v13, v10
	v_fma_f32 v5, -v5, v12, v11
	v_div_fmas_f32 v5, v5, v10, v12
	v_div_fixup_f32 v8, v5, v8, 1.0
	v_mul_f32_e32 v6, v6, v8
	v_mul_f32_e32 v7, v7, v9
	s_nop 0
	v_cvt_pk_bf16_f32 v5, v6, v7
	flat_store_dwordx2 v[36:37], v[4:5] offset:448
	flat_load_dwordx2 v[4:5], v[38:39] offset:224
	s_waitcnt vmcnt(0) lgkmcnt(0)
; DEV int bid_() { int t = blockIdx.x; asm volatile("" : "+s"(t)); return t; }
; DEV int gdim_() { int t = gridDim.x; asm volatile("" : "+s"(t)); return t; }
; DEV float bflo(unsigned u) { return __uint_as_float(u << 16); }
; DEV float bfhi(unsigned u) { return __uint_as_float(u & 0xffff0000u); }
; DEV float sigm(float x) { return 1.f / (1.f + __expf(-x)); }
; #define P (*launderP(lp))
; __device__ __forceinline__ void ret_out_item(PREF P, int w, const u16* ST, char* smem) {
;     ...
; #pragma unroll
;   for (int d = 0; d < 8; ++d) {
;     {
;       u32x2 pvv = park[d];
;       uint2 g = *(const uint2*)(grow + d * 16);
;       float g0 = bflo(g.x), g1 = bfhi(g.x), g2 = bflo(g.y), g3 = bfhi(g.y);
;       uint2 o;
;       o.x = pack2((bflo(pvv.x) - mu) * rs * g0 * sigm(g0), (bfhi(pvv.x) - mu) * rs * g1 * sigm(g1));
;       o.y = pack2((bflo(pvv.y) - mu) * rs * g2 * sigm(g2), (bfhi(pvv.y) - mu) * rs * g3 * sigm(g3));
;       *(uint2*)(orow + d * 16) = o;
;     }
;     {
;       uint2 g = *(const uint2*)(grow + 128 + d * 16);
;       float g0 = bflo(g.x), g1 = bfhi(g.x), g2 = bflo(g.y), g3 = bfhi(g.y);
;       uint2 o;
;       o.x = pack2((oT[d][0] - mu) * rs * g0 * sigm(g0), (oT[d][1] - mu) * rs * g1 * sigm(g1));
;       o.y = pack2((oT[d][2] - mu) * rs * g2 * sigm(g2), (oT[d][3] - mu) * rs * g3 * sigm(g3));
;       *(uint2*)(orow + 128 + d * 16) = o;
;     }
;   }
; __global__ void __launch_bounds__(NTHR, 2) fwd_megakernel(Params Pk) {
;     ...
;       for (int w = bid_(); w < 1024; w += gdim_()) ret_out_item(P, w, ST, smem);
	v_lshlrev_b32_e32 v6, 16, v4
	v_and_b32_e32 v7, 0xffff0000, v4
	v_lshlrev_b32_e32 v8, 16, v5
	v_and_b32_e32 v9, 0xffff0000, v5
	v_lshlrev_b32_e32 v4, 16, v101
	v_and_b32_e32 v5, 0xffff0000, v101
	v_sub_f32_e32 v4, v4, v29
	v_sub_f32_e32 v5, v5, v29
	v_mul_f32_e32 v10, 0xbfb8aa3b, v6
	v_mul_f32_e32 v4, v4, v30
	v_mul_f32_e32 v5, v5, v30
	v_exp_f32_e32 v10, v10
	v_mul_f32_e32 v4, v4, v6
	v_mul_f32_e32 v5, v5, v7
	v_mul_f32_e32 v6, 0xbfb8aa3b, v7
	v_exp_f32_e32 v11, v6
	s_nop 0
	v_pk_add_f32 v[6:7], v[10:11], 1.0 op_sel_hi:[1,0]
	s_nop 0
	v_div_scale_f32 v10, s[0:1], v7, v7, 1.0
	v_rcp_f32_e32 v11, v10
	s_nop 0
	v_fma_f32 v12, -v10, v11, 1.0
	v_fmac_f32_e32 v11, v12, v11
	v_div_scale_f32 v12, vcc, 1.0, v7, 1.0
	v_mul_f32_e32 v13, v12, v11
	v_fma_f32 v14, -v10, v13, v12
	v_fmac_f32_e32 v13, v14, v11
	v_fma_f32 v10, -v10, v13, v12
	v_div_fmas_f32 v10, v10, v11, v13
	v_div_fixup_f32 v7, v10, v7, 1.0
	v_div_scale_f32 v10, s[0:1], v6, v6, 1.0
	v_rcp_f32_e32 v11, v10
	s_nop 0
	v_fma_f32 v12, -v10, v11, 1.0
	v_fmac_f32_e32 v11, v12, v11
	v_div_scale_f32 v12, vcc, 1.0, v6, 1.0
	v_mul_f32_e32 v13, v12, v11
	v_fma_f32 v14, -v10, v13, v12
	v_fmac_f32_e32 v13, v14, v11
	v_fma_f32 v10, -v10, v13, v12
	v_div_fmas_f32 v10, v10, v11, v13
	v_div_fixup_f32 v6, v10, v6, 1.0
	v_mul_f32_e32 v4, v4, v6
	v_mul_f32_e32 v5, v5, v7
	v_lshlrev_b32_e32 v6, 16, v100
	v_cvt_pk_bf16_f32 v4, v4, v5
	v_mul_f32_e32 v5, 0xbfb8aa3b, v8
	v_exp_f32_e32 v10, v5
	v_mul_f32_e32 v5, 0xbfb8aa3b, v9
	v_exp_f32_e32 v11, v5
	v_and_b32_e32 v7, 0xffff0000, v100
	v_sub_f32_e32 v6, v6, v29
	v_sub_f32_e32 v7, v7, v29
	s_nop 0
	v_mul_f32_e32 v6, v6, v30
	v_mul_f32_e32 v7, v7, v30
	s_nop 0
	v_mul_f32_e32 v6, v6, v8
	v_mul_f32_e32 v7, v7, v9
	v_pk_add_f32 v[8:9], v[10:11], 1.0 op_sel_hi:[1,0]
	s_nop 0
	v_div_scale_f32 v5, s[0:1], v9, v9, 1.0
	v_rcp_f32_e32 v10, v5
	s_nop 0
	v_fma_f32 v11, -v5, v10, 1.0
	v_fmac_f32_e32 v10, v11, v10
	v_div_scale_f32 v11, vcc, 1.0, v9, 1.0
	v_mul_f32_e32 v12, v11, v10
	v_fma_f32 v13, -v5, v12, v11
	v_fmac_f32_e32 v12, v13, v10
	v_fma_f32 v5, -v5, v12, v11
	v_div_fmas_f32 v5, v5, v10, v12
	v_div_fixup_f32 v9, v5, v9, 1.0
	v_div_scale_f32 v5, s[0:1], v8, v8, 1.0
	v_rcp_f32_e32 v10, v5
	s_nop 0
	v_fma_f32 v11, -v5, v10, 1.0
	v_fmac_f32_e32 v10, v11, v10
	v_div_scale_f32 v11, vcc, 1.0, v8, 1.0
	v_mul_f32_e32 v12, v11, v10
	v_fma_f32 v13, -v5, v12, v11
	v_fmac_f32_e32 v12, v13, v10
	v_fma_f32 v5, -v5, v12, v11
	v_div_fmas_f32 v5, v5, v10, v12
	v_div_fixup_f32 v8, v5, v8, 1.0
	v_mul_f32_e32 v6, v6, v8
	v_mul_f32_e32 v7, v7, v9
	s_nop 0
	v_cvt_pk_bf16_f32 v5, v6, v7
	flat_store_dwordx2 v[36:37], v[4:5] offset:224
	flat_load_dwordx2 v[4:5], v[38:39] offset:480
	s_waitcnt vmcnt(0) lgkmcnt(0)
	v_lshlrev_b32_e32 v6, 16, v4
	v_and_b32_e32 v7, 0xffff0000, v4
	v_mul_f32_e32 v8, 0xbfb8aa3b, v6
	v_mul_f32_e32 v0, v0, v6
	v_mul_f32_e32 v1, v1, v7
	v_mul_f32_e32 v6, 0xbfb8aa3b, v7
	v_exp_f32_e32 v8, v8
	v_exp_f32_e32 v9, v6
	v_lshlrev_b32_e32 v4, 16, v5
	v_and_b32_e32 v5, 0xffff0000, v5
	v_mul_f32_e32 v2, v2, v4
	v_mul_f32_e32 v3, v3, v5
	v_pk_add_f32 v[6:7], v[8:9], 1.0 op_sel_hi:[1,0]
	s_nop 0
	v_div_scale_f32 v8, s[0:1], v7, v7, 1.0
	v_rcp_f32_e32 v9, v8
	s_nop 0
	v_fma_f32 v10, -v8, v9, 1.0
	v_fmac_f32_e32 v9, v10, v9
	v_div_scale_f32 v10, vcc, 1.0, v7, 1.0
	v_mul_f32_e32 v11, v10, v9
	v_fma_f32 v12, -v8, v11, v10
	v_fmac_f32_e32 v11, v12, v9
	v_fma_f32 v8, -v8, v11, v10
	v_div_fmas_f32 v8, v8, v9, v11
	v_div_fixup_f32 v7, v8, v7, 1.0
	v_div_scale_f32 v8, s[0:1], v6, v6, 1.0
	v_rcp_f32_e32 v9, v8
	s_nop 0
	v_fma_f32 v10, -v8, v9, 1.0
	v_fmac_f32_e32 v9, v10, v9
	v_div_scale_f32 v10, vcc, 1.0, v6, 1.0
	v_mul_f32_e32 v11, v10, v9
	v_fma_f32 v12, -v8, v11, v10
	v_fmac_f32_e32 v11, v12, v9
	v_fma_f32 v8, -v8, v11, v10
	v_div_fmas_f32 v8, v8, v9, v11
	v_div_fixup_f32 v6, v8, v6, 1.0
	v_mul_f32_e32 v0, v0, v6
	v_mul_f32_e32 v1, v1, v7
	s_nop 0
	v_cvt_pk_bf16_f32 v0, v0, v1
	v_mul_f32_e32 v1, 0xbfb8aa3b, v4
	v_exp_f32_e32 v6, v1
	v_mul_f32_e32 v1, 0xbfb8aa3b, v5
	v_exp_f32_e32 v7, v1
	s_nop 0
	v_pk_add_f32 v[4:5], v[6:7], 1.0 op_sel_hi:[1,0]
	s_nop 0
	v_div_scale_f32 v1, s[0:1], v5, v5, 1.0
	v_rcp_f32_e32 v6, v1
	s_nop 0
	v_fma_f32 v7, -v1, v6, 1.0
	v_fmac_f32_e32 v6, v7, v6
	v_div_scale_f32 v7, vcc, 1.0, v5, 1.0
	v_mul_f32_e32 v8, v7, v6
	v_fma_f32 v9, -v1, v8, v7
	v_fmac_f32_e32 v8, v9, v6
	v_fma_f32 v1, -v1, v8, v7
	v_div_fmas_f32 v1, v1, v6, v8
	v_div_fixup_f32 v5, v1, v5, 1.0
	v_div_scale_f32 v1, s[0:1], v4, v4, 1.0
	v_rcp_f32_e32 v6, v1
	v_readlane_b32 s0, v251, 6
	v_readlane_b32 s1, v251, 7
	v_fma_f32 v7, -v1, v6, 1.0
	v_fmac_f32_e32 v6, v7, v6
	v_div_scale_f32 v7, vcc, 1.0, v4, 1.0
	v_mul_f32_e32 v8, v7, v6
	v_fma_f32 v9, -v1, v8, v7
	v_fmac_f32_e32 v8, v9, v6
	v_fma_f32 v1, -v1, v8, v7
	v_div_fmas_f32 v1, v1, v6, v8
	v_div_fixup_f32 v4, v1, v4, 1.0
	v_mul_f32_e32 v2, v2, v4
	v_mul_f32_e32 v3, v3, v5
	s_nop 0
	v_cvt_pk_bf16_f32 v1, v2, v3
	flat_store_dwordx2 v[36:37], v[0:1] offset:480
	s_add_i32 s44, s0, s44
	s_cmpk_gt_i32 s44, 0x3ff
	s_cbranch_scc1 .LBB0_349

; __device__ __forceinline__ void ret_out_item(PREF P, int w, const u16* ST, char* smem) {
;     ...
;     for (int jt = 0; jt < 8; ++jt)
; #pragma unroll
;       for (int r = 0; r < 4; ++r) {
;         int diff = i - (jt * 16 + q * 4 + r);
;         float dcy = diff >= 0 ? __builtin_amdgcn_exp2f(l2f * (float)diff) : __builtin_amdgcn_exp2f(l2b * (float)(-diff));
;         sT[jt][r] *= dcy;
;       }
.LBB0_337:
	s_or_b64 exec, exec, s[16:17]
	v_sub_u32_e32 v48, 0, v93
	v_max_i32_e32 v48, v93, v48
	v_cvt_f32_u32_e32 v48, v48
	v_cndmask_b32_e64 v49, v85, v88, s[96:97]
	v_cndmask_b32_e64 v50, v85, v88, s[94:95]
	v_cndmask_b32_e64 v51, v85, v88, s[92:93]
	v_mul_f32_e32 v48, v49, v48
	v_sub_u32_e32 v49, 0, v92
	v_max_i32_e32 v49, v92, v49
	v_cvt_f32_u32_e32 v49, v49
	v_exp_f32_e32 v48, v48
	v_and_b32_e32 v118, 8, v87
	v_mul_f32_e32 v49, v50, v49
	v_sub_u32_e32 v50, 0, v91
	v_max_i32_e32 v50, v91, v50
	v_cvt_f32_u32_e32 v50, v50
	v_exp_f32_e32 v49, v49
	v_mul_f32_e32 v50, v51, v50
	v_sub_u32_e32 v51, 0, v90
	v_max_i32_e32 v51, v90, v51
	v_cvt_f32_u32_e32 v51, v51
	v_cndmask_b32_e64 v90, v85, v88, s[90:91]
	v_exp_f32_e32 v50, v50
	v_mul_f32_e32 v16, v48, v16
	v_mul_f32_e32 v17, v49, v17
	v_mul_f32_e32 v51, v90, v51
	v_sub_u32_e32 v90, 0, v52
	v_max_i32_e32 v52, v52, v90
	v_cvt_f32_u32_e32 v52, v52
	v_cndmask_b32_e64 v90, v85, v88, s[88:89]
	v_exp_f32_e32 v51, v51
	v_mul_f32_e32 v52, v90, v52
	v_sub_u32_e32 v90, 0, v53
	v_max_i32_e32 v53, v53, v90
	v_cvt_f32_u32_e32 v53, v53
	v_cndmask_b32_e64 v90, v85, v88, s[86:87]
	v_exp_f32_e32 v52, v52
	v_mul_f32_e32 v18, v50, v18
	v_mul_f32_e32 v19, v51, v19
	v_mul_f32_e32 v53, v90, v53
	v_sub_u32_e32 v90, 0, v54
	v_max_i32_e32 v54, v54, v90
	v_cvt_f32_u32_e32 v54, v54
	v_cndmask_b32_e64 v90, v85, v88, s[84:85]
	v_exp_f32_e32 v53, v53
	v_mul_f32_e32 v54, v90, v54
	v_sub_u32_e32 v90, 0, v55
	v_max_i32_e32 v55, v55, v90
	v_cvt_f32_u32_e32 v55, v55
	v_cndmask_b32_e64 v90, v85, v88, s[82:83]
	v_exp_f32_e32 v54, v54
	v_mul_f32_e32 v20, v52, v20
	v_mul_f32_e32 v21, v53, v21
	v_mul_f32_e32 v55, v90, v55
	v_sub_u32_e32 v90, 0, v56
	v_max_i32_e32 v56, v56, v90
	v_cvt_f32_u32_e32 v56, v56
	v_cndmask_b32_e64 v90, v85, v88, s[80:81]
	v_exp_f32_e32 v55, v55
	v_mul_f32_e32 v56, v90, v56
	v_sub_u32_e32 v90, 0, v57
	v_max_i32_e32 v57, v57, v90
	v_cvt_f32_u32_e32 v57, v57
	v_cndmask_b32_e64 v90, v85, v88, s[78:79]
	v_exp_f32_e32 v56, v56
	v_mul_f32_e32 v22, v54, v22
	v_mul_f32_e32 v23, v55, v23
	v_mul_f32_e32 v57, v90, v57
	v_sub_u32_e32 v90, 0, v58
	v_max_i32_e32 v58, v58, v90
	v_cvt_f32_u32_e32 v58, v58
	v_cndmask_b32_e64 v90, v85, v88, s[76:77]
	v_exp_f32_e32 v57, v57
	v_mul_f32_e32 v58, v90, v58
	v_sub_u32_e32 v90, 0, v59
	v_max_i32_e32 v59, v59, v90
	v_cvt_f32_u32_e32 v59, v59
	v_cndmask_b32_e64 v90, v85, v88, s[74:75]
	v_exp_f32_e32 v58, v58
	v_mul_f32_e32 v24, v56, v24
	v_mul_f32_e32 v25, v57, v25
	v_mul_f32_e32 v59, v90, v59
	v_sub_u32_e32 v90, 0, v60
	v_max_i32_e32 v60, v60, v90
	v_cvt_f32_u32_e32 v60, v60
	v_cndmask_b32_e64 v90, v85, v88, s[72:73]
	v_exp_f32_e32 v59, v59
	v_cvt_pk_bf16_f32 v24, v24, v25
	v_mul_f32_e32 v60, v90, v60
	v_sub_u32_e32 v90, 0, v61
	v_max_i32_e32 v61, v61, v90
	v_cvt_f32_u32_e32 v61, v61
	v_cndmask_b32_e64 v90, v85, v88, s[70:71]
	v_exp_f32_e32 v60, v60
	v_mul_f32_e32 v26, v58, v26
	v_mul_f32_e32 v27, v59, v27
	v_mul_f32_e32 v61, v90, v61
	v_sub_u32_e32 v90, 0, v62
	v_max_i32_e32 v62, v62, v90
	v_cvt_f32_u32_e32 v62, v62
	v_cndmask_b32_e64 v90, v85, v88, s[68:69]
	v_exp_f32_e32 v61, v61
	v_cvt_pk_bf16_f32 v25, v26, v27
	v_mul_f32_e32 v62, v90, v62
	v_sub_u32_e32 v90, 0, v63
	v_max_i32_e32 v63, v63, v90
	v_cvt_f32_u32_e32 v63, v63
	v_cndmask_b32_e64 v90, v85, v88, s[66:67]
	v_exp_f32_e32 v62, v62
	v_mul_f32_e32 v28, v60, v28
	v_mul_f32_e32 v29, v61, v29
	v_mul_f32_e32 v63, v90, v63
	v_sub_u32_e32 v90, 0, v66
	v_max_i32_e32 v66, v66, v90
	v_cvt_f32_u32_e32 v66, v66
	v_cndmask_b32_e64 v90, v85, v88, s[64:65]
	v_exp_f32_e32 v63, v63
	v_cvt_pk_bf16_f32 v26, v28, v29
	v_mul_f32_e32 v66, v90, v66
	v_sub_u32_e32 v90, 0, v67
	v_max_i32_e32 v67, v67, v90
	v_cvt_f32_u32_e32 v67, v67
	v_cndmask_b32_e64 v90, v85, v88, s[62:63]
	v_exp_f32_e32 v66, v66
	v_mul_f32_e32 v30, v62, v30
	v_mul_f32_e32 v31, v63, v31
	v_mul_f32_e32 v67, v90, v67
	v_sub_u32_e32 v90, 0, v72
	v_max_i32_e32 v72, v72, v90
	v_cvt_f32_u32_e32 v72, v72
	v_cndmask_b32_e64 v90, v85, v88, s[60:61]
	v_exp_f32_e32 v67, v67
	v_cvt_pk_bf16_f32 v27, v30, v31
	v_mul_f32_e32 v72, v90, v72
	v_sub_u32_e32 v90, 0, v73
	v_max_i32_e32 v73, v73, v90
	v_cvt_f32_u32_e32 v73, v73
	v_cndmask_b32_e64 v90, v85, v88, s[0:1]
	s_mov_b64 s[0:1], src_shared_base
	v_exp_f32_e32 v72, v72
	v_mul_f32_e32 v73, v90, v73
	v_sub_u32_e32 v90, 0, v74
	v_max_i32_e32 v74, v74, v90
	v_cvt_f32_u32_e32 v74, v74
	v_cndmask_b32_e64 v90, v85, v88, s[56:57]
	v_exp_f32_e32 v73, v73
	v_mul_f32_e32 v32, v66, v32
	v_mul_f32_e32 v33, v67, v33
	v_mul_f32_e32 v74, v90, v74
	v_sub_u32_e32 v90, 0, v75
	v_max_i32_e32 v75, v75, v90
	v_cvt_f32_u32_e32 v75, v75
	v_cndmask_b32_e64 v90, v85, v88, s[54:55]
	v_exp_f32_e32 v74, v74
	v_lshrrev_b32_e32 v67, 1, v86
	v_mul_f32_e32 v75, v90, v75
	v_sub_u32_e32 v90, 0, v76
	v_max_i32_e32 v76, v76, v90
	v_cvt_f32_u32_e32 v76, v76
	v_cndmask_b32_e64 v90, v85, v88, s[52:53]
	v_exp_f32_e32 v75, v75
	v_xor_b32_e32 v28, v67, v65
	v_mul_f32_e32 v76, v90, v76
	v_sub_u32_e32 v90, 0, v77
	v_max_i32_e32 v77, v77, v90
	v_cvt_f32_u32_e32 v77, v77
	v_cndmask_b32_e64 v90, v85, v88, s[50:51]
	v_exp_f32_e32 v76, v76
	v_lshlrev_b32_e32 v119, 4, v28
	v_mul_f32_e32 v77, v90, v77
	v_sub_u32_e32 v90, 0, v78
	v_max_i32_e32 v78, v78, v90
	v_cvt_f32_u32_e32 v78, v78
	v_cndmask_b32_e64 v90, v85, v88, s[48:49]
	v_exp_f32_e32 v77, v77
	v_bitop3_b32 v28, v67, v65, 2 bitop3:0x36
	v_mul_f32_e32 v78, v90, v78
	v_sub_u32_e32 v90, 0, v79
	v_max_i32_e32 v79, v79, v90
	v_cvt_f32_u32_e32 v79, v79
	v_cndmask_b32_e64 v90, v85, v88, s[46:47]
	v_exp_f32_e32 v78, v78
	v_mul_f32_e32 v34, v72, v34
	v_mul_f32_e32 v35, v73, v35
	v_mul_f32_e32 v79, v90, v79
	v_sub_u32_e32 v90, 0, v80
; DEV void ro_pv(const char* buf, const bf16x8 (&pf)[4], f32x4 (&oT)[8], int l15, int q) {
; #pragma unroll
;   for (int d = 0; d < 8; ++d) oT[d] = f32x4{0.f, 0.f, 0.f, 0.f};
;   const unsigned base = lds_off(buf) + (unsigned)(l15 * 256 + (q & 1) * 8);
; #pragma unroll
;   for (int j2 = 0; j2 < 4; ++j2) {
;     const unsigned a0 = base + (unsigned)((((j2 * 4 + (q >> 1)) ^ l15) & 15) << 4);
;     const unsigned a1 = base + (unsigned)((((j2 * 4 + (q >> 1) + 2) ^ l15) & 15) << 4);
;     u32x2 v0[8], v1[8];
;     asm volatile(
;         "ds_read_b64 %0, %16\n\t"
;         "ds_read_b64 %1, %16 offset:4096\n\t"
;         "ds_read_b64 %2, %16 offset:8192\n\t"
;         "ds_read_b64 %3, %16 offset:12288\n\t"
;         "ds_read_b64 %4, %16 offset:16384\n\t"
;         "ds_read_b64 %5, %16 offset:20480\n\t"
;         "ds_read_b64 %6, %16 offset:24576\n\t"
;         "ds_read_b64 %7, %16 offset:28672\n\t"
;         "ds_read_b64 %8, %17\n\t"
;         "ds_read_b64 %9, %17 offset:4096\n\t"
;         "ds_read_b64 %10, %17 offset:8192\n\t"
;         "ds_read_b64 %11, %17 offset:12288\n\t"
;         "ds_read_b64 %12, %17 offset:16384\n\t"
;         "ds_read_b64 %13, %17 offset:20480\n\t"
;         "ds_read_b64 %14, %17 offset:24576\n\t"
;         "ds_read_b64 %15, %17 offset:28672\n\t"
;         "s_waitcnt lgkmcnt(0)"
;         : "=&v"(v0[0]), "=&v"(v0[1]), "=&v"(v0[2]), "=&v"(v0[3]), "=&v"(v0[4]), "=&v"(v0[5]), "=&v"(v0[6]), "=&v"(v0[7]),
;           "=&v"(v1[0]), "=&v"(v1[1]), "=&v"(v1[2]), "=&v"(v1[3]), "=&v"(v1[4]), "=&v"(v1[5]), "=&v"(v1[6]), "=&v"(v1[7])
;         : "v"(a0), "v"(a1)
;         : "memory");
; #pragma unroll
; __device__ __forceinline__ void ret_out_item(PREF P, int w, const u16* ST, char* smem) {
;     ...
;     for (int jt = 0; jt < 8; ++jt)
; #pragma unroll
;       for (int r = 0; r < 4; ++r) {
;         int diff = i - (jt * 16 + q * 4 + r);
;         float dcy = diff >= 0 ? __builtin_amdgcn_exp2f(l2f * (float)diff) : __builtin_amdgcn_exp2f(l2b * (float)(-diff));
;         sT[jt][r] *= dcy;
;       }
; #pragma unroll
;     for (int j2 = 0; j2 < 4; ++j2) {
;       u32x4 pp;
;       pp.x = pack2(sT[2 * j2][0], sT[2 * j2][1]);
;       pp.y = pack2(sT[2 * j2][2], sT[2 * j2][3]);
;       pp.z = pack2(sT[2 * j2 + 1][0], sT[2 * j2 + 1][1]);
;       pp.w = pack2(sT[2 * j2 + 1][2], sT[2 * j2 + 1][3]);
;       pf[j2] = __builtin_bit_cast(bf16x8, pp);
;     }
	v_max_i32_e32 v80, v80, v90
	v_cvt_f32_u32_e32 v80, v80
	v_cndmask_b32_e64 v90, v85, v88, s[44:45]
	v_exp_f32_e32 v79, v79
	v_mul_f32_e32 v36, v74, v36
	v_mul_f32_e32 v37, v75, v37
	v_mul_f32_e32 v80, v90, v80
	v_sub_u32_e32 v90, 0, v81
	v_max_i32_e32 v81, v81, v90
	v_cvt_f32_u32_e32 v81, v81
	v_cndmask_b32_e64 v90, v85, v88, s[42:43]
	v_exp_f32_e32 v80, v80
	v_mul_f32_e32 v38, v76, v38
	v_mul_f32_e32 v39, v77, v39
	v_mul_f32_e32 v81, v90, v81
	v_sub_u32_e32 v90, 0, v82
	v_max_i32_e32 v82, v82, v90
	v_cvt_f32_u32_e32 v82, v82
	v_cndmask_b32_e64 v90, v85, v88, s[40:41]
	v_exp_f32_e32 v81, v81
	v_mul_f32_e32 v48, v78, v40
	v_mul_f32_e32 v49, v79, v41
	v_mul_f32_e32 v82, v90, v82
	v_sub_u32_e32 v90, 0, v83
	v_max_i32_e32 v83, v83, v90
	v_cvt_f32_u32_e32 v83, v83
	v_cndmask_b32_e64 v90, v85, v88, s[38:39]
	v_exp_f32_e32 v82, v82
	v_mul_f32_e32 v50, v80, v42
	v_mul_f32_e32 v51, v81, v43
	v_mul_f32_e32 v83, v90, v83
	v_sub_u32_e32 v90, 0, v84
	v_max_i32_e32 v84, v84, v90
	v_cvt_f32_u32_e32 v84, v84
	v_cndmask_b32_e64 v90, v85, v88, s[36:37]
	v_cndmask_b32_e64 v85, v85, v88, s[4:5]
	v_readlane_b32 s4, v251, 55
	v_mul_f32_e32 v84, v90, v84
	v_sub_u32_e32 v90, 0, v89
	v_max_i32_e32 v89, v89, v90
	v_cvt_f32_u32_e32 v88, v89
	v_exp_f32_e32 v83, v83
	v_exp_f32_e32 v84, v84
	s_mov_b32 s0, s4
	v_mul_f32_e32 v85, v85, v88
	v_exp_f32_e32 v85, v85
	s_cmp_lg_u64 s[0:1], 0
	s_cselect_b32 s0, 0x8000, -1
	v_add_u32_e32 v127, s0, v110
	v_mul_f32_e32 v44, v82, v44
	v_mul_f32_e32 v45, v83, v45
	v_mul_f32_e32 v46, v84, v46
	v_mul_f32_e32 v47, v85, v47
	v_add_u32_e32 v66, v118, v127
	v_lshlrev_b32_e32 v120, 4, v28
	v_cvt_pk_bf16_f32 v40, v16, v17
	v_cvt_pk_bf16_f32 v41, v18, v19
	v_cvt_pk_bf16_f32 v42, v20, v21
	v_cvt_pk_bf16_f32 v43, v22, v23
	v_cvt_pk_bf16_f32 v20, v32, v33
	v_cvt_pk_bf16_f32 v21, v34, v35
	v_cvt_pk_bf16_f32 v22, v36, v37
	v_cvt_pk_bf16_f32 v23, v38, v39
	v_cvt_pk_bf16_f32 v16, v48, v49
	v_cvt_pk_bf16_f32 v17, v50, v51
	v_cvt_pk_bf16_f32 v18, v44, v45
	v_cvt_pk_bf16_f32 v19, v46, v47
	v_add_u32_e32 v72, v119, v66
	v_add_u32_e32 v73, v120, v66
	ds_read_b64 v[60:61], v72
	ds_read_b64 v[56:57], v72 offset:4096
	ds_read_b64 v[52:53], v72 offset:8192
	ds_read_b64 v[48:49], v72 offset:12288
	ds_read_b64 v[44:45], v72 offset:16384
	ds_read_b64 v[36:37], v72 offset:20480
	ds_read_b64 v[32:33], v72 offset:24576
	ds_read_b64 v[28:29], v72 offset:28672
	ds_read_b64 v[62:63], v73
	ds_read_b64 v[58:59], v73 offset:4096
	ds_read_b64 v[54:55], v73 offset:8192
	ds_read_b64 v[50:51], v73 offset:12288
	ds_read_b64 v[46:47], v73 offset:16384
	ds_read_b64 v[38:39], v73 offset:20480
	ds_read_b64 v[34:35], v73 offset:24576
	ds_read_b64 v[30:31], v73 offset:28672
	s_waitcnt lgkmcnt(0)
	v_bitop3_b32 v72, v67, v65, 4 bitop3:0x36
	v_mfma_f32_16x16x32_bf16 v[60:63], v[60:63], v[40:43], 0
	v_lshlrev_b32_e32 v121, 4, v72
	v_bitop3_b32 v72, v67, v65, 6 bitop3:0x36
	v_lshlrev_b32_e32 v122, 4, v72
	v_mfma_f32_16x16x32_bf16 v[56:59], v[56:59], v[40:43], 0
	v_add_u32_e32 v114, v121, v66
	v_add_u32_e32 v115, v122, v66
	ds_read_b64 v[104:105], v114
	ds_read_b64 v[100:101], v114 offset:4096
	ds_read_b64 v[92:93], v114 offset:8192
	ds_read_b64 v[88:89], v114 offset:12288
	ds_read_b64 v[84:85], v114 offset:16384
	ds_read_b64 v[80:81], v114 offset:20480
	ds_read_b64 v[76:77], v114 offset:24576
	ds_read_b64 v[72:73], v114 offset:28672
	ds_read_b64 v[106:107], v115
	ds_read_b64 v[102:103], v115 offset:4096
	ds_read_b64 v[94:95], v115 offset:8192
	ds_read_b64 v[90:91], v115 offset:12288
	ds_read_b64 v[86:87], v115 offset:16384
	ds_read_b64 v[82:83], v115 offset:20480
	ds_read_b64 v[78:79], v115 offset:24576
	ds_read_b64 v[74:75], v115 offset:28672
	s_waitcnt lgkmcnt(0)
; #define MFMA(a, b, c) __builtin_amdgcn_mfma_f32_16x16x32_bf16((a), (b), (c), 0, 0, 0)
; template <class F>
; DEV void dma_rows256(F rowptr, int nrows, char* lds) {
;   const int lane = tid_() & 63, wid = tid_() >> 6;
;   for (int blk = wid; blk < (nrows >> 2); blk += 4) {
;     const int row = blk * 4 + (lane >> 4);
;     const int c = (lane & 15) ^ (row & 15);
;     const u16* src = rowptr(row) + c * 8;
; DEV void ro_pv(const char* buf, const bf16x8 (&pf)[4], f32x4 (&oT)[8], int l15, int q) {
; #pragma unroll
;   for (int d = 0; d < 8; ++d) oT[d] = f32x4{0.f, 0.f, 0.f, 0.f};
;   const unsigned base = lds_off(buf) + (unsigned)(l15 * 256 + (q & 1) * 8);
; #pragma unroll
;   for (int j2 = 0; j2 < 4; ++j2) {
;     const unsigned a0 = base + (unsigned)((((j2 * 4 + (q >> 1)) ^ l15) & 15) << 4);
;     const unsigned a1 = base + (unsigned)((((j2 * 4 + (q >> 1) + 2) ^ l15) & 15) << 4);
;     u32x2 v0[8], v1[8];
;     asm volatile(
;         "ds_read_b64 %0, %16\n\t"
;         "ds_read_b64 %1, %16 offset:4096\n\t"
;         "ds_read_b64 %2, %16 offset:8192\n\t"
;         "ds_read_b64 %3, %16 offset:12288\n\t"
;         "ds_read_b64 %4, %16 offset:16384\n\t"
;         "ds_read_b64 %5, %16 offset:20480\n\t"
;         "ds_read_b64 %6, %16 offset:24576\n\t"
;         "ds_read_b64 %7, %16 offset:28672\n\t"
;         "ds_read_b64 %8, %17\n\t"
;         "ds_read_b64 %9, %17 offset:4096\n\t"
;         "ds_read_b64 %10, %17 offset:8192\n\t"
;         "ds_read_b64 %11, %17 offset:12288\n\t"
;         "ds_read_b64 %12, %17 offset:16384\n\t"
;         "ds_read_b64 %13, %17 offset:20480\n\t"
;         "ds_read_b64 %14, %17 offset:24576\n\t"
;         "ds_read_b64 %15, %17 offset:28672\n\t"
;         "s_waitcnt lgkmcnt(0)"
;         : "=&v"(v0[0]), "=&v"(v0[1]), "=&v"(v0[2]), "=&v"(v0[3]), "=&v"(v0[4]), "=&v"(v0[5]), "=&v"(v0[6]), "=&v"(v0[7]),
;           "=&v"(v1[0]), "=&v"(v1[1]), "=&v"(v1[2]), "=&v"(v1[3]), "=&v"(v1[4]), "=&v"(v1[5]), "=&v"(v1[6]), "=&v"(v1[7])
;         : "v"(a0), "v"(a1)
;         : "memory");
; #pragma unroll
;     for (int dvt = 0; dvt < 8; ++dvt) {
;       u32x4 vv = {v0[dvt].x, v0[dvt].y, v1[dvt].x, v1[dvt].y};
;       oT[dvt] = MFMA(__builtin_bit_cast(bf16x8, vv), pf[j2], oT[dvt]);
;     }
;   }
; __device__ __forceinline__ void ret_out_item(PREF P, int w, const u16* ST, char* smem) {
;     ...
;   RO_WAIT_SYNC();
;   RO_DMA_R(Y, 1, 0);
	v_mfma_f32_16x16x32_bf16 v[52:55], v[52:55], v[40:43], 0
	v_readlane_b32 s5, v251, 56
	v_writelane_b32 v251, s4, 55
	v_mfma_f32_16x16x32_bf16 v[48:51], v[48:51], v[40:43], 0
	s_nop 0
	v_writelane_b32 v251, s5, 56
	v_mfma_f32_16x16x32_bf16 v[44:47], v[44:47], v[40:43], 0
	v_mfma_f32_16x16x32_bf16 v[36:39], v[36:39], v[40:43], 0
	v_mfma_f32_16x16x32_bf16 v[32:35], v[32:35], v[40:43], 0
	v_mfma_f32_16x16x32_bf16 v[28:31], v[28:31], v[40:43], 0
	v_mfma_f32_16x16x32_bf16 v[60:63], v[104:107], v[24:27], v[60:63]
	v_mfma_f32_16x16x32_bf16 v[56:59], v[100:103], v[24:27], v[56:59]
	v_mfma_f32_16x16x32_bf16 v[52:55], v[92:95], v[24:27], v[52:55]
	v_mfma_f32_16x16x32_bf16 v[48:51], v[88:91], v[24:27], v[48:51]
	v_mfma_f32_16x16x32_bf16 v[44:47], v[84:87], v[24:27], v[44:47]
	v_mfma_f32_16x16x32_bf16 v[36:39], v[80:83], v[24:27], v[36:39]
	v_mfma_f32_16x16x32_bf16 v[32:35], v[76:79], v[24:27], v[32:35]
	v_mfma_f32_16x16x32_bf16 v[28:31], v[72:75], v[24:27], v[28:31]
	v_bitop3_b32 v72, v67, v65, 8 bitop3:0x36
	v_lshlrev_b32_e32 v123, 4, v72
	v_bitop3_b32 v72, v67, v65, 10 bitop3:0x36
	v_lshlrev_b32_e32 v124, 4, v72
	v_add_u32_e32 v114, v123, v66
	v_add_u32_e32 v115, v124, v66
	ds_read_b64 v[104:105], v114
	ds_read_b64 v[100:101], v114 offset:4096
	ds_read_b64 v[92:93], v114 offset:8192
	ds_read_b64 v[88:89], v114 offset:12288
	ds_read_b64 v[84:85], v114 offset:16384
	ds_read_b64 v[80:81], v114 offset:20480
	ds_read_b64 v[76:77], v114 offset:24576
	ds_read_b64 v[72:73], v114 offset:28672
	ds_read_b64 v[106:107], v115
	ds_read_b64 v[102:103], v115 offset:4096
	ds_read_b64 v[94:95], v115 offset:8192
	ds_read_b64 v[90:91], v115 offset:12288
	ds_read_b64 v[86:87], v115 offset:16384
	ds_read_b64 v[82:83], v115 offset:20480
	ds_read_b64 v[78:79], v115 offset:24576
	ds_read_b64 v[74:75], v115 offset:28672
	s_waitcnt lgkmcnt(0)
	s_nop 0
	v_mfma_f32_16x16x32_bf16 v[60:63], v[104:107], v[20:23], v[60:63]
	v_mfma_f32_16x16x32_bf16 v[56:59], v[100:103], v[20:23], v[56:59]
	v_mfma_f32_16x16x32_bf16 v[52:55], v[92:95], v[20:23], v[52:55]
	v_mfma_f32_16x16x32_bf16 v[48:51], v[88:91], v[20:23], v[48:51]
	v_mfma_f32_16x16x32_bf16 v[84:87], v[84:87], v[20:23], v[44:47]
	v_mfma_f32_16x16x32_bf16 v[80:83], v[80:83], v[20:23], v[36:39]
	v_mfma_f32_16x16x32_bf16 v[76:79], v[76:79], v[20:23], v[32:35]
	v_mfma_f32_16x16x32_bf16 v[72:75], v[72:75], v[20:23], v[28:31]
	s_nop 2
	v_bitop3_b32 v28, v67, v65, 12 bitop3:0x36
	v_lshlrev_b32_e32 v125, 4, v28
	v_bitop3_b32 v28, v67, v65, 14 bitop3:0x36
	v_lshlrev_b32_e32 v126, 4, v28
	v_add_u32_e32 v114, v125, v66
	v_add_u32_e32 v65, v126, v66
	ds_read_b64 v[28:29], v114
	ds_read_b64 v[32:33], v114 offset:4096
	ds_read_b64 v[36:37], v114 offset:8192
	ds_read_b64 v[44:45], v114 offset:12288
	ds_read_b64 v[104:105], v114 offset:16384
	ds_read_b64 v[100:101], v114 offset:20480
	ds_read_b64 v[92:93], v114 offset:24576
	ds_read_b64 v[88:89], v114 offset:28672
	ds_read_b64 v[30:31], v65
	ds_read_b64 v[34:35], v65 offset:4096
	ds_read_b64 v[38:39], v65 offset:8192
	ds_read_b64 v[46:47], v65 offset:12288
	ds_read_b64 v[106:107], v65 offset:16384
	ds_read_b64 v[102:103], v65 offset:20480
	ds_read_b64 v[94:95], v65 offset:24576
	ds_read_b64 v[90:91], v65 offset:28672
	s_waitcnt lgkmcnt(0)
	v_mov_b32_e32 v65, v188
	v_mfma_f32_16x16x32_bf16 v[28:31], v[28:31], v[16:19], v[60:63]
	v_mov_b32_e32 v66, v188
	v_mfma_f32_16x16x32_bf16 v[32:35], v[32:35], v[16:19], v[56:59]
	v_mfma_f32_16x16x32_bf16 v[36:39], v[36:39], v[16:19], v[52:55]
	v_mfma_f32_16x16x32_bf16 v[44:47], v[44:47], v[16:19], v[48:51]
	v_mfma_f32_16x16x32_bf16 v[48:51], v[104:107], v[16:19], v[84:87]
	v_mfma_f32_16x16x32_bf16 v[52:55], v[100:103], v[16:19], v[80:83]
	v_mfma_f32_16x16x32_bf16 v[56:59], v[92:95], v[16:19], v[76:79]
	v_mfma_f32_16x16x32_bf16 v[60:63], v[88:91], v[16:19], v[72:75]
	s_waitcnt vmcnt(0)
	s_waitcnt vmcnt(0) lgkmcnt(0)
	s_barrier
	s_nop 0
	v_ashrrev_i32_e32 v66, 6, v66
	v_cmp_gt_i32_e32 vcc, 32, v66
	s_and_saveexec_b64 s[0:1], vcc
	s_mov_b64 s[18:19], 0x1000
	v_readlane_b32 s58, v251, 63
	v_readlane_b32 s59, v250, 0
	s_cbranch_execz .LBB0_340
	v_and_b32_e32 v67, 63, v65
	v_bfe_u32 v72, v65, 4, 2
	v_lshlrev_b32_e32 v67, 4, v67
	v_readlane_b32 s4, v250, 3
	v_add_u32_e32 v74, -4, v66
	v_lshl_or_b32 v67, v66, 10, v67
	s_add_i32 s4, s4, s6
	v_lshl_or_b32 v66, v66, 2, v72
	v_add_u32_e32 v75, 0x8000, v67
	s_ashr_i32 s5, s4, 31
	v_ashrrev_i32_e32 v67, 31, v66
	s_lshl_b64 s[4:5], s[4:5], 16
	v_lshlrev_b64 v[72:73], 8, v[66:67]
	v_lshl_add_u64 v[72:73], s[4:5], 0, v[72:73]
	v_lshl_add_u64 v[72:73], v[96:97], 0, v[72:73]
	s_mov_b64 s[4:5], 0

; #define MFMA(a, b, c) __builtin_amdgcn_mfma_f32_16x16x32_bf16((a), (b), (c), 0, 0, 0)
; DEV float bflo(unsigned u) { return __uint_as_float(u << 16); }
; DEV float bfhi(unsigned u) { return __uint_as_float(u & 0xffff0000u); }
; DEV unsigned lds_off(const char* p) { return (unsigned)(unsigned long)((__attribute__((address_space(3))) const char*)p); }
; DEV void ro_cross(const char* buf, float xi, const bf16x8 (&qf)[4], f32x4 (&oT)[8], int l15, int q) {
;   const unsigned base = lds_off(buf) + (unsigned)(l15 * 256);
; #pragma unroll
;   for (int kd = 0; kd < 4; ++kd) {
;     u32x4 raw = __builtin_bit_cast(u32x4, qf[kd]);
;     u32x4 o;
;     o.x = pack2(bflo(raw.x) * xi, bfhi(raw.x) * xi);
;     o.y = pack2(bflo(raw.y) * xi, bfhi(raw.y) * xi);
;     o.z = pack2(bflo(raw.z) * xi, bfhi(raw.z) * xi);
;     o.w = pack2(bflo(raw.w) * xi, bfhi(raw.w) * xi);
;     bf16x8 qs = __builtin_bit_cast(bf16x8, o);
;     const unsigned a0 = base + (unsigned)((((kd * 4 + q) ^ l15) & 15) << 4);
;     bf16x8 ra[8];
;     asm volatile(
;         "ds_read_b128 %0, %8\n\t"
;         "ds_read_b128 %1, %8 offset:4096\n\t"
;         "ds_read_b128 %2, %8 offset:8192\n\t"
;         "ds_read_b128 %3, %8 offset:12288\n\t"
;         "ds_read_b128 %4, %8 offset:16384\n\t"
;         "ds_read_b128 %5, %8 offset:20480\n\t"
;         "ds_read_b128 %6, %8 offset:24576\n\t"
;         "ds_read_b128 %7, %8 offset:28672\n\t"
;         "s_waitcnt lgkmcnt(0)"
;         : "=&v"(ra[0]), "=&v"(ra[1]), "=&v"(ra[2]), "=&v"(ra[3]), "=&v"(ra[4]), "=&v"(ra[5]), "=&v"(ra[6]), "=&v"(ra[7])
;         : "v"(a0)
;         : "memory");
; #pragma unroll
;     for (int dvt = 0; dvt < 8; ++dvt) oT[dvt] = MFMA(ra[dvt], qs, oT[dvt]);
;   }
.LBB0_340:
	s_or_b64 exec, exec, s[0:1]
	v_lshlrev_b32_e32 v72, 16, v12
	v_and_b32_e32 v73, 0xffff0000, v12
	v_mul_f32_e32 v66, v64, v72
	v_mul_f32_e32 v67, v64, v73
	v_lshlrev_b32_e32 v74, 16, v13
	v_and_b32_e32 v75, 0xffff0000, v13
	v_cvt_pk_bf16_f32 v12, v66, v67
	v_mul_f32_e32 v66, v64, v74
	v_mul_f32_e32 v67, v64, v75
	v_lshlrev_b32_e32 v76, 16, v14
	v_and_b32_e32 v77, 0xffff0000, v14
	v_cvt_pk_bf16_f32 v13, v66, v67
	v_mul_f32_e32 v66, v64, v76
	v_mul_f32_e32 v67, v64, v77
	v_lshlrev_b32_e32 v78, 16, v15
	v_and_b32_e32 v79, 0xffff0000, v15
	v_cvt_pk_bf16_f32 v14, v66, v67
	v_mul_f32_e32 v66, v64, v78
	v_mul_f32_e32 v67, v64, v79
	v_cvt_pk_bf16_f32 v15, v66, v67
	v_add_u32_e32 v117, v113, v110
	ds_read_b128 v[80:83], v117
	ds_read_b128 v[84:87], v117 offset:4096
	ds_read_b128 v[88:91], v117 offset:8192
	ds_read_b128 v[92:95], v117 offset:12288
	ds_read_b128 v[100:103], v117 offset:16384
	ds_read_b128 v[104:107], v117 offset:20480
	ds_read_b128 v[128:131], v117 offset:24576
	ds_read_b128 v[132:135], v117 offset:28672
	s_waitcnt lgkmcnt(0)
	v_add_u32_e32 v115, v111, v110
	v_mfma_f32_16x16x32_bf16 v[28:31], v[80:83], v[12:15], v[28:31]
	v_lshlrev_b32_e32 v80, 16, v8
	v_and_b32_e32 v81, 0xffff0000, v8
	v_lshlrev_b32_e32 v82, 16, v9
	v_and_b32_e32 v83, 0xffff0000, v9
	v_mfma_f32_16x16x32_bf16 v[32:35], v[84:87], v[12:15], v[32:35]
	v_mul_f32_e64 v8, v64, v82
	v_mul_f32_e64 v9, v64, v83
	v_lshlrev_b32_e32 v84, 16, v10
	v_and_b32_e32 v85, 0xffff0000, v10
	v_mfma_f32_16x16x32_bf16 v[36:39], v[88:91], v[12:15], v[36:39]
	v_lshlrev_b32_e32 v86, 16, v11
	v_and_b32_e32 v87, 0xffff0000, v11
	v_add_u32_e32 v114, v112, v110
	v_mfma_f32_16x16x32_bf16 v[88:91], v[92:95], v[12:15], v[44:47]
	v_add_u32_e32 v116, v71, v110
	v_readlane_b32 s44, v250, 2
	s_nop 0
	v_mul_f32_e32 v44, v64, v80
	v_mul_f32_e32 v45, v64, v81
	v_cvt_pk_bf16_f32 v44, v44, v45
	v_cvt_pk_bf16_f32 v45, v8, v9
	v_mul_f32_e32 v8, v64, v84
	v_mul_f32_e32 v9, v64, v85
	v_cvt_pk_bf16_f32 v46, v8, v9
	v_mul_f32_e32 v8, v64, v86
	v_mul_f32_e32 v9, v64, v87
	v_mfma_f32_16x16x32_bf16 v[48:51], v[100:103], v[12:15], v[48:51]
	v_cvt_pk_bf16_f32 v47, v8, v9
	v_mfma_f32_16x16x32_bf16 v[52:55], v[104:107], v[12:15], v[52:55]
	v_mfma_f32_16x16x32_bf16 v[56:59], v[128:131], v[12:15], v[56:59]
	v_mfma_f32_16x16x32_bf16 v[60:63], v[132:135], v[12:15], v[60:63]
	ds_read_b128 v[8:11], v115
	ds_read_b128 v[92:95], v115 offset:4096
	ds_read_b128 v[100:103], v115 offset:8192
	ds_read_b128 v[104:107], v115 offset:12288
	ds_read_b128 v[128:131], v115 offset:16384
	ds_read_b128 v[132:135], v115 offset:20480
	ds_read_b128 v[136:139], v115 offset:24576
	ds_read_b128 v[140:143], v115 offset:28672
	s_waitcnt lgkmcnt(0)
	s_nop 0
	v_mfma_f32_16x16x32_bf16 v[8:11], v[8:11], v[44:47], v[28:31]
	v_mfma_f32_16x16x32_bf16 v[28:31], v[92:95], v[44:47], v[32:35]
	v_lshlrev_b32_e32 v92, 16, v6
	v_and_b32_e32 v93, 0xffff0000, v6
	v_lshlrev_b32_e32 v94, 16, v7
	v_mfma_f32_16x16x32_bf16 v[32:35], v[100:103], v[44:47], v[36:39]
	v_and_b32_e32 v95, 0xffff0000, v7
	v_mfma_f32_16x16x32_bf16 v[36:39], v[104:107], v[44:47], v[88:91]
	s_nop 2
	v_lshlrev_b32_e32 v88, 16, v4
	v_and_b32_e32 v89, 0xffff0000, v4
	v_mul_f32_e32 v66, v64, v88
	v_mul_f32_e32 v67, v64, v89
	v_lshlrev_b32_e32 v90, 16, v5
	v_and_b32_e32 v91, 0xffff0000, v5
	v_cvt_pk_bf16_f32 v4, v66, v67
	v_mul_f32_e32 v66, v64, v90
	v_mul_f32_e32 v67, v64, v91
	v_mfma_f32_16x16x32_bf16 v[48:51], v[128:131], v[44:47], v[48:51]
	v_cvt_pk_bf16_f32 v5, v66, v67
	v_mul_f32_e32 v66, v64, v92
	v_mul_f32_e32 v67, v64, v93
	v_cvt_pk_bf16_f32 v6, v66, v67
	v_mfma_f32_16x16x32_bf16 v[52:55], v[132:135], v[44:47], v[52:55]
	v_mul_f32_e64 v66, v64, v94
	v_mul_f32_e64 v67, v64, v95
	v_cvt_pk_bf16_f32 v7, v66, v67
	v_mfma_f32_16x16x32_bf16 v[56:59], v[136:139], v[44:47], v[56:59]
	v_mfma_f32_16x16x32_bf16 v[60:63], v[140:143], v[44:47], v[60:63]
	ds_read_b128 v[100:103], v114
	ds_read_b128 v[104:107], v114 offset:4096
	ds_read_b128 v[128:131], v114 offset:8192
	ds_read_b128 v[132:135], v114 offset:12288
	ds_read_b128 v[136:139], v114 offset:16384
	ds_read_b128 v[140:143], v114 offset:20480
	ds_read_b128 v[144:147], v114 offset:24576
	ds_read_b128 v[148:151], v114 offset:28672
	s_waitcnt lgkmcnt(0)
	s_nop 0
	v_mfma_f32_16x16x32_bf16 v[8:11], v[100:103], v[4:7], v[8:11]
	v_lshlrev_b32_e32 v100, 16, v0
	v_and_b32_e32 v101, 0xffff0000, v0
	v_lshlrev_b32_e32 v102, 16, v1
	v_mfma_f32_16x16x32_bf16 v[32:35], v[128:131], v[4:7], v[32:35]
	v_and_b32_e32 v103, 0xffff0000, v1
	v_mfma_f32_16x16x32_bf16 v[128:131], v[136:139], v[4:7], v[48:51]
	s_nop 2
	v_mul_f32_e64 v48, v64, v100
	v_mul_f32_e64 v49, v64, v101
	v_mfma_f32_16x16x32_bf16 v[28:31], v[104:107], v[4:7], v[28:31]
	v_cvt_pk_bf16_f32 v0, v48, v49
	v_mul_f32_e32 v48, v64, v102
	v_mul_f32_e32 v49, v64, v103
	v_lshlrev_b32_e32 v104, 16, v2
	v_mfma_f32_16x16x32_bf16 v[36:39], v[132:135], v[4:7], v[36:39]
	v_and_b32_e32 v105, 0xffff0000, v2
	v_cvt_pk_bf16_f32 v1, v48, v49
	v_mul_f32_e32 v48, v64, v104
	v_mul_f32_e32 v49, v64, v105
	v_mfma_f32_16x16x32_bf16 v[132:135], v[140:143], v[4:7], v[52:55]
	v_lshlrev_b32_e32 v106, 16, v3
	v_and_b32_e32 v107, 0xffff0000, v3
	v_cvt_pk_bf16_f32 v2, v48, v49
	v_mfma_f32_16x16x32_bf16 v[136:139], v[144:147], v[4:7], v[56:59]
	v_mul_f32_e64 v48, v64, v106
	v_mul_f32_e64 v49, v64, v107
	v_cvt_pk_bf16_f32 v3, v48, v49
	v_mfma_f32_16x16x32_bf16 v[140:143], v[148:151], v[4:7], v[60:63]
	ds_read_b128 v[48:51], v116
	ds_read_b128 v[52:55], v116 offset:4096
	ds_read_b128 v[56:59], v116 offset:8192
	ds_read_b128 v[60:63], v116 offset:12288
	ds_read_b128 v[64:67], v116 offset:16384
	ds_read_b128 v[144:147], v116 offset:20480
	ds_read_b128 v[148:151], v116 offset:24576
	ds_read_b128 v[152:155], v116 offset:28672
	s_waitcnt lgkmcnt(0)
	s_nop 0
	v_mfma_f32_16x16x32_bf16 v[8:11], v[48:51], v[0:3], v[8:11]
	v_mfma_f32_16x16x32_bf16 v[28:31], v[52:55], v[0:3], v[28:31]
	v_mfma_f32_16x16x32_bf16 v[32:35], v[56:59], v[0:3], v[32:35]
	v_mfma_f32_16x16x32_bf16 v[48:51], v[60:63], v[0:3], v[36:39]
	v_mfma_f32_16x16x32_bf16 v[52:55], v[64:67], v[0:3], v[128:131]
	s_nop 1
	v_mov_b32_e32 v38, v188
	v_mov_b32_e32 v36, v188
	v_mfma_f32_16x16x32_bf16 v[56:59], v[144:147], v[0:3], v[132:135]
	v_mfma_f32_16x16x32_bf16 v[60:63], v[148:151], v[0:3], v[136:139]
	v_mfma_f32_16x16x32_bf16 v[64:67], v[152:155], v[0:3], v[140:143]
	s_waitcnt vmcnt(0)
	s_waitcnt vmcnt(0) lgkmcnt(0)
	s_barrier
; DEV int tid_() { int t = threadIdx.x; asm volatile("" : "+v"(t)); return t; }
; #define RO_DMA_V(d, hf) dma_rows256([&](int row) { return vbase + (size_t)((hf) * 128 + row) * TS; }, 128, d)
; template <class F>
; DEV void dma_rows256(F rowptr, int nrows, char* lds) {
;   const int lane = tid_() & 63, wid = tid_() >> 6;
;   for (int blk = wid; blk < (nrows >> 2); blk += 4) {
;     const int row = blk * 4 + (lane >> 4);
;     const int c = (lane & 15) ^ (row & 15);
;     const u16* src = rowptr(row) + c * 8;
;     __builtin_amdgcn_global_load_lds((const unsigned*)src, (unsigned*)(lds + blk * 1024 + lane * 16), 16, 0, 0);
;   }
; __device__ __forceinline__ void ret_out_item(PREF P, int w, const u16* ST, char* smem) {
;     ...
;   RO_DMA_V(X, 1);
	s_nop 0
	v_ashrrev_i32_e32 v36, 6, v36
	v_cmp_gt_i32_e32 vcc, 32, v36
	s_and_saveexec_b64 s[0:1], vcc
	s_movk_i32 s31, 0x70
	s_mov_b64 s[16:17], 0x40000
	s_cbranch_execz .LBB0_343
	v_and_b32_e32 v37, 63, v38
	v_bfe_u32 v129, v38, 4, 2
	v_lshlrev_b32_e32 v37, 4, v37
	v_lshl_or_b32 v129, v36, 2, v129
	v_add_u32_e32 v39, -4, v36
	v_lshl_or_b32 v128, v36, 10, v37
	v_add_u32_e32 v36, 0x80, v129
	s_lshl_b64 s[4:5], s[14:15], 1
	v_readlane_b32 s14, v250, 1
	v_ashrrev_i32_e32 v37, 31, v36
	s_add_u32 s4, s4, s14
	v_lshlrev_b64 v[36:37], 14, v[36:37]
	s_addc_u32 s5, s5, 0
	v_lshl_add_u64 v[36:37], s[4:5], 0, v[36:37]
	v_lshl_add_u64 v[36:37], v[68:69], 0, v[36:37]
	s_mov_b64 s[4:5], 0

; #define MFMA(a, b, c) __builtin_amdgcn_mfma_f32_16x16x32_bf16((a), (b), (c), 0, 0, 0)
; DEV float bflo(unsigned u) { return __uint_as_float(u << 16); }
; DEV float bfhi(unsigned u) { return __uint_as_float(u & 0xffff0000u); }
; DEV unsigned lds_off(const char* p) { return (unsigned)(unsigned long)((__attribute__((address_space(3))) const char*)p); }
; #define RO_WAIT_SYNC() do { asm volatile("s_waitcnt vmcnt(0)" : "+v"(oT[0]), "+v"(oT[1]), "+v"(oT[2]), "+v"(oT[3]), \
;     "+v"(oT[4]), "+v"(oT[5]), "+v"(oT[6]), "+v"(oT[7]) : : "memory"); __syncthreads(); } while (0)
; DEV void ro_cross(const char* buf, float xi, const bf16x8 (&qf)[4], f32x4 (&oT)[8], int l15, int q) {
;   const unsigned base = lds_off(buf) + (unsigned)(l15 * 256);
; #pragma unroll
;   for (int kd = 0; kd < 4; ++kd) {
;     u32x4 raw = __builtin_bit_cast(u32x4, qf[kd]);
;     u32x4 o;
;     o.x = pack2(bflo(raw.x) * xi, bfhi(raw.x) * xi);
;     o.y = pack2(bflo(raw.y) * xi, bfhi(raw.y) * xi);
;     o.z = pack2(bflo(raw.z) * xi, bfhi(raw.z) * xi);
;     o.w = pack2(bflo(raw.w) * xi, bfhi(raw.w) * xi);
;     bf16x8 qs = __builtin_bit_cast(bf16x8, o);
;     const unsigned a0 = base + (unsigned)((((kd * 4 + q) ^ l15) & 15) << 4);
;     bf16x8 ra[8];
;     asm volatile(
;         "ds_read_b128 %0, %8\n\t"
;         "ds_read_b128 %1, %8 offset:4096\n\t"
;         "ds_read_b128 %2, %8 offset:8192\n\t"
;         "ds_read_b128 %3, %8 offset:12288\n\t"
;         "ds_read_b128 %4, %8 offset:16384\n\t"
;         "ds_read_b128 %5, %8 offset:20480\n\t"
;         "ds_read_b128 %6, %8 offset:24576\n\t"
;         "ds_read_b128 %7, %8 offset:28672\n\t"
;         "s_waitcnt lgkmcnt(0)"
;         : "=&v"(ra[0]), "=&v"(ra[1]), "=&v"(ra[2]), "=&v"(ra[3]), "=&v"(ra[4]), "=&v"(ra[5]), "=&v"(ra[6]), "=&v"(ra[7])
;         : "v"(a0)
;         : "memory");
; #pragma unroll
;     for (int dvt = 0; dvt < 8; ++dvt) oT[dvt] = MFMA(ra[dvt], qs, oT[dvt]);
;   }
; __device__ __forceinline__ void ret_out_item(PREF P, int w, const u16* ST, char* smem) {
;     ...
; #pragma unroll
;   for (int d = 0; d < 8; ++d) {
; #pragma unroll
;     for (int r = 0; r < 4; ++r) { float v = oT[d][r]; ssum += v; ssq += v * v; }
;     park[d].x = pack2(oT[d][0], oT[d][1]);
;     park[d].y = pack2(oT[d][2], oT[d][3]);
;   }
;   RO_WAIT_SYNC();
;   RO_DMA_R(Y, 0, 1);
.LBB0_343:
	s_mov_b64 s[60:61], 0x40000
	s_or_b64 exec, exec, s[0:1]
	v_mul_f32_e32 v36, v70, v72
	v_mul_f32_e32 v37, v70, v73
	v_mul_f32_e32 v38, v70, v74
	v_mul_f32_e32 v39, v70, v75
	v_cvt_pk_bf16_f32 v36, v36, v37
	v_cvt_pk_bf16_f32 v37, v38, v39
	v_mul_f32_e32 v38, v70, v76
	v_mul_f32_e32 v39, v70, v77
	v_mul_f32_e32 v68, v70, v78
	v_mul_f32_e32 v69, v70, v79
	v_cvt_pk_bf16_f32 v38, v38, v39
	v_cvt_pk_bf16_f32 v39, v68, v69
	v_add_u32_e32 v113, v113, v127
	ds_read_b128 v[72:75], v113
	ds_read_b128 v[76:79], v113 offset:4096
	ds_read_b128 v[128:131], v113 offset:8192
	ds_read_b128 v[132:135], v113 offset:12288
	ds_read_b128 v[136:139], v113 offset:16384
	ds_read_b128 v[140:143], v113 offset:20480
	ds_read_b128 v[144:147], v113 offset:24576
	ds_read_b128 v[148:151], v113 offset:28672
	s_waitcnt lgkmcnt(0)
	v_mul_f32_e32 v68, v70, v86
	v_mul_f32_e32 v69, v70, v87
	v_mfma_f32_16x16x32_bf16 v[8:11], v[72:75], v[36:39], v[8:11]
	v_add_u32_e32 v111, v111, v127
	v_add_u32_e32 v112, v112, v127
	v_mfma_f32_16x16x32_bf16 v[28:31], v[76:79], v[36:39], v[28:31]
	v_mfma_f32_16x16x32_bf16 v[72:75], v[128:131], v[36:39], v[32:35]
	v_mfma_f32_16x16x32_bf16 v[48:51], v[132:135], v[36:39], v[48:51]
	s_nop 1
	v_mul_f32_e64 v32, v70, v80
	v_mul_f32_e64 v33, v70, v81
	v_mul_f32_e32 v34, v70, v82
	v_mul_f32_e32 v35, v70, v83
	v_cvt_pk_bf16_f32 v32, v32, v33
	v_mfma_f32_16x16x32_bf16 v[52:55], v[136:139], v[36:39], v[52:55]
	v_cvt_pk_bf16_f32 v33, v34, v35
	v_mul_f32_e32 v34, v70, v84
	v_mul_f32_e32 v35, v70, v85
	v_cvt_pk_bf16_f32 v34, v34, v35
	v_mfma_f32_16x16x32_bf16 v[56:59], v[140:143], v[36:39], v[56:59]
	v_cvt_pk_bf16_f32 v35, v68, v69
	v_mul_f32_e32 v68, v70, v94
	v_mul_f32_e32 v69, v70, v95
	v_mfma_f32_16x16x32_bf16 v[60:63], v[144:147], v[36:39], v[60:63]
	ds_read_b128 v[76:79], v111
	ds_read_b128 v[80:83], v111 offset:4096
	ds_read_b128 v[84:87], v111 offset:8192
	ds_read_b128 v[128:131], v111 offset:12288
	ds_read_b128 v[132:135], v111 offset:16384
	ds_read_b128 v[136:139], v111 offset:20480
	ds_read_b128 v[140:143], v111 offset:24576
	ds_read_b128 v[144:147], v111 offset:28672
	s_waitcnt lgkmcnt(0)
	v_mfma_f32_16x16x32_bf16 v[64:67], v[148:151], v[36:39], v[64:67]
	v_mfma_f32_16x16x32_bf16 v[76:79], v[76:79], v[32:35], v[8:11]
	v_mfma_f32_16x16x32_bf16 v[28:31], v[80:83], v[32:35], v[28:31]
	s_nop 1
	v_mul_f32_e64 v8, v70, v88
	v_mul_f32_e64 v9, v70, v89
	v_mul_f32_e32 v10, v70, v90
	v_mul_f32_e32 v11, v70, v91
	v_cvt_pk_bf16_f32 v8, v8, v9
	v_mfma_f32_16x16x32_bf16 v[72:75], v[84:87], v[32:35], v[72:75]
	v_cvt_pk_bf16_f32 v9, v10, v11
	v_mul_f32_e32 v10, v70, v92
	v_mul_f32_e32 v11, v70, v93
	v_cvt_pk_bf16_f32 v10, v10, v11
	v_mfma_f32_16x16x32_bf16 v[48:51], v[128:131], v[32:35], v[48:51]
	v_cvt_pk_bf16_f32 v11, v68, v69
	v_mfma_f32_16x16x32_bf16 v[52:55], v[132:135], v[32:35], v[52:55]
	v_mfma_f32_16x16x32_bf16 v[56:59], v[136:139], v[32:35], v[56:59]
	v_mfma_f32_16x16x32_bf16 v[60:63], v[140:143], v[32:35], v[60:63]
	ds_read_b128 v[80:83], v112
	ds_read_b128 v[84:87], v112 offset:4096
	ds_read_b128 v[88:91], v112 offset:8192
	ds_read_b128 v[92:95], v112 offset:12288
	ds_read_b128 v[128:131], v112 offset:16384
	ds_read_b128 v[132:135], v112 offset:20480
	ds_read_b128 v[136:139], v112 offset:24576
	ds_read_b128 v[140:143], v112 offset:28672
	s_waitcnt lgkmcnt(0)
	v_mfma_f32_16x16x32_bf16 v[64:67], v[144:147], v[32:35], v[64:67]
	v_mfma_f32_16x16x32_bf16 v[76:79], v[80:83], v[8:11], v[76:79]
	v_mfma_f32_16x16x32_bf16 v[80:83], v[84:87], v[8:11], v[28:31]
	v_mfma_f32_16x16x32_bf16 v[72:75], v[88:91], v[8:11], v[72:75]
	s_nop 1
	v_mul_f32_e64 v28, v70, v100
	v_mul_f32_e64 v29, v70, v101
	v_mul_f32_e32 v30, v70, v102
	v_mul_f32_e32 v31, v70, v103
	v_cvt_pk_bf16_f32 v28, v28, v29
	v_mfma_f32_16x16x32_bf16 v[48:51], v[92:95], v[8:11], v[48:51]
	v_cvt_pk_bf16_f32 v29, v30, v31
	v_mul_f32_e32 v30, v70, v104
	v_mul_f32_e32 v31, v70, v105
	v_cvt_pk_bf16_f32 v30, v30, v31
	v_mfma_f32_16x16x32_bf16 v[52:55], v[128:131], v[8:11], v[52:55]
	v_add_u32_e32 v102, v71, v127
	v_mfma_f32_16x16x32_bf16 v[56:59], v[132:135], v[8:11], v[56:59]
	v_mfma_f32_16x16x32_bf16 v[60:63], v[136:139], v[8:11], v[60:63]
	v_mfma_f32_16x16x32_bf16 v[84:87], v[140:143], v[8:11], v[64:67]
	s_nop 2
	v_mul_f32_e64 v64, v70, v106
	v_mul_f32_e64 v65, v70, v107
	v_cvt_pk_bf16_f32 v31, v64, v65
	ds_read_b128 v[64:67], v102
	ds_read_b128 v[68:71], v102 offset:4096
	ds_read_b128 v[88:91], v102 offset:8192
	ds_read_b128 v[92:95], v102 offset:12288
	ds_read_b128 v[104:107], v102 offset:16384
	ds_read_b128 v[128:131], v102 offset:20480
	ds_read_b128 v[132:135], v102 offset:24576
	ds_read_b128 v[136:139], v102 offset:28672
	s_waitcnt lgkmcnt(0)
	s_nop 1
	v_mfma_f32_16x16x32_bf16 v[64:67], v[64:67], v[28:31], v[76:79]
	v_mfma_f32_16x16x32_bf16 v[68:71], v[68:71], v[28:31], v[80:83]
	v_mfma_f32_16x16x32_bf16 v[72:75], v[88:91], v[28:31], v[72:75]
	v_mfma_f32_16x16x32_bf16 v[76:79], v[92:95], v[28:31], v[48:51]
	v_mfma_f32_16x16x32_bf16 v[80:83], v[104:107], v[28:31], v[52:55]
	s_nop 3
	v_mov_b64_e32 v[48:49], v[64:65]
	v_mov_b64_e32 v[106:107], v[70:71]
	v_mov_b64_e32 v[50:51], v[66:67]
	v_mfma_f32_16x16x32_bf16 v[88:91], v[136:139], v[28:31], v[84:87]
	v_mov_b64_e32 v[138:139], v[74:75]
	v_mov_b64_e32 v[104:105], v[68:69]
	v_mov_b64_e32 v[136:137], v[72:73]
	v_mfma_f32_16x16x32_bf16 v[84:87], v[128:131], v[28:31], v[56:59]
	v_mov_b64_e32 v[130:131], v[82:83]
	s_nop 2
	v_mov_b64_e32 v[52:53], v[88:89]
	v_mov_b64_e32 v[54:55], v[90:91]
	v_mfma_f32_16x16x32_bf16 v[92:95], v[132:135], v[28:31], v[60:63]
	v_mov_b64_e32 v[56:57], v[76:77]
	v_mov_b64_e32 v[142:143], v[86:87]
	v_mov_b64_e32 v[58:59], v[78:79]
	v_mov_b64_e32 v[128:129], v[80:81]
	v_mov_b64_e32 v[140:141], v[84:85]
	s_nop 2
	v_mov_b64_e32 v[60:61], v[92:93]
	v_mov_b64_e32 v[62:63], v[94:95]
	s_waitcnt vmcnt(0)
	s_waitcnt vmcnt(0) lgkmcnt(0)
	v_mov_b32_e32 v50, v188
	v_mov_b32_e32 v48, v188
	s_barrier
	s_nop 0
	v_ashrrev_i32_e32 v48, 6, v48
	v_cmp_gt_i32_e32 vcc, 32, v48
	s_and_saveexec_b64 s[0:1], vcc
	s_mov_b64 s[16:17], 0x1000
	s_cbranch_execz .LBB0_346
	v_and_b32_e32 v49, 63, v50
	v_bfe_u32 v53, v50, 4, 2
	v_lshlrev_b32_e32 v49, 4, v49
	v_readlane_b32 s4, v250, 3
	v_lshl_or_b32 v53, v48, 2, v53
	v_add_u32_e32 v51, -4, v48
	v_lshl_or_b32 v49, v48, 10, v49
	s_add_i32 s4, s4, s6
	v_add_u32_e32 v48, 0x80, v53
	v_add_u32_e32 v52, 0x8000, v49
	s_ashr_i32 s5, s4, 31
	v_ashrrev_i32_e32 v49, 31, v48
	s_lshl_b64 s[4:5], s[4:5], 16
	v_lshlrev_b64 v[48:49], 8, v[48:49]
	v_lshl_add_u64 v[48:49], s[4:5], 0, v[48:49]
	v_lshl_add_u64 v[48:49], v[184:185], 0, v[48:49]
	s_mov_b64 s[4:5], 0

; DEV f32x4 mma_step(bf16x8 a, bf16x8 b, f32x4 c) { return MFMA(a, b, c); }
; template <class FragT, class AccT>
; DEV void gemm_core_t(const char* __restrict__ A, size_t lda_bytes, const char* __restrict__ Bt, size_t ldb_bytes, int kbytes,
;                      int m0, int n0, int Sshift, int dl, char* smem, AccT (&acc)[4][4]) {
;     ...
;   for (int kt = 0; kt < nk; ++kt) {
;     const unsigned so = (unsigned)(kt & 1) * 32768u;
;     char* nxt = smem + ((kt + 1) & 1) * 32768;
;     if (kt + 1 < nk) {
; #pragma unroll
;       for (int u = 0; u < 4; ++u) {
;         __builtin_amdgcn_global_load_lds((const unsigned*)(ap[u] + (size_t)(kt + 1) * 128), (unsigned*)(nxt + (wid * 4 + u) * 1024 + lane * 16), 16, 0, 0);
;         __builtin_amdgcn_global_load_lds((const unsigned*)(bp[u] + (size_t)(kt + 1) * 128), (unsigned*)(nxt + 16384 + (wid * 4 + u) * 1024 + lane * 16), 16, 0, 0);
;       }
;     }
;     FragT xa[2][4], wb[2][4];
;     asm volatile(
;         "ds_read_b128 %0, %16\n\t"
;         "ds_read_b128 %1, %16 offset:2048\n\t"
;         "ds_read_b128 %2, %16 offset:4096\n\t"
;         "ds_read_b128 %3, %16 offset:6144\n\t"
;         "ds_read_b128 %4, %18\n\t"
;         "ds_read_b128 %5, %18 offset:2048\n\t"
;         "ds_read_b128 %6, %18 offset:8192\n\t"
;         "ds_read_b128 %7, %18 offset:10240\n\t"
;         "ds_read_b128 %8, %17\n\t"
;         "ds_read_b128 %9, %17 offset:2048\n\t"
;         "ds_read_b128 %10, %17 offset:4096\n\t"
;         "ds_read_b128 %11, %17 offset:6144\n\t"
;         "ds_read_b128 %12, %19\n\t"
;         "ds_read_b128 %13, %19 offset:2048\n\t"
;         "ds_read_b128 %14, %19 offset:8192\n\t"
;         "ds_read_b128 %15, %19 offset:10240\n\t"
;         "s_waitcnt lgkmcnt(8)"
;         : "=&v"(xa[0][0]), "=&v"(xa[0][1]), "=&v"(xa[0][2]), "=&v"(xa[0][3]), "=&v"(wb[0][0]), "=&v"(wb[0][1]), "=&v"(wb[0][2]),
;           "=&v"(wb[0][3]), "=&v"(xa[1][0]), "=&v"(xa[1][1]), "=&v"(xa[1][2]), "=&v"(xa[1][3]), "=&v"(wb[1][0]), "=&v"(wb[1][1]),
;           "=&v"(wb[1][2]), "=&v"(wb[1][3])
;         : "v"(a0 + so), "v"((a0 ^ 64u) + so), "v"(b0 + so), "v"((b0 ^ 64u) + so)
;         : "memory");
;     __builtin_amdgcn_s_setprio(1);
; #pragma unroll
;     for (int i = 0; i < 4; ++i)
; #pragma unroll
;       for (int j = 0; j < 4; ++j) acc[i][j] = mma_step(wb[0][j], xa[0][i], acc[i][j]);
;     asm volatile("s_waitcnt lgkmcnt(0)"
.LBB0_400:
	s_add_i32 s16, s6, 0xffff8000
	s_and_b32 s16, s16, 0x8000
	v_add_u32_e32 v85, s16, v81
	v_add_u32_e32 v90, s16, v84
	v_or_b32_e32 v91, s16, v82
	v_or_b32_e32 v95, s16, v83
	s_and_b32 s16, s6, 0x8000
	s_add_i32 s16, s16, s62
	s_mov_b32 m0, s16
	ds_read_b128 v[86:89], v85
	global_load_lds_dwordx4 v78, s[64:65]
	ds_read_b128 v[96:99], v85 offset:2048
	s_add_i32 m0, s16, 0x4000
	ds_read_b128 v[100:103], v85 offset:4096
	global_load_lds_dwordx4 v76, s[66:67]
	ds_read_b128 v[104:107], v85 offset:6144
	s_add_i32 m0, s16, 0x400
	ds_read_b128 v[108:111], v91
	global_load_lds_dwordx4 v74, s[64:65]
	ds_read_b128 v[112:115], v91 offset:2048
	s_add_i32 m0, s16, 0x4400
	ds_read_b128 v[116:119], v91 offset:8192
	global_load_lds_dwordx4 v72, s[66:67]
	ds_read_b128 v[120:123], v91 offset:10240
	ds_read_b128 v[124:127], v90
	ds_read_b128 v[128:131], v90 offset:2048
	ds_read_b128 v[132:135], v90 offset:4096
	ds_read_b128 v[136:139], v90 offset:6144
	ds_read_b128 v[140:143], v95
	ds_read_b128 v[144:147], v95 offset:2048
	ds_read_b128 v[148:151], v95 offset:8192
	ds_read_b128 v[152:155], v95 offset:10240
	s_waitcnt lgkmcnt(8)
	s_setprio 1
	v_mfma_f32_16x16x32_bf16 v[60:63], v[108:111], v[86:89], v[60:63]
	v_mfma_f32_16x16x32_bf16 v[56:59], v[112:115], v[86:89], v[56:59]
	s_add_i32 m0, s16, 0x800
	v_mfma_f32_16x16x32_bf16 v[52:55], v[116:119], v[86:89], v[52:55]
	global_load_lds_dwordx4 v70, s[64:65]
	v_mfma_f32_16x16x32_bf16 v[48:51], v[120:123], v[86:89], v[48:51]
	v_mfma_f32_16x16x32_bf16 v[44:47], v[108:111], v[96:99], v[44:47]
	v_mfma_f32_16x16x32_bf16 v[40:43], v[112:115], v[96:99], v[40:43]
	s_add_i32 m0, s16, 0x4800
	v_mfma_f32_16x16x32_bf16 v[36:39], v[116:119], v[96:99], v[36:39]
	global_load_lds_dwordx4 v68, s[66:67]
	v_mfma_f32_16x16x32_bf16 v[32:35], v[120:123], v[96:99], v[32:35]
	v_mfma_f32_16x16x32_bf16 v[28:31], v[108:111], v[100:103], v[28:31]
	v_mfma_f32_16x16x32_bf16 v[24:27], v[112:115], v[100:103], v[24:27]
	s_add_i32 m0, s16, 0xc00
	v_mfma_f32_16x16x32_bf16 v[20:23], v[116:119], v[100:103], v[20:23]
	global_load_lds_dwordx4 v66, s[64:65]
	v_mfma_f32_16x16x32_bf16 v[16:19], v[120:123], v[100:103], v[16:19]
	v_mfma_f32_16x16x32_bf16 v[12:15], v[108:111], v[104:107], v[12:15]
	v_mfma_f32_16x16x32_bf16 v[8:11], v[112:115], v[104:107], v[8:11]
	s_add_i32 m0, s16, 0x4c00
	v_mfma_f32_16x16x32_bf16 v[4:7], v[116:119], v[104:107], v[4:7]
	global_load_lds_dwordx4 v64, s[66:67]
	v_mfma_f32_16x16x32_bf16 v[0:3], v[120:123], v[104:107], v[0:3]
	s_waitcnt lgkmcnt(0)
	s_nop 0
	v_mfma_f32_16x16x32_bf16 v[60:63], v[140:143], v[124:127], v[60:63]
	v_mfma_f32_16x16x32_bf16 v[56:59], v[144:147], v[124:127], v[56:59]
	v_mfma_f32_16x16x32_bf16 v[52:55], v[148:151], v[124:127], v[52:55]
	v_mfma_f32_16x16x32_bf16 v[48:51], v[152:155], v[124:127], v[48:51]
	v_mfma_f32_16x16x32_bf16 v[44:47], v[140:143], v[128:131], v[44:47]
	v_mfma_f32_16x16x32_bf16 v[40:43], v[144:147], v[128:131], v[40:43]
	v_mfma_f32_16x16x32_bf16 v[36:39], v[148:151], v[128:131], v[36:39]
	v_mfma_f32_16x16x32_bf16 v[32:35], v[152:155], v[128:131], v[32:35]
	v_mfma_f32_16x16x32_bf16 v[28:31], v[140:143], v[132:135], v[28:31]
	v_mfma_f32_16x16x32_bf16 v[24:27], v[144:147], v[132:135], v[24:27]
	v_mfma_f32_16x16x32_bf16 v[20:23], v[148:151], v[132:135], v[20:23]
	v_mfma_f32_16x16x32_bf16 v[16:19], v[152:155], v[132:135], v[16:19]
	v_mfma_f32_16x16x32_bf16 v[12:15], v[140:143], v[136:139], v[12:15]
	v_mfma_f32_16x16x32_bf16 v[8:11], v[144:147], v[136:139], v[8:11]
	v_mfma_f32_16x16x32_bf16 v[4:7], v[148:151], v[136:139], v[4:7]
	v_mfma_f32_16x16x32_bf16 v[0:3], v[152:155], v[136:139], v[0:3]
	s_setprio 0
	s_waitcnt vmcnt(0)
	s_add_u32 s4, s4, 0x80
	s_addc_u32 s5, s5, 0
	s_add_u32 s64, s64, 0x80
	s_addc_u32 s65, s65, 0
	s_add_u32 s66, s66, 0x80
	s_addc_u32 s67, s67, 0
	s_add_i32 s6, s6, 0x8000
	s_cmpk_lg_i32 s4, 0xf80
	s_waitcnt vmcnt(0) lgkmcnt(0)
	s_barrier
	s_cbranch_scc1 .LBB0_400
	v_add_u32_e32 v95, 0x8000, v81
	v_add_u32_e32 v132, 0x8000, v84
	v_or_b32_e32 v133, 0x8000, v82
	v_or_b32_e32 v134, 0x8000, v83
	ds_read_b128 v[64:67], v95
	ds_read_b128 v[68:71], v95 offset:2048
	ds_read_b128 v[72:75], v95 offset:4096
	ds_read_b128 v[76:79], v95 offset:6144
	ds_read_b128 v[80:83], v133
	ds_read_b128 v[84:87], v133 offset:2048
	ds_read_b128 v[88:91], v133 offset:8192
	ds_read_b128 v[96:99], v133 offset:10240
	ds_read_b128 v[100:103], v132
	ds_read_b128 v[104:107], v132 offset:2048
	ds_read_b128 v[108:111], v132 offset:4096
	ds_read_b128 v[112:115], v132 offset:6144
	ds_read_b128 v[116:119], v134
	ds_read_b128 v[120:123], v134 offset:2048
	ds_read_b128 v[124:127], v134 offset:8192
	ds_read_b128 v[128:131], v134 offset:10240
	s_waitcnt lgkmcnt(8)
	s_mov_b32 s16, 0x8000
	s_setprio 1
	v_mfma_f32_16x16x32_bf16 v[60:63], v[80:83], v[64:67], v[60:63]
	v_mfma_f32_16x16x32_bf16 v[56:59], v[84:87], v[64:67], v[56:59]
	v_mfma_f32_16x16x32_bf16 v[52:55], v[88:91], v[64:67], v[52:55]
	v_mfma_f32_16x16x32_bf16 v[48:51], v[96:99], v[64:67], v[48:51]
	v_mfma_f32_16x16x32_bf16 v[44:47], v[80:83], v[68:71], v[44:47]
	v_mfma_f32_16x16x32_bf16 v[40:43], v[84:87], v[68:71], v[40:43]
	v_mfma_f32_16x16x32_bf16 v[36:39], v[88:91], v[68:71], v[36:39]
	v_mfma_f32_16x16x32_bf16 v[32:35], v[96:99], v[68:71], v[32:35]
	v_mfma_f32_16x16x32_bf16 v[28:31], v[80:83], v[72:75], v[28:31]
	v_mfma_f32_16x16x32_bf16 v[24:27], v[84:87], v[72:75], v[24:27]
	v_mfma_f32_16x16x32_bf16 v[20:23], v[88:91], v[72:75], v[20:23]
	v_mfma_f32_16x16x32_bf16 v[16:19], v[96:99], v[72:75], v[16:19]
	v_mfma_f32_16x16x32_bf16 v[12:15], v[80:83], v[76:79], v[12:15]
	v_mfma_f32_16x16x32_bf16 v[8:11], v[84:87], v[76:79], v[8:11]
	v_mfma_f32_16x16x32_bf16 v[4:7], v[88:91], v[76:79], v[4:7]
	v_mfma_f32_16x16x32_bf16 v[0:3], v[96:99], v[76:79], v[0:3]
	s_waitcnt lgkmcnt(0)
	s_nop 0
	v_mfma_f32_16x16x32_bf16 v[60:63], v[116:119], v[100:103], v[60:63]
	v_mfma_f32_16x16x32_bf16 v[70:73], v[120:123], v[100:103], v[56:59]
	v_mfma_f32_16x16x32_bf16 v[52:55], v[124:127], v[100:103], v[52:55]
	v_mfma_f32_16x16x32_bf16 v[48:51], v[128:131], v[100:103], v[48:51]
	v_mfma_f32_16x16x32_bf16 v[44:47], v[116:119], v[104:107], v[44:47]
	v_mfma_f32_16x16x32_bf16 v[40:43], v[120:123], v[104:107], v[40:43]
	v_mfma_f32_16x16x32_bf16 v[36:39], v[124:127], v[104:107], v[36:39]
	v_mfma_f32_16x16x32_bf16 v[32:35], v[128:131], v[104:107], v[32:35]
	v_mfma_f32_16x16x32_bf16 v[28:31], v[116:119], v[108:111], v[28:31]
	v_mfma_f32_16x16x32_bf16 v[24:27], v[120:123], v[108:111], v[24:27]
	v_mfma_f32_16x16x32_bf16 v[20:23], v[124:127], v[108:111], v[20:23]
	v_mfma_f32_16x16x32_bf16 v[16:19], v[128:131], v[108:111], v[16:19]
	v_mfma_f32_16x16x32_bf16 v[12:15], v[116:119], v[112:115], v[12:15]
	v_mfma_f32_16x16x32_bf16 v[8:11], v[120:123], v[112:115], v[8:11]
	v_mfma_f32_16x16x32_bf16 v[4:7], v[124:127], v[112:115], v[4:7]
	v_mfma_f32_16x16x32_bf16 v[0:3], v[128:131], v[112:115], v[0:3]
	s_setprio 0
	s_waitcnt vmcnt(0)
	s_barrier
; #define P (*launderP(lp))
; DEV void store_nat(u16* buf, int ld, int row, int col, f32x4 v) {
;   uint2 o; o.x = pack2(v[0], v[1]); o.y = pack2(v[2], v[3]);
;   *(uint2*)(buf + (size_t)row * ld + col) = o;
; }
; __device__ __forceinline__ void phase_gemm2(PREF P, char* smem) {
;     ...
; #pragma unroll
;     for (int i = 0; i < 4; ++i)
; #pragma unroll
;       for (int j = 0; j < 4; ++j) {
;         const int row = m0 + wm * 64 + i * 16 + l15, col = n0 + (j & 1) * 16 + wn * 32 + (j >> 1) * 64 + q * 4;
;         const unsigned g = *(const unsigned*)((const u8*)P.GA + (size_t)row * 2048 + col);
;         f32x4 v;
;         v[0] = (float)(g & 255u) * (1.f / 255.f) * acc[i][j][0]; v[1] = (float)((g >> 8) & 255u) * (1.f / 255.f) * acc[i][j][1];
;         v[2] = (float)((g >> 16) & 255u) * (1.f / 255.f) * acc[i][j][2]; v[3] = (float)(g >> 24) * (1.f / 255.f) * acc[i][j][3];
;         store_nat(P.merged, 2048, row, col, v);
;       }
	ds_read_b64 v[66:67], v92 offset:296
	ds_read_b64 v[74:75], v92 offset:336
	v_add_u32_e32 v56, s15, v93
	v_ashrrev_i32_e32 v57, 31, v56
	v_or_b32_e32 v64, s0, v94
	v_lshlrev_b64 v[68:69], 11, v[56:57]
	s_waitcnt lgkmcnt(1)
	v_lshl_add_u64 v[66:67], v[66:67], 0, v[68:69]
	v_ashrrev_i32_e32 v65, 31, v64
	v_lshl_add_u64 v[66:67], v[66:67], 0, v[64:65]
	v_lshlrev_b64 v[58:59], 12, v[56:57]
	flat_load_dword v57, v[66:67]
	s_mov_b32 s4, 0x3b808081
	s_add_i32 s18, s18, s17
	s_waitcnt vmcnt(0) lgkmcnt(0)
	v_cvt_f32_ubyte1_e32 v67, v57
	v_cvt_f32_ubyte0_e32 v66, v57
	v_mul_f32_e32 v66, s4, v66
	v_mul_f32_e32 v67, s4, v67
	s_nop 0
	v_mul_f32_e32 v60, v60, v66
	v_mul_f32_e32 v61, v61, v67
	v_cvt_f32_ubyte3_e32 v67, v57
	v_cvt_f32_ubyte2_e32 v66, v57
	v_mul_f32_e32 v66, s4, v66
	v_mul_f32_e32 v67, s4, v67
	v_cvt_pk_bf16_f32 v60, v60, v61
	v_mul_f32_e32 v62, v62, v66
	v_mul_f32_e32 v63, v63, v67
	v_lshlrev_b64 v[66:67], 1, v[64:65]
	v_cvt_pk_bf16_f32 v61, v62, v63
	v_lshl_add_u64 v[62:63], v[74:75], 0, v[58:59]
	v_lshl_add_u64 v[62:63], v[62:63], 0, v[66:67]
	flat_store_dwordx2 v[62:63], v[60:61]
	ds_read_b64 v[60:61], v92 offset:296
	ds_read_b64 v[62:63], v92 offset:336
	s_waitcnt lgkmcnt(0)
	v_lshl_add_u64 v[60:61], v[60:61], 0, v[68:69]
	v_lshl_add_u64 v[60:61], v[60:61], 0, v[64:65]
	flat_load_dword v57, v[60:61] offset:16
	v_lshl_add_u64 v[62:63], v[62:63], 0, v[58:59]
	v_lshl_add_u64 v[62:63], v[62:63], 0, v[66:67]
	s_waitcnt vmcnt(0) lgkmcnt(0)
	v_cvt_f32_ubyte1_e32 v61, v57
	v_cvt_f32_ubyte0_e32 v60, v57
	v_mul_f32_e32 v60, s4, v60
	v_mul_f32_e32 v61, s4, v61
	s_nop 0
	v_mul_f32_e32 v60, v70, v60
	v_mul_f32_e32 v61, v71, v61
	v_cvt_f32_ubyte3_e32 v71, v57
	v_cvt_f32_ubyte2_e32 v70, v57
	v_mul_f32_e32 v70, s4, v70
	v_mul_f32_e32 v71, s4, v71
	v_cvt_pk_bf16_f32 v60, v60, v61
	v_mul_f32_e32 v70, v72, v70
	v_mul_f32_e32 v71, v73, v71
	s_nop 0
	v_cvt_pk_bf16_f32 v61, v70, v71
	flat_store_dwordx2 v[62:63], v[60:61] offset:32
	ds_read_b64 v[60:61], v92 offset:296
	ds_read_b64 v[62:63], v92 offset:336
	s_waitcnt lgkmcnt(0)
	v_lshl_add_u64 v[60:61], v[60:61], 0, v[68:69]
	v_lshl_add_u64 v[60:61], v[60:61], 0, v[64:65]
	flat_load_dword v57, v[60:61] offset:64
	s_waitcnt vmcnt(0) lgkmcnt(0)
	v_cvt_f32_ubyte1_e32 v61, v57
	v_cvt_f32_ubyte0_e32 v60, v57
	v_mul_f32_e32 v60, s4, v60
	v_mul_f32_e32 v61, s4, v61
	s_nop 0
	v_mul_f32_e32 v52, v52, v60
	v_mul_f32_e32 v53, v53, v61
	v_cvt_f32_ubyte3_e32 v61, v57
	v_cvt_f32_ubyte2_e32 v60, v57
	v_mul_f32_e32 v60, s4, v60
	v_mul_f32_e32 v61, s4, v61
	v_cvt_pk_bf16_f32 v52, v52, v53
	v_mul_f32_e32 v54, v54, v60
	v_mul_f32_e32 v55, v55, v61
	s_nop 0
	v_cvt_pk_bf16_f32 v53, v54, v55
	v_lshl_add_u64 v[54:55], v[62:63], 0, v[58:59]
	v_lshl_add_u64 v[54:55], v[54:55], 0, v[66:67]
	flat_store_dwordx2 v[54:55], v[52:53] offset:128
	ds_read_b64 v[52:53], v92 offset:296
	ds_read_b64 v[54:55], v92 offset:336
	s_waitcnt lgkmcnt(0)
	v_lshl_add_u64 v[52:53], v[52:53], 0, v[68:69]
	v_lshl_add_u64 v[52:53], v[52:53], 0, v[64:65]
	flat_load_dword v57, v[52:53] offset:80
	s_waitcnt vmcnt(0) lgkmcnt(0)
	v_cvt_f32_ubyte1_e32 v53, v57
	v_cvt_f32_ubyte0_e32 v52, v57
	v_mul_f32_e32 v52, s4, v52
	v_mul_f32_e32 v53, s4, v53
	s_nop 0
	v_mul_f32_e32 v48, v48, v52
	v_mul_f32_e32 v49, v49, v53
	v_cvt_f32_ubyte3_e32 v53, v57
	v_cvt_f32_ubyte2_e32 v52, v57
	v_mul_f32_e32 v52, s4, v52
	v_mul_f32_e32 v53, s4, v53
	v_cvt_pk_bf16_f32 v48, v48, v49
	v_mul_f32_e32 v50, v50, v52
	v_mul_f32_e32 v51, v51, v53
	s_nop 0
	v_cvt_pk_bf16_f32 v49, v50, v51
	v_lshl_add_u64 v[50:51], v[54:55], 0, v[58:59]
	v_lshl_add_u64 v[50:51], v[50:51], 0, v[66:67]
	flat_store_dwordx2 v[50:51], v[48:49] offset:160
	ds_read_b64 v[50:51], v92 offset:296
	ds_read_b64 v[52:53], v92 offset:336
	v_or_b32_e32 v48, 16, v56
	v_ashrrev_i32_e32 v49, 31, v48
	v_lshlrev_b64 v[72:73], 11, v[48:49]
	s_waitcnt lgkmcnt(0)
	v_lshl_add_u64 v[50:51], v[50:51], 0, v[72:73]
	v_lshl_add_u64 v[50:51], v[50:51], 0, v[64:65]
	flat_load_dword v54, v[50:51]
	v_lshlrev_b64 v[48:49], 12, v[48:49]
	s_waitcnt vmcnt(0) lgkmcnt(0)
	v_cvt_f32_ubyte1_e32 v51, v54
	v_cvt_f32_ubyte0_e32 v50, v54
	v_mul_f32_e32 v50, s4, v50
	v_mul_f32_e32 v51, s4, v51
	s_nop 0
	v_mul_f32_e32 v44, v44, v50
	v_mul_f32_e32 v45, v45, v51
	v_cvt_f32_ubyte3_e32 v51, v54
	v_cvt_f32_ubyte2_e32 v50, v54
	v_mul_f32_e32 v50, s4, v50
	v_mul_f32_e32 v51, s4, v51
	v_cvt_pk_bf16_f32 v44, v44, v45
	v_mul_f32_e32 v46, v46, v50
	v_mul_f32_e32 v47, v47, v51
	s_nop 0
	v_cvt_pk_bf16_f32 v45, v46, v47
	v_lshl_add_u64 v[46:47], v[52:53], 0, v[48:49]
	v_lshl_add_u64 v[46:47], v[46:47], 0, v[66:67]
	flat_store_dwordx2 v[46:47], v[44:45]
	ds_read_b64 v[44:45], v92 offset:296
	ds_read_b64 v[46:47], v92 offset:336
	s_waitcnt lgkmcnt(0)
	v_lshl_add_u64 v[44:45], v[44:45], 0, v[72:73]
	v_lshl_add_u64 v[44:45], v[44:45], 0, v[64:65]
	flat_load_dword v50, v[44:45] offset:16
	s_waitcnt vmcnt(0) lgkmcnt(0)
	v_cvt_f32_ubyte1_e32 v45, v50
	v_cvt_f32_ubyte0_e32 v44, v50
	v_mul_f32_e32 v44, s4, v44
	v_mul_f32_e32 v45, s4, v45
	s_nop 0
	v_mul_f32_e32 v40, v40, v44
	v_mul_f32_e32 v41, v41, v45
	v_cvt_f32_ubyte3_e32 v45, v50
	v_cvt_f32_ubyte2_e32 v44, v50
	v_mul_f32_e32 v44, s4, v44
	v_mul_f32_e32 v45, s4, v45
	v_cvt_pk_bf16_f32 v40, v40, v41
	v_mul_f32_e32 v42, v42, v44
	v_mul_f32_e32 v43, v43, v45
	s_nop 0
	v_cvt_pk_bf16_f32 v41, v42, v43
	v_lshl_add_u64 v[42:43], v[46:47], 0, v[48:49]
	v_lshl_add_u64 v[42:43], v[42:43], 0, v[66:67]
	flat_store_dwordx2 v[42:43], v[40:41] offset:32
	ds_read_b64 v[40:41], v92 offset:296
	ds_read_b64 v[42:43], v92 offset:336
	s_waitcnt lgkmcnt(0)
	v_lshl_add_u64 v[40:41], v[40:41], 0, v[72:73]
	v_lshl_add_u64 v[40:41], v[40:41], 0, v[64:65]
	flat_load_dword v44, v[40:41] offset:64
	s_waitcnt vmcnt(0) lgkmcnt(0)
; #define P (*launderP(lp))
; DEV void store_nat(u16* buf, int ld, int row, int col, f32x4 v) {
;   uint2 o; o.x = pack2(v[0], v[1]); o.y = pack2(v[2], v[3]);
;   *(uint2*)(buf + (size_t)row * ld + col) = o;
; }
; __device__ __forceinline__ void phase_gemm2(PREF P, char* smem) {
;     ...
; #pragma unroll
;     for (int i = 0; i < 4; ++i)
; #pragma unroll
;       for (int j = 0; j < 4; ++j) {
;         const int row = m0 + wm * 64 + i * 16 + l15, col = n0 + (j & 1) * 16 + wn * 32 + (j >> 1) * 64 + q * 4;
;         const unsigned g = *(const unsigned*)((const u8*)P.GA + (size_t)row * 2048 + col);
;         f32x4 v;
;         v[0] = (float)(g & 255u) * (1.f / 255.f) * acc[i][j][0]; v[1] = (float)((g >> 8) & 255u) * (1.f / 255.f) * acc[i][j][1];
;         v[2] = (float)((g >> 16) & 255u) * (1.f / 255.f) * acc[i][j][2]; v[3] = (float)(g >> 24) * (1.f / 255.f) * acc[i][j][3];
;         store_nat(P.merged, 2048, row, col, v);
;       }
	v_cvt_f32_ubyte1_e32 v41, v44
	v_cvt_f32_ubyte0_e32 v40, v44
	v_mul_f32_e32 v40, s4, v40
	v_mul_f32_e32 v41, s4, v41
	s_nop 0
	v_mul_f32_e32 v36, v36, v40
	v_mul_f32_e32 v37, v37, v41
	v_cvt_f32_ubyte3_e32 v41, v44
	v_cvt_f32_ubyte2_e32 v40, v44
	v_mul_f32_e32 v40, s4, v40
	v_mul_f32_e32 v41, s4, v41
	v_cvt_pk_bf16_f32 v36, v36, v37
	v_mul_f32_e32 v38, v38, v40
	v_mul_f32_e32 v39, v39, v41
	s_nop 0
	v_cvt_pk_bf16_f32 v37, v38, v39
	v_lshl_add_u64 v[38:39], v[42:43], 0, v[48:49]
	v_lshl_add_u64 v[38:39], v[38:39], 0, v[66:67]
	flat_store_dwordx2 v[38:39], v[36:37] offset:128
	ds_read_b64 v[36:37], v92 offset:296
	ds_read_b64 v[38:39], v92 offset:336
	s_waitcnt lgkmcnt(0)
	v_lshl_add_u64 v[36:37], v[36:37], 0, v[72:73]
	v_lshl_add_u64 v[36:37], v[36:37], 0, v[64:65]
	flat_load_dword v40, v[36:37] offset:80
	s_waitcnt vmcnt(0) lgkmcnt(0)
	v_cvt_f32_ubyte1_e32 v37, v40
	v_cvt_f32_ubyte0_e32 v36, v40
	v_mul_f32_e32 v36, s4, v36
	v_mul_f32_e32 v37, s4, v37
	s_nop 0
	v_mul_f32_e32 v32, v32, v36
	v_mul_f32_e32 v33, v33, v37
	v_cvt_f32_ubyte3_e32 v37, v40
	v_cvt_f32_ubyte2_e32 v36, v40
	v_mul_f32_e32 v36, s4, v36
	v_mul_f32_e32 v37, s4, v37
	v_cvt_pk_bf16_f32 v32, v32, v33
	v_mul_f32_e32 v34, v34, v36
	v_mul_f32_e32 v35, v35, v37
	s_nop 0
	v_cvt_pk_bf16_f32 v33, v34, v35
	v_lshl_add_u64 v[34:35], v[38:39], 0, v[48:49]
	v_lshl_add_u64 v[34:35], v[34:35], 0, v[66:67]
	flat_store_dwordx2 v[34:35], v[32:33] offset:160
	ds_read_b64 v[34:35], v92 offset:296
	ds_read_b64 v[36:37], v92 offset:336
	v_or_b32_e32 v32, 32, v56
	v_ashrrev_i32_e32 v33, 31, v32
	v_lshlrev_b64 v[74:75], 11, v[32:33]
	s_waitcnt lgkmcnt(0)
	v_lshl_add_u64 v[34:35], v[34:35], 0, v[74:75]
	v_lshl_add_u64 v[34:35], v[34:35], 0, v[64:65]
	flat_load_dword v38, v[34:35]
	v_lshlrev_b64 v[32:33], 12, v[32:33]
	s_waitcnt vmcnt(0) lgkmcnt(0)
	v_cvt_f32_ubyte1_e32 v35, v38
	v_cvt_f32_ubyte0_e32 v34, v38
	v_mul_f32_e32 v34, s4, v34
	v_mul_f32_e32 v35, s4, v35
	s_nop 0
	v_mul_f32_e32 v28, v28, v34
	v_mul_f32_e32 v29, v29, v35
	v_cvt_f32_ubyte3_e32 v35, v38
	v_cvt_f32_ubyte2_e32 v34, v38
	v_mul_f32_e32 v34, s4, v34
	v_mul_f32_e32 v35, s4, v35
	v_cvt_pk_bf16_f32 v28, v28, v29
	v_mul_f32_e32 v30, v30, v34
	v_mul_f32_e32 v31, v31, v35
	s_nop 0
	v_cvt_pk_bf16_f32 v29, v30, v31
	v_lshl_add_u64 v[30:31], v[36:37], 0, v[32:33]
	v_lshl_add_u64 v[30:31], v[30:31], 0, v[66:67]
	flat_store_dwordx2 v[30:31], v[28:29]
	ds_read_b64 v[28:29], v92 offset:296
	ds_read_b64 v[30:31], v92 offset:336
	s_waitcnt lgkmcnt(0)
	v_lshl_add_u64 v[28:29], v[28:29], 0, v[74:75]
	v_lshl_add_u64 v[28:29], v[28:29], 0, v[64:65]
	flat_load_dword v34, v[28:29] offset:16
	s_waitcnt vmcnt(0) lgkmcnt(0)
	v_cvt_f32_ubyte1_e32 v29, v34
	v_cvt_f32_ubyte0_e32 v28, v34
	v_mul_f32_e32 v28, s4, v28
	v_mul_f32_e32 v29, s4, v29
	s_nop 0
	v_mul_f32_e32 v24, v24, v28
	v_mul_f32_e32 v25, v25, v29
	v_cvt_f32_ubyte3_e32 v29, v34
	v_cvt_f32_ubyte2_e32 v28, v34
	v_mul_f32_e32 v28, s4, v28
	v_mul_f32_e32 v29, s4, v29
	v_cvt_pk_bf16_f32 v24, v24, v25
	v_mul_f32_e32 v26, v26, v28
	v_mul_f32_e32 v27, v27, v29
	s_nop 0
	v_cvt_pk_bf16_f32 v25, v26, v27
	v_lshl_add_u64 v[26:27], v[30:31], 0, v[32:33]
	v_lshl_add_u64 v[26:27], v[26:27], 0, v[66:67]
	flat_store_dwordx2 v[26:27], v[24:25] offset:32
	ds_read_b64 v[24:25], v92 offset:296
	ds_read_b64 v[26:27], v92 offset:336
	s_waitcnt lgkmcnt(0)
	v_lshl_add_u64 v[24:25], v[24:25], 0, v[74:75]
	v_lshl_add_u64 v[24:25], v[24:25], 0, v[64:65]
	flat_load_dword v28, v[24:25] offset:64
	s_waitcnt vmcnt(0) lgkmcnt(0)
	v_cvt_f32_ubyte1_e32 v25, v28
	v_cvt_f32_ubyte0_e32 v24, v28
	v_mul_f32_e32 v24, s4, v24
	v_mul_f32_e32 v25, s4, v25
	s_nop 0
	v_mul_f32_e32 v20, v20, v24
	v_mul_f32_e32 v21, v21, v25
	v_cvt_f32_ubyte3_e32 v25, v28
	v_cvt_f32_ubyte2_e32 v24, v28
	v_mul_f32_e32 v24, s4, v24
	v_mul_f32_e32 v25, s4, v25
	v_cvt_pk_bf16_f32 v20, v20, v21
	v_mul_f32_e32 v22, v22, v24
	v_mul_f32_e32 v23, v23, v25
	s_nop 0
	v_cvt_pk_bf16_f32 v21, v22, v23
	v_lshl_add_u64 v[22:23], v[26:27], 0, v[32:33]
	v_lshl_add_u64 v[22:23], v[22:23], 0, v[66:67]
	flat_store_dwordx2 v[22:23], v[20:21] offset:128
	ds_read_b64 v[20:21], v92 offset:296
	ds_read_b64 v[22:23], v92 offset:336
	s_waitcnt lgkmcnt(0)
	v_lshl_add_u64 v[20:21], v[20:21], 0, v[74:75]
	v_lshl_add_u64 v[20:21], v[20:21], 0, v[64:65]
	flat_load_dword v24, v[20:21] offset:80
	s_waitcnt vmcnt(0) lgkmcnt(0)
	v_cvt_f32_ubyte1_e32 v21, v24
	v_cvt_f32_ubyte0_e32 v20, v24
	v_mul_f32_e32 v20, s4, v20
	v_mul_f32_e32 v21, s4, v21
	s_nop 0
	v_mul_f32_e32 v16, v16, v20
	v_mul_f32_e32 v17, v17, v21
	v_cvt_f32_ubyte3_e32 v21, v24
	v_cvt_f32_ubyte2_e32 v20, v24
	v_mul_f32_e32 v20, s4, v20
	v_mul_f32_e32 v21, s4, v21
	v_cvt_pk_bf16_f32 v16, v16, v17
	v_mul_f32_e32 v18, v18, v20
	v_mul_f32_e32 v19, v19, v21
	v_mov_b32_e32 v24, v188
	v_cvt_pk_bf16_f32 v17, v18, v19
	v_lshl_add_u64 v[18:19], v[22:23], 0, v[32:33]
	v_lshl_add_u64 v[18:19], v[18:19], 0, v[66:67]
	flat_store_dwordx2 v[18:19], v[16:17] offset:160
	ds_read_b64 v[18:19], v92 offset:296
	ds_read_b64 v[20:21], v92 offset:336
	v_or_b32_e32 v16, 48, v56
	v_ashrrev_i32_e32 v17, 31, v16
	v_lshlrev_b64 v[70:71], 11, v[16:17]
	s_waitcnt lgkmcnt(0)
	v_lshl_add_u64 v[18:19], v[18:19], 0, v[70:71]
	v_lshl_add_u64 v[18:19], v[18:19], 0, v[64:65]
	flat_load_dword v22, v[18:19]
	v_lshlrev_b64 v[16:17], 12, v[16:17]
	s_waitcnt vmcnt(0) lgkmcnt(0)
; DEV int tid_() { int t = threadIdx.x; asm volatile("" : "+v"(t)); return t; }
; #define P (*launderP(lp))
; template <class FragT, class AccT>
; DEV void gemm_core_t(const char* __restrict__ A, size_t lda_bytes, const char* __restrict__ Bt, size_t ldb_bytes, int kbytes,
;                      int m0, int n0, int Sshift, int dl, char* smem, AccT (&acc)[4][4]) {
;   const int tid = tid_(), lane = tid & 63, wid = tid >> 6, wm = wid >> 1, wn = wid & 1;
;   const int l15 = lane & 15, q = lane >> 4;
;   const int srow = lane >> 3, schunk = (lane & 7) ^ (lane >> 3);
;   const char* ap[4];
;   const char* bp[4];
; #pragma unroll
;   for (int u = 0; u < 4; ++u) {
;     int r = (wid * 4 + u) * 8 + srow;
;     int ar = rowmap(m0 + r, Sshift, dl);
;     ap[u] = A + (size_t)ar * lda_bytes + schunk * 16;
;     bp[u] = Bt + (size_t)(n0 + r) * ldb_bytes + schunk * 16;
;   }
; __device__ __forceinline__ void phase_gemm2(PREF P, char* smem) {
;     ...
; #pragma unroll
;     for (int i = 0; i < 4; ++i)
; #pragma unroll
;       for (int j = 0; j < 4; ++j) {
;         const int row = m0 + wm * 64 + i * 16 + l15, col = n0 + (j & 1) * 16 + wn * 32 + (j >> 1) * 64 + q * 4;
;         const unsigned g = *(const unsigned*)((const u8*)P.GA + (size_t)row * 2048 + col);
;         f32x4 v;
;         v[0] = (float)(g & 255u) * (1.f / 255.f) * acc[i][j][0]; v[1] = (float)((g >> 8) & 255u) * (1.f / 255.f) * acc[i][j][1];
;         v[2] = (float)((g >> 16) & 255u) * (1.f / 255.f) * acc[i][j][2]; v[3] = (float)(g >> 24) * (1.f / 255.f) * acc[i][j][3];
;         store_nat(P.merged, 2048, row, col, v);
;       }
	v_cvt_f32_ubyte1_e32 v19, v22
	v_cvt_f32_ubyte0_e32 v18, v22
	v_mul_f32_e32 v18, s4, v18
	v_mul_f32_e32 v19, s4, v19
	s_nop 0
	v_mul_f32_e32 v12, v12, v18
	v_mul_f32_e32 v13, v13, v19
	v_cvt_f32_ubyte3_e32 v19, v22
	v_cvt_f32_ubyte2_e32 v18, v22
	v_mul_f32_e32 v18, s4, v18
	v_mul_f32_e32 v19, s4, v19
	v_cvt_pk_bf16_f32 v12, v12, v13
	v_mul_f32_e32 v14, v14, v18
	v_mul_f32_e32 v15, v15, v19
	s_nop 0
	v_cvt_pk_bf16_f32 v13, v14, v15
	v_lshl_add_u64 v[14:15], v[20:21], 0, v[16:17]
	v_lshl_add_u64 v[14:15], v[14:15], 0, v[66:67]
	flat_store_dwordx2 v[14:15], v[12:13]
	ds_read_b64 v[12:13], v92 offset:296
	ds_read_b64 v[14:15], v92 offset:336
	s_waitcnt lgkmcnt(0)
	v_lshl_add_u64 v[12:13], v[12:13], 0, v[70:71]
	v_lshl_add_u64 v[12:13], v[12:13], 0, v[64:65]
	flat_load_dword v18, v[12:13] offset:16
	s_waitcnt vmcnt(0) lgkmcnt(0)
	v_cvt_f32_ubyte1_e32 v13, v18
	v_cvt_f32_ubyte0_e32 v12, v18
	v_mul_f32_e32 v12, s4, v12
	v_mul_f32_e32 v13, s4, v13
	s_nop 0
	v_mul_f32_e32 v8, v8, v12
	v_mul_f32_e32 v9, v9, v13
	v_cvt_f32_ubyte3_e32 v13, v18
	v_cvt_f32_ubyte2_e32 v12, v18
	v_mul_f32_e32 v12, s4, v12
	v_mul_f32_e32 v13, s4, v13
	v_cvt_pk_bf16_f32 v8, v8, v9
	v_mul_f32_e32 v10, v10, v12
	v_mul_f32_e32 v11, v11, v13
	s_nop 0
	v_cvt_pk_bf16_f32 v9, v10, v11
	v_lshl_add_u64 v[10:11], v[14:15], 0, v[16:17]
	v_lshl_add_u64 v[10:11], v[10:11], 0, v[66:67]
	flat_store_dwordx2 v[10:11], v[8:9] offset:32
	ds_read_b64 v[8:9], v92 offset:296
	ds_read_b64 v[10:11], v92 offset:336
	s_waitcnt lgkmcnt(0)
	v_lshl_add_u64 v[8:9], v[8:9], 0, v[70:71]
	v_lshl_add_u64 v[8:9], v[8:9], 0, v[64:65]
	flat_load_dword v12, v[8:9] offset:64
	s_waitcnt vmcnt(0) lgkmcnt(0)
	v_cvt_f32_ubyte1_e32 v9, v12
	v_cvt_f32_ubyte0_e32 v8, v12
	v_mul_f32_e32 v8, s4, v8
	v_mul_f32_e32 v9, s4, v9
	s_nop 0
	v_mul_f32_e32 v4, v4, v8
	v_mul_f32_e32 v5, v5, v9
	v_cvt_f32_ubyte3_e32 v9, v12
	v_cvt_f32_ubyte2_e32 v8, v12
	v_mul_f32_e32 v8, s4, v8
	v_mul_f32_e32 v9, s4, v9
	v_cvt_pk_bf16_f32 v4, v4, v5
	v_mul_f32_e32 v6, v6, v8
	v_mul_f32_e32 v7, v7, v9
	s_nop 0
	v_cvt_pk_bf16_f32 v5, v6, v7
	v_lshl_add_u64 v[6:7], v[10:11], 0, v[16:17]
	v_lshl_add_u64 v[6:7], v[6:7], 0, v[66:67]
	flat_store_dwordx2 v[6:7], v[4:5] offset:128
	ds_read_b64 v[4:5], v92 offset:296
	ds_read_b64 v[6:7], v92 offset:336
	s_waitcnt lgkmcnt(0)
	v_lshl_add_u64 v[4:5], v[4:5], 0, v[70:71]
	v_lshl_add_u64 v[4:5], v[4:5], 0, v[64:65]
	flat_load_dword v8, v[4:5] offset:80
	s_waitcnt vmcnt(0) lgkmcnt(0)
	v_cvt_f32_ubyte1_e32 v5, v8
	v_cvt_f32_ubyte0_e32 v4, v8
	v_mul_f32_e32 v4, s4, v4
	v_mul_f32_e32 v5, s4, v5
	s_nop 0
	v_mul_f32_e32 v0, v0, v4
	v_mul_f32_e32 v1, v1, v5
	v_cvt_f32_ubyte3_e32 v5, v8
	v_cvt_f32_ubyte2_e32 v4, v8
	v_mul_f32_e32 v4, s4, v4
	v_mul_f32_e32 v5, s4, v5
	v_cvt_pk_bf16_f32 v0, v0, v1
	v_mul_f32_e32 v2, v2, v4
	v_mul_f32_e32 v3, v3, v5
	s_nop 0
	v_cvt_pk_bf16_f32 v1, v2, v3
	v_lshl_add_u64 v[2:3], v[6:7], 0, v[16:17]
	v_lshl_add_u64 v[2:3], v[2:3], 0, v[66:67]
	flat_store_dwordx2 v[2:3], v[0:1] offset:160
	ds_read_b64 v[0:1], v92 offset:328
	ds_read_b64 v[2:3], v92 offset:176
	s_waitcnt lgkmcnt(0)
	v_ashrrev_i32_e32 v26, 6, v24
	v_bfe_u32 v6, v24, 3, 3
	v_lshlrev_b32_e32 v7, 5, v26
	v_or_b32_e32 v22, v7, v6
	v_or_b32_e32 v16, 8, v22
	v_or_b32_e32 v20, 16, v22
	v_or_b32_e32 v27, 24, v22
	v_bitop3_b32 v4, v6, v24, 7 bitop3:0x78
	v_add_u32_e32 v10, s15, v22
	v_add_u32_e32 v12, s0, v22
	v_add_u32_e32 v14, s15, v16
	v_add_u32_e32 v18, s15, v20
	v_add_u32_e32 v22, s15, v27
	v_lshlrev_b32_e32 v180, 4, v4
	v_ashrrev_i32_e32 v11, 31, v10
	v_ashrrev_i32_e32 v15, 31, v14
	v_ashrrev_i32_e32 v19, 31, v18
	v_ashrrev_i32_e32 v23, 31, v22
	v_lshl_add_u64 v[4:5], v[0:1], 0, v[180:181]
	v_lshlrev_b64 v[10:11], 11, v[10:11]
	v_lshlrev_b64 v[14:15], 11, v[14:15]
	v_lshlrev_b64 v[18:19], 11, v[18:19]
	v_lshlrev_b64 v[22:23], 11, v[22:23]
	v_lshl_add_u64 v[10:11], v[4:5], 0, v[10:11]
	v_lshl_add_u64 v[14:15], v[4:5], 0, v[14:15]
	v_add_u32_e32 v16, s0, v16
	v_lshl_add_u64 v[18:19], v[4:5], 0, v[18:19]
	v_add_u32_e32 v20, s0, v20
	v_lshl_add_u64 v[4:5], v[4:5], 0, v[22:23]
	v_add_u32_e32 v22, s0, v27
	v_ashrrev_i32_e32 v13, 31, v12
	v_ashrrev_i32_e32 v17, 31, v16
	v_ashrrev_i32_e32 v21, 31, v20
	v_ashrrev_i32_e32 v23, 31, v22
	v_lshl_add_u64 v[8:9], v[2:3], 0, v[180:181]
	v_lshlrev_b64 v[12:13], 11, v[12:13]
	v_lshlrev_b64 v[16:17], 11, v[16:17]
	v_lshlrev_b64 v[20:21], 11, v[20:21]
	v_lshlrev_b64 v[22:23], 11, v[22:23]
	v_and_b32_e32 v25, 63, v24
	v_lshl_add_u64 v[12:13], v[8:9], 0, v[12:13]
	v_lshl_add_u64 v[16:17], v[8:9], 0, v[16:17]
	v_lshl_add_u64 v[20:21], v[8:9], 0, v[20:21]
	v_lshl_add_u64 v[8:9], v[8:9], 0, v[22:23]
	v_lshlrev_b32_e32 v23, 12, v26
	v_lshl_or_b32 v95, v25, 4, v23
	s_barrier
; template <class FragT, class AccT>
; DEV void gemm_core_t(const char* __restrict__ A, size_t lda_bytes, const char* __restrict__ Bt, size_t ldb_bytes, int kbytes,
;                      int m0, int n0, int Sshift, int dl, char* smem, AccT (&acc)[4][4]) {
;     ...
; #pragma unroll
;   for (int i = 0; i < 4; ++i)
; #pragma unroll
;     for (int j = 0; j < 4; ++j) acc[i][j] = AccT{0, 0, 0, 0};
;   const int nk = kbytes >> 7;
;   __syncthreads();
; #pragma unroll
;   for (int u = 0; u < 4; ++u) {
;     __builtin_amdgcn_global_load_lds((const unsigned*)ap[u], (unsigned*)(smem + (wid * 4 + u) * 1024 + lane * 16), 16, 0, 0);
;     __builtin_amdgcn_global_load_lds((const unsigned*)bp[u], (unsigned*)(smem + 16384 + (wid * 4 + u) * 1024 + lane * 16), 16, 0, 0);
;   }
;   const unsigned sbase = (unsigned)(unsigned long)((__attribute__((address_space(3))) char*)smem);
;   const unsigned sq0 = (unsigned)((q ^ (l15 & 7)) << 4);
;   const unsigned a0 = sbase + (unsigned)((wm * 64 + l15) * 128) + sq0;
;   const unsigned b0 = sbase + 16384u + (unsigned)((wn * 32 + l15) * 128) + sq0;
;   asm volatile("s_waitcnt vmcnt(0)" ::: "memory");
;   __syncthreads();
	v_readfirstlane_b32 s4, v95
	s_mov_b32 m0, s4
	s_nop 0
	global_load_lds_dwordx4 v[10:11], off
	v_add_u32_e32 v10, 0x4000, v95
	v_and_b32_e32 v22, 15, v24
	v_readfirstlane_b32 s4, v10
	v_or_b32_e32 v10, 0x400, v95
	s_mov_b32 m0, s4
	v_readfirstlane_b32 s4, v10
	v_add_u32_e32 v10, 0x4400, v95
	global_load_lds_dwordx4 v[12:13], off
	s_mov_b32 m0, s4
	v_readfirstlane_b32 s4, v10
	v_or_b32_e32 v10, 0x800, v95
	global_load_lds_dwordx4 v[14:15], off
	s_mov_b32 m0, s4
	v_readfirstlane_b32 s4, v10
	v_add_u32_e32 v10, 0x4800, v95
	global_load_lds_dwordx4 v[16:17], off
	s_mov_b32 m0, s4
	v_readfirstlane_b32 s4, v10
	v_or_b32_e32 v10, 0xc00, v95
	global_load_lds_dwordx4 v[18:19], off
	s_mov_b32 m0, s4
	v_readfirstlane_b32 s4, v10
	global_load_lds_dwordx4 v[20:21], off
	s_mov_b32 m0, s4
	s_nop 0
	global_load_lds_dwordx4 v[4:5], off
	v_add_u32_e32 v4, 0x4c00, v95
	v_lshrrev_b32_e32 v5, 1, v24
	v_readfirstlane_b32 s4, v4
	s_mov_b32 m0, s4
	v_lshlrev_b32_e32 v4, 4, v24
	global_load_lds_dwordx4 v[8:9], off
	v_bitop3_b32 v4, v25, s31, v4 bitop3:0x48
	s_mov_b32 s4, 0x1ffffc0
	v_and_or_b32 v8, v7, 32, v22
	v_and_or_b32 v5, v5, s4, v22
	v_lshl_or_b32 v8, v8, 7, v4
	v_lshlrev_b32_e32 v5, 7, v5
	v_or_b32_e32 v97, 0x4000, v8
	v_bitop3_b32 v98, v8, 64, v219 bitop3:0x36
	v_or_b32_e32 v8, 24, v6
	v_or_b32_e32 v96, v4, v5
	v_bitop3_b32 v99, v4, 64, v5 bitop3:0x36
	v_add3_u32 v4, s1, v8, v7
	v_ashrrev_i32_e32 v5, 31, v4
	s_mov_b64 s[4:5], 0x80
	v_lshlrev_b64 v[4:5], 11, v[4:5]
	v_lshl_add_u64 v[2:3], v[2:3], 0, s[4:5]
	v_or_b32_e32 v4, v4, v180
	v_lshl_add_u64 v[76:77], v[2:3], 0, v[4:5]
	v_add3_u32 v4, s18, v8, v7
	v_ashrrev_i32_e32 v5, 31, v4
	v_lshlrev_b64 v[4:5], 11, v[4:5]
	v_lshl_add_u64 v[0:1], v[0:1], 0, s[4:5]
	v_or_b32_e32 v4, v4, v180
	v_or_b32_e32 v8, 16, v6
	v_lshl_add_u64 v[78:79], v[0:1], 0, v[4:5]
	v_add3_u32 v4, s1, v8, v7
	v_ashrrev_i32_e32 v5, 31, v4
	v_lshlrev_b64 v[4:5], 11, v[4:5]
	v_or_b32_e32 v4, v4, v180
	v_lshl_add_u64 v[80:81], v[2:3], 0, v[4:5]
	v_add3_u32 v4, s18, v8, v7
	v_ashrrev_i32_e32 v5, 31, v4
	v_lshlrev_b64 v[4:5], 11, v[4:5]
	v_or_b32_e32 v4, v4, v180
	v_or_b32_e32 v8, 8, v6
	v_lshl_add_u64 v[82:83], v[0:1], 0, v[4:5]
	v_add3_u32 v4, s1, v8, v7
	v_ashrrev_i32_e32 v5, 31, v4
	v_lshlrev_b64 v[4:5], 11, v[4:5]
	v_or_b32_e32 v4, v4, v180
	v_lshl_add_u64 v[84:85], v[2:3], 0, v[4:5]
	v_add3_u32 v4, s18, v8, v7
	v_ashrrev_i32_e32 v5, 31, v4
	v_lshlrev_b64 v[4:5], 11, v[4:5]
	v_or_b32_e32 v4, v4, v180
	v_lshl_add_u64 v[86:87], v[0:1], 0, v[4:5]
	v_add3_u32 v4, s1, v6, v7
	v_ashrrev_i32_e32 v5, 31, v4
	v_lshlrev_b64 v[4:5], 11, v[4:5]
	v_or_b32_e32 v4, v4, v180
	v_lshl_add_u64 v[88:89], v[2:3], 0, v[4:5]
	v_add3_u32 v2, s18, v6, v7
	v_ashrrev_i32_e32 v3, 31, v2
	v_lshlrev_b64 v[2:3], 11, v[2:3]
	v_or_b32_e32 v2, v2, v180
	v_lshl_add_u64 v[90:91], v[0:1], 0, v[2:3]
	v_mov_b32_e32 v0, 0
	s_mov_b64 s[4:5], 0
	v_mov_b32_e32 v1, v0
	v_mov_b32_e32 v2, v0
	v_mov_b32_e32 v3, v0
	v_mov_b32_e32 v4, v0
	v_mov_b32_e32 v5, v0
	v_mov_b32_e32 v6, v0
	v_mov_b32_e32 v7, v0
	v_mov_b32_e32 v8, v0
	v_mov_b32_e32 v9, v0
	v_mov_b32_e32 v10, v0
	v_mov_b32_e32 v11, v0
	v_mov_b32_e32 v12, v0
	v_mov_b32_e32 v13, v0
	v_mov_b32_e32 v14, v0
	v_mov_b32_e32 v15, v0
	v_mov_b32_e32 v16, v0
	v_mov_b32_e32 v17, v0
	v_mov_b32_e32 v18, v0
	v_mov_b32_e32 v19, v0
	v_mov_b32_e32 v20, v0
	v_mov_b32_e32 v21, v0
	v_mov_b32_e32 v22, v0
	v_mov_b32_e32 v23, v0
	v_mov_b32_e32 v24, v0
	v_mov_b32_e32 v25, v0
	v_mov_b32_e32 v26, v0
	v_mov_b32_e32 v27, v0
	v_mov_b32_e32 v28, v0
	v_mov_b32_e32 v29, v0
	v_mov_b32_e32 v30, v0
	v_mov_b32_e32 v31, v0
	v_mov_b32_e32 v32, v0
	v_mov_b32_e32 v33, v0
	v_mov_b32_e32 v34, v0
	v_mov_b32_e32 v35, v0
	v_mov_b32_e32 v36, v0
	v_mov_b32_e32 v37, v0
	v_mov_b32_e32 v38, v0
	v_mov_b32_e32 v39, v0
	v_mov_b32_e32 v40, v0
	v_mov_b32_e32 v41, v0
	v_mov_b32_e32 v42, v0
	v_mov_b32_e32 v43, v0
	v_mov_b32_e32 v44, v0
	v_mov_b32_e32 v45, v0
	v_mov_b32_e32 v46, v0
	v_mov_b32_e32 v47, v0
	v_mov_b32_e32 v48, v0
	v_mov_b32_e32 v49, v0
	v_mov_b32_e32 v50, v0
	v_mov_b32_e32 v51, v0
	v_mov_b32_e32 v52, v0
	v_mov_b32_e32 v53, v0
	v_mov_b32_e32 v54, v0
	v_mov_b32_e32 v55, v0
	v_mov_b32_e32 v56, v0
	v_mov_b32_e32 v57, v0
	v_mov_b32_e32 v58, v0
	v_mov_b32_e32 v59, v0
	v_mov_b32_e32 v60, v0
	v_mov_b32_e32 v61, v0
	v_mov_b32_e32 v62, v0
	v_mov_b32_e32 v63, v0
	v_readfirstlane_b32 s64, v90
	v_readfirstlane_b32 s65, v91
	v_readfirstlane_b32 s66, v88
	v_readfirstlane_b32 s67, v89
	v_readfirstlane_b32 s62, v95
	s_sub_u32 s64, s64, 0x80000000
	s_subb_u32 s65, s65, 0
	s_sub_u32 s66, s66, 0x80000000
	s_subb_u32 s67, s67, 0
	v_subrev_u32_e32 v90, s64, v90
	v_subrev_u32_e32 v88, s66, v88
	v_subrev_u32_e32 v86, s64, v86
	v_subrev_u32_e32 v84, s66, v84
	v_subrev_u32_e32 v82, s64, v82
	v_subrev_u32_e32 v80, s66, v80
	v_subrev_u32_e32 v78, s64, v78
	v_subrev_u32_e32 v76, s66, v76
	s_waitcnt vmcnt(0) lgkmcnt(0)
	s_barrier
; DEV f32x4 mma_step(bf16x8 a, bf16x8 b, f32x4 c) { return MFMA(a, b, c); }
; template <class FragT, class AccT>
; DEV void gemm_core_t(const char* __restrict__ A, size_t lda_bytes, const char* __restrict__ Bt, size_t ldb_bytes, int kbytes,
;                      int m0, int n0, int Sshift, int dl, char* smem, AccT (&acc)[4][4]) {
;     ...
;   for (int kt = 0; kt < nk; ++kt) {
;     const unsigned so = (unsigned)(kt & 1) * 32768u;
;     char* nxt = smem + ((kt + 1) & 1) * 32768;
;     if (kt + 1 < nk) {
; #pragma unroll
;       for (int u = 0; u < 4; ++u) {
;         __builtin_amdgcn_global_load_lds((const unsigned*)(ap[u] + (size_t)(kt + 1) * 128), (unsigned*)(nxt + (wid * 4 + u) * 1024 + lane * 16), 16, 0, 0);
;         __builtin_amdgcn_global_load_lds((const unsigned*)(bp[u] + (size_t)(kt + 1) * 128), (unsigned*)(nxt + 16384 + (wid * 4 + u) * 1024 + lane * 16), 16, 0, 0);
;       }
;     }
;     FragT xa[2][4], wb[2][4];
;     asm volatile(
;         "ds_read_b128 %0, %16\n\t"
;         "ds_read_b128 %1, %16 offset:2048\n\t"
;         "ds_read_b128 %2, %16 offset:4096\n\t"
;         "ds_read_b128 %3, %16 offset:6144\n\t"
;         "ds_read_b128 %4, %18\n\t"
;         "ds_read_b128 %5, %18 offset:2048\n\t"
;         "ds_read_b128 %6, %18 offset:8192\n\t"
;         "ds_read_b128 %7, %18 offset:10240\n\t"
;         "ds_read_b128 %8, %17\n\t"
;         "ds_read_b128 %9, %17 offset:2048\n\t"
;         "ds_read_b128 %10, %17 offset:4096\n\t"
;         "ds_read_b128 %11, %17 offset:6144\n\t"
;         "ds_read_b128 %12, %19\n\t"
;         "ds_read_b128 %13, %19 offset:2048\n\t"
;         "ds_read_b128 %14, %19 offset:8192\n\t"
;         "ds_read_b128 %15, %19 offset:10240\n\t"
;         "s_waitcnt lgkmcnt(8)"
;         : "=&v"(xa[0][0]), "=&v"(xa[0][1]), "=&v"(xa[0][2]), "=&v"(xa[0][3]), "=&v"(wb[0][0]), "=&v"(wb[0][1]), "=&v"(wb[0][2]),
;           "=&v"(wb[0][3]), "=&v"(xa[1][0]), "=&v"(xa[1][1]), "=&v"(xa[1][2]), "=&v"(xa[1][3]), "=&v"(wb[1][0]), "=&v"(wb[1][1]),
;           "=&v"(wb[1][2]), "=&v"(wb[1][3])
;         : "v"(a0 + so), "v"((a0 ^ 64u) + so), "v"(b0 + so), "v"((b0 ^ 64u) + so)
;         : "memory");
;     __builtin_amdgcn_s_setprio(1);
; #pragma unroll
;     for (int i = 0; i < 4; ++i)
; #pragma unroll
;       for (int j = 0; j < 4; ++j) acc[i][j] = mma_step(wb[0][j], xa[0][i], acc[i][j]);
;     asm volatile("s_waitcnt lgkmcnt(0)"
.LBB0_402:
	s_add_i32 s1, s16, 0xffff8000
	s_and_b32 s1, s1, 0x8000
	v_add_u32_e32 v164, s1, v96
	v_add_u32_e32 v165, s1, v99
	v_or_b32_e32 v166, s1, v97
	v_or_b32_e32 v167, s1, v98
	s_and_b32 s1, s16, 0x8000
	s_add_i32 s1, s1, s62
	s_mov_b32 m0, s1
	ds_read_b128 v[100:103], v164
	global_load_lds_dwordx4 v90, s[64:65]
	ds_read_b128 v[104:107], v164 offset:2048
	s_add_i32 m0, s1, 0x4000
	ds_read_b128 v[108:111], v164 offset:4096
	global_load_lds_dwordx4 v88, s[66:67]
	ds_read_b128 v[112:115], v164 offset:6144
	s_add_i32 m0, s1, 0x400
	ds_read_b128 v[116:119], v166
	global_load_lds_dwordx4 v86, s[64:65]
	ds_read_b128 v[120:123], v166 offset:2048
	s_add_i32 m0, s1, 0x4400
	ds_read_b128 v[124:127], v166 offset:8192
	global_load_lds_dwordx4 v84, s[66:67]
	ds_read_b128 v[128:131], v166 offset:10240
	ds_read_b128 v[132:135], v165
	ds_read_b128 v[136:139], v165 offset:2048
	ds_read_b128 v[140:143], v165 offset:4096
	ds_read_b128 v[144:147], v165 offset:6144
	ds_read_b128 v[148:151], v167
	ds_read_b128 v[152:155], v167 offset:2048
	ds_read_b128 v[156:159], v167 offset:8192
	ds_read_b128 v[160:163], v167 offset:10240
	s_waitcnt lgkmcnt(8)
	s_setprio 1
	v_mfma_f32_16x16x32_bf16 v[60:63], v[116:119], v[100:103], v[60:63]
	v_mfma_f32_16x16x32_bf16 v[56:59], v[120:123], v[100:103], v[56:59]
	s_add_i32 m0, s1, 0x800
	v_mfma_f32_16x16x32_bf16 v[52:55], v[124:127], v[100:103], v[52:55]
	global_load_lds_dwordx4 v82, s[64:65]
	v_mfma_f32_16x16x32_bf16 v[48:51], v[128:131], v[100:103], v[48:51]
	v_mfma_f32_16x16x32_bf16 v[44:47], v[116:119], v[104:107], v[44:47]
	v_mfma_f32_16x16x32_bf16 v[40:43], v[120:123], v[104:107], v[40:43]
	s_add_i32 m0, s1, 0x4800
	v_mfma_f32_16x16x32_bf16 v[36:39], v[124:127], v[104:107], v[36:39]
	global_load_lds_dwordx4 v80, s[66:67]
	v_mfma_f32_16x16x32_bf16 v[32:35], v[128:131], v[104:107], v[32:35]
	v_mfma_f32_16x16x32_bf16 v[28:31], v[116:119], v[108:111], v[28:31]
	v_mfma_f32_16x16x32_bf16 v[24:27], v[120:123], v[108:111], v[24:27]
	s_add_i32 m0, s1, 0xc00
	v_mfma_f32_16x16x32_bf16 v[20:23], v[124:127], v[108:111], v[20:23]
	global_load_lds_dwordx4 v78, s[64:65]
	v_mfma_f32_16x16x32_bf16 v[16:19], v[128:131], v[108:111], v[16:19]
	v_mfma_f32_16x16x32_bf16 v[12:15], v[116:119], v[112:115], v[12:15]
	v_mfma_f32_16x16x32_bf16 v[8:11], v[120:123], v[112:115], v[8:11]
	s_add_i32 m0, s1, 0x4c00
	v_mfma_f32_16x16x32_bf16 v[4:7], v[124:127], v[112:115], v[4:7]
	global_load_lds_dwordx4 v76, s[66:67]
	v_mfma_f32_16x16x32_bf16 v[0:3], v[128:131], v[112:115], v[0:3]
	s_waitcnt lgkmcnt(0)
	s_nop 0
	v_mfma_f32_16x16x32_bf16 v[60:63], v[148:151], v[132:135], v[60:63]
	v_mfma_f32_16x16x32_bf16 v[56:59], v[152:155], v[132:135], v[56:59]
	v_mfma_f32_16x16x32_bf16 v[52:55], v[156:159], v[132:135], v[52:55]
	v_mfma_f32_16x16x32_bf16 v[48:51], v[160:163], v[132:135], v[48:51]
	v_mfma_f32_16x16x32_bf16 v[44:47], v[148:151], v[136:139], v[44:47]
	v_mfma_f32_16x16x32_bf16 v[40:43], v[152:155], v[136:139], v[40:43]
	v_mfma_f32_16x16x32_bf16 v[36:39], v[156:159], v[136:139], v[36:39]
	v_mfma_f32_16x16x32_bf16 v[32:35], v[160:163], v[136:139], v[32:35]
	v_mfma_f32_16x16x32_bf16 v[28:31], v[148:151], v[140:143], v[28:31]
	v_mfma_f32_16x16x32_bf16 v[24:27], v[152:155], v[140:143], v[24:27]
	v_mfma_f32_16x16x32_bf16 v[20:23], v[156:159], v[140:143], v[20:23]
	v_mfma_f32_16x16x32_bf16 v[16:19], v[160:163], v[140:143], v[16:19]
	v_mfma_f32_16x16x32_bf16 v[12:15], v[148:151], v[144:147], v[12:15]
	v_mfma_f32_16x16x32_bf16 v[8:11], v[152:155], v[144:147], v[8:11]
	v_mfma_f32_16x16x32_bf16 v[4:7], v[156:159], v[144:147], v[4:7]
	v_mfma_f32_16x16x32_bf16 v[0:3], v[160:163], v[144:147], v[0:3]
	s_setprio 0
	s_waitcnt vmcnt(0)
	s_add_u32 s4, s4, 0x80
	s_addc_u32 s5, s5, 0
	s_add_u32 s64, s64, 0x80
	s_addc_u32 s65, s65, 0
	s_add_u32 s66, s66, 0x80
	s_addc_u32 s67, s67, 0
	s_add_i32 s16, s16, 0x8000
	s_cmpk_lg_i32 s4, 0x780
	s_waitcnt vmcnt(0) lgkmcnt(0)
	s_barrier
	s_cbranch_scc1 .LBB0_402
	v_add_u32_e32 v95, 0x8000, v96
	v_add_u32_e32 v144, 0x8000, v99
	v_or_b32_e32 v145, 0x8000, v97
	v_or_b32_e32 v146, 0x8000, v98
	ds_read_b128 v[76:79], v95
	ds_read_b128 v[80:83], v95 offset:2048
	ds_read_b128 v[84:87], v95 offset:4096
	ds_read_b128 v[88:91], v95 offset:6144
	ds_read_b128 v[96:99], v145
	ds_read_b128 v[100:103], v145 offset:2048
	ds_read_b128 v[104:107], v145 offset:8192
	ds_read_b128 v[108:111], v145 offset:10240
	ds_read_b128 v[112:115], v144
	ds_read_b128 v[116:119], v144 offset:2048
	ds_read_b128 v[120:123], v144 offset:4096
	ds_read_b128 v[124:127], v144 offset:6144
	ds_read_b128 v[128:131], v146
	ds_read_b128 v[132:135], v146 offset:2048
	ds_read_b128 v[136:139], v146 offset:8192
	ds_read_b128 v[140:143], v146 offset:10240
	s_waitcnt lgkmcnt(8)
	s_setprio 1
	v_mfma_f32_16x16x32_bf16 v[60:63], v[96:99], v[76:79], v[60:63]
	v_mfma_f32_16x16x32_bf16 v[56:59], v[100:103], v[76:79], v[56:59]
	v_mfma_f32_16x16x32_bf16 v[52:55], v[104:107], v[76:79], v[52:55]
	v_mfma_f32_16x16x32_bf16 v[48:51], v[108:111], v[76:79], v[48:51]
	v_mfma_f32_16x16x32_bf16 v[44:47], v[96:99], v[80:83], v[44:47]
	v_mfma_f32_16x16x32_bf16 v[40:43], v[100:103], v[80:83], v[40:43]
	v_mfma_f32_16x16x32_bf16 v[36:39], v[104:107], v[80:83], v[36:39]
	v_mfma_f32_16x16x32_bf16 v[32:35], v[108:111], v[80:83], v[32:35]
	v_mfma_f32_16x16x32_bf16 v[28:31], v[96:99], v[84:87], v[28:31]
	v_mfma_f32_16x16x32_bf16 v[24:27], v[100:103], v[84:87], v[24:27]
	v_mfma_f32_16x16x32_bf16 v[20:23], v[104:107], v[84:87], v[20:23]
	v_mfma_f32_16x16x32_bf16 v[16:19], v[108:111], v[84:87], v[16:19]
	v_mfma_f32_16x16x32_bf16 v[12:15], v[96:99], v[88:91], v[12:15]
	v_mfma_f32_16x16x32_bf16 v[8:11], v[100:103], v[88:91], v[8:11]
	v_mfma_f32_16x16x32_bf16 v[4:7], v[104:107], v[88:91], v[4:7]
	v_mfma_f32_16x16x32_bf16 v[0:3], v[108:111], v[88:91], v[0:3]
	s_waitcnt lgkmcnt(0)
	s_nop 0
	v_mfma_f32_16x16x32_bf16 v[60:63], v[128:131], v[112:115], v[60:63]
	v_mfma_f32_16x16x32_bf16 v[76:79], v[132:135], v[112:115], v[56:59]
	v_mfma_f32_16x16x32_bf16 v[80:83], v[136:139], v[112:115], v[52:55]
	v_mfma_f32_16x16x32_bf16 v[52:55], v[140:143], v[112:115], v[48:51]
	v_mfma_f32_16x16x32_bf16 v[48:51], v[128:131], v[116:119], v[44:47]
	v_mfma_f32_16x16x32_bf16 v[44:47], v[132:135], v[116:119], v[40:43]
	v_mfma_f32_16x16x32_bf16 v[40:43], v[136:139], v[116:119], v[36:39]
	v_mfma_f32_16x16x32_bf16 v[36:39], v[140:143], v[116:119], v[32:35]
	v_mfma_f32_16x16x32_bf16 v[32:35], v[128:131], v[120:123], v[28:31]
	v_mfma_f32_16x16x32_bf16 v[28:31], v[132:135], v[120:123], v[24:27]
	v_mfma_f32_16x16x32_bf16 v[24:27], v[136:139], v[120:123], v[20:23]
	v_mfma_f32_16x16x32_bf16 v[20:23], v[140:143], v[120:123], v[16:19]
	v_mfma_f32_16x16x32_bf16 v[16:19], v[128:131], v[124:127], v[12:15]
	v_mfma_f32_16x16x32_bf16 v[12:15], v[132:135], v[124:127], v[8:11]
	v_mfma_f32_16x16x32_bf16 v[8:11], v[136:139], v[124:127], v[4:7]
	v_mfma_f32_16x16x32_bf16 v[4:7], v[140:143], v[124:127], v[0:3]
	s_setprio 0
	s_waitcnt vmcnt(0)
	s_barrier
; DEV float bflo(unsigned u) { return __uint_as_float(u << 16); }
; DEV float bfhi(unsigned u) { return __uint_as_float(u & 0xffff0000u); }
; #define P (*launderP(lp))
; __device__ __forceinline__ void phase_gemm2(PREF P, char* smem) {
;     ...
; #pragma unroll
;     for (int i = 0; i < 4; ++i)
; #pragma unroll
;       for (int j = 0; j < 4; ++j) {
;         const int row = m0 + wm * 64 + i * 16 + l15, col = n0 + (j & 1) * 16 + wn * 32 + (j >> 1) * 64 + q * 4;
;         const unsigned g = *(const unsigned*)((const u8*)P.GB + (size_t)row * 2048 + col);
;         uint2 pr = *(const uint2*)(P.merged + (size_t)row * 2048 + col);
;         f32x4 v;
;         v[0] = bflo(pr.x) + (float)(g & 255u) * (1.f / 255.f) * acc[i][j][0];
;         v[1] = bfhi(pr.x) + (float)((g >> 8) & 255u) * (1.f / 255.f) * acc[i][j][1];
;         v[2] = bflo(pr.y) + (float)((g >> 16) & 255u) * (1.f / 255.f) * acc[i][j][2];
;         v[3] = bfhi(pr.y) + (float)(g >> 24) * (1.f / 255.f) * acc[i][j][3];
;         acc[i][j] = v;
;       }
	s_nop 0
	ds_read2_b64 v[0:3], v92 offset0:38 offset1:42
	s_mov_b32 s4, 0x3b808081
	s_mov_b32 s1, 0xfffffc0
	s_waitcnt lgkmcnt(0)
	v_lshl_add_u64 v[56:57], v[0:1], 0, v[68:69]
	v_lshl_add_u64 v[58:59], v[68:69], 1, v[2:3]
	v_lshl_add_u64 v[84:85], v[56:57], 0, v[64:65]
	flat_load_dword v88, v[84:85]
	v_lshl_add_u64 v[86:87], v[58:59], 0, v[66:67]
	flat_load_dwordx2 v[58:59], v[86:87]
	s_waitcnt vmcnt(0) lgkmcnt(0)
	v_cvt_f32_ubyte1_e32 v69, v88
	v_cvt_f32_ubyte0_e32 v68, v88
	v_lshlrev_b32_e32 v56, 16, v58
	v_and_b32_e32 v57, 0xffff0000, v58
	v_mul_f32_e32 v68, s4, v68
	v_mul_f32_e32 v69, s4, v69
	v_lshlrev_b32_e32 v58, 16, v59
	v_fmac_f32_e32 v56, v60, v68
	v_fmac_f32_e32 v57, v61, v69
	v_cvt_f32_ubyte3_e32 v61, v88
	v_cvt_f32_ubyte2_e32 v60, v88
	v_and_b32_e32 v59, 0xffff0000, v59
	v_mul_f32_e32 v60, s4, v60
	v_mul_f32_e32 v61, s4, v61
	s_nop 0
	v_fmac_f32_e32 v58, v62, v60
	v_fmac_f32_e32 v59, v63, v61
	flat_load_dword v88, v[84:85] offset:16
	flat_load_dwordx2 v[62:63], v[86:87] offset:32
	s_waitcnt vmcnt(0) lgkmcnt(0)
	v_cvt_f32_ubyte1_e32 v69, v88
	v_cvt_f32_ubyte0_e32 v68, v88
	v_lshlrev_b32_e32 v60, 16, v62
	v_and_b32_e32 v61, 0xffff0000, v62
	v_mul_f32_e32 v68, s4, v68
	v_mul_f32_e32 v69, s4, v69
	v_lshlrev_b32_e32 v62, 16, v63
	v_fmac_f32_e32 v60, v76, v68
	v_fmac_f32_e32 v61, v77, v69
	v_cvt_f32_ubyte3_e32 v69, v88
	v_cvt_f32_ubyte2_e32 v68, v88
	flat_load_dword v88, v[84:85] offset:64
	flat_load_dwordx2 v[76:77], v[86:87] offset:128
	v_and_b32_e32 v63, 0xffff0000, v63
	v_mul_f32_e32 v68, s4, v68
	v_mul_f32_e32 v69, s4, v69
	s_nop 0
	v_fmac_f32_e32 v62, v78, v68
	v_fmac_f32_e32 v63, v79, v69
	s_waitcnt vmcnt(0) lgkmcnt(0)
	v_cvt_f32_ubyte1_e32 v79, v88
	v_cvt_f32_ubyte0_e32 v78, v88
	v_lshlrev_b32_e32 v68, 16, v76
	v_and_b32_e32 v69, 0xffff0000, v76
	v_mul_f32_e32 v78, s4, v78
	v_mul_f32_e32 v79, s4, v79
	v_lshlrev_b32_e32 v76, 16, v77
	v_fmac_f32_e32 v68, v80, v78
	v_fmac_f32_e32 v69, v81, v79
	v_cvt_f32_ubyte3_e32 v79, v88
	v_cvt_f32_ubyte2_e32 v78, v88
	v_and_b32_e32 v77, 0xffff0000, v77
	v_mul_f32_e32 v78, s4, v78
	v_mul_f32_e32 v79, s4, v79
	s_nop 0
	v_fmac_f32_e32 v76, v82, v78
	v_fmac_f32_e32 v77, v83, v79
	flat_load_dword v84, v[84:85] offset:80
	s_nop 0
	flat_load_dwordx2 v[78:79], v[86:87] offset:160
	s_waitcnt vmcnt(0) lgkmcnt(0)
	v_cvt_f32_ubyte1_e32 v83, v84
	v_cvt_f32_ubyte0_e32 v82, v84
	v_lshlrev_b32_e32 v80, 16, v78
	v_and_b32_e32 v81, 0xffff0000, v78
	v_mul_f32_e32 v82, s4, v82
	v_mul_f32_e32 v83, s4, v83
	v_lshlrev_b32_e32 v78, 16, v79
	v_fma_f32 v52, v52, v82, v80
	v_fma_f32 v53, v53, v83, v81
	v_cvt_f32_ubyte3_e32 v81, v84
	v_cvt_f32_ubyte2_e32 v80, v84
	v_and_b32_e32 v79, 0xffff0000, v79
	v_mul_f32_e32 v80, s4, v80
	v_mul_f32_e32 v81, s4, v81
	v_cvt_pk_bf16_f32 v52, v52, v53
	v_fma_f32 v54, v54, v80, v78
	v_fma_f32 v55, v55, v81, v79
	v_lshl_add_u64 v[78:79], v[0:1], 0, v[72:73]
	v_lshl_add_u64 v[72:73], v[72:73], 1, v[2:3]
	v_lshl_add_u64 v[78:79], v[78:79], 0, v[64:65]
	flat_load_dword v86, v[78:79]
	v_lshl_add_u64 v[72:73], v[72:73], 0, v[66:67]
	flat_load_dwordx2 v[80:81], v[72:73]
	v_cvt_pk_bf16_f32 v53, v54, v55
	s_waitcnt vmcnt(0) lgkmcnt(0)
	v_cvt_f32_ubyte1_e32 v85, v86
	v_cvt_f32_ubyte0_e32 v84, v86
	v_lshlrev_b32_e32 v82, 16, v80
	v_and_b32_e32 v83, 0xffff0000, v80
	v_mul_f32_e32 v84, s4, v84
	v_mul_f32_e32 v85, s4, v85
	v_lshlrev_b32_e32 v80, 16, v81
	v_fma_f32 v48, v48, v84, v82
	v_fma_f32 v49, v49, v85, v83
	v_cvt_f32_ubyte3_e32 v83, v86
	v_cvt_f32_ubyte2_e32 v82, v86
	v_and_b32_e32 v81, 0xffff0000, v81
	v_mul_f32_e32 v82, s4, v82
	v_mul_f32_e32 v83, s4, v83
	s_nop 0
	v_fma_f32 v50, v50, v82, v80
	v_fma_f32 v51, v51, v83, v81
	flat_load_dword v86, v[78:79] offset:16
	flat_load_dwordx2 v[80:81], v[72:73] offset:32
	s_waitcnt vmcnt(0) lgkmcnt(0)
	v_cvt_f32_ubyte1_e32 v85, v86
	v_cvt_f32_ubyte0_e32 v84, v86
	v_lshlrev_b32_e32 v82, 16, v80
	v_and_b32_e32 v83, 0xffff0000, v80
	v_mul_f32_e32 v84, s4, v84
	v_mul_f32_e32 v85, s4, v85
	v_lshlrev_b32_e32 v80, 16, v81
	v_fma_f32 v44, v44, v84, v82
	v_fma_f32 v45, v45, v85, v83
	v_cvt_f32_ubyte3_e32 v83, v86
	v_cvt_f32_ubyte2_e32 v82, v86
	v_and_b32_e32 v81, 0xffff0000, v81
	v_mul_f32_e32 v82, s4, v82
	v_mul_f32_e32 v83, s4, v83
	v_cvt_pk_bf16_f32 v44, v44, v45
	v_fma_f32 v46, v46, v82, v80
	v_fma_f32 v47, v47, v83, v81
	flat_load_dword v86, v[78:79] offset:64
	flat_load_dwordx2 v[80:81], v[72:73] offset:128
	v_cvt_pk_bf16_f32 v45, v46, v47
	s_waitcnt vmcnt(0) lgkmcnt(0)
	v_cvt_f32_ubyte1_e32 v85, v86
	v_cvt_f32_ubyte0_e32 v84, v86
	v_lshlrev_b32_e32 v82, 16, v80
	v_and_b32_e32 v83, 0xffff0000, v80
	v_mul_f32_e32 v84, s4, v84
	v_mul_f32_e32 v85, s4, v85
	v_lshlrev_b32_e32 v80, 16, v81
	v_fma_f32 v40, v40, v84, v82
	v_fma_f32 v41, v41, v85, v83
	v_cvt_f32_ubyte3_e32 v83, v86
	v_cvt_f32_ubyte2_e32 v82, v86
	v_and_b32_e32 v81, 0xffff0000, v81
	v_mul_f32_e32 v82, s4, v82
	v_mul_f32_e32 v83, s4, v83
	s_nop 0
	v_fma_f32 v42, v42, v82, v80
	v_fma_f32 v43, v43, v83, v81
	flat_load_dword v82, v[78:79] offset:80
	s_nop 0
	flat_load_dwordx2 v[72:73], v[72:73] offset:160
	s_waitcnt vmcnt(0) lgkmcnt(0)
	v_cvt_f32_ubyte1_e32 v81, v82
	v_cvt_f32_ubyte0_e32 v80, v82
	v_lshlrev_b32_e32 v78, 16, v72
	v_and_b32_e32 v79, 0xffff0000, v72
	v_mul_f32_e32 v80, s4, v80
	v_mul_f32_e32 v81, s4, v81
	v_lshlrev_b32_e32 v72, 16, v73
	v_fma_f32 v36, v36, v80, v78
	v_fma_f32 v37, v37, v81, v79
	v_cvt_f32_ubyte3_e32 v79, v82
	v_cvt_f32_ubyte2_e32 v78, v82
	v_and_b32_e32 v73, 0xffff0000, v73
	v_mul_f32_e32 v78, s4, v78
	v_mul_f32_e32 v79, s4, v79
	v_cvt_pk_bf16_f32 v36, v36, v37
	v_fma_f32 v38, v38, v78, v72
	v_fma_f32 v39, v39, v79, v73
	v_lshl_add_u64 v[72:73], v[0:1], 0, v[74:75]
	v_lshl_add_u64 v[78:79], v[74:75], 1, v[2:3]
	v_lshl_add_u64 v[74:75], v[72:73], 0, v[64:65]
	flat_load_dword v84, v[74:75]
	v_lshl_add_u64 v[72:73], v[78:79], 0, v[66:67]
	flat_load_dwordx2 v[78:79], v[72:73]
	v_lshl_add_u64 v[0:1], v[0:1], 0, v[70:71]
	v_lshl_add_u64 v[70:71], v[70:71], 1, v[2:3]
	v_cvt_pk_bf16_f32 v37, v38, v39
	s_waitcnt vmcnt(0) lgkmcnt(0)
; DEV int tid_() { int t = threadIdx.x; asm volatile("" : "+v"(t)); return t; }
; DEV float bflo(unsigned u) { return __uint_as_float(u << 16); }
; DEV float bfhi(unsigned u) { return __uint_as_float(u & 0xffff0000u); }
; #define P (*launderP(lp))
; DEV void stage_tile_bf16(char* smem, const f32x4 (&v)[4][4], u16* buf, int ld, int m0, int col0) {
;   const int tid = tid_(), lane = tid & 63, wid = tid >> 6, wm = wid >> 1, wn = wid & 1, l15 = lane & 15, q = lane >> 4;
; #pragma unroll
;   for (int i = 0; i < 4; ++i)
; #pragma unroll
;     for (int j = 0; j < 4; ++j) {
;       const int rl = wm * 64 + i * 16 + l15, cl = (j & 1) * 16 + wn * 32 + (j >> 1) * 64 + q * 4;
;       u32x2 o; o.x = pack2(v[i][j][0], v[i][j][1]); o.y = pack2(v[i][j][2], v[i][j][3]);
;       *(u32x2*)(smem + rl * 272 + cl * 2) = o;
;     }
;   __syncthreads();
; __device__ __forceinline__ void phase_gemm2(PREF P, char* smem) {
;     ...
; #pragma unroll
;     for (int i = 0; i < 4; ++i)
; #pragma unroll
;       for (int j = 0; j < 4; ++j) {
;         const int row = m0 + wm * 64 + i * 16 + l15, col = n0 + (j & 1) * 16 + wn * 32 + (j >> 1) * 64 + q * 4;
;         const unsigned g = *(const unsigned*)((const u8*)P.GB + (size_t)row * 2048 + col);
;         uint2 pr = *(const uint2*)(P.merged + (size_t)row * 2048 + col);
;         f32x4 v;
;         v[0] = bflo(pr.x) + (float)(g & 255u) * (1.f / 255.f) * acc[i][j][0];
;         v[1] = bfhi(pr.x) + (float)((g >> 8) & 255u) * (1.f / 255.f) * acc[i][j][1];
;         v[2] = bflo(pr.y) + (float)((g >> 16) & 255u) * (1.f / 255.f) * acc[i][j][2];
;         v[3] = bfhi(pr.y) + (float)(g >> 24) * (1.f / 255.f) * acc[i][j][3];
;         acc[i][j] = v;
;       }
	v_cvt_f32_ubyte1_e32 v83, v84
	v_cvt_f32_ubyte0_e32 v82, v84
	v_lshlrev_b32_e32 v80, 16, v78
	v_and_b32_e32 v81, 0xffff0000, v78
	v_mul_f32_e32 v82, s4, v82
	v_mul_f32_e32 v83, s4, v83
	v_lshlrev_b32_e32 v78, 16, v79
	v_fma_f32 v32, v32, v82, v80
	v_fma_f32 v33, v33, v83, v81
	v_cvt_f32_ubyte3_e32 v81, v84
	v_cvt_f32_ubyte2_e32 v80, v84
	v_and_b32_e32 v79, 0xffff0000, v79
	v_mul_f32_e32 v80, s4, v80
	v_mul_f32_e32 v81, s4, v81
	s_nop 0
	v_fma_f32 v34, v34, v80, v78
	v_fma_f32 v35, v35, v81, v79
	flat_load_dword v84, v[74:75] offset:16
	flat_load_dwordx2 v[78:79], v[72:73] offset:32
	s_waitcnt vmcnt(0) lgkmcnt(0)
	v_cvt_f32_ubyte1_e32 v83, v84
	v_cvt_f32_ubyte0_e32 v82, v84
	v_lshlrev_b32_e32 v80, 16, v78
	v_and_b32_e32 v81, 0xffff0000, v78
	v_mul_f32_e32 v82, s4, v82
	v_mul_f32_e32 v83, s4, v83
	v_lshlrev_b32_e32 v78, 16, v79
	v_fma_f32 v28, v28, v82, v80
	v_fma_f32 v29, v29, v83, v81
	v_cvt_f32_ubyte3_e32 v81, v84
	v_cvt_f32_ubyte2_e32 v80, v84
	v_and_b32_e32 v79, 0xffff0000, v79
	v_mul_f32_e32 v80, s4, v80
	v_mul_f32_e32 v81, s4, v81
	v_cvt_pk_bf16_f32 v28, v28, v29
	v_fma_f32 v30, v30, v80, v78
	v_fma_f32 v31, v31, v81, v79
	flat_load_dword v84, v[74:75] offset:64
	flat_load_dwordx2 v[78:79], v[72:73] offset:128
	v_cvt_pk_bf16_f32 v29, v30, v31
	s_waitcnt vmcnt(0) lgkmcnt(0)
	v_cvt_f32_ubyte1_e32 v83, v84
	v_cvt_f32_ubyte0_e32 v82, v84
	v_lshlrev_b32_e32 v80, 16, v78
	v_and_b32_e32 v81, 0xffff0000, v78
	v_mul_f32_e32 v82, s4, v82
	v_mul_f32_e32 v83, s4, v83
	v_lshlrev_b32_e32 v78, 16, v79
	v_fma_f32 v24, v24, v82, v80
	v_fma_f32 v25, v25, v83, v81
	v_cvt_f32_ubyte3_e32 v81, v84
	v_cvt_f32_ubyte2_e32 v80, v84
	v_and_b32_e32 v79, 0xffff0000, v79
	v_mul_f32_e32 v80, s4, v80
	v_mul_f32_e32 v81, s4, v81
	s_nop 0
	v_fma_f32 v26, v26, v80, v78
	v_fma_f32 v27, v27, v81, v79
	flat_load_dword v80, v[74:75] offset:80
	s_nop 0
	flat_load_dwordx2 v[72:73], v[72:73] offset:160
	s_waitcnt vmcnt(0) lgkmcnt(0)
	v_cvt_f32_ubyte1_e32 v79, v80
	v_cvt_f32_ubyte0_e32 v78, v80
	v_lshlrev_b32_e32 v74, 16, v72
	v_and_b32_e32 v75, 0xffff0000, v72
	v_mul_f32_e32 v78, s4, v78
	v_mul_f32_e32 v79, s4, v79
	v_lshlrev_b32_e32 v72, 16, v73
	v_fma_f32 v20, v20, v78, v74
	v_fma_f32 v21, v21, v79, v75
	v_cvt_f32_ubyte3_e32 v75, v80
	v_cvt_f32_ubyte2_e32 v74, v80
	v_and_b32_e32 v73, 0xffff0000, v73
	v_mul_f32_e32 v74, s4, v74
	v_mul_f32_e32 v75, s4, v75
	v_cvt_pk_bf16_f32 v20, v20, v21
	v_fma_f32 v22, v22, v74, v72
	v_fma_f32 v23, v23, v75, v73
	v_lshl_add_u64 v[72:73], v[0:1], 0, v[64:65]
	flat_load_dword v74, v[72:73]
	v_lshl_add_u64 v[64:65], v[70:71], 0, v[66:67]
	flat_load_dwordx2 v[66:67], v[64:65]
	v_cvt_pk_bf16_f32 v21, v22, v23
	s_waitcnt vmcnt(0) lgkmcnt(0)
	v_cvt_f32_ubyte1_e32 v71, v74
	v_cvt_f32_ubyte0_e32 v70, v74
	v_lshlrev_b32_e32 v0, 16, v66
	v_and_b32_e32 v1, 0xffff0000, v66
	v_mul_f32_e32 v70, s4, v70
	v_mul_f32_e32 v71, s4, v71
	v_cvt_f32_ubyte2_e32 v66, v74
	v_fmac_f32_e32 v0, v16, v70
	v_fmac_f32_e32 v1, v17, v71
	v_lshlrev_b32_e32 v16, 16, v67
	v_and_b32_e32 v17, 0xffff0000, v67
	v_cvt_f32_ubyte3_e32 v67, v74
	v_mul_f32_e32 v66, s4, v66
	v_mul_f32_e32 v67, s4, v67
	v_cvt_pk_bf16_f32 v0, v0, v1
	v_fmac_f32_e32 v16, v18, v66
	v_fmac_f32_e32 v17, v19, v67
	flat_load_dword v74, v[72:73] offset:16
	flat_load_dwordx2 v[18:19], v[64:65] offset:32
	v_cvt_pk_bf16_f32 v1, v16, v17
	s_waitcnt vmcnt(0) lgkmcnt(0)
	v_cvt_f32_ubyte1_e32 v71, v74
	v_cvt_f32_ubyte0_e32 v70, v74
	v_lshlrev_b32_e32 v66, 16, v18
	v_and_b32_e32 v67, 0xffff0000, v18
	v_mul_f32_e32 v70, s4, v70
	v_mul_f32_e32 v71, s4, v71
	v_lshlrev_b32_e32 v18, 16, v19
	v_fma_f32 v12, v12, v70, v66
	v_fma_f32 v13, v13, v71, v67
	v_cvt_f32_ubyte3_e32 v67, v74
	v_cvt_f32_ubyte2_e32 v66, v74
	v_and_b32_e32 v19, 0xffff0000, v19
	v_mul_f32_e32 v66, s4, v66
	v_mul_f32_e32 v67, s4, v67
	v_cvt_pk_bf16_f32 v12, v12, v13
	v_fma_f32 v14, v14, v66, v18
	v_fma_f32 v15, v15, v67, v19
	flat_load_dword v74, v[72:73] offset:64
	flat_load_dwordx2 v[18:19], v[64:65] offset:128
	v_cvt_pk_bf16_f32 v13, v14, v15
	s_waitcnt vmcnt(0) lgkmcnt(0)
	v_cvt_f32_ubyte1_e32 v71, v74
	v_cvt_f32_ubyte0_e32 v70, v74
	v_lshlrev_b32_e32 v66, 16, v18
	v_and_b32_e32 v67, 0xffff0000, v18
	v_mul_f32_e32 v70, s4, v70
	v_mul_f32_e32 v71, s4, v71
	v_lshlrev_b32_e32 v18, 16, v19
	v_fma_f32 v8, v8, v70, v66
	v_fma_f32 v9, v9, v71, v67
	v_cvt_f32_ubyte3_e32 v67, v74
	v_cvt_f32_ubyte2_e32 v66, v74
	v_and_b32_e32 v19, 0xffff0000, v19
	v_mul_f32_e32 v66, s4, v66
	v_mul_f32_e32 v67, s4, v67
	s_nop 0
	v_fma_f32 v10, v10, v66, v18
	v_fma_f32 v11, v11, v67, v19
	flat_load_dword v70, v[72:73] offset:80
	flat_load_dwordx2 v[18:19], v[64:65] offset:160
	s_waitcnt vmcnt(0) lgkmcnt(0)
	v_cvt_f32_ubyte1_e32 v67, v70
	v_cvt_f32_ubyte0_e32 v66, v70
	v_lshlrev_b32_e32 v64, 16, v18
	v_and_b32_e32 v65, 0xffff0000, v18
	v_mul_f32_e32 v66, s4, v66
	v_mul_f32_e32 v67, s4, v67
	v_lshlrev_b32_e32 v18, 16, v19
	v_fma_f32 v4, v4, v66, v64
	v_fma_f32 v5, v5, v67, v65
	v_cvt_f32_ubyte3_e32 v65, v70
	v_cvt_f32_ubyte2_e32 v64, v70
	v_and_b32_e32 v19, 0xffff0000, v19
	v_mul_f32_e32 v64, s4, v64
	v_mul_f32_e32 v65, s4, v65
	v_cvt_pk_bf16_f32 v4, v4, v5
	v_fma_f32 v6, v6, v64, v18
	v_fma_f32 v7, v7, v65, v19
	v_mov_b32_e32 v64, v188
	v_cvt_pk_bf16_f32 v18, v56, v57
	v_and_b32_e32 v65, 15, v64
	v_lshrrev_b32_e32 v66, 1, v64
	v_and_b32_e32 v56, 64, v64
	v_and_or_b32 v67, v66, s1, v65
	v_and_or_b32 v56, v66, 24, v56
	v_cvt_pk_bf16_f32 v19, v58, v59
	v_mad_u64_u32 v[56:57], s[4:5], v67, s11, v[56:57]
	v_cvt_pk_bf16_f32 v58, v60, v61
	v_cvt_pk_bf16_f32 v59, v62, v63
	ds_write2_b64 v56, v[18:19], v[58:59] offset1:4
	v_cvt_pk_bf16_f32 v18, v68, v69
	v_cvt_pk_bf16_f32 v19, v76, v77
	ds_write2_b64 v56, v[18:19], v[52:53] offset0:16 offset1:20
	v_cvt_pk_bf16_f32 v18, v48, v49
	v_cvt_pk_bf16_f32 v19, v50, v51
	v_add_u32_e32 v46, 0x1000, v56
	v_add_u32_e32 v14, 0x3000, v56
	ds_write2_b64 v46, v[18:19], v[44:45] offset0:32 offset1:36
	v_cvt_pk_bf16_f32 v18, v40, v41
	v_cvt_pk_bf16_f32 v19, v42, v43
	ds_write2_b64 v14, v[0:1], v[12:13] offset0:96 offset1:100
	v_cvt_pk_bf16_f32 v0, v8, v9
	v_cvt_pk_bf16_f32 v1, v10, v11
	v_cvt_pk_bf16_f32 v5, v6, v7
	s_ashr_i32 s1, s0, 31
	ds_write2_b64 v46, v[18:19], v[36:37] offset0:48 offset1:52
	v_cvt_pk_bf16_f32 v18, v32, v33
	v_cvt_pk_bf16_f32 v19, v34, v35
	v_add_u32_e32 v30, 0x2000, v56
	ds_write2_b64 v14, v[0:1], v[4:5] offset0:112 offset1:116
	v_lshlrev_b32_e32 v180, 4, v65
	v_lshl_add_u64 v[0:1], s[0:1], 1, v[2:3]
	v_ashrrev_i32_e32 v6, 4, v64
	ds_write2_b64 v30, v[18:19], v[28:29] offset0:64 offset1:68
	v_cvt_pk_bf16_f32 v18, v24, v25
	v_cvt_pk_bf16_f32 v19, v26, v27
	v_lshl_add_u64 v[4:5], v[0:1], 0, v[180:181]
	v_mad_u64_u32 v[0:1], s[0:1], v6, s11, v[180:181]
	ds_write2_b64 v30, v[18:19], v[20:21] offset0:80 offset1:84
	s_waitcnt lgkmcnt(0)
	s_barrier
; DEV void stage_tile_bf16(char* smem, const f32x4 (&v)[4][4], u16* buf, int ld, int m0, int col0) {
;     ...
; #pragma unroll
;   for (int k = 0; k < 8; ++k) {
;     const int chunk = tid + 256 * k, rl = chunk >> 4, c16 = chunk & 15;
;     u32x4 d = *(const u32x4*)(smem + rl * 272 + c16 * 16);
;     *(u32x4*)(buf + (size_t)(m0 + rl) * ld + col0 + c16 * 8) = d;
;   }
	ds_read_b128 v[0:3], v0
	v_add_u32_e32 v6, s15, v6
	v_ashrrev_i32_e32 v7, 31, v6
	v_lshlrev_b64 v[6:7], 12, v[6:7]
	v_lshl_add_u64 v[6:7], v[4:5], 0, v[6:7]
	s_waitcnt lgkmcnt(0)
	flat_store_dwordx4 v[6:7], v[0:3]
	s_nop 1
	v_add_u32_e32 v0, 0x100, v64
	v_ashrrev_i32_e32 v6, 4, v0
	v_mad_u64_u32 v[0:1], s[0:1], v6, s11, v[180:181]
	ds_read_b128 v[0:3], v0
	v_add_u32_e32 v6, s15, v6
	v_ashrrev_i32_e32 v7, 31, v6
	v_lshlrev_b64 v[6:7], 12, v[6:7]
	v_lshl_add_u64 v[6:7], v[4:5], 0, v[6:7]
	s_waitcnt lgkmcnt(0)
	flat_store_dwordx4 v[6:7], v[0:3]
	s_nop 1
	v_add_u32_e32 v0, 0x200, v64
	v_ashrrev_i32_e32 v6, 4, v0
	v_mad_u64_u32 v[0:1], s[0:1], v6, s11, v[180:181]
	ds_read_b128 v[0:3], v0
	v_add_u32_e32 v6, s15, v6
	v_ashrrev_i32_e32 v7, 31, v6
	v_lshlrev_b64 v[6:7], 12, v[6:7]
	v_lshl_add_u64 v[6:7], v[4:5], 0, v[6:7]
	s_waitcnt lgkmcnt(0)
	flat_store_dwordx4 v[6:7], v[0:3]
	s_nop 1
	v_add_u32_e32 v0, 0x300, v64
	v_ashrrev_i32_e32 v6, 4, v0
	v_mad_u64_u32 v[0:1], s[0:1], v6, s11, v[180:181]
	ds_read_b128 v[0:3], v0
	v_add_u32_e32 v6, s15, v6
	v_ashrrev_i32_e32 v7, 31, v6
	v_lshlrev_b64 v[6:7], 12, v[6:7]
	v_lshl_add_u64 v[6:7], v[4:5], 0, v[6:7]
	s_waitcnt lgkmcnt(0)
	flat_store_dwordx4 v[6:7], v[0:3]
	s_nop 1
	v_add_u32_e32 v0, 0x400, v64
	v_ashrrev_i32_e32 v6, 4, v0
	v_mad_u64_u32 v[0:1], s[0:1], v6, s11, v[180:181]
	ds_read_b128 v[0:3], v0
	v_add_u32_e32 v6, s15, v6
	v_ashrrev_i32_e32 v7, 31, v6
	v_lshlrev_b64 v[6:7], 12, v[6:7]
	v_lshl_add_u64 v[6:7], v[4:5], 0, v[6:7]
	s_waitcnt lgkmcnt(0)
	flat_store_dwordx4 v[6:7], v[0:3]
	s_nop 1
	v_add_u32_e32 v0, 0x500, v64
	v_ashrrev_i32_e32 v6, 4, v0
	v_mad_u64_u32 v[0:1], s[0:1], v6, s11, v[180:181]
	ds_read_b128 v[0:3], v0
	v_add_u32_e32 v6, s15, v6
	v_ashrrev_i32_e32 v7, 31, v6
	v_lshlrev_b64 v[6:7], 12, v[6:7]
	v_lshl_add_u64 v[6:7], v[4:5], 0, v[6:7]
	s_waitcnt lgkmcnt(0)
	flat_store_dwordx4 v[6:7], v[0:3]
	s_nop 1
	v_add_u32_e32 v0, 0x600, v64
	v_ashrrev_i32_e32 v6, 4, v0
	v_mad_u64_u32 v[0:1], s[0:1], v6, s11, v[180:181]
	ds_read_b128 v[0:3], v0
	v_add_u32_e32 v6, s15, v6
	v_ashrrev_i32_e32 v7, 31, v6
	v_lshlrev_b64 v[6:7], 12, v[6:7]
	v_lshl_add_u64 v[6:7], v[4:5], 0, v[6:7]
	s_waitcnt lgkmcnt(0)
	flat_store_dwordx4 v[6:7], v[0:3]
	s_nop 1
	v_add_u32_e32 v0, 0x700, v64
	v_ashrrev_i32_e32 v6, 4, v0
	v_mad_u64_u32 v[0:1], s[0:1], v6, s11, v[180:181]
	ds_read_b128 v[0:3], v0
	v_add_u32_e32 v6, s15, v6
	v_ashrrev_i32_e32 v7, 31, v6
	v_lshlrev_b64 v[6:7], 12, v[6:7]
	v_lshl_add_u64 v[4:5], v[4:5], 0, v[6:7]
	v_readlane_b32 s0, v251, 6
	s_waitcnt lgkmcnt(0)
	flat_store_dwordx4 v[4:5], v[0:3]
	s_add_i32 s14, s0, s14
	s_cmpk_lt_i32 s14, 0x400
	v_readlane_b32 s1, v251, 7
	s_cbranch_scc1 .LBB0_399

; DEV f32x4 mma_step(bf16x8 a, bf16x8 b, f32x4 c) { return MFMA(a, b, c); }
; template <class FragT, class AccT>
; DEV void gemm_core_t(const char* __restrict__ A, size_t lda_bytes, const char* __restrict__ Bt, size_t ldb_bytes, int kbytes,
;                      int m0, int n0, int Sshift, int dl, char* smem, AccT (&acc)[4][4]) {
;     ...
;   for (int kt = 0; kt < nk; ++kt) {
;     const unsigned so = (unsigned)(kt & 1) * 32768u;
;     char* nxt = smem + ((kt + 1) & 1) * 32768;
;     if (kt + 1 < nk) {
; #pragma unroll
;       for (int u = 0; u < 4; ++u) {
;         __builtin_amdgcn_global_load_lds((const unsigned*)(ap[u] + (size_t)(kt + 1) * 128), (unsigned*)(nxt + (wid * 4 + u) * 1024 + lane * 16), 16, 0, 0);
;         __builtin_amdgcn_global_load_lds((const unsigned*)(bp[u] + (size_t)(kt + 1) * 128), (unsigned*)(nxt + 16384 + (wid * 4 + u) * 1024 + lane * 16), 16, 0, 0);
;       }
;     }
;     FragT xa[2][4], wb[2][4];
;     asm volatile(
;         "ds_read_b128 %0, %16\n\t"
;         "ds_read_b128 %1, %16 offset:2048\n\t"
;         "ds_read_b128 %2, %16 offset:4096\n\t"
;         "ds_read_b128 %3, %16 offset:6144\n\t"
;         "ds_read_b128 %4, %18\n\t"
;         "ds_read_b128 %5, %18 offset:2048\n\t"
;         "ds_read_b128 %6, %18 offset:8192\n\t"
;         "ds_read_b128 %7, %18 offset:10240\n\t"
;         "ds_read_b128 %8, %17\n\t"
;         "ds_read_b128 %9, %17 offset:2048\n\t"
;         "ds_read_b128 %10, %17 offset:4096\n\t"
;         "ds_read_b128 %11, %17 offset:6144\n\t"
;         "ds_read_b128 %12, %19\n\t"
;         "ds_read_b128 %13, %19 offset:2048\n\t"
;         "ds_read_b128 %14, %19 offset:8192\n\t"
;         "ds_read_b128 %15, %19 offset:10240\n\t"
;         "s_waitcnt lgkmcnt(8)"
;         : "=&v"(xa[0][0]), "=&v"(xa[0][1]), "=&v"(xa[0][2]), "=&v"(xa[0][3]), "=&v"(wb[0][0]), "=&v"(wb[0][1]), "=&v"(wb[0][2]),
;           "=&v"(wb[0][3]), "=&v"(xa[1][0]), "=&v"(xa[1][1]), "=&v"(xa[1][2]), "=&v"(xa[1][3]), "=&v"(wb[1][0]), "=&v"(wb[1][1]),
;           "=&v"(wb[1][2]), "=&v"(wb[1][3])
;         : "v"(a0 + so), "v"((a0 ^ 64u) + so), "v"(b0 + so), "v"((b0 ^ 64u) + so)
;         : "memory");
;     __builtin_amdgcn_s_setprio(1);
; #pragma unroll
;     for (int i = 0; i < 4; ++i)
; #pragma unroll
;       for (int j = 0; j < 4; ++j) acc[i][j] = mma_step(wb[0][j], xa[0][i], acc[i][j]);
;     asm volatile("s_waitcnt lgkmcnt(0)"
.LBB0_459:
	s_add_i32 s15, s1, 0xffff8000
	s_and_b32 s15, s15, 0x8000
	v_add_u32_e32 v154, s15, v86
	v_add_u32_e32 v155, s15, v89
	v_or_b32_e32 v156, s15, v87
	v_or_b32_e32 v157, s15, v88
	s_and_b32 s15, s1, 0x8000
	s_add_i32 s15, s15, s62
	s_mov_b32 m0, s15
	ds_read_b128 v[90:93], v154
	global_load_lds_dwordx4 v80, s[64:65]
	ds_read_b128 v[94:97], v154 offset:2048
	s_add_i32 m0, s15, 0x4000
	ds_read_b128 v[98:101], v154 offset:4096
	global_load_lds_dwordx4 v78, s[66:67]
	ds_read_b128 v[102:105], v154 offset:6144
	s_add_i32 m0, s15, 0x400
	ds_read_b128 v[106:109], v156
	global_load_lds_dwordx4 v76, s[64:65]
	ds_read_b128 v[110:113], v156 offset:2048
	s_add_i32 m0, s15, 0x4400
	ds_read_b128 v[114:117], v156 offset:8192
	global_load_lds_dwordx4 v74, s[66:67]
	ds_read_b128 v[118:121], v156 offset:10240
	ds_read_b128 v[122:125], v155
	ds_read_b128 v[126:129], v155 offset:2048
	ds_read_b128 v[130:133], v155 offset:4096
	ds_read_b128 v[134:137], v155 offset:6144
	ds_read_b128 v[138:141], v157
	ds_read_b128 v[142:145], v157 offset:2048
	ds_read_b128 v[146:149], v157 offset:8192
	ds_read_b128 v[150:153], v157 offset:10240
	s_waitcnt lgkmcnt(8)
	s_setprio 1
	v_mfma_f32_16x16x32_bf16 v[60:63], v[106:109], v[90:93], v[60:63]
	v_mfma_f32_16x16x32_bf16 v[56:59], v[110:113], v[90:93], v[56:59]
	s_add_i32 m0, s15, 0x800
	v_mfma_f32_16x16x32_bf16 v[52:55], v[114:117], v[90:93], v[52:55]
	global_load_lds_dwordx4 v72, s[64:65]
	v_mfma_f32_16x16x32_bf16 v[48:51], v[118:121], v[90:93], v[48:51]
	v_mfma_f32_16x16x32_bf16 v[44:47], v[106:109], v[94:97], v[44:47]
	v_mfma_f32_16x16x32_bf16 v[40:43], v[110:113], v[94:97], v[40:43]
	s_add_i32 m0, s15, 0x4800
	v_mfma_f32_16x16x32_bf16 v[36:39], v[114:117], v[94:97], v[36:39]
	global_load_lds_dwordx4 v70, s[66:67]
	v_mfma_f32_16x16x32_bf16 v[32:35], v[118:121], v[94:97], v[32:35]
	v_mfma_f32_16x16x32_bf16 v[28:31], v[106:109], v[98:101], v[28:31]
	v_mfma_f32_16x16x32_bf16 v[24:27], v[110:113], v[98:101], v[24:27]
	s_add_i32 m0, s15, 0xc00
	v_mfma_f32_16x16x32_bf16 v[20:23], v[114:117], v[98:101], v[20:23]
	global_load_lds_dwordx4 v68, s[64:65]
	v_mfma_f32_16x16x32_bf16 v[16:19], v[118:121], v[98:101], v[16:19]
	v_mfma_f32_16x16x32_bf16 v[12:15], v[106:109], v[102:105], v[12:15]
	v_mfma_f32_16x16x32_bf16 v[8:11], v[110:113], v[102:105], v[8:11]
	s_add_i32 m0, s15, 0x4c00
	v_mfma_f32_16x16x32_bf16 v[4:7], v[114:117], v[102:105], v[4:7]
	global_load_lds_dwordx4 v66, s[66:67]
	v_mfma_f32_16x16x32_bf16 v[0:3], v[118:121], v[102:105], v[0:3]
	s_waitcnt lgkmcnt(0)
	s_nop 0
	v_mfma_f32_16x16x32_bf16 v[60:63], v[138:141], v[122:125], v[60:63]
	v_mfma_f32_16x16x32_bf16 v[56:59], v[142:145], v[122:125], v[56:59]
	v_mfma_f32_16x16x32_bf16 v[52:55], v[146:149], v[122:125], v[52:55]
	v_mfma_f32_16x16x32_bf16 v[48:51], v[150:153], v[122:125], v[48:51]
	v_mfma_f32_16x16x32_bf16 v[44:47], v[138:141], v[126:129], v[44:47]
	v_mfma_f32_16x16x32_bf16 v[40:43], v[142:145], v[126:129], v[40:43]
	v_mfma_f32_16x16x32_bf16 v[36:39], v[146:149], v[126:129], v[36:39]
	v_mfma_f32_16x16x32_bf16 v[32:35], v[150:153], v[126:129], v[32:35]
	v_mfma_f32_16x16x32_bf16 v[28:31], v[138:141], v[130:133], v[28:31]
	v_mfma_f32_16x16x32_bf16 v[24:27], v[142:145], v[130:133], v[24:27]
	v_mfma_f32_16x16x32_bf16 v[20:23], v[146:149], v[130:133], v[20:23]
	v_mfma_f32_16x16x32_bf16 v[16:19], v[150:153], v[130:133], v[16:19]
	v_mfma_f32_16x16x32_bf16 v[12:15], v[138:141], v[134:137], v[12:15]
	v_mfma_f32_16x16x32_bf16 v[8:11], v[142:145], v[134:137], v[8:11]
	v_mfma_f32_16x16x32_bf16 v[4:7], v[146:149], v[134:137], v[4:7]
	v_mfma_f32_16x16x32_bf16 v[0:3], v[150:153], v[134:137], v[0:3]
	s_setprio 0
	s_waitcnt vmcnt(0)
	s_add_u32 s4, s4, 0x80
	s_addc_u32 s5, s5, 0
	s_add_u32 s64, s64, 0x80
	s_addc_u32 s65, s65, 0
	s_add_u32 s66, s66, 0x80
	s_addc_u32 s67, s67, 0
	s_add_i32 s1, s1, 0x8000
	s_cmpk_lg_i32 s4, 0xf80
	s_waitcnt vmcnt(0) lgkmcnt(0)
	s_barrier
	s_cbranch_scc1 .LBB0_459
	v_add_u32_e32 v85, 0x8000, v86
	v_add_u32_e32 v134, 0x8000, v89
	v_or_b32_e32 v135, 0x8000, v87
	v_or_b32_e32 v136, 0x8000, v88
	ds_read_b128 v[66:69], v85
	ds_read_b128 v[70:73], v85 offset:2048
	ds_read_b128 v[74:77], v85 offset:4096
	ds_read_b128 v[78:81], v85 offset:6144
	ds_read_b128 v[86:89], v135
	ds_read_b128 v[90:93], v135 offset:2048
	ds_read_b128 v[94:97], v135 offset:8192
	ds_read_b128 v[98:101], v135 offset:10240
	ds_read_b128 v[102:105], v134
	ds_read_b128 v[106:109], v134 offset:2048
	ds_read_b128 v[110:113], v134 offset:4096
	ds_read_b128 v[114:117], v134 offset:6144
	ds_read_b128 v[118:121], v136
	ds_read_b128 v[122:125], v136 offset:2048
	ds_read_b128 v[126:129], v136 offset:8192
	ds_read_b128 v[130:133], v136 offset:10240
	s_waitcnt lgkmcnt(8)
	s_setprio 1
	v_mfma_f32_16x16x32_bf16 v[60:63], v[86:89], v[66:69], v[60:63]
	v_mfma_f32_16x16x32_bf16 v[56:59], v[90:93], v[66:69], v[56:59]
	v_mfma_f32_16x16x32_bf16 v[52:55], v[94:97], v[66:69], v[52:55]
	v_mfma_f32_16x16x32_bf16 v[48:51], v[98:101], v[66:69], v[48:51]
	v_mfma_f32_16x16x32_bf16 v[44:47], v[86:89], v[70:73], v[44:47]
	v_mfma_f32_16x16x32_bf16 v[40:43], v[90:93], v[70:73], v[40:43]
	v_mfma_f32_16x16x32_bf16 v[36:39], v[94:97], v[70:73], v[36:39]
	v_mfma_f32_16x16x32_bf16 v[32:35], v[98:101], v[70:73], v[32:35]
	v_mfma_f32_16x16x32_bf16 v[28:31], v[86:89], v[74:77], v[28:31]
	v_mfma_f32_16x16x32_bf16 v[24:27], v[90:93], v[74:77], v[24:27]
	v_mfma_f32_16x16x32_bf16 v[20:23], v[94:97], v[74:77], v[20:23]
	v_mfma_f32_16x16x32_bf16 v[16:19], v[98:101], v[74:77], v[16:19]
	v_mfma_f32_16x16x32_bf16 v[12:15], v[86:89], v[78:81], v[12:15]
	v_mfma_f32_16x16x32_bf16 v[8:11], v[90:93], v[78:81], v[8:11]
	v_mfma_f32_16x16x32_bf16 v[4:7], v[94:97], v[78:81], v[4:7]
	v_mfma_f32_16x16x32_bf16 v[0:3], v[98:101], v[78:81], v[0:3]
	s_waitcnt lgkmcnt(0)
; DEV int tid_() { int t = threadIdx.x; asm volatile("" : "+v"(t)); return t; }
; #define P (*launderP(lp))
; DEV void stage_tile_bf16(char* smem, const f32x4 (&v)[4][4], u16* buf, int ld, int m0, int col0) {
;   const int tid = tid_(), lane = tid & 63, wid = tid >> 6, wm = wid >> 1, wn = wid & 1, l15 = lane & 15, q = lane >> 4;
; #pragma unroll
;   for (int i = 0; i < 4; ++i)
; #pragma unroll
;     for (int j = 0; j < 4; ++j) {
;       const int rl = wm * 64 + i * 16 + l15, cl = (j & 1) * 16 + wn * 32 + (j >> 1) * 64 + q * 4;
;       u32x2 o; o.x = pack2(v[i][j][0], v[i][j][1]); o.y = pack2(v[i][j][2], v[i][j][3]);
;       *(u32x2*)(smem + rl * 272 + cl * 2) = o;
;     }
;   __syncthreads();
; __device__ __forceinline__ void phase_gemm3(PREF P, int slab, char* smem) {
;     ...
;     for (int i = 0; i < 4; ++i)
; #pragma unroll
;       for (int j = 0; j < 4; ++j) {
;         const int row = m0 + wm * 64 + i * 16 + l15, col = n0 + (j & 1) * 16 + wn * 32 + (j >> 1) * 64 + q * 4;
;         float4 xv = *(const float4*)(xs + (size_t)row * 2048 + col);
;         f32x4 o;
;         o[0] = DN_ALPHA * xv.x + acc[i][j][0]; o[1] = DN_ALPHA * xv.y + acc[i][j][1];
;         o[2] = DN_ALPHA * xv.z + acc[i][j][2]; o[3] = DN_ALPHA * xv.w + acc[i][j][3];
;         acc[i][j] = o;
;       }
;     stage_tile_bf16(smem, acc, (u16*)P.y, 2048, m0, n0);
	s_nop 0
	v_mfma_f32_16x16x32_bf16 v[60:63], v[118:121], v[102:105], v[60:63]
	v_mfma_f32_16x16x32_bf16 v[56:59], v[122:125], v[102:105], v[56:59]
	v_mfma_f32_16x16x32_bf16 v[52:55], v[126:129], v[102:105], v[52:55]
	v_mfma_f32_16x16x32_bf16 v[48:51], v[130:133], v[102:105], v[48:51]
	v_mfma_f32_16x16x32_bf16 v[44:47], v[118:121], v[106:109], v[44:47]
	v_mfma_f32_16x16x32_bf16 v[40:43], v[122:125], v[106:109], v[40:43]
	v_mfma_f32_16x16x32_bf16 v[36:39], v[126:129], v[106:109], v[36:39]
	v_mfma_f32_16x16x32_bf16 v[32:35], v[130:133], v[106:109], v[32:35]
	v_mfma_f32_16x16x32_bf16 v[66:69], v[118:121], v[110:113], v[28:31]
	v_mfma_f32_16x16x32_bf16 v[70:73], v[122:125], v[110:113], v[24:27]
	v_mfma_f32_16x16x32_bf16 v[74:77], v[126:129], v[110:113], v[20:23]
	v_mfma_f32_16x16x32_bf16 v[78:81], v[130:133], v[110:113], v[16:19]
	v_mfma_f32_16x16x32_bf16 v[86:89], v[118:121], v[114:117], v[12:15]
	v_mfma_f32_16x16x32_bf16 v[90:93], v[122:125], v[114:117], v[8:11]
	v_mfma_f32_16x16x32_bf16 v[94:97], v[126:129], v[114:117], v[4:7]
	v_mfma_f32_16x16x32_bf16 v[0:3], v[130:133], v[114:117], v[0:3]
	s_setprio 0
	v_add_u32_e32 v98, s14, v83
	v_or_b32_e32 v4, s0, v84
	v_ashrrev_i32_e32 v99, 31, v98
	v_ashrrev_i32_e32 v5, 31, v4
	v_lshlrev_b64 v[6:7], 13, v[98:99]
	v_lshl_add_u64 v[6:7], v[64:65], 0, v[6:7]
	v_lshlrev_b64 v[100:101], 2, v[4:5]
	v_lshl_add_u64 v[12:13], v[6:7], 0, v[100:101]
	s_waitcnt vmcnt(0)
	s_barrier
	flat_load_dwordx4 v[4:7], v[12:13]
	flat_load_dwordx4 v[8:11], v[12:13] offset:256
	v_or_b32_e32 v16, 16, v98
	v_ashrrev_i32_e32 v17, 31, v16
	v_lshlrev_b64 v[16:17], 13, v[16:17]
	v_lshl_add_u64 v[16:17], v[64:65], 0, v[16:17]
	v_lshl_add_u64 v[28:29], v[16:17], 0, v[100:101]
	flat_load_dwordx4 v[24:27], v[28:29] offset:256
	s_mov_b32 s1, 0xfffffc0
	flat_load_dwordx4 v[16:19], v[28:29]
	flat_load_dwordx4 v[20:23], v[28:29] offset:64
	s_waitcnt vmcnt(0) lgkmcnt(0)
	v_fmac_f32_e32 v60, s28, v4
	v_fmac_f32_e32 v61, s28, v5
	v_fmac_f32_e32 v62, s28, v6
	v_fmac_f32_e32 v63, s28, v7
	flat_load_dwordx4 v[4:7], v[12:13] offset:64
	v_fma_f32 v8, v8, s28, v52
	v_fma_f32 v9, v9, s28, v53
	flat_load_dwordx4 v[12:15], v[12:13] offset:320
	v_fma_f32 v10, v10, s28, v54
	v_fma_f32 v11, v11, s28, v55
	flat_load_dwordx4 v[28:31], v[28:29] offset:320
	v_fma_f32 v24, v24, s28, v36
	v_fma_f32 v25, v25, s28, v37
	v_fma_f32 v26, v26, s28, v38
	v_fma_f32 v27, v27, s28, v39
	v_fma_f32 v16, v16, s28, v44
	v_fma_f32 v17, v17, s28, v45
	v_fma_f32 v18, v18, s28, v46
	v_fma_f32 v19, v19, s28, v47
	v_fma_f32 v20, v20, s28, v40
	v_fma_f32 v21, v21, s28, v41
	v_fma_f32 v22, v22, s28, v42
	v_fma_f32 v23, v23, s28, v43
	s_waitcnt vmcnt(0) lgkmcnt(0)
	v_fma_f32 v4, v4, s28, v56
	v_fma_f32 v5, v5, s28, v57
	v_fma_f32 v6, v6, s28, v58
	v_fma_f32 v7, v7, s28, v59
	v_fma_f32 v12, v12, s28, v48
	v_fma_f32 v13, v13, s28, v49
	v_fma_f32 v14, v14, s28, v50
	v_fma_f32 v15, v15, s28, v51
	v_fma_f32 v28, v28, s28, v32
	v_fma_f32 v29, v29, s28, v33
	v_or_b32_e32 v32, 32, v98
	v_ashrrev_i32_e32 v33, 31, v32
	v_lshlrev_b64 v[32:33], 13, v[32:33]
	v_lshl_add_u64 v[32:33], v[64:65], 0, v[32:33]
	v_lshl_add_u64 v[44:45], v[32:33], 0, v[100:101]
	v_fma_f32 v30, v30, s28, v34
	v_fma_f32 v31, v31, s28, v35
	flat_load_dwordx4 v[32:35], v[44:45]
	flat_load_dwordx4 v[36:39], v[44:45] offset:64
	flat_load_dwordx4 v[40:43], v[44:45] offset:256
	v_cvt_pk_bf16_f32 v4, v4, v5
	flat_load_dwordx4 v[44:47], v[44:45] offset:320
	v_cvt_pk_bf16_f32 v5, v6, v7
	v_cvt_pk_bf16_f32 v6, v12, v13
	v_cvt_pk_bf16_f32 v7, v14, v15
	s_waitcnt vmcnt(0) lgkmcnt(0)
	v_fma_f32 v32, v32, s28, v66
	v_fma_f32 v33, v33, s28, v67
	v_fma_f32 v34, v34, s28, v68
	v_fma_f32 v35, v35, s28, v69
	v_fma_f32 v36, v36, s28, v70
	v_fma_f32 v37, v37, s28, v71
	v_fma_f32 v38, v38, s28, v72
	v_fma_f32 v39, v39, s28, v73
	v_fma_f32 v48, v44, s28, v78
	v_fma_f32 v49, v45, s28, v79
	v_or_b32_e32 v44, 48, v98
	v_ashrrev_i32_e32 v45, 31, v44
	v_lshlrev_b64 v[44:45], 13, v[44:45]
	v_lshl_add_u64 v[44:45], v[64:65], 0, v[44:45]
	v_lshl_add_u64 v[52:53], v[44:45], 0, v[100:101]
	v_fma_f32 v50, v46, s28, v80
	v_fma_f32 v51, v47, s28, v81
	flat_load_dwordx4 v[44:47], v[52:53]
	v_mov_b32_e32 v72, v188
	v_fma_f32 v40, v40, s28, v74
	v_fma_f32 v41, v41, s28, v75
	v_fma_f32 v42, v42, s28, v76
	v_fma_f32 v43, v43, s28, v77
	s_waitcnt vmcnt(0) lgkmcnt(0)
	v_fma_f32 v54, v44, s28, v86
	v_fma_f32 v55, v45, s28, v87
	v_fma_f32 v56, v46, s28, v88
	v_fma_f32 v57, v47, s28, v89
	flat_load_dwordx4 v[44:47], v[52:53] offset:64
	s_waitcnt vmcnt(0) lgkmcnt(0)
	v_fma_f32 v58, v44, s28, v90
	v_fma_f32 v59, v45, s28, v91
	v_fma_f32 v66, v46, s28, v92
	v_fma_f32 v67, v47, s28, v93
	flat_load_dwordx4 v[44:47], v[52:53] offset:256
	s_waitcnt vmcnt(0) lgkmcnt(0)
	v_fma_f32 v68, v44, s28, v94
	v_fma_f32 v69, v45, s28, v95
	v_fma_f32 v70, v46, s28, v96
	v_fma_f32 v71, v47, s28, v97
	flat_load_dwordx4 v[44:47], v[52:53] offset:320
	s_waitcnt vmcnt(0) lgkmcnt(0)
	v_fmac_f32_e32 v0, s28, v44
	v_fmac_f32_e32 v1, s28, v45
	v_fmac_f32_e32 v2, s28, v46
	v_fmac_f32_e32 v3, s28, v47
	ds_read_b64 v[44:45], v82 offset:376
	v_cvt_pk_bf16_f32 v46, v60, v61
	v_and_b32_e32 v73, 15, v72
	v_lshrrev_b32_e32 v52, 1, v72
	v_and_b32_e32 v60, 64, v72
	v_and_or_b32 v53, v52, s1, v73
	v_and_or_b32 v52, v52, 24, v60
	v_cvt_pk_bf16_f32 v47, v62, v63
	v_mad_u64_u32 v[52:53], s[4:5], v53, s11, v[52:53]
	ds_write2_b64 v52, v[46:47], v[4:5] offset1:4
	v_cvt_pk_bf16_f32 v4, v8, v9
	v_cvt_pk_bf16_f32 v5, v10, v11
	ds_write2_b64 v52, v[4:5], v[6:7] offset0:16 offset1:20
	v_cvt_pk_bf16_f32 v4, v16, v17
	v_cvt_pk_bf16_f32 v5, v18, v19
	v_cvt_pk_bf16_f32 v6, v20, v21
	v_cvt_pk_bf16_f32 v7, v22, v23
	v_add_u32_e32 v8, 0x1000, v52
	ds_write2_b64 v8, v[4:5], v[6:7] offset0:32 offset1:36
	v_cvt_pk_bf16_f32 v4, v24, v25
	v_cvt_pk_bf16_f32 v5, v26, v27
	v_cvt_pk_bf16_f32 v6, v28, v29
	v_cvt_pk_bf16_f32 v7, v30, v31
	ds_write2_b64 v8, v[4:5], v[6:7] offset0:48 offset1:52
	v_cvt_pk_bf16_f32 v4, v32, v33
	v_cvt_pk_bf16_f32 v5, v34, v35
	v_cvt_pk_bf16_f32 v6, v36, v37
	v_cvt_pk_bf16_f32 v7, v38, v39
	v_add_u32_e32 v8, 0x2000, v52
	ds_write2_b64 v8, v[4:5], v[6:7] offset0:64 offset1:68
	v_cvt_pk_bf16_f32 v4, v40, v41
	v_cvt_pk_bf16_f32 v5, v42, v43
	v_cvt_pk_bf16_f32 v6, v48, v49
	v_cvt_pk_bf16_f32 v7, v50, v51
	ds_write2_b64 v8, v[4:5], v[6:7] offset0:80 offset1:84
	v_cvt_pk_bf16_f32 v4, v54, v55
	v_cvt_pk_bf16_f32 v5, v56, v57
	v_cvt_pk_bf16_f32 v6, v58, v59
	v_cvt_pk_bf16_f32 v7, v66, v67
	v_add_u32_e32 v8, 0x3000, v52
	ds_write2_b64 v8, v[4:5], v[6:7] offset0:96 offset1:100
	v_cvt_pk_bf16_f32 v4, v68, v69
	v_cvt_pk_bf16_f32 v5, v70, v71
	v_cvt_pk_bf16_f32 v0, v0, v1
	v_cvt_pk_bf16_f32 v1, v2, v3
	s_ashr_i32 s1, s0, 31
	ds_write2_b64 v8, v[4:5], v[0:1] offset0:112 offset1:116
	v_lshlrev_b32_e32 v180, 4, v73
	s_waitcnt lgkmcnt(8)
	v_lshl_add_u64 v[0:1], s[0:1], 1, v[44:45]
	v_ashrrev_i32_e32 v6, 4, v72
	v_lshl_add_u64 v[4:5], v[0:1], 0, v[180:181]
	v_mad_u64_u32 v[0:1], s[0:1], v6, s11, v[180:181]
	s_waitcnt lgkmcnt(0)
	s_barrier
; DEV void stage_tile_bf16(char* smem, const f32x4 (&v)[4][4], u16* buf, int ld, int m0, int col0) {
;     ...
; #pragma unroll
;   for (int k = 0; k < 8; ++k) {
;     const int chunk = tid + 256 * k, rl = chunk >> 4, c16 = chunk & 15;
;     u32x4 d = *(const u32x4*)(smem + rl * 272 + c16 * 16);
;     *(u32x4*)(buf + (size_t)(m0 + rl) * ld + col0 + c16 * 8) = d;
;   }
	ds_read_b128 v[0:3], v0
	v_add_u32_e32 v6, s14, v6
	v_ashrrev_i32_e32 v7, 31, v6
	v_lshlrev_b64 v[6:7], 12, v[6:7]
	v_lshl_add_u64 v[6:7], v[4:5], 0, v[6:7]
	s_waitcnt lgkmcnt(0)
	flat_store_dwordx4 v[6:7], v[0:3]
	s_nop 1
	v_add_u32_e32 v0, 0x100, v72
	v_ashrrev_i32_e32 v6, 4, v0
	v_mad_u64_u32 v[0:1], s[0:1], v6, s11, v[180:181]
	ds_read_b128 v[0:3], v0
	v_add_u32_e32 v6, s14, v6
	v_ashrrev_i32_e32 v7, 31, v6
	v_lshlrev_b64 v[6:7], 12, v[6:7]
	v_lshl_add_u64 v[6:7], v[4:5], 0, v[6:7]
	s_waitcnt lgkmcnt(0)
	flat_store_dwordx4 v[6:7], v[0:3]
	s_nop 1
	v_add_u32_e32 v0, 0x200, v72
	v_ashrrev_i32_e32 v6, 4, v0
	v_mad_u64_u32 v[0:1], s[0:1], v6, s11, v[180:181]
	ds_read_b128 v[0:3], v0
	v_add_u32_e32 v6, s14, v6
	v_ashrrev_i32_e32 v7, 31, v6
	v_lshlrev_b64 v[6:7], 12, v[6:7]
	v_lshl_add_u64 v[6:7], v[4:5], 0, v[6:7]
	s_waitcnt lgkmcnt(0)
	flat_store_dwordx4 v[6:7], v[0:3]
	s_nop 1
	v_add_u32_e32 v0, 0x300, v72
	v_ashrrev_i32_e32 v6, 4, v0
	v_mad_u64_u32 v[0:1], s[0:1], v6, s11, v[180:181]
	ds_read_b128 v[0:3], v0
	v_add_u32_e32 v6, s14, v6
	v_ashrrev_i32_e32 v7, 31, v6
	v_lshlrev_b64 v[6:7], 12, v[6:7]
	v_lshl_add_u64 v[6:7], v[4:5], 0, v[6:7]
	s_waitcnt lgkmcnt(0)
	flat_store_dwordx4 v[6:7], v[0:3]
	s_nop 1
	v_add_u32_e32 v0, 0x400, v72
	v_ashrrev_i32_e32 v6, 4, v0
	v_mad_u64_u32 v[0:1], s[0:1], v6, s11, v[180:181]
	ds_read_b128 v[0:3], v0
	v_add_u32_e32 v6, s14, v6
	v_ashrrev_i32_e32 v7, 31, v6
	v_lshlrev_b64 v[6:7], 12, v[6:7]
	v_lshl_add_u64 v[6:7], v[4:5], 0, v[6:7]
	s_waitcnt lgkmcnt(0)
	flat_store_dwordx4 v[6:7], v[0:3]
	s_nop 1
	v_add_u32_e32 v0, 0x500, v72
	v_ashrrev_i32_e32 v6, 4, v0
	v_mad_u64_u32 v[0:1], s[0:1], v6, s11, v[180:181]
	ds_read_b128 v[0:3], v0
	v_add_u32_e32 v6, s14, v6
	v_ashrrev_i32_e32 v7, 31, v6
	v_lshlrev_b64 v[6:7], 12, v[6:7]
	v_lshl_add_u64 v[6:7], v[4:5], 0, v[6:7]
	s_waitcnt lgkmcnt(0)
	flat_store_dwordx4 v[6:7], v[0:3]
	s_nop 1
	v_add_u32_e32 v0, 0x600, v72
	v_ashrrev_i32_e32 v6, 4, v0
	v_mad_u64_u32 v[0:1], s[0:1], v6, s11, v[180:181]
	ds_read_b128 v[0:3], v0
	v_add_u32_e32 v6, s14, v6
	v_ashrrev_i32_e32 v7, 31, v6
	v_lshlrev_b64 v[6:7], 12, v[6:7]
	v_lshl_add_u64 v[6:7], v[4:5], 0, v[6:7]
	s_waitcnt lgkmcnt(0)
	flat_store_dwordx4 v[6:7], v[0:3]
	s_nop 1
	v_add_u32_e32 v0, 0x700, v72
	v_ashrrev_i32_e32 v6, 4, v0
	v_mad_u64_u32 v[0:1], s[0:1], v6, s11, v[180:181]
	ds_read_b128 v[0:3], v0
	v_add_u32_e32 v6, s14, v6
	v_ashrrev_i32_e32 v7, 31, v6
	v_lshlrev_b64 v[6:7], 12, v[6:7]
	v_lshl_add_u64 v[4:5], v[4:5], 0, v[6:7]
	v_readlane_b32 s0, v251, 6
	s_waitcnt lgkmcnt(0)
	flat_store_dwordx4 v[4:5], v[0:3]
	s_add_i32 s6, s0, s6
	s_cmpk_lt_i32 s6, 0x400
	v_readlane_b32 s1, v251, 7
	s_cbranch_scc1 .LBB0_458

; DEV float bflo(unsigned u) { return __uint_as_float(u << 16); }
; DEV float bfhi(unsigned u) { return __uint_as_float(u & 0xffff0000u); }
; #define P (*launderP(lp))
; __device__ __forceinline__ void phase_ln1(PREF P) {
;     ...
;     const u16* yr = (const u16*)P.y + (size_t)t * 2048;
;     float v[32];
; #pragma unroll
;     for (int u = 0; u < 4; ++u) {
;       u32x4 a = *(const u32x4*)(yr + u * 512 + lane * 8);
;       v[u * 8 + 0] = bflo(a.x); v[u * 8 + 1] = bfhi(a.x); v[u * 8 + 2] = bflo(a.y); v[u * 8 + 3] = bfhi(a.y);
;       v[u * 8 + 4] = bflo(a.z); v[u * 8 + 5] = bfhi(a.z); v[u * 8 + 6] = bflo(a.w); v[u * 8 + 7] = bfhi(a.w);
;     }
;     float s = 0.f;
; #pragma unroll
;     for (int e = 0; e < 32; ++e) s += v[e];
;     const float mu = wsum(s) * (1.f / 2048.f);
;     float vs = 0.f;
; #pragma unroll
;     for (int e = 0; e < 32; ++e) { float d = v[e] - mu; vs += d * d; }
;     const float rs = rsqrtf(wsum(vs) * (1.f / 2048.f) + LN_EPS);
.LBB0_512:
	ds_read_b64 v[30:31], v52 offset:344
	ds_read_b64 v[0:1], v52 offset:376
	v_ashrrev_i32_e32 v21, 31, v20
	v_lshlrev_b64 v[18:19], 12, v[20:21]
	v_lshlrev_b32_e32 v180, 1, v22
	v_lshlrev_b32_e32 v16, 2, v22
	s_waitcnt lgkmcnt(0)
	v_lshl_add_u64 v[0:1], v[0:1], 0, v[18:19]
	v_lshl_add_u64 v[0:1], v[0:1], 0, v[180:181]
	flat_load_dwordx4 v[40:43], v[0:1]
	flat_load_dwordx4 v[44:47], v[0:1] offset:1024
	flat_load_dwordx4 v[48:51], v[0:1] offset:2048
	flat_load_dwordx4 v[60:63], v[0:1] offset:3072
	ds_read2_b64 v[0:3], v52 offset0:10 offset1:11
	v_mov_b32_e32 v17, v181
	s_mov_b32 s6, 0x800000
	v_lshl_add_u64 v[30:31], v[30:31], 0, v[18:19]
	v_lshl_add_u64 v[30:31], v[30:31], 0, v[180:181]
	s_waitcnt lgkmcnt(0)
	v_lshl_add_u64 v[8:9], v[0:1], 0, v[16:17]
	v_lshl_add_u64 v[12:13], v[2:3], 0, v[16:17]
	flat_load_dwordx4 v[0:3], v[8:9] offset:16
	flat_load_dwordx4 v[4:7], v[12:13] offset:16
	s_nop 0
	flat_load_dwordx4 v[8:11], v[8:9]
	s_nop 0
	flat_load_dwordx4 v[12:15], v[12:13]
	v_lshlrev_b64 v[28:29], 11, v[20:21]
	s_waitcnt vmcnt(0)
	v_lshlrev_b32_e32 v38, 16, v40
	v_and_b32_e32 v39, 0xffff0000, v40
	v_add_f32_e32 v25, 0, v38
	v_lshlrev_b32_e32 v36, 16, v41
	v_add_f32_e32 v25, v25, v39
	v_and_b32_e32 v37, 0xffff0000, v41
	v_add_f32_e32 v25, v25, v36
	v_lshlrev_b32_e32 v34, 16, v42
	v_add_f32_e32 v25, v25, v37
	v_and_b32_e32 v35, 0xffff0000, v42
	v_add_f32_e32 v25, v25, v34
	v_lshlrev_b32_e32 v32, 16, v43
	v_add_f32_e32 v25, v25, v35
	v_and_b32_e32 v33, 0xffff0000, v43
	v_add_f32_e32 v25, v25, v32
	v_add_f32_e32 v25, v25, v33
	v_lshlrev_b32_e32 v64, 16, v44
	v_and_b32_e32 v65, 0xffff0000, v44
	v_add_f32_e32 v25, v25, v64
	v_lshlrev_b32_e32 v42, 16, v46
	v_and_b32_e32 v43, 0xffff0000, v46
	v_lshlrev_b32_e32 v46, 16, v45
	v_add_f32_e32 v25, v25, v65
	v_lshlrev_b32_e32 v40, 16, v47
	v_and_b32_e32 v41, 0xffff0000, v47
	v_and_b32_e32 v47, 0xffff0000, v45
	v_add_f32_e32 v25, v25, v46
	v_add_f32_e32 v25, v25, v47
	v_add_f32_e32 v25, v25, v42
	v_add_f32_e32 v25, v25, v43
	v_add_f32_e32 v25, v25, v40
	v_add_f32_e32 v25, v25, v41
	v_lshlrev_b32_e32 v44, 16, v48
	v_and_b32_e32 v45, 0xffff0000, v48
	v_add_f32_e32 v25, v25, v44
	v_lshlrev_b32_e32 v68, 16, v50
	v_and_b32_e32 v69, 0xffff0000, v50
	v_lshlrev_b32_e32 v50, 16, v49
	v_add_f32_e32 v25, v25, v45
	v_lshlrev_b32_e32 v66, 16, v51
	v_and_b32_e32 v67, 0xffff0000, v51
	v_and_b32_e32 v51, 0xffff0000, v49
	v_add_f32_e32 v25, v25, v50
	v_add_f32_e32 v25, v25, v51
	v_add_f32_e32 v25, v25, v68
	v_add_f32_e32 v25, v25, v69
	v_add_f32_e32 v25, v25, v66
	v_add_f32_e32 v25, v25, v67
	v_lshlrev_b32_e32 v74, 16, v60
	v_and_b32_e32 v75, 0xffff0000, v60
	v_add_f32_e32 v25, v25, v74
	v_lshlrev_b32_e32 v72, 16, v62
	v_and_b32_e32 v73, 0xffff0000, v62
	v_lshlrev_b32_e32 v62, 16, v61
	v_add_f32_e32 v25, v25, v75
	v_lshlrev_b32_e32 v70, 16, v63
	v_and_b32_e32 v71, 0xffff0000, v63
	v_and_b32_e32 v63, 0xffff0000, v61
	v_add_f32_e32 v25, v25, v62
	v_add_f32_e32 v25, v25, v63
	v_add_f32_e32 v25, v25, v72
	v_add_f32_e32 v25, v25, v73
	v_add_f32_e32 v25, v25, v70
	v_add_f32_e32 v25, v25, v71
	ds_bpermute_b32 v27, v53, v25
	s_waitcnt lgkmcnt(0)
	v_add_f32_e32 v25, v25, v27
	ds_bpermute_b32 v27, v54, v25
	s_waitcnt lgkmcnt(0)
	v_add_f32_e32 v25, v25, v27
	ds_bpermute_b32 v27, v55, v25
	s_waitcnt lgkmcnt(0)
	v_add_f32_e32 v25, v25, v27
	ds_bpermute_b32 v27, v56, v25
	s_waitcnt lgkmcnt(0)
	v_add_f32_e32 v25, v25, v27
	ds_bpermute_b32 v27, v57, v25
	s_waitcnt lgkmcnt(0)
	v_add_f32_e32 v25, v25, v27
	ds_bpermute_b32 v27, v58, v25
	s_waitcnt lgkmcnt(0)
	v_add_f32_e32 v25, v25, v27
	v_mul_f32_e32 v60, 0x3a000000, v25
	v_sub_f32_e32 v76, v38, v60
	v_sub_f32_e32 v77, v39, v60
	v_sub_f32_e32 v80, v36, v60
	v_sub_f32_e32 v81, v37, v60
	v_mul_f32_e32 v78, v76, v76
	v_mul_f32_e32 v79, v77, v77
	v_mul_f32_e32 v82, v80, v80
	v_mul_f32_e32 v83, v81, v81
	v_add_f32_e32 v25, v78, v79
	v_sub_f32_e32 v84, v34, v60
	v_sub_f32_e32 v85, v35, v60
	v_add_f32_e32 v25, v82, v25
	v_mul_f32_e32 v86, v84, v84
	v_mul_f32_e32 v87, v85, v85
	v_add_f32_e32 v25, v83, v25
	v_sub_f32_e32 v88, v32, v60
	v_sub_f32_e32 v89, v33, v60
	v_add_f32_e32 v25, v86, v25
	v_mul_f32_e32 v32, v88, v88
	v_mul_f32_e32 v33, v89, v89
	v_add_f32_e32 v25, v87, v25
	v_sub_f32_e32 v90, v64, v60
	v_sub_f32_e32 v91, v65, v60
	v_add_f32_e32 v25, v32, v25
	v_mul_f32_e32 v64, v90, v90
	v_mul_f32_e32 v65, v91, v91
	v_add_f32_e32 v25, v33, v25
	v_sub_f32_e32 v92, v46, v60
	v_sub_f32_e32 v93, v47, v60
	v_add_f32_e32 v25, v64, v25
	v_mul_f32_e32 v94, v92, v92
	v_mul_f32_e32 v95, v93, v93
	v_add_f32_e32 v25, v65, v25
	v_sub_f32_e32 v96, v42, v60
	v_sub_f32_e32 v97, v43, v60
	v_add_f32_e32 v25, v94, v25
	v_mul_f32_e32 v42, v96, v96
	v_mul_f32_e32 v43, v97, v97
	v_add_f32_e32 v25, v95, v25
	v_sub_f32_e32 v98, v40, v60
	v_sub_f32_e32 v99, v41, v60
	v_add_f32_e32 v25, v42, v25
	v_mul_f32_e32 v100, v98, v98
	v_mul_f32_e32 v101, v99, v99
	v_add_f32_e32 v25, v43, v25
	v_sub_f32_e32 v44, v44, v60
	v_sub_f32_e32 v45, v45, v60
	v_add_f32_e32 v25, v100, v25
	v_mul_f32_e32 v102, v44, v44
	v_mul_f32_e32 v103, v45, v45
	v_add_f32_e32 v25, v101, v25
	v_sub_f32_e32 v46, v50, v60
	v_sub_f32_e32 v47, v51, v60
	v_add_f32_e32 v25, v102, v25
	v_mul_f32_e32 v104, v46, v46
	v_mul_f32_e32 v105, v47, v47
	v_add_f32_e32 v25, v103, v25
	v_sub_f32_e32 v48, v68, v60
	v_sub_f32_e32 v49, v69, v60
	v_add_f32_e32 v25, v104, v25
	v_mul_f32_e32 v68, v48, v48
	v_mul_f32_e32 v69, v49, v49
	v_add_f32_e32 v25, v105, v25
	v_sub_f32_e32 v50, v66, v60
	v_sub_f32_e32 v51, v67, v60
	v_add_f32_e32 v25, v68, v25
	v_mul_f32_e32 v66, v50, v50
	v_mul_f32_e32 v67, v51, v51
	v_add_f32_e32 v25, v69, v25
	v_sub_f32_e32 v34, v74, v60
	v_sub_f32_e32 v35, v75, v60
	v_add_f32_e32 v25, v66, v25
	v_mul_f32_e32 v74, v34, v34
	v_mul_f32_e32 v75, v35, v35
	v_add_f32_e32 v25, v67, v25
	v_sub_f32_e32 v36, v62, v60
	v_sub_f32_e32 v37, v63, v60
	v_add_f32_e32 v25, v74, v25
	v_mul_f32_e32 v62, v36, v36
	v_mul_f32_e32 v63, v37, v37
	v_add_f32_e32 v25, v75, v25
	v_sub_f32_e32 v38, v72, v60
	v_sub_f32_e32 v39, v73, v60
	v_add_f32_e32 v25, v62, v25
	v_mul_f32_e32 v72, v38, v38
	v_mul_f32_e32 v73, v39, v39
	v_add_f32_e32 v25, v63, v25
	v_sub_f32_e32 v40, v70, v60
	v_sub_f32_e32 v41, v71, v60
	v_add_f32_e32 v25, v72, v25
	v_mul_f32_e32 v60, v40, v40
	v_mul_f32_e32 v61, v41, v41
	v_add_f32_e32 v25, v73, v25
	v_add_f32_e32 v25, v60, v25
	v_add_f32_e32 v25, v61, v25
	ds_bpermute_b32 v27, v53, v25
	s_waitcnt lgkmcnt(0)
; #define P (*launderP(lp))
; __device__ __forceinline__ void phase_ln1(PREF P) {
;     ...
;     const float mu = wsum(s) * (1.f / 2048.f);
;     float vs = 0.f;
; #pragma unroll
;     for (int e = 0; e < 32; ++e) { float d = v[e] - mu; vs += d * d; }
;     const float rs = rsqrtf(wsum(vs) * (1.f / 2048.f) + LN_EPS);
; #pragma unroll
;     for (int u = 0; u < 4; ++u) {
;       const int c = u * 512 + lane * 8;
;       float4 g0 = *(const float4*)(P.ln1_g + c), g1 = *(const float4*)(P.ln1_g + c + 4);
;       float4 b0 = *(const float4*)(P.ln1_b + c), b1 = *(const float4*)(P.ln1_b + c + 4);
;       uint4 o;
;       o.x = pack2((v[u * 8 + 0] - mu) * rs * g0.x + b0.x, (v[u * 8 + 1] - mu) * rs * g0.y + b0.y);
;       o.y = pack2((v[u * 8 + 2] - mu) * rs * g0.z + b0.z, (v[u * 8 + 3] - mu) * rs * g0.w + b0.w);
;       o.z = pack2((v[u * 8 + 4] - mu) * rs * g1.x + b1.x, (v[u * 8 + 5] - mu) * rs * g1.y + b1.y);
;       o.w = pack2((v[u * 8 + 6] - mu) * rs * g1.z + b1.z, (v[u * 8 + 7] - mu) * rs * g1.w + b1.w);
;       *(uint4*)(P.hb + (size_t)t * 2048 + c) = o;
;     }
;     float am = 0.f;
; #pragma unroll
;     for (int u = 0; u < 4; ++u) {
;       const int c = u * 512 + lane * 8;
;       float4 g0 = *(const float4*)(P.ln1_g + c), g1 = *(const float4*)(P.ln1_g + c + 4);
;       float4 b0 = *(const float4*)(P.ln1_b + c), b1 = *(const float4*)(P.ln1_b + c + 4);
;       v[u * 8 + 0] = (v[u * 8 + 0] - mu) * rs * g0.x + b0.x; v[u * 8 + 1] = (v[u * 8 + 1] - mu) * rs * g0.y + b0.y;
;       v[u * 8 + 2] = (v[u * 8 + 2] - mu) * rs * g0.z + b0.z; v[u * 8 + 3] = (v[u * 8 + 3] - mu) * rs * g0.w + b0.w;
;       v[u * 8 + 4] = (v[u * 8 + 4] - mu) * rs * g1.x + b1.x; v[u * 8 + 5] = (v[u * 8 + 5] - mu) * rs * g1.y + b1.y;
;       v[u * 8 + 6] = (v[u * 8 + 6] - mu) * rs * g1.z + b1.z; v[u * 8 + 7] = (v[u * 8 + 7] - mu) * rs * g1.w + b1.w;
;     }
	v_add_f32_e32 v25, v25, v27
	ds_bpermute_b32 v27, v54, v25
	s_waitcnt lgkmcnt(0)
	v_add_f32_e32 v25, v25, v27
	ds_bpermute_b32 v27, v55, v25
	s_waitcnt lgkmcnt(0)
	v_add_f32_e32 v25, v25, v27
	ds_bpermute_b32 v27, v56, v25
	s_waitcnt lgkmcnt(0)
	v_add_f32_e32 v25, v25, v27
	ds_bpermute_b32 v27, v57, v25
	s_waitcnt lgkmcnt(0)
	v_add_f32_e32 v25, v25, v27
	ds_bpermute_b32 v27, v58, v25
	s_waitcnt lgkmcnt(0)
	v_add_f32_e32 v25, v25, v27
	v_fmamk_f32 v25, v25, 0x3a000000, v191
	v_cmp_gt_f32_e32 vcc, s6, v25
	v_mul_f32_e32 v27, 0x4b800000, v25
	s_nop 0
	v_cndmask_b32_e32 v25, v25, v27, vcc
	v_rsq_f32_e32 v25, v25
	s_nop 0
	v_mul_f32_e32 v27, 0x45800000, v25
	v_cndmask_b32_e32 v42, v25, v27, vcc
	v_mul_f32_e32 v32, v76, v42
	v_mul_f32_e32 v33, v77, v42
	v_mov_b32_e32 v25, v181
	v_fma_f32 v8, v8, v32, v12
	v_fma_f32 v9, v9, v33, v13
	v_mul_f32_e32 v44, v44, v42
	v_mul_f32_e32 v45, v45, v42
	v_cvt_pk_bf16_f32 v12, v8, v9
	v_mul_f32_e32 v8, v80, v42
	v_mul_f32_e32 v9, v81, v42
	v_mul_f32_e32 v46, v46, v42
	v_mul_f32_e32 v47, v47, v42
	v_fma_f32 v10, v10, v8, v14
	v_fma_f32 v11, v11, v9, v15
	v_mul_f32_e32 v48, v48, v42
	v_mul_f32_e32 v49, v49, v42
	v_cvt_pk_bf16_f32 v13, v10, v11
	v_mul_f32_e32 v10, v84, v42
	v_mul_f32_e32 v11, v85, v42
	v_mul_f32_e32 v50, v50, v42
	v_mul_f32_e32 v51, v51, v42
	v_fma_f32 v0, v0, v10, v4
	v_fma_f32 v1, v1, v11, v5
	v_mov_b32_e32 v27, v181
	v_cvt_pk_bf16_f32 v14, v0, v1
	v_mul_f32_e32 v0, v88, v42
	v_mul_f32_e32 v1, v89, v42
	v_mul_f32_e32 v72, v34, v42
	v_mul_f32_e32 v73, v35, v42
	v_fma_f32 v2, v2, v0, v6
	v_fma_f32 v3, v3, v1, v7
	v_mul_f32_e32 v74, v36, v42
	v_mul_f32_e32 v75, v37, v42
	v_cvt_pk_bf16_f32 v15, v2, v3
	flat_store_dwordx4 v[30:31], v[12:15]
	ds_read2_b64 v[2:5], v52 offset0:10 offset1:11
	v_mul_f32_e32 v30, v98, v42
	v_mul_f32_e32 v31, v99, v42
	v_mul_f32_e32 v76, v38, v42
	v_mul_f32_e32 v77, v39, v42
	v_mul_f32_e32 v78, v40, v42
	v_mul_f32_e32 v79, v41, v42
	s_waitcnt lgkmcnt(0)
	v_lshl_add_u64 v[2:3], v[2:3], 0, v[16:17]
	flat_load_dwordx4 v[12:15], v[2:3] offset:2048
	flat_load_dwordx4 v[60:63], v[2:3] offset:2064
	v_lshl_add_u64 v[2:3], v[4:5], 0, v[16:17]
	flat_load_dwordx4 v[4:7], v[2:3] offset:2048
	flat_load_dwordx4 v[64:67], v[2:3] offset:2064
	v_mul_f32_e32 v2, v90, v42
	v_mul_f32_e32 v3, v91, v42
	s_waitcnt vmcnt(0) lgkmcnt(0)
	v_fmac_f32_e32 v4, v12, v2
	v_fmac_f32_e32 v5, v13, v3
	s_nop 0
	v_cvt_pk_bf16_f32 v12, v4, v5
	v_mul_f32_e32 v4, v92, v42
	v_mul_f32_e32 v5, v93, v42
	s_nop 0
	v_fmac_f32_e32 v6, v14, v4
	v_fmac_f32_e32 v7, v15, v5
	s_nop 0
	v_cvt_pk_bf16_f32 v13, v6, v7
	v_mul_f32_e32 v6, v96, v42
	v_mul_f32_e32 v7, v97, v42
	s_nop 0
	v_fma_f32 v14, v60, v6, v64
	v_fma_f32 v15, v61, v7, v65
	v_fma_f32 v60, v62, v30, v66
	v_fma_f32 v61, v63, v31, v67
	v_cvt_pk_bf16_f32 v14, v14, v15
	v_cvt_pk_bf16_f32 v15, v60, v61
	ds_read_b64 v[60:61], v52 offset:344
	s_waitcnt lgkmcnt(0)
	v_lshl_add_u64 v[60:61], v[60:61], 0, v[18:19]
	v_lshl_add_u64 v[60:61], v[60:61], 0, v[180:181]
	flat_store_dwordx4 v[60:61], v[12:15] offset:1024
	ds_read2_b64 v[12:15], v52 offset0:10 offset1:11
	s_waitcnt lgkmcnt(0)
	v_lshl_add_u64 v[68:69], v[14:15], 0, v[24:25]
	v_lshl_add_u64 v[12:13], v[12:13], 0, v[24:25]
	flat_load_dwordx4 v[60:63], v[12:13]
	flat_load_dwordx4 v[64:67], v[12:13] offset:16
	s_nop 0
	flat_load_dwordx4 v[12:15], v[68:69]
	s_nop 0
	flat_load_dwordx4 v[68:71], v[68:69] offset:16
	s_waitcnt vmcnt(0) lgkmcnt(0)
	v_fmac_f32_e32 v12, v60, v44
	v_fmac_f32_e32 v13, v61, v45
	v_fmac_f32_e32 v14, v62, v46
	v_fmac_f32_e32 v15, v63, v47
	v_cvt_pk_bf16_f32 v12, v12, v13
	v_cvt_pk_bf16_f32 v13, v14, v15
	v_fma_f32 v14, v64, v48, v68
	v_fma_f32 v15, v65, v49, v69
	v_fma_f32 v60, v66, v50, v70
	v_fma_f32 v61, v67, v51, v71
	v_cvt_pk_bf16_f32 v14, v14, v15
	v_cvt_pk_bf16_f32 v15, v60, v61
	ds_read_b64 v[60:61], v52 offset:344
	s_waitcnt lgkmcnt(0)
	v_lshl_add_u64 v[60:61], v[60:61], 0, v[18:19]
	v_lshl_add_u64 v[60:61], v[60:61], 0, v[180:181]
	flat_store_dwordx4 v[60:61], v[12:15] offset:2048
	ds_read2_b64 v[12:15], v52 offset0:10 offset1:11
	s_waitcnt lgkmcnt(0)
	v_lshl_add_u64 v[68:69], v[14:15], 0, v[26:27]
	v_lshl_add_u64 v[12:13], v[12:13], 0, v[26:27]
	flat_load_dwordx4 v[60:63], v[12:13]
	flat_load_dwordx4 v[64:67], v[12:13] offset:16
	s_nop 0
	flat_load_dwordx4 v[12:15], v[68:69]
	s_nop 0
	flat_load_dwordx4 v[68:71], v[68:69] offset:16
	s_waitcnt vmcnt(0) lgkmcnt(0)
	v_fmac_f32_e32 v12, v60, v72
	v_fmac_f32_e32 v13, v61, v73
	v_fmac_f32_e32 v14, v62, v74
	v_fmac_f32_e32 v15, v63, v75
	v_cvt_pk_bf16_f32 v12, v12, v13
	v_cvt_pk_bf16_f32 v13, v14, v15
	v_fma_f32 v14, v76, v64, v68
	v_fma_f32 v15, v77, v65, v69
	v_fma_f32 v34, v78, v66, v70
	v_fma_f32 v35, v79, v67, v71
	v_cvt_pk_bf16_f32 v14, v14, v15
	v_cvt_pk_bf16_f32 v15, v34, v35
	ds_read_b64 v[34:35], v52 offset:344
	s_waitcnt lgkmcnt(0)
	v_lshl_add_u64 v[18:19], v[34:35], 0, v[18:19]
	v_lshl_add_u64 v[18:19], v[18:19], 0, v[180:181]
	flat_store_dwordx4 v[18:19], v[12:15] offset:3072
	ds_read2_b64 v[38:41], v52 offset0:10 offset1:11
	s_waitcnt lgkmcnt(0)
	v_lshl_add_u64 v[18:19], v[38:39], 0, v[16:17]
	v_lshl_add_u64 v[42:43], v[40:41], 0, v[16:17]
	flat_load_dwordx4 v[12:15], v[18:19]
	flat_load_dwordx4 v[34:37], v[18:19] offset:16
	flat_load_dwordx4 v[60:63], v[42:43]
	flat_load_dwordx4 v[64:67], v[42:43] offset:16
	s_waitcnt vmcnt(0) lgkmcnt(0)
	v_fma_f32 v59, v32, v12, v60
	v_fma_f32 v60, v33, v13, v61
	v_fma_f32 v61, v8, v14, v62
	v_fmac_f32_e32 v63, v9, v15
	v_fma_f32 v62, v10, v34, v64
	v_fma_f32 v64, v11, v35, v65
	flat_load_dwordx4 v[8:11], v[18:19] offset:2048
	flat_load_dwordx4 v[68:71], v[18:19] offset:2064
	s_nop 0
	flat_load_dwordx4 v[16:19], v[42:43] offset:2048
	flat_load_dwordx4 v[12:15], v[42:43] offset:2064
	v_fma_f32 v65, v0, v36, v66
	v_fmac_f32_e32 v67, v1, v37
	s_waitcnt vmcnt(0) lgkmcnt(0)
; #define P (*launderP(lp))
; DEV unsigned q4(float a, float b, float c, float d, float inv, int off) {
;   int qa = (int)rintf(a * inv), qb = (int)rintf(b * inv), qc = (int)rintf(c * inv), qd = (int)rintf(d * inv);
;   qa = min(max(qa, -127), 127) + off; qb = min(max(qb, -127), 127) + off;
;   qc = min(max(qc, -127), 127) + off; qd = min(max(qd, -127), 127) + off;
;   return (unsigned)(qa & 255) | ((unsigned)(qb & 255) << 8) | ((unsigned)(qc & 255) << 16) | ((unsigned)(qd & 255) << 24);
; __device__ __forceinline__ void phase_ln1(PREF P) {
;     ...
;     float am = 0.f;
; #pragma unroll
;     for (int u = 0; u < 4; ++u) {
;       const int c = u * 512 + lane * 8;
;       float4 g0 = *(const float4*)(P.ln1_g + c), g1 = *(const float4*)(P.ln1_g + c + 4);
;       float4 b0 = *(const float4*)(P.ln1_b + c), b1 = *(const float4*)(P.ln1_b + c + 4);
;       v[u * 8 + 0] = (v[u * 8 + 0] - mu) * rs * g0.x + b0.x; v[u * 8 + 1] = (v[u * 8 + 1] - mu) * rs * g0.y + b0.y;
;       v[u * 8 + 2] = (v[u * 8 + 2] - mu) * rs * g0.z + b0.z; v[u * 8 + 3] = (v[u * 8 + 3] - mu) * rs * g0.w + b0.w;
;       v[u * 8 + 4] = (v[u * 8 + 4] - mu) * rs * g1.x + b1.x; v[u * 8 + 5] = (v[u * 8 + 5] - mu) * rs * g1.y + b1.y;
;       v[u * 8 + 6] = (v[u * 8 + 6] - mu) * rs * g1.z + b1.z; v[u * 8 + 7] = (v[u * 8 + 7] - mu) * rs * g1.w + b1.w;
;     }
; #pragma unroll
;     for (int e = 0; e < 32; ++e) am = fmaxf(am, fabsf(v[e]));
;     am = wmax(am);
;     const float sc = am > 0.f ? am * (1.f / 127.f) : 1.f;
;     const float inv = 1.f / sc;
; #pragma unroll
;     for (int u = 0; u < 4; ++u) {
;       u32x2 o;
;       o.x = q4(v[u * 8 + 0], v[u * 8 + 1], v[u * 8 + 2], v[u * 8 + 3], inv, 0);
;       o.y = q4(v[u * 8 + 4], v[u * 8 + 5], v[u * 8 + 6], v[u * 8 + 7], inv, 0);
	v_fma_f32 v35, v4, v10, v18
	v_fmac_f32_e32 v19, v5, v11
	v_lshl_add_u64 v[4:5], v[38:39], 0, v[24:25]
	v_fma_f32 v37, v2, v8, v16
	v_fma_f32 v36, v3, v9, v17
	v_fma_f32 v34, v6, v68, v12
	v_fma_f32 v33, v7, v69, v13
	v_fma_f32 v32, v30, v70, v14
	v_fmac_f32_e32 v15, v31, v71
	flat_load_dwordx4 v[0:3], v[4:5]
	flat_load_dwordx4 v[68:71], v[4:5] offset:16
	v_lshl_add_u64 v[4:5], v[40:41], 0, v[24:25]
	flat_load_dwordx4 v[10:13], v[4:5]
	flat_load_dwordx4 v[6:9], v[4:5] offset:16
	s_waitcnt vmcnt(0) lgkmcnt(0)
	v_fma_f32 v30, v44, v0, v10
	v_fma_f32 v25, v45, v1, v11
	v_lshl_add_u64 v[0:1], v[38:39], 0, v[26:27]
	v_fma_f32 v18, v46, v2, v12
	v_fmac_f32_e32 v13, v47, v3
	v_fma_f32 v17, v48, v68, v6
	v_fma_f32 v16, v49, v69, v7
	flat_load_dwordx4 v[42:45], v[0:1]
	flat_load_dwordx4 v[46:49], v[0:1] offset:16
	v_lshl_add_u64 v[0:1], v[40:41], 0, v[26:27]
	flat_load_dwordx4 v[4:7], v[0:1]
	s_nop 0
	flat_load_dwordx4 v[0:3], v[0:1] offset:16
	v_fma_f32 v14, v50, v70, v8
	v_fmac_f32_e32 v9, v51, v71
	s_waitcnt vmcnt(0) lgkmcnt(0)
	v_fma_f32 v10, v74, v44, v6
	v_fma_f32 v6, v76, v46, v0
	v_max3_f32 v0, |v59|, 0, |v60|
	v_max3_f32 v0, v0, |v61|, |v63|
	v_max3_f32 v0, v0, |v62|, |v64|
	v_max3_f32 v0, v0, |v65|, |v67|
	v_max3_f32 v0, v0, |v37|, |v36|
	v_max3_f32 v0, v0, |v35|, |v19|
	v_max3_f32 v0, v0, |v34|, |v33|
	v_max3_f32 v0, v0, |v32|, |v15|
	v_max3_f32 v0, v0, |v30|, |v25|
	v_max3_f32 v0, v0, |v18|, |v13|
	v_max3_f32 v0, v0, |v17|, |v16|
	v_fma_f32 v12, v72, v42, v4
	v_fma_f32 v11, v73, v43, v5
	v_max3_f32 v0, v0, |v14|, |v9|
	v_fmac_f32_e32 v7, v75, v45
	v_max3_f32 v0, v0, |v12|, |v11|
	v_fma_f32 v5, v77, v47, v1
	v_max3_f32 v0, v0, |v10|, |v7|
	v_fma_f32 v4, v78, v48, v2
	v_fmac_f32_e32 v3, v79, v49
	v_max3_f32 v0, v0, |v6|, |v5|
	v_max3_f32 v0, v0, |v4|, |v3|
	ds_bpermute_b32 v1, v53, v0
	s_waitcnt lgkmcnt(0)
	v_max_f32_e32 v1, v1, v1
	v_max_f32_e32 v0, v0, v1
	ds_bpermute_b32 v1, v54, v0
	s_waitcnt lgkmcnt(0)
	v_max_f32_e32 v1, v1, v1
	v_max_f32_e32 v0, v0, v1
	ds_bpermute_b32 v1, v55, v0
	s_waitcnt lgkmcnt(0)
	v_max_f32_e32 v1, v1, v1
	v_max_f32_e32 v0, v0, v1
	ds_bpermute_b32 v1, v56, v0
	s_waitcnt lgkmcnt(0)
	v_max_f32_e32 v1, v1, v1
	v_max_f32_e32 v0, v0, v1
	ds_bpermute_b32 v1, v57, v0
	s_waitcnt lgkmcnt(0)
	v_max_f32_e32 v1, v1, v1
	v_max_f32_e32 v0, v0, v1
	ds_bpermute_b32 v1, v58, v0
	s_waitcnt lgkmcnt(0)
	v_max_f32_e32 v1, v1, v1
	v_max_f32_e32 v0, v0, v1
	v_cmp_lt_f32_e32 vcc, 0, v0
	v_mul_f32_e32 v0, 0x3c010204, v0
	s_nop 0
	v_cndmask_b32_e32 v2, 1.0, v0, vcc
	v_div_scale_f32 v0, s[14:15], v2, v2, 1.0
	v_rcp_f32_e32 v1, v0
	s_nop 0
	v_fma_f32 v8, -v0, v1, 1.0
	v_fmac_f32_e32 v1, v8, v1
	v_div_scale_f32 v8, vcc, 1.0, v2, 1.0
	v_mul_f32_e32 v27, v8, v1
	v_fma_f32 v31, -v0, v27, v8
	v_fmac_f32_e32 v27, v31, v1
	v_fma_f32 v0, -v0, v27, v8
	v_div_fmas_f32 v0, v0, v1, v27
	v_div_fixup_f32 v8, v0, v2, 1.0
	v_mul_f32_e32 v1, v60, v8
	v_mul_f32_e32 v27, v61, v8
	v_mul_f32_e32 v0, v59, v8
	v_rndne_f32_e32 v1, v1
	v_rndne_f32_e32 v27, v27
	v_mul_f32_e32 v31, v63, v8
	v_rndne_f32_e32 v0, v0
	v_cvt_i32_f32_e32 v1, v1
	v_cvt_i32_f32_e32 v27, v27
	v_rndne_f32_e32 v31, v31
	v_cvt_i32_f32_e32 v0, v0
	v_cvt_i32_f32_e32 v31, v31
	v_med3_i32 v1, v1, s29, v189
	v_med3_i32 v27, v27, s29, v189
	v_med3_i32 v0, v0, s29, v189
	v_med3_i32 v31, v31, s29, v189
	v_lshlrev_b32_e32 v1, 8, v1
	v_lshlrev_b32_e32 v27, 16, v27
	v_and_b32_e32 v1, 0xff00, v1
	v_and_b32_e32 v27, 0xff0000, v27
	v_perm_b32 v0, v31, v0, s33
	v_or3_b32 v0, v0, v1, v27
	v_mul_f32_e32 v1, v62, v8
	v_mul_f32_e32 v38, v67, v8
	v_rndne_f32_e32 v1, v1
	v_rndne_f32_e32 v38, v38
	v_cvt_i32_f32_e32 v1, v1
	v_cvt_i32_f32_e32 v38, v38
	v_mul_f32_e32 v27, v64, v8
	v_mul_f32_e32 v31, v65, v8
	v_rndne_f32_e32 v27, v27
	v_rndne_f32_e32 v31, v31
	v_cvt_i32_f32_e32 v27, v27
	v_cvt_i32_f32_e32 v31, v31
	v_med3_i32 v1, v1, s29, v189
	v_med3_i32 v38, v38, s29, v189
	v_perm_b32 v1, v38, v1, s33
	ds_read_b64 v[38:39], v52 offset:488
	v_med3_i32 v27, v27, s29, v189
	v_med3_i32 v31, v31, s29, v189
	v_lshlrev_b32_e32 v27, 8, v27
	v_lshlrev_b32_e32 v31, 16, v31
	v_and_b32_e32 v27, 0xff00, v27
	v_and_b32_e32 v31, 0xff0000, v31
	s_waitcnt lgkmcnt(0)
; #define P (*launderP(lp))
; DEV unsigned q4(float a, float b, float c, float d, float inv, int off) {
;   int qa = (int)rintf(a * inv), qb = (int)rintf(b * inv), qc = (int)rintf(c * inv), qd = (int)rintf(d * inv);
;   qa = min(max(qa, -127), 127) + off; qb = min(max(qb, -127), 127) + off;
;   qc = min(max(qc, -127), 127) + off; qd = min(max(qd, -127), 127) + off;
;   return (unsigned)(qa & 255) | ((unsigned)(qb & 255) << 8) | ((unsigned)(qc & 255) << 16) | ((unsigned)(qd & 255) << 24);
; __device__ __forceinline__ void phase_ln1(PREF P) {
;     ...
; #pragma unroll
;     for (int u = 0; u < 4; ++u) {
;       u32x2 o;
;       o.x = q4(v[u * 8 + 0], v[u * 8 + 1], v[u * 8 + 2], v[u * 8 + 3], inv, 0);
;       o.y = q4(v[u * 8 + 4], v[u * 8 + 5], v[u * 8 + 6], v[u * 8 + 7], inv, 0);
;       *(u32x2*)(P.h8 + (size_t)t * 2048 + u * 512 + lane * 8) = o;
;     }
	v_lshl_add_u64 v[38:39], v[38:39], 0, v[28:29]
	v_or3_b32 v1, v1, v27, v31
	v_lshl_add_u64 v[38:39], v[38:39], 0, v[22:23]
	flat_store_dwordx2 v[38:39], v[0:1]
	v_mul_f32_e32 v1, v36, v8
	v_mul_f32_e32 v27, v35, v8
	v_mul_f32_e32 v0, v37, v8
	v_rndne_f32_e32 v1, v1
	v_rndne_f32_e32 v27, v27
	v_mul_f32_e32 v19, v19, v8
	v_rndne_f32_e32 v0, v0
	v_cvt_i32_f32_e32 v1, v1
	v_cvt_i32_f32_e32 v27, v27
	v_rndne_f32_e32 v19, v19
	v_cvt_i32_f32_e32 v0, v0
	v_cvt_i32_f32_e32 v19, v19
	v_med3_i32 v1, v1, s29, v189
	v_med3_i32 v27, v27, s29, v189
	v_med3_i32 v0, v0, s29, v189
	v_med3_i32 v19, v19, s29, v189
	v_lshlrev_b32_e32 v1, 8, v1
	v_lshlrev_b32_e32 v27, 16, v27
	v_and_b32_e32 v1, 0xff00, v1
	v_and_b32_e32 v27, 0xff0000, v27
	v_perm_b32 v0, v19, v0, s33
	v_or3_b32 v0, v0, v1, v27
	v_mul_f32_e32 v19, v33, v8
	v_mul_f32_e32 v27, v32, v8
	v_mul_f32_e32 v1, v34, v8
	v_rndne_f32_e32 v19, v19
	v_rndne_f32_e32 v27, v27
	v_mul_f32_e32 v15, v15, v8
	v_rndne_f32_e32 v1, v1
	v_cvt_i32_f32_e32 v19, v19
	v_cvt_i32_f32_e32 v27, v27
	v_rndne_f32_e32 v15, v15
	v_cvt_i32_f32_e32 v1, v1
	v_cvt_i32_f32_e32 v15, v15
	ds_read_b64 v[32:33], v52 offset:488
	v_med3_i32 v19, v19, s29, v189
	v_med3_i32 v27, v27, s29, v189
	v_med3_i32 v1, v1, s29, v189
	v_med3_i32 v15, v15, s29, v189
	v_lshlrev_b32_e32 v19, 8, v19
	v_lshlrev_b32_e32 v27, 16, v27
	v_and_b32_e32 v19, 0xff00, v19
	v_and_b32_e32 v27, 0xff0000, v27
	v_perm_b32 v1, v15, v1, s33
	s_waitcnt lgkmcnt(0)
	v_lshl_add_u64 v[32:33], v[32:33], 0, v[28:29]
	v_or3_b32 v1, v1, v19, v27
	v_lshl_add_u64 v[32:33], v[32:33], 0, v[22:23]
	flat_store_dwordx2 v[32:33], v[0:1] offset:512
	v_mul_f32_e32 v1, v25, v8
	v_mul_f32_e32 v15, v18, v8
	v_mul_f32_e32 v0, v30, v8
	v_rndne_f32_e32 v1, v1
	v_rndne_f32_e32 v15, v15
	v_mul_f32_e32 v13, v13, v8
	v_rndne_f32_e32 v0, v0
	v_cvt_i32_f32_e32 v1, v1
	v_cvt_i32_f32_e32 v15, v15
	v_rndne_f32_e32 v13, v13
	v_cvt_i32_f32_e32 v0, v0
	v_cvt_i32_f32_e32 v13, v13
	v_med3_i32 v1, v1, s29, v189
	v_med3_i32 v15, v15, s29, v189
	v_med3_i32 v0, v0, s29, v189
	v_med3_i32 v13, v13, s29, v189
	v_lshlrev_b32_e32 v1, 8, v1
	v_lshlrev_b32_e32 v15, 16, v15
	v_and_b32_e32 v1, 0xff00, v1
	v_and_b32_e32 v15, 0xff0000, v15
	v_perm_b32 v0, v13, v0, s33
	v_mul_f32_e32 v13, v16, v8
	v_mul_f32_e32 v14, v14, v8
	v_or3_b32 v0, v0, v1, v15
	v_mul_f32_e32 v1, v17, v8
	v_rndne_f32_e32 v13, v13
	v_rndne_f32_e32 v14, v14
	v_mul_f32_e32 v9, v9, v8
	v_rndne_f32_e32 v1, v1
	v_cvt_i32_f32_e32 v13, v13
	v_cvt_i32_f32_e32 v14, v14
	v_rndne_f32_e32 v9, v9
	v_cvt_i32_f32_e32 v1, v1
	v_cvt_i32_f32_e32 v9, v9
	v_med3_i32 v13, v13, s29, v189
	v_med3_i32 v14, v14, s29, v189
	v_med3_i32 v1, v1, s29, v189
	v_med3_i32 v9, v9, s29, v189
	v_lshlrev_b32_e32 v13, 8, v13
	v_lshlrev_b32_e32 v14, 16, v14
	v_and_b32_e32 v13, 0xff00, v13
	v_and_b32_e32 v14, 0xff0000, v14
	v_perm_b32 v1, v9, v1, s33
	v_or3_b32 v1, v1, v13, v14
	ds_read_b64 v[14:15], v52 offset:488
	v_mul_f32_e32 v9, v10, v8
	v_rndne_f32_e32 v9, v9
	v_mul_f32_e32 v7, v7, v8
	v_cvt_i32_f32_e32 v9, v9
	s_waitcnt lgkmcnt(0)
	v_lshl_add_u64 v[14:15], v[14:15], 0, v[28:29]
	v_lshl_add_u64 v[14:15], v[14:15], 0, v[22:23]
	flat_store_dwordx2 v[14:15], v[0:1] offset:1024
	v_mul_f32_e32 v1, v11, v8
	v_mul_f32_e32 v0, v12, v8
	v_rndne_f32_e32 v1, v1
	v_rndne_f32_e32 v0, v0
	v_cvt_i32_f32_e32 v1, v1
	v_rndne_f32_e32 v7, v7
	v_cvt_i32_f32_e32 v0, v0
	v_cvt_i32_f32_e32 v7, v7
	v_med3_i32 v1, v1, s29, v189
	v_med3_i32 v9, v9, s29, v189
	v_med3_i32 v0, v0, s29, v189
	v_med3_i32 v7, v7, s29, v189
	v_lshlrev_b32_e32 v1, 8, v1
	v_lshlrev_b32_e32 v9, 16, v9
	v_and_b32_e32 v1, 0xff00, v1
	v_and_b32_e32 v9, 0xff0000, v9
	v_perm_b32 v0, v7, v0, s33
	v_mul_f32_e32 v5, v5, v8
	v_mul_f32_e32 v4, v4, v8
	v_or3_b32 v0, v0, v1, v9
	v_mul_f32_e32 v1, v6, v8
	v_rndne_f32_e32 v5, v5
	v_rndne_f32_e32 v4, v4
	v_mul_f32_e32 v3, v3, v8
	v_rndne_f32_e32 v1, v1
	v_cvt_i32_f32_e32 v5, v5
	v_cvt_i32_f32_e32 v4, v4
	v_rndne_f32_e32 v3, v3
	v_cvt_i32_f32_e32 v1, v1
	v_cvt_i32_f32_e32 v3, v3
	v_med3_i32 v5, v5, s29, v189
	v_med3_i32 v4, v4, s29, v189
	v_med3_i32 v1, v1, s29, v189
	v_med3_i32 v3, v3, s29, v189
	v_lshlrev_b32_e32 v5, 8, v5
	v_lshlrev_b32_e32 v4, 16, v4
	v_and_b32_e32 v5, 0xff00, v5
	v_and_b32_e32 v4, 0xff0000, v4
	v_perm_b32 v1, v3, v1, s33
	v_or3_b32 v1, v1, v5, v4
	ds_read_b64 v[4:5], v52 offset:488
	s_waitcnt lgkmcnt(0)
	v_lshl_add_u64 v[4:5], v[4:5], 0, v[28:29]
	v_lshl_add_u64 v[4:5], v[4:5], 0, v[22:23]
	flat_store_dwordx2 v[4:5], v[0:1] offset:1536
	s_and_saveexec_b64 s[14:15], s[36:37]
	s_cbranch_execz .LBB0_511
	ds_read_b64 v[0:1], v52 offset:448
	s_waitcnt lgkmcnt(0)
	v_lshl_add_u64 v[0:1], v[20:21], 2, v[0:1]
	flat_store_dword v[0:1], v2
	s_branch .LBB0_511

; DEV f32x4 mma_step(bf16x8 a, bf16x8 b, f32x4 c) { return MFMA(a, b, c); }
; template <class FragT, class AccT>
; DEV void gemm_core_t(const char* __restrict__ A, size_t lda_bytes, const char* __restrict__ Bt, size_t ldb_bytes, int kbytes,
;                      int m0, int n0, int Sshift, int dl, char* smem, AccT (&acc)[4][4]) {
;     ...
;   for (int kt = 0; kt < nk; ++kt) {
;     const unsigned so = (unsigned)(kt & 1) * 32768u;
;     char* nxt = smem + ((kt + 1) & 1) * 32768;
;     if (kt + 1 < nk) {
; #pragma unroll
;       for (int u = 0; u < 4; ++u) {
;         __builtin_amdgcn_global_load_lds((const unsigned*)(ap[u] + (size_t)(kt + 1) * 128), (unsigned*)(nxt + (wid * 4 + u) * 1024 + lane * 16), 16, 0, 0);
;         __builtin_amdgcn_global_load_lds((const unsigned*)(bp[u] + (size_t)(kt + 1) * 128), (unsigned*)(nxt + 16384 + (wid * 4 + u) * 1024 + lane * 16), 16, 0, 0);
;       }
;     }
;     FragT xa[2][4], wb[2][4];
;     asm volatile(
;         "ds_read_b128 %0, %16\n\t"
;         "ds_read_b128 %1, %16 offset:2048\n\t"
;         "ds_read_b128 %2, %16 offset:4096\n\t"
;         "ds_read_b128 %3, %16 offset:6144\n\t"
;         "ds_read_b128 %4, %18\n\t"
;         "ds_read_b128 %5, %18 offset:2048\n\t"
;         "ds_read_b128 %6, %18 offset:8192\n\t"
;         "ds_read_b128 %7, %18 offset:10240\n\t"
;         "ds_read_b128 %8, %17\n\t"
;         "ds_read_b128 %9, %17 offset:2048\n\t"
;         "ds_read_b128 %10, %17 offset:4096\n\t"
;         "ds_read_b128 %11, %17 offset:6144\n\t"
;         "ds_read_b128 %12, %19\n\t"
;         "ds_read_b128 %13, %19 offset:2048\n\t"
;         "ds_read_b128 %14, %19 offset:8192\n\t"
;         "ds_read_b128 %15, %19 offset:10240\n\t"
;         "s_waitcnt lgkmcnt(8)"
;         : "=&v"(xa[0][0]), "=&v"(xa[0][1]), "=&v"(xa[0][2]), "=&v"(xa[0][3]), "=&v"(wb[0][0]), "=&v"(wb[0][1]), "=&v"(wb[0][2]),
;           "=&v"(wb[0][3]), "=&v"(xa[1][0]), "=&v"(xa[1][1]), "=&v"(xa[1][2]), "=&v"(xa[1][3]), "=&v"(wb[1][0]), "=&v"(wb[1][1]),
;           "=&v"(wb[1][2]), "=&v"(wb[1][3])
;         : "v"(a0 + so), "v"((a0 ^ 64u) + so), "v"(b0 + so), "v"((b0 ^ 64u) + so)
;         : "memory");
;     __builtin_amdgcn_s_setprio(1);
; #pragma unroll
;     for (int i = 0; i < 4; ++i)
; #pragma unroll
;       for (int j = 0; j < 4; ++j) acc[i][j] = mma_step(wb[0][j], xa[0][i], acc[i][j]);
;     asm volatile("s_waitcnt lgkmcnt(0)"
.LBB0_565:
	s_add_i32 s15, s1, 0xffff8000
	s_and_b32 s15, s15, 0x8000
	v_add_u32_e32 v152, s15, v84
	v_add_u32_e32 v153, s15, v87
	v_or_b32_e32 v154, s15, v85
	v_or_b32_e32 v155, s15, v86
	s_and_b32 s15, s1, 0x8000
	s_add_i32 s15, s15, s62
	s_mov_b32 m0, s15
	ds_read_b128 v[88:91], v152
	global_load_lds_dwordx4 v78, s[64:65]
	ds_read_b128 v[92:95], v152 offset:2048
	s_add_i32 m0, s15, 0x4000
	ds_read_b128 v[96:99], v152 offset:4096
	global_load_lds_dwordx4 v76, s[66:67]
	ds_read_b128 v[100:103], v152 offset:6144
	s_add_i32 m0, s15, 0x400
	ds_read_b128 v[104:107], v154
	global_load_lds_dwordx4 v74, s[64:65]
	ds_read_b128 v[108:111], v154 offset:2048
	s_add_i32 m0, s15, 0x4400
	ds_read_b128 v[112:115], v154 offset:8192
	global_load_lds_dwordx4 v72, s[66:67]
	ds_read_b128 v[116:119], v154 offset:10240
	ds_read_b128 v[120:123], v153
	ds_read_b128 v[124:127], v153 offset:2048
	ds_read_b128 v[128:131], v153 offset:4096
	ds_read_b128 v[132:135], v153 offset:6144
	ds_read_b128 v[136:139], v155
	ds_read_b128 v[140:143], v155 offset:2048
	ds_read_b128 v[144:147], v155 offset:8192
	ds_read_b128 v[148:151], v155 offset:10240
	s_waitcnt lgkmcnt(8)
	s_setprio 1
	v_mfma_i32_16x16x64_i8 v[60:63], v[104:107], v[88:91], v[60:63]
	v_mfma_i32_16x16x64_i8 v[56:59], v[108:111], v[88:91], v[56:59]
	s_add_i32 m0, s15, 0x800
	v_mfma_i32_16x16x64_i8 v[52:55], v[112:115], v[88:91], v[52:55]
	global_load_lds_dwordx4 v70, s[64:65]
	v_mfma_i32_16x16x64_i8 v[48:51], v[116:119], v[88:91], v[48:51]
	v_mfma_i32_16x16x64_i8 v[44:47], v[104:107], v[92:95], v[44:47]
	v_mfma_i32_16x16x64_i8 v[40:43], v[108:111], v[92:95], v[40:43]
	s_add_i32 m0, s15, 0x4800
	v_mfma_i32_16x16x64_i8 v[36:39], v[112:115], v[92:95], v[36:39]
	global_load_lds_dwordx4 v68, s[66:67]
	v_mfma_i32_16x16x64_i8 v[32:35], v[116:119], v[92:95], v[32:35]
	v_mfma_i32_16x16x64_i8 v[28:31], v[104:107], v[96:99], v[28:31]
	v_mfma_i32_16x16x64_i8 v[24:27], v[108:111], v[96:99], v[24:27]
	s_add_i32 m0, s15, 0xc00
	v_mfma_i32_16x16x64_i8 v[20:23], v[112:115], v[96:99], v[20:23]
	global_load_lds_dwordx4 v66, s[64:65]
	v_mfma_i32_16x16x64_i8 v[16:19], v[116:119], v[96:99], v[16:19]
	v_mfma_i32_16x16x64_i8 v[12:15], v[104:107], v[100:103], v[12:15]
	v_mfma_i32_16x16x64_i8 v[8:11], v[108:111], v[100:103], v[8:11]
	s_add_i32 m0, s15, 0x4c00
	v_mfma_i32_16x16x64_i8 v[4:7], v[112:115], v[100:103], v[4:7]
	global_load_lds_dwordx4 v64, s[66:67]
	v_mfma_i32_16x16x64_i8 v[0:3], v[116:119], v[100:103], v[0:3]
	s_waitcnt lgkmcnt(0)
	s_nop 0
	v_mfma_i32_16x16x64_i8 v[60:63], v[136:139], v[120:123], v[60:63]
	v_mfma_i32_16x16x64_i8 v[56:59], v[140:143], v[120:123], v[56:59]
	v_mfma_i32_16x16x64_i8 v[52:55], v[144:147], v[120:123], v[52:55]
	v_mfma_i32_16x16x64_i8 v[48:51], v[148:151], v[120:123], v[48:51]
	v_mfma_i32_16x16x64_i8 v[44:47], v[136:139], v[124:127], v[44:47]
	v_mfma_i32_16x16x64_i8 v[40:43], v[140:143], v[124:127], v[40:43]
	v_mfma_i32_16x16x64_i8 v[36:39], v[144:147], v[124:127], v[36:39]
	v_mfma_i32_16x16x64_i8 v[32:35], v[148:151], v[124:127], v[32:35]
	v_mfma_i32_16x16x64_i8 v[28:31], v[136:139], v[128:131], v[28:31]
	v_mfma_i32_16x16x64_i8 v[24:27], v[140:143], v[128:131], v[24:27]
	v_mfma_i32_16x16x64_i8 v[20:23], v[144:147], v[128:131], v[20:23]
	v_mfma_i32_16x16x64_i8 v[16:19], v[148:151], v[128:131], v[16:19]
	v_mfma_i32_16x16x64_i8 v[12:15], v[136:139], v[132:135], v[12:15]
	v_mfma_i32_16x16x64_i8 v[8:11], v[140:143], v[132:135], v[8:11]
	v_mfma_i32_16x16x64_i8 v[4:7], v[144:147], v[132:135], v[4:7]
	v_mfma_i32_16x16x64_i8 v[0:3], v[148:151], v[132:135], v[0:3]
	s_setprio 0
	s_waitcnt vmcnt(0)
	s_add_u32 s4, s4, 0x80
	s_addc_u32 s5, s5, 0
	s_add_u32 s64, s64, 0x80
	s_addc_u32 s65, s65, 0
	s_add_u32 s66, s66, 0x80
	s_addc_u32 s67, s67, 0
	s_add_i32 s1, s1, 0x8000
	s_cmpk_lg_i32 s4, 0x780
	s_waitcnt vmcnt(0) lgkmcnt(0)
	s_barrier
	s_cbranch_scc1 .LBB0_565
	v_add_u32_e32 v83, 0x8000, v84
	v_add_u32_e32 v132, 0x8000, v87
	v_or_b32_e32 v133, 0x8000, v85
	v_or_b32_e32 v134, 0x8000, v86
	ds_read_b128 v[64:67], v83
	ds_read_b128 v[68:71], v83 offset:2048
	ds_read_b128 v[72:75], v83 offset:4096
	ds_read_b128 v[76:79], v83 offset:6144
	ds_read_b128 v[84:87], v133
	ds_read_b128 v[88:91], v133 offset:2048
	ds_read_b128 v[92:95], v133 offset:8192
	ds_read_b128 v[96:99], v133 offset:10240
	ds_read_b128 v[100:103], v132
	ds_read_b128 v[104:107], v132 offset:2048
	ds_read_b128 v[108:111], v132 offset:4096
	ds_read_b128 v[112:115], v132 offset:6144
	ds_read_b128 v[116:119], v134
	ds_read_b128 v[120:123], v134 offset:2048
	ds_read_b128 v[124:127], v134 offset:8192
	ds_read_b128 v[128:131], v134 offset:10240
	s_waitcnt lgkmcnt(8)
	s_setprio 1
	v_mfma_i32_16x16x64_i8 v[60:63], v[84:87], v[64:67], v[60:63]
	v_mfma_i32_16x16x64_i8 v[56:59], v[88:91], v[64:67], v[56:59]
	v_mfma_i32_16x16x64_i8 v[52:55], v[92:95], v[64:67], v[52:55]
	v_mfma_i32_16x16x64_i8 v[48:51], v[96:99], v[64:67], v[48:51]
	v_mfma_i32_16x16x64_i8 v[44:47], v[84:87], v[68:71], v[44:47]
	v_mfma_i32_16x16x64_i8 v[40:43], v[88:91], v[68:71], v[40:43]
	v_mfma_i32_16x16x64_i8 v[36:39], v[92:95], v[68:71], v[36:39]
	v_mfma_i32_16x16x64_i8 v[32:35], v[96:99], v[68:71], v[32:35]
	v_mfma_i32_16x16x64_i8 v[28:31], v[84:87], v[72:75], v[28:31]
	v_mfma_i32_16x16x64_i8 v[24:27], v[88:91], v[72:75], v[24:27]
	v_mfma_i32_16x16x64_i8 v[20:23], v[92:95], v[72:75], v[20:23]
	v_mfma_i32_16x16x64_i8 v[16:19], v[96:99], v[72:75], v[16:19]
	v_mfma_i32_16x16x64_i8 v[12:15], v[84:87], v[76:79], v[12:15]
	v_mfma_i32_16x16x64_i8 v[8:11], v[88:91], v[76:79], v[8:11]
	v_mfma_i32_16x16x64_i8 v[4:7], v[92:95], v[76:79], v[4:7]
	v_mfma_i32_16x16x64_i8 v[0:3], v[96:99], v[76:79], v[0:3]
	s_waitcnt lgkmcnt(0)
	s_nop 0
	v_mfma_i32_16x16x64_i8 v[60:63], v[116:119], v[100:103], v[60:63]
	v_mfma_i32_16x16x64_i8 v[56:59], v[120:123], v[100:103], v[56:59]
	v_mfma_i32_16x16x64_i8 v[52:55], v[124:127], v[100:103], v[52:55]
	v_mfma_i32_16x16x64_i8 v[64:67], v[128:131], v[100:103], v[48:51]
	v_mfma_i32_16x16x64_i8 v[44:47], v[116:119], v[104:107], v[44:47]
	v_mfma_i32_16x16x64_i8 v[48:51], v[120:123], v[104:107], v[40:43]
	v_mfma_i32_16x16x64_i8 v[38:41], v[124:127], v[104:107], v[36:39]
	v_mfma_i32_16x16x64_i8 v[68:71], v[128:131], v[104:107], v[32:35]
	v_mfma_i32_16x16x64_i8 v[28:31], v[116:119], v[108:111], v[28:31]
	v_mfma_i32_16x16x64_i8 v[34:37], v[120:123], v[108:111], v[24:27]
	v_mfma_i32_16x16x64_i8 v[72:75], v[124:127], v[108:111], v[20:23]
	v_mfma_i32_16x16x64_i8 v[76:79], v[128:131], v[108:111], v[16:19]
	v_mfma_i32_16x16x64_i8 v[12:15], v[116:119], v[112:115], v[12:15]
	v_mfma_i32_16x16x64_i8 v[84:87], v[120:123], v[112:115], v[8:11]
	v_mfma_i32_16x16x64_i8 v[88:91], v[124:127], v[112:115], v[4:7]
	v_mfma_i32_16x16x64_i8 v[92:95], v[128:131], v[112:115], v[0:3]
	s_setprio 0
	s_waitcnt vmcnt(0)
	s_barrier
; #define P (*launderP(lp))
; __device__ __forceinline__ void phase_gemm45(PREF P, char* smem, int which) {
;     ...
; #pragma unroll
;       for (int i = 0; i < 4; ++i) {
;         const int row = m0 + wm * 64 + i * 16 + l15;
;     ...
; #pragma unroll
;         for (int j = 0; j < 4; ++j) {
;           const int col = n0 + (j & 1) * 16 + wn * 32 + (j >> 1) * 64 + q * 4;
;           const float4 swc = *(const float4*)(P.swq + col);
;           f32x4 v;
;           v[0] = (float)iacc[i][j][0] * shr * swc.x; v[1] = (float)iacc[i][j][1] * shr * swc.y;
;           v[2] = (float)iacc[i][j][2] * shr * swc.z; v[3] = (float)iacc[i][j][3] * shr * swc.w;
;           acc[i][j] = v;
;         }
;       }
	s_nop 0
	ds_read2_b64 v[0:3], v80 offset0:55 offset1:56
	v_add_u32_e32 v4, s14, v81
	v_or_b32_e32 v6, s0, v82
	v_ashrrev_i32_e32 v7, 31, v6
	v_ashrrev_i32_e32 v5, 31, v4
	s_waitcnt lgkmcnt(0)
	v_lshl_add_u64 v[96:97], v[6:7], 2, v[0:1]
	v_lshl_add_u64 v[0:1], v[4:5], 2, v[2:3]
	flat_load_dword v98, v[0:1]
	flat_load_dword v100, v[0:1] offset:64
	flat_load_dword v102, v[0:1] offset:128
	flat_load_dword v104, v[0:1] offset:192
	flat_load_dwordx4 v[4:7], v[96:97]
	v_cvt_f32_i32_e32 v1, v61
	v_cvt_f32_i32_e32 v0, v60
	v_cvt_f32_i32_e32 v21, v53
	v_cvt_f32_i32_e32 v20, v52
	s_mov_b32 s1, 0xfffffc0
	s_waitcnt vmcnt(0) lgkmcnt(0)
	v_mul_f32_e32 v0, v98, v0
	v_mul_f32_e32 v1, v98, v1
	v_mul_f32_e32 v20, v98, v20
	v_mul_f32_e32 v21, v98, v21
	v_mul_f32_e32 v18, v4, v0
	v_mul_f32_e32 v19, v5, v1
	v_cvt_f32_i32_e32 v1, v45
	v_cvt_f32_i32_e32 v0, v44
	v_cvt_pk_bf16_f32 v18, v18, v19
	v_mul_f32_e32 v0, v100, v0
	v_mul_f32_e32 v1, v100, v1
	v_mul_f32_e32 v8, v4, v0
	v_mul_f32_e32 v9, v5, v1
	v_cvt_f32_i32_e32 v1, v29
	v_cvt_f32_i32_e32 v0, v28
	v_cvt_pk_bf16_f32 v8, v8, v9
	v_mul_f32_e32 v0, v102, v0
	v_mul_f32_e32 v1, v102, v1
	v_mul_f32_e32 v2, v4, v0
	v_mul_f32_e32 v3, v5, v1
	v_cvt_f32_i32_e32 v1, v13
	v_cvt_f32_i32_e32 v0, v12
	v_cvt_pk_bf16_f32 v2, v2, v3
	v_mul_f32_e32 v0, v104, v0
	v_mul_f32_e32 v1, v104, v1
	v_mul_f32_e32 v0, v4, v0
	v_mul_f32_e32 v1, v5, v1
	v_cvt_f32_i32_e32 v5, v63
	v_cvt_f32_i32_e32 v4, v62
	v_cvt_pk_bf16_f32 v0, v0, v1
	v_mul_f32_e32 v4, v98, v4
	v_mul_f32_e32 v5, v98, v5
	v_mul_f32_e32 v26, v4, v6
	v_mul_f32_e32 v27, v5, v7
	v_cvt_f32_i32_e32 v5, v47
	v_cvt_f32_i32_e32 v4, v46
	flat_load_dwordx4 v[44:47], v[96:97] offset:256
	v_cvt_pk_bf16_f32 v19, v26, v27
	v_mul_f32_e32 v4, v100, v4
	v_mul_f32_e32 v5, v100, v5
	v_mul_f32_e32 v16, v6, v4
	v_mul_f32_e32 v17, v7, v5
	v_cvt_f32_i32_e32 v5, v31
	v_cvt_f32_i32_e32 v4, v30
	flat_load_dwordx4 v[28:31], v[96:97] offset:64
	v_cvt_pk_bf16_f32 v9, v16, v17
	v_mul_f32_e32 v4, v102, v4
	v_mul_f32_e32 v5, v102, v5
	v_mul_f32_e32 v10, v6, v4
	v_mul_f32_e32 v11, v7, v5
	v_cvt_f32_i32_e32 v5, v15
	v_cvt_f32_i32_e32 v4, v14
	v_cvt_f32_i32_e32 v15, v59
	v_cvt_f32_i32_e32 v14, v58
	v_cvt_pk_bf16_f32 v3, v10, v11
	v_mul_f32_e32 v4, v104, v4
	v_mul_f32_e32 v5, v104, v5
	v_mul_f32_e32 v4, v6, v4
	v_mul_f32_e32 v5, v7, v5
	v_cvt_f32_i32_e32 v7, v57
	v_cvt_f32_i32_e32 v6, v56
	v_mul_f32_e32 v14, v98, v14
	v_mul_f32_e32 v15, v98, v15
	v_cvt_pk_bf16_f32 v1, v4, v5
	v_mul_f32_e32 v6, v98, v6
	v_mul_f32_e32 v7, v98, v7
	s_waitcnt vmcnt(0) lgkmcnt(0)
	v_mul_f32_e32 v32, v6, v28
	v_mul_f32_e32 v33, v7, v29
	v_cvt_f32_i32_e32 v7, v49
	v_cvt_f32_i32_e32 v6, v48
	v_mul_f32_e32 v42, v14, v30
	v_mul_f32_e32 v43, v15, v31
	v_cvt_f32_i32_e32 v15, v51
	v_cvt_f32_i32_e32 v14, v50
	v_mul_f32_e32 v6, v100, v6
	v_mul_f32_e32 v7, v100, v7
	v_mul_f32_e32 v22, v28, v6
	v_mul_f32_e32 v23, v29, v7
	v_cvt_f32_i32_e32 v7, v35
	v_mul_f32_e32 v14, v100, v14
	v_mul_f32_e32 v15, v100, v15
	v_cvt_f32_i32_e32 v6, v34
	v_mul_f32_e32 v34, v30, v14
	v_mul_f32_e32 v35, v31, v15
	v_cvt_f32_i32_e32 v15, v37
	v_cvt_f32_i32_e32 v14, v36
	v_mul_f32_e32 v48, v20, v44
	v_mul_f32_e32 v49, v21, v45
	v_cvt_f32_i32_e32 v21, v39
	v_cvt_f32_i32_e32 v20, v38
	v_mul_f32_e32 v14, v102, v14
	v_mul_f32_e32 v15, v102, v15
	v_mul_f32_e32 v24, v30, v14
	v_mul_f32_e32 v25, v31, v15
	v_cvt_f32_i32_e32 v15, v87
	v_cvt_f32_i32_e32 v14, v86
	v_mul_f32_e32 v20, v100, v20
	v_mul_f32_e32 v21, v100, v21
	v_mul_f32_e32 v38, v44, v20
	v_mul_f32_e32 v39, v45, v21
	v_cvt_f32_i32_e32 v21, v73
	v_mul_f32_e32 v14, v104, v14
	v_mul_f32_e32 v15, v104, v15
	v_mul_f32_e32 v14, v30, v14
	v_mul_f32_e32 v15, v31, v15
	v_cvt_f32_i32_e32 v31, v55
	v_cvt_f32_i32_e32 v30, v54
	v_cvt_f32_i32_e32 v20, v72
	v_cvt_f32_i32_e32 v37, v65
	v_cvt_f32_i32_e32 v36, v64
	v_mul_f32_e32 v30, v98, v30
	v_mul_f32_e32 v31, v98, v31
	v_mul_f32_e32 v56, v30, v46
	v_mul_f32_e32 v57, v31, v47
	v_cvt_f32_i32_e32 v31, v41
	v_cvt_f32_i32_e32 v30, v40
	v_mul_f32_e32 v6, v102, v6
	v_mul_f32_e32 v7, v102, v7
	v_mul_f32_e32 v36, v98, v36
	v_mul_f32_e32 v37, v98, v37
	v_mul_f32_e32 v12, v28, v6
	v_mul_f32_e32 v13, v29, v7
	v_mul_f32_e32 v30, v100, v30
	v_mul_f32_e32 v31, v100, v31
	v_mul_f32_e32 v50, v46, v30
	v_mul_f32_e32 v51, v47, v31
	v_cvt_f32_i32_e32 v31, v75
	v_cvt_f32_i32_e32 v30, v74
	flat_load_dwordx4 v[72:75], v[96:97] offset:320
	v_cvt_f32_i32_e32 v7, v85
	v_cvt_f32_i32_e32 v6, v84
	v_mul_f32_e32 v30, v102, v30
	v_mul_f32_e32 v31, v102, v31
	v_mul_f32_e32 v40, v46, v30
	v_mul_f32_e32 v41, v47, v31
	v_cvt_f32_i32_e32 v31, v91
	v_cvt_f32_i32_e32 v30, v90
	v_mul_f32_e32 v6, v104, v6
	v_mul_f32_e32 v7, v104, v7
	v_mul_f32_e32 v20, v102, v20
	v_mul_f32_e32 v21, v102, v21
	v_mul_f32_e32 v6, v28, v6
	v_mul_f32_e32 v7, v29, v7
	v_mul_f32_e32 v30, v104, v30
	v_mul_f32_e32 v31, v104, v31
	v_mul_f32_e32 v30, v46, v30
	v_mul_f32_e32 v31, v47, v31
	v_cvt_f32_i32_e32 v47, v67
	v_cvt_f32_i32_e32 v46, v66
	v_mul_f32_e32 v28, v44, v20
	v_mul_f32_e32 v29, v45, v21
	v_cvt_f32_i32_e32 v21, v89
	v_cvt_f32_i32_e32 v20, v88
	v_mul_f32_e32 v46, v98, v46
	v_mul_f32_e32 v47, v98, v47
	v_mov_b32_e32 v66, v188
	ds_read_b64 v[64:65], v80 offset:352
	v_mul_f32_e32 v20, v104, v20
	v_mul_f32_e32 v21, v104, v21
	v_and_b32_e32 v67, 15, v66
	v_and_b32_e32 v26, 64, v66
	v_cvt_pk_bf16_f32 v32, v32, v33
	v_cvt_pk_bf16_f32 v33, v42, v43
	v_mul_f32_e32 v20, v44, v20
	v_mul_f32_e32 v21, v45, v21
	v_cvt_pk_bf16_f32 v16, v22, v23
	v_cvt_pk_bf16_f32 v17, v34, v35
	v_lshlrev_b32_e32 v180, 4, v67
	s_waitcnt vmcnt(0) lgkmcnt(0)
; DEV int tid_() { int t = threadIdx.x; asm volatile("" : "+v"(t)); return t; }
; #define P (*launderP(lp))
; DEV void stage_tile_bf16(char* smem, const f32x4 (&v)[4][4], u16* buf, int ld, int m0, int col0) {
;   const int tid = tid_(), lane = tid & 63, wid = tid >> 6, wm = wid >> 1, wn = wid & 1, l15 = lane & 15, q = lane >> 4;
; #pragma unroll
;   for (int i = 0; i < 4; ++i)
; #pragma unroll
;     for (int j = 0; j < 4; ++j) {
;       const int rl = wm * 64 + i * 16 + l15, cl = (j & 1) * 16 + wn * 32 + (j >> 1) * 64 + q * 4;
;       u32x2 o; o.x = pack2(v[i][j][0], v[i][j][1]); o.y = pack2(v[i][j][2], v[i][j][3]);
;       *(u32x2*)(smem + rl * 272 + cl * 2) = o;
;     }
;   __syncthreads();
; #pragma unroll
;   for (int k = 0; k < 8; ++k) {
;     const int chunk = tid + 256 * k, rl = chunk >> 4, c16 = chunk & 15;
;     u32x4 d = *(const u32x4*)(smem + rl * 272 + c16 * 16);
;     *(u32x4*)(buf + (size_t)(m0 + rl) * ld + col0 + c16 * 8) = d;
;   }
; __device__ __forceinline__ void phase_gemm45(PREF P, char* smem, int which) {
;     ...
; #pragma unroll
;       for (int i = 0; i < 4; ++i) {
;         const int row = m0 + wm * 64 + i * 16 + l15;
;     ...
; #pragma unroll
;         for (int j = 0; j < 4; ++j) {
;           const int col = n0 + (j & 1) * 16 + wn * 32 + (j >> 1) * 64 + q * 4;
;           const float4 swc = *(const float4*)(P.swq + col);
;           f32x4 v;
;           v[0] = (float)iacc[i][j][0] * shr * swc.x; v[1] = (float)iacc[i][j][1] * shr * swc.y;
;           v[2] = (float)iacc[i][j][2] * shr * swc.z; v[3] = (float)iacc[i][j][3] * shr * swc.w;
;           acc[i][j] = v;
;         }
;       }
;       stage_tile_bf16(smem, acc, P.qb, 2048, m0, n0);
	v_mul_f32_e32 v58, v36, v72
	v_mul_f32_e32 v59, v37, v73
	v_cvt_f32_i32_e32 v37, v69
	v_cvt_f32_i32_e32 v36, v68
	v_mul_f32_e32 v62, v46, v74
	v_mul_f32_e32 v63, v47, v75
	v_cvt_f32_i32_e32 v47, v71
	v_cvt_f32_i32_e32 v46, v70
	v_mul_f32_e32 v36, v100, v36
	v_mul_f32_e32 v37, v100, v37
	v_mul_f32_e32 v52, v72, v36
	v_mul_f32_e32 v53, v73, v37
	v_cvt_f32_i32_e32 v37, v77
	v_mul_f32_e32 v46, v100, v46
	v_mul_f32_e32 v47, v100, v47
	v_cvt_f32_i32_e32 v36, v76
	v_mul_f32_e32 v60, v74, v46
	v_mul_f32_e32 v61, v75, v47
	v_cvt_f32_i32_e32 v47, v79
	v_cvt_f32_i32_e32 v46, v78
	v_lshrrev_b32_e32 v68, 1, v66
	v_and_or_b32 v69, v68, s1, v67
	v_and_or_b32 v26, v68, 24, v26
	v_mul_f32_e32 v36, v102, v36
	v_mul_f32_e32 v37, v102, v37
	v_mul_f32_e32 v46, v102, v46
	v_mul_f32_e32 v47, v102, v47
	v_mad_u64_u32 v[26:27], s[4:5], v69, s11, v[26:27]
	v_mul_f32_e32 v44, v72, v36
	v_mul_f32_e32 v45, v73, v37
	v_cvt_f32_i32_e32 v37, v93
	v_cvt_f32_i32_e32 v36, v92
	v_mul_f32_e32 v54, v74, v46
	v_mul_f32_e32 v55, v75, v47
	v_cvt_f32_i32_e32 v47, v95
	v_cvt_f32_i32_e32 v46, v94
	ds_write2_b64 v26, v[18:19], v[32:33] offset1:4
	v_cvt_pk_bf16_f32 v18, v48, v49
	v_cvt_pk_bf16_f32 v19, v56, v57
	v_cvt_pk_bf16_f32 v32, v58, v59
	v_cvt_pk_bf16_f32 v33, v62, v63
	ds_write2_b64 v26, v[18:19], v[32:33] offset0:16 offset1:20
	v_add_u32_e32 v18, 0x1000, v26
	ds_write2_b64 v18, v[8:9], v[16:17] offset0:32 offset1:36
	v_cvt_pk_bf16_f32 v8, v38, v39
	v_cvt_pk_bf16_f32 v9, v50, v51
	v_cvt_pk_bf16_f32 v16, v52, v53
	v_cvt_pk_bf16_f32 v17, v60, v61
	ds_write2_b64 v18, v[8:9], v[16:17] offset0:48 offset1:52
	v_cvt_pk_bf16_f32 v8, v12, v13
	v_cvt_pk_bf16_f32 v9, v24, v25
	v_add_u32_e32 v10, 0x2000, v26
	v_mul_f32_e32 v36, v104, v36
	v_mul_f32_e32 v37, v104, v37
	v_mul_f32_e32 v46, v104, v46
	v_mul_f32_e32 v47, v104, v47
	ds_write2_b64 v10, v[2:3], v[8:9] offset0:64 offset1:68
	v_cvt_pk_bf16_f32 v2, v28, v29
	v_cvt_pk_bf16_f32 v3, v40, v41
	v_cvt_pk_bf16_f32 v8, v44, v45
	v_cvt_pk_bf16_f32 v9, v54, v55
	v_mul_f32_e32 v36, v72, v36
	v_mul_f32_e32 v37, v73, v37
	v_mul_f32_e32 v46, v74, v46
	v_mul_f32_e32 v47, v75, v47
	ds_write2_b64 v10, v[2:3], v[8:9] offset0:80 offset1:84
	v_cvt_pk_bf16_f32 v2, v6, v7
	v_cvt_pk_bf16_f32 v3, v14, v15
	v_add_u32_e32 v4, 0x3000, v26
	ds_write2_b64 v4, v[0:1], v[2:3] offset0:96 offset1:100
	v_cvt_pk_bf16_f32 v0, v20, v21
	v_cvt_pk_bf16_f32 v1, v30, v31
	v_cvt_pk_bf16_f32 v2, v36, v37
	v_cvt_pk_bf16_f32 v3, v46, v47
	s_ashr_i32 s1, s0, 31
	ds_write2_b64 v4, v[0:1], v[2:3] offset0:112 offset1:116
	v_lshl_add_u64 v[0:1], s[0:1], 1, v[64:65]
	v_ashrrev_i32_e32 v6, 4, v66
	v_lshl_add_u64 v[4:5], v[0:1], 0, v[180:181]
	v_mad_u64_u32 v[0:1], s[0:1], v6, s11, v[180:181]
	s_waitcnt lgkmcnt(0)
	s_barrier
	ds_read_b128 v[0:3], v0
	v_add_u32_e32 v6, s14, v6
	v_ashrrev_i32_e32 v7, 31, v6
	v_lshlrev_b64 v[6:7], 12, v[6:7]
	v_lshl_add_u64 v[6:7], v[4:5], 0, v[6:7]
	s_waitcnt lgkmcnt(0)
	flat_store_dwordx4 v[6:7], v[0:3]
	s_nop 1
	v_add_u32_e32 v0, 0x100, v66
	v_ashrrev_i32_e32 v6, 4, v0
	v_mad_u64_u32 v[0:1], s[0:1], v6, s11, v[180:181]
	ds_read_b128 v[0:3], v0
	v_add_u32_e32 v6, s14, v6
	v_ashrrev_i32_e32 v7, 31, v6
	v_lshlrev_b64 v[6:7], 12, v[6:7]
	v_lshl_add_u64 v[6:7], v[4:5], 0, v[6:7]
	s_waitcnt lgkmcnt(0)
	flat_store_dwordx4 v[6:7], v[0:3]
	s_nop 1
	v_add_u32_e32 v0, 0x200, v66
	v_ashrrev_i32_e32 v6, 4, v0
	v_mad_u64_u32 v[0:1], s[0:1], v6, s11, v[180:181]
	ds_read_b128 v[0:3], v0
	v_add_u32_e32 v6, s14, v6
	v_ashrrev_i32_e32 v7, 31, v6
	v_lshlrev_b64 v[6:7], 12, v[6:7]
	v_lshl_add_u64 v[6:7], v[4:5], 0, v[6:7]
	s_waitcnt lgkmcnt(0)
	flat_store_dwordx4 v[6:7], v[0:3]
	s_nop 1
	v_add_u32_e32 v0, 0x300, v66
	v_ashrrev_i32_e32 v6, 4, v0
	v_mad_u64_u32 v[0:1], s[0:1], v6, s11, v[180:181]
	ds_read_b128 v[0:3], v0
	v_add_u32_e32 v6, s14, v6
	v_ashrrev_i32_e32 v7, 31, v6
	v_lshlrev_b64 v[6:7], 12, v[6:7]
	v_lshl_add_u64 v[6:7], v[4:5], 0, v[6:7]
	s_waitcnt lgkmcnt(0)
	flat_store_dwordx4 v[6:7], v[0:3]
	s_nop 1
	v_add_u32_e32 v0, 0x400, v66
	v_ashrrev_i32_e32 v6, 4, v0
	v_mad_u64_u32 v[0:1], s[0:1], v6, s11, v[180:181]
	ds_read_b128 v[0:3], v0
	v_add_u32_e32 v6, s14, v6
	v_ashrrev_i32_e32 v7, 31, v6
	v_lshlrev_b64 v[6:7], 12, v[6:7]
	v_lshl_add_u64 v[6:7], v[4:5], 0, v[6:7]
	s_waitcnt lgkmcnt(0)
	flat_store_dwordx4 v[6:7], v[0:3]
	s_nop 1
	v_add_u32_e32 v0, 0x500, v66
	v_ashrrev_i32_e32 v6, 4, v0
	v_mad_u64_u32 v[0:1], s[0:1], v6, s11, v[180:181]
	ds_read_b128 v[0:3], v0
	v_add_u32_e32 v6, s14, v6
	v_ashrrev_i32_e32 v7, 31, v6
	v_lshlrev_b64 v[6:7], 12, v[6:7]
	v_lshl_add_u64 v[6:7], v[4:5], 0, v[6:7]
	s_waitcnt lgkmcnt(0)
	flat_store_dwordx4 v[6:7], v[0:3]
	s_nop 1
	v_add_u32_e32 v0, 0x600, v66
	v_ashrrev_i32_e32 v6, 4, v0
	v_mad_u64_u32 v[0:1], s[0:1], v6, s11, v[180:181]
	ds_read_b128 v[0:3], v0
	v_add_u32_e32 v6, s14, v6
	v_ashrrev_i32_e32 v7, 31, v6
	v_lshlrev_b64 v[6:7], 12, v[6:7]
	v_lshl_add_u64 v[6:7], v[4:5], 0, v[6:7]
	s_waitcnt lgkmcnt(0)
	flat_store_dwordx4 v[6:7], v[0:3]
	s_nop 1
	v_add_u32_e32 v0, 0x700, v66
	v_ashrrev_i32_e32 v6, 4, v0
	v_mad_u64_u32 v[0:1], s[0:1], v6, s11, v[180:181]
	ds_read_b128 v[0:3], v0
	v_add_u32_e32 v6, s14, v6
	v_ashrrev_i32_e32 v7, 31, v6
	v_lshlrev_b64 v[6:7], 12, v[6:7]
	v_lshl_add_u64 v[4:5], v[4:5], 0, v[6:7]
	v_readlane_b32 s0, v251, 6
	s_waitcnt lgkmcnt(0)
	flat_store_dwordx4 v[4:5], v[0:3]
	s_add_i32 s6, s0, s6
	s_cmpk_lt_i32 s6, 0x400
	v_readlane_b32 s1, v251, 7
	s_cbranch_scc1 .LBB0_564

; DEV f32x4 mma_step(bf16x8 a, bf16x8 b, f32x4 c) { return MFMA(a, b, c); }
; template <class FragT, class AccT>
; DEV void gemm_core_t(const char* __restrict__ A, size_t lda_bytes, const char* __restrict__ Bt, size_t ldb_bytes, int kbytes,
;                      int m0, int n0, int Sshift, int dl, char* smem, AccT (&acc)[4][4]) {
;     ...
;   for (int kt = 0; kt < nk; ++kt) {
;     const unsigned so = (unsigned)(kt & 1) * 32768u;
;     char* nxt = smem + ((kt + 1) & 1) * 32768;
;     if (kt + 1 < nk) {
; #pragma unroll
;       for (int u = 0; u < 4; ++u) {
;         __builtin_amdgcn_global_load_lds((const unsigned*)(ap[u] + (size_t)(kt + 1) * 128), (unsigned*)(nxt + (wid * 4 + u) * 1024 + lane * 16), 16, 0, 0);
;         __builtin_amdgcn_global_load_lds((const unsigned*)(bp[u] + (size_t)(kt + 1) * 128), (unsigned*)(nxt + 16384 + (wid * 4 + u) * 1024 + lane * 16), 16, 0, 0);
;       }
;     }
;     FragT xa[2][4], wb[2][4];
;     asm volatile(
;         "ds_read_b128 %0, %16\n\t"
;         "ds_read_b128 %1, %16 offset:2048\n\t"
;         "ds_read_b128 %2, %16 offset:4096\n\t"
;         "ds_read_b128 %3, %16 offset:6144\n\t"
;         "ds_read_b128 %4, %18\n\t"
;         "ds_read_b128 %5, %18 offset:2048\n\t"
;         "ds_read_b128 %6, %18 offset:8192\n\t"
;         "ds_read_b128 %7, %18 offset:10240\n\t"
;         "ds_read_b128 %8, %17\n\t"
;         "ds_read_b128 %9, %17 offset:2048\n\t"
;         "ds_read_b128 %10, %17 offset:4096\n\t"
;         "ds_read_b128 %11, %17 offset:6144\n\t"
;         "ds_read_b128 %12, %19\n\t"
;         "ds_read_b128 %13, %19 offset:2048\n\t"
;         "ds_read_b128 %14, %19 offset:8192\n\t"
;         "ds_read_b128 %15, %19 offset:10240\n\t"
;         "s_waitcnt lgkmcnt(8)"
;         : "=&v"(xa[0][0]), "=&v"(xa[0][1]), "=&v"(xa[0][2]), "=&v"(xa[0][3]), "=&v"(wb[0][0]), "=&v"(wb[0][1]), "=&v"(wb[0][2]),
;           "=&v"(wb[0][3]), "=&v"(xa[1][0]), "=&v"(xa[1][1]), "=&v"(xa[1][2]), "=&v"(xa[1][3]), "=&v"(wb[1][0]), "=&v"(wb[1][1]),
;           "=&v"(wb[1][2]), "=&v"(wb[1][3])
;         : "v"(a0 + so), "v"((a0 ^ 64u) + so), "v"(b0 + so), "v"((b0 ^ 64u) + so)
;         : "memory");
;     __builtin_amdgcn_s_setprio(1);
; #pragma unroll
;     for (int i = 0; i < 4; ++i)
; #pragma unroll
;       for (int j = 0; j < 4; ++j) acc[i][j] = mma_step(wb[0][j], xa[0][i], acc[i][j]);
;     asm volatile("s_waitcnt lgkmcnt(0)"
.LBB0_624:
	s_add_i32 s6, s5, 0xffff8000
	s_and_b32 s6, s6, 0x8000
	v_add_u32_e32 v152, s6, v84
	v_add_u32_e32 v153, s6, v87
	v_or_b32_e32 v154, s6, v85
	v_or_b32_e32 v155, s6, v86
	s_and_b32 s6, s5, 0x8000
	s_add_i32 s6, s6, s62
	s_mov_b32 m0, s6
	ds_read_b128 v[88:91], v152
	global_load_lds_dwordx4 v78, s[64:65]
	ds_read_b128 v[92:95], v152 offset:2048
	s_add_i32 m0, s6, 0x4000
	ds_read_b128 v[96:99], v152 offset:4096
	global_load_lds_dwordx4 v76, s[66:67]
	ds_read_b128 v[100:103], v152 offset:6144
	s_add_i32 m0, s6, 0x400
	ds_read_b128 v[104:107], v154
	global_load_lds_dwordx4 v74, s[64:65]
	ds_read_b128 v[108:111], v154 offset:2048
	s_add_i32 m0, s6, 0x4400
	ds_read_b128 v[112:115], v154 offset:8192
	global_load_lds_dwordx4 v72, s[66:67]
	ds_read_b128 v[116:119], v154 offset:10240
	ds_read_b128 v[120:123], v153
	ds_read_b128 v[124:127], v153 offset:2048
	ds_read_b128 v[128:131], v153 offset:4096
	ds_read_b128 v[132:135], v153 offset:6144
	ds_read_b128 v[136:139], v155
	ds_read_b128 v[140:143], v155 offset:2048
	ds_read_b128 v[144:147], v155 offset:8192
	ds_read_b128 v[148:151], v155 offset:10240
	s_waitcnt lgkmcnt(8)
	s_setprio 1
	v_mfma_i32_16x16x64_i8 v[60:63], v[104:107], v[88:91], v[60:63]
	v_mfma_i32_16x16x64_i8 v[56:59], v[108:111], v[88:91], v[56:59]
	s_add_i32 m0, s6, 0x800
	v_mfma_i32_16x16x64_i8 v[52:55], v[112:115], v[88:91], v[52:55]
	global_load_lds_dwordx4 v70, s[64:65]
	v_mfma_i32_16x16x64_i8 v[48:51], v[116:119], v[88:91], v[48:51]
	v_mfma_i32_16x16x64_i8 v[44:47], v[104:107], v[92:95], v[44:47]
	v_mfma_i32_16x16x64_i8 v[40:43], v[108:111], v[92:95], v[40:43]
	s_add_i32 m0, s6, 0x4800
	v_mfma_i32_16x16x64_i8 v[36:39], v[112:115], v[92:95], v[36:39]
	global_load_lds_dwordx4 v68, s[66:67]
	v_mfma_i32_16x16x64_i8 v[32:35], v[116:119], v[92:95], v[32:35]
	v_mfma_i32_16x16x64_i8 v[28:31], v[104:107], v[96:99], v[28:31]
	v_mfma_i32_16x16x64_i8 v[24:27], v[108:111], v[96:99], v[24:27]
	s_add_i32 m0, s6, 0xc00
	v_mfma_i32_16x16x64_i8 v[20:23], v[112:115], v[96:99], v[20:23]
	global_load_lds_dwordx4 v66, s[64:65]
	v_mfma_i32_16x16x64_i8 v[16:19], v[116:119], v[96:99], v[16:19]
	v_mfma_i32_16x16x64_i8 v[12:15], v[104:107], v[100:103], v[12:15]
	v_mfma_i32_16x16x64_i8 v[8:11], v[108:111], v[100:103], v[8:11]
	s_add_i32 m0, s6, 0x4c00
	v_mfma_i32_16x16x64_i8 v[4:7], v[112:115], v[100:103], v[4:7]
	global_load_lds_dwordx4 v64, s[66:67]
	v_mfma_i32_16x16x64_i8 v[0:3], v[116:119], v[100:103], v[0:3]
	s_waitcnt lgkmcnt(0)
	s_nop 0
	v_mfma_i32_16x16x64_i8 v[60:63], v[136:139], v[120:123], v[60:63]
	v_mfma_i32_16x16x64_i8 v[56:59], v[140:143], v[120:123], v[56:59]
	v_mfma_i32_16x16x64_i8 v[52:55], v[144:147], v[120:123], v[52:55]
	v_mfma_i32_16x16x64_i8 v[48:51], v[148:151], v[120:123], v[48:51]
	v_mfma_i32_16x16x64_i8 v[44:47], v[136:139], v[124:127], v[44:47]
	v_mfma_i32_16x16x64_i8 v[40:43], v[140:143], v[124:127], v[40:43]
	v_mfma_i32_16x16x64_i8 v[36:39], v[144:147], v[124:127], v[36:39]
	v_mfma_i32_16x16x64_i8 v[32:35], v[148:151], v[124:127], v[32:35]
	v_mfma_i32_16x16x64_i8 v[28:31], v[136:139], v[128:131], v[28:31]
	v_mfma_i32_16x16x64_i8 v[24:27], v[140:143], v[128:131], v[24:27]
	v_mfma_i32_16x16x64_i8 v[20:23], v[144:147], v[128:131], v[20:23]
	v_mfma_i32_16x16x64_i8 v[16:19], v[148:151], v[128:131], v[16:19]
	v_mfma_i32_16x16x64_i8 v[12:15], v[136:139], v[132:135], v[12:15]
	v_mfma_i32_16x16x64_i8 v[8:11], v[140:143], v[132:135], v[8:11]
	v_mfma_i32_16x16x64_i8 v[4:7], v[144:147], v[132:135], v[4:7]
	v_mfma_i32_16x16x64_i8 v[0:3], v[148:151], v[132:135], v[0:3]
	s_setprio 0
	s_waitcnt vmcnt(0)
	s_add_u32 s14, s14, 0x80
	s_addc_u32 s15, s15, 0
	s_add_u32 s64, s64, 0x80
	s_addc_u32 s65, s65, 0
	s_add_u32 s66, s66, 0x80
	s_addc_u32 s67, s67, 0
	s_add_i32 s5, s5, 0x8000
	s_cmpk_lg_i32 s14, 0x780
	s_waitcnt vmcnt(0) lgkmcnt(0)
	s_barrier
	s_cbranch_scc1 .LBB0_624
	v_add_u32_e32 v83, 0x8000, v84
	v_add_u32_e32 v132, 0x8000, v87
	v_or_b32_e32 v133, 0x8000, v85
	v_or_b32_e32 v134, 0x8000, v86
	ds_read_b128 v[64:67], v83
	ds_read_b128 v[68:71], v83 offset:2048
	ds_read_b128 v[72:75], v83 offset:4096
	ds_read_b128 v[76:79], v83 offset:6144
	ds_read_b128 v[84:87], v133
	ds_read_b128 v[88:91], v133 offset:2048
	ds_read_b128 v[92:95], v133 offset:8192
	ds_read_b128 v[96:99], v133 offset:10240
	ds_read_b128 v[100:103], v132
	ds_read_b128 v[104:107], v132 offset:2048
	ds_read_b128 v[108:111], v132 offset:4096
	ds_read_b128 v[112:115], v132 offset:6144
	ds_read_b128 v[116:119], v134
	ds_read_b128 v[120:123], v134 offset:2048
	ds_read_b128 v[124:127], v134 offset:8192
	ds_read_b128 v[128:131], v134 offset:10240
	s_waitcnt lgkmcnt(8)
	s_setprio 1
	v_mfma_i32_16x16x64_i8 v[60:63], v[84:87], v[64:67], v[60:63]
	v_mfma_i32_16x16x64_i8 v[56:59], v[88:91], v[64:67], v[56:59]
	v_mfma_i32_16x16x64_i8 v[52:55], v[92:95], v[64:67], v[52:55]
	v_mfma_i32_16x16x64_i8 v[48:51], v[96:99], v[64:67], v[48:51]
	v_mfma_i32_16x16x64_i8 v[44:47], v[84:87], v[68:71], v[44:47]
	v_mfma_i32_16x16x64_i8 v[40:43], v[88:91], v[68:71], v[40:43]
	v_mfma_i32_16x16x64_i8 v[36:39], v[92:95], v[68:71], v[36:39]
	v_mfma_i32_16x16x64_i8 v[32:35], v[96:99], v[68:71], v[32:35]
	v_mfma_i32_16x16x64_i8 v[28:31], v[84:87], v[72:75], v[28:31]
	v_mfma_i32_16x16x64_i8 v[24:27], v[88:91], v[72:75], v[24:27]
	v_mfma_i32_16x16x64_i8 v[20:23], v[92:95], v[72:75], v[20:23]
	v_mfma_i32_16x16x64_i8 v[68:71], v[96:99], v[72:75], v[16:19]
	v_mfma_i32_16x16x64_i8 v[72:75], v[84:87], v[76:79], v[12:15]
	v_mfma_i32_16x16x64_i8 v[8:11], v[88:91], v[76:79], v[8:11]
	v_mfma_i32_16x16x64_i8 v[4:7], v[92:95], v[76:79], v[4:7]
	v_mfma_i32_16x16x64_i8 v[0:3], v[96:99], v[76:79], v[0:3]
	s_waitcnt lgkmcnt(0)
	s_nop 0
	v_mfma_i32_16x16x64_i8 v[84:87], v[116:119], v[100:103], v[60:63]
	v_mfma_i32_16x16x64_i8 v[16:19], v[120:123], v[100:103], v[56:59]
	v_mfma_i32_16x16x64_i8 v[12:15], v[124:127], v[100:103], v[52:55]
	v_mfma_i32_16x16x64_i8 v[64:67], v[128:131], v[100:103], v[48:51]
	v_mfma_i32_16x16x64_i8 v[60:63], v[116:119], v[104:107], v[44:47]
	v_mfma_i32_16x16x64_i8 v[56:59], v[120:123], v[104:107], v[40:43]
	v_mfma_i32_16x16x64_i8 v[52:55], v[124:127], v[104:107], v[36:39]
	v_mfma_i32_16x16x64_i8 v[48:51], v[128:131], v[104:107], v[32:35]
	v_mfma_i32_16x16x64_i8 v[44:47], v[116:119], v[108:111], v[28:31]
	v_mfma_i32_16x16x64_i8 v[40:43], v[120:123], v[108:111], v[24:27]
	v_mfma_i32_16x16x64_i8 v[36:39], v[124:127], v[108:111], v[20:23]
	v_mfma_i32_16x16x64_i8 v[32:35], v[128:131], v[108:111], v[68:71]
	v_mfma_i32_16x16x64_i8 v[20:23], v[116:119], v[112:115], v[72:75]
	v_mfma_i32_16x16x64_i8 v[8:11], v[120:123], v[112:115], v[8:11]
	v_mfma_i32_16x16x64_i8 v[4:7], v[124:127], v[112:115], v[4:7]
	v_mfma_i32_16x16x64_i8 v[0:3], v[128:131], v[112:115], v[0:3]
	s_setprio 0
	s_waitcnt vmcnt(0)
	s_barrier
; #define P (*launderP(lp))
; DEV float sigm(float x) { return 1.f / (1.f + __expf(-x)); }
; __device__ __forceinline__ void phase_gemm45(PREF P, char* smem, int which) {
;     ...
; #pragma unroll
;         for (int i = 0; i < 4; ++i) {
;           const int row = m0 + wm * 64 + i * 16 + l15;
;     ...
; #pragma unroll
;           for (int j = 0; j < 4; ++j) {
;             const int col = n0 + (j & 1) * 16 + wn * 32 + (j >> 1) * 64 + q * 4;
;             const float4 swc = *(const float4*)(P.swpg + col);
;             part[i][j][0] = pack2(sigm((float)iacc[i][j][0] * shr * swc.x), sigm((float)iacc[i][j][1] * shr * swc.y));
;             part[i][j][1] = pack2(sigm((float)iacc[i][j][2] * shr * swc.z), sigm((float)iacc[i][j][3] * shr * swc.w));
;           }
;         }
	ds_read2_b64 v[24:27], v80 offset0:54 offset1:56
	v_add_u32_e32 v28, s17, v81
	v_or_b32_e32 v30, s4, v82
	v_ashrrev_i32_e32 v29, 31, v28
	v_ashrrev_i32_e32 v31, 31, v30
	s_waitcnt lgkmcnt(0)
	v_lshl_add_u64 v[68:69], v[28:29], 2, v[26:27]
	v_lshl_add_u64 v[70:71], v[30:31], 2, v[24:25]
	flat_load_dword v78, v[68:69]
	flat_load_dwordx4 v[24:27], v[70:71]
	v_cvt_f32_i32_e32 v28, v84
	v_cvt_f32_i32_e32 v29, v85
	v_cvt_f32_i32_e32 v16, v16
	v_cvt_f32_i32_e32 v17, v17
	v_cvt_f32_i32_e32 v12, v12
	v_cvt_f32_i32_e32 v13, v13
	v_cvt_f32_i32_e32 v64, v64
	v_cvt_f32_i32_e32 v65, v65
	v_cvt_f32_i32_e32 v60, v60
	v_cvt_f32_i32_e32 v61, v61
	v_cvt_f32_i32_e32 v56, v56
	v_cvt_f32_i32_e32 v57, v57
	v_cvt_f32_i32_e32 v52, v52
	v_cvt_f32_i32_e32 v53, v53
	v_cvt_f32_i32_e32 v48, v48
	v_cvt_f32_i32_e32 v49, v49
	v_cvt_f32_i32_e32 v44, v44
	v_cvt_f32_i32_e32 v45, v45
	v_cvt_f32_i32_e32 v40, v40
	v_cvt_f32_i32_e32 v41, v41
	v_cvt_f32_i32_e32 v36, v36
	v_cvt_f32_i32_e32 v37, v37
	v_cvt_f32_i32_e32 v32, v32
	v_cvt_f32_i32_e32 v33, v33
	v_cvt_f32_i32_e32 v20, v20
	v_cvt_f32_i32_e32 v21, v21
	v_cvt_f32_i32_e32 v8, v8
	v_cvt_f32_i32_e32 v9, v9
	v_cvt_f32_i32_e32 v4, v4
	v_cvt_f32_i32_e32 v5, v5
	v_cvt_f32_i32_e32 v0, v0
	v_cvt_f32_i32_e32 v1, v1
	s_mov_b32 s44, 0x1ffffc0
	s_mov_b64 s[46:47], 0x80
	s_waitcnt vmcnt(0) lgkmcnt(0)
	v_mul_f32_e32 v28, v78, v28
	v_mul_f32_e32 v29, v78, v29
	v_mul_f32_e32 v28, v24, v28
	v_mul_f32_e32 v29, v29, v25
	v_mul_f32_e32 v28, 0xbfb8aa3b, v28
	v_mul_f32_e32 v29, 0xbfb8aa3b, v29
	v_exp_f32_e32 v28, v28
	v_exp_f32_e32 v29, v29
	v_mul_f32_e32 v16, v78, v16
	v_mul_f32_e32 v17, v78, v17
	v_mul_f32_e32 v12, v78, v12
	v_pk_add_f32 v[28:29], v[28:29], 1.0 op_sel_hi:[1,0]
	v_mul_f32_e32 v13, v78, v13
	v_div_scale_f32 v30, s[14:15], v29, v29, 1.0
	v_rcp_f32_e32 v31, v30
	v_mul_f32_e32 v64, v78, v64
	v_mul_f32_e32 v65, v78, v65
	v_fma_f32 v72, -v30, v31, 1.0
	v_fmac_f32_e32 v31, v72, v31
	v_div_scale_f32 v72, vcc, 1.0, v29, 1.0
	v_mul_f32_e32 v73, v72, v31
	v_fma_f32 v74, -v30, v73, v72
	v_fmac_f32_e32 v73, v74, v31
	v_fma_f32 v30, -v30, v73, v72
	v_div_fmas_f32 v30, v30, v31, v73
	v_div_fixup_f32 v29, v30, v29, 1.0
	v_div_scale_f32 v30, s[14:15], v28, v28, 1.0
	v_rcp_f32_e32 v31, v30
	s_nop 0
	v_fma_f32 v72, -v30, v31, 1.0
	v_fmac_f32_e32 v31, v72, v31
	v_div_scale_f32 v72, vcc, 1.0, v28, 1.0
	v_mul_f32_e32 v73, v72, v31
	v_fma_f32 v74, -v30, v73, v72
	v_fmac_f32_e32 v73, v74, v31
	v_fma_f32 v30, -v30, v73, v72
	v_div_fmas_f32 v30, v30, v31, v73
	v_div_fixup_f32 v28, v30, v28, 1.0
	v_cvt_pk_bf16_f32 v72, v28, v29
	v_cvt_f32_i32_e32 v28, v86
	v_cvt_f32_i32_e32 v29, v87
	v_mul_f32_e32 v28, v78, v28
	v_mul_f32_e32 v29, v78, v29
	v_mul_f32_e32 v28, v28, v26
	v_mul_f32_e32 v29, v29, v27
	v_mul_f32_e32 v28, 0xbfb8aa3b, v28
	v_mul_f32_e32 v29, 0xbfb8aa3b, v29
	v_exp_f32_e32 v28, v28
	v_exp_f32_e32 v29, v29
	s_nop 0
	v_pk_add_f32 v[28:29], v[28:29], 1.0 op_sel_hi:[1,0]
	s_nop 0
	v_div_scale_f32 v30, s[14:15], v29, v29, 1.0
	v_rcp_f32_e32 v31, v30
	s_nop 0
	v_fma_f32 v73, -v30, v31, 1.0
	v_fmac_f32_e32 v31, v73, v31
	v_div_scale_f32 v73, vcc, 1.0, v29, 1.0
	v_mul_f32_e32 v74, v73, v31
	v_fma_f32 v75, -v30, v74, v73
	v_fmac_f32_e32 v74, v75, v31
	v_fma_f32 v30, -v30, v74, v73
	v_div_fmas_f32 v30, v30, v31, v74
	v_div_fixup_f32 v29, v30, v29, 1.0
	v_div_scale_f32 v30, s[14:15], v28, v28, 1.0
	v_rcp_f32_e32 v31, v30
	s_nop 0
	v_fma_f32 v73, -v30, v31, 1.0
	v_fmac_f32_e32 v31, v73, v31
	v_div_scale_f32 v73, vcc, 1.0, v28, 1.0
	v_mul_f32_e32 v74, v73, v31
	v_fma_f32 v75, -v30, v74, v73
	v_fmac_f32_e32 v74, v75, v31
	v_fma_f32 v30, -v30, v74, v73
	v_div_fmas_f32 v30, v30, v31, v74
	v_div_fixup_f32 v28, v30, v28, 1.0
	v_cvt_pk_bf16_f32 v73, v28, v29
	flat_load_dwordx4 v[28:31], v[70:71] offset:64
	s_waitcnt vmcnt(0) lgkmcnt(0)
	v_mul_f32_e32 v16, v16, v28
	v_mul_f32_e32 v17, v17, v29
	v_mul_f32_e32 v16, 0xbfb8aa3b, v16
	v_mul_f32_e32 v17, 0xbfb8aa3b, v17
	v_exp_f32_e32 v16, v16
	v_exp_f32_e32 v17, v17
	s_nop 0
	v_pk_add_f32 v[16:17], v[16:17], 1.0 op_sel_hi:[1,0]
	s_nop 0
	v_div_scale_f32 v74, s[14:15], v17, v17, 1.0
	v_rcp_f32_e32 v75, v74
	s_nop 0
	v_fma_f32 v76, -v74, v75, 1.0
	v_fmac_f32_e32 v75, v76, v75
	v_div_scale_f32 v76, vcc, 1.0, v17, 1.0
	v_mul_f32_e32 v77, v76, v75
	v_fma_f32 v79, -v74, v77, v76
	v_fmac_f32_e32 v77, v79, v75
	v_fma_f32 v74, -v74, v77, v76
	v_div_fmas_f32 v74, v74, v75, v77
	v_div_fixup_f32 v17, v74, v17, 1.0
	v_div_scale_f32 v74, s[14:15], v16, v16, 1.0
	v_rcp_f32_e32 v75, v74
	s_nop 0
	v_fma_f32 v76, -v74, v75, 1.0
	v_fmac_f32_e32 v75, v76, v75
	v_div_scale_f32 v76, vcc, 1.0, v16, 1.0
	v_mul_f32_e32 v77, v76, v75
	v_fma_f32 v79, -v74, v77, v76
	v_fmac_f32_e32 v77, v79, v75
	v_fma_f32 v74, -v74, v77, v76
	v_div_fmas_f32 v74, v74, v75, v77
	v_div_fixup_f32 v16, v74, v16, 1.0
	v_cvt_pk_bf16_f32 v74, v16, v17
	v_cvt_f32_i32_e32 v16, v18
	v_cvt_f32_i32_e32 v17, v19
	v_mul_f32_e32 v16, v78, v16
	v_mul_f32_e32 v17, v78, v17
	v_mul_f32_e32 v16, v16, v30
	v_mul_f32_e32 v17, v17, v31
	v_mul_f32_e32 v16, 0xbfb8aa3b, v16
	v_mul_f32_e32 v17, 0xbfb8aa3b, v17
	v_exp_f32_e32 v16, v16
	v_exp_f32_e32 v17, v17
	s_nop 0
	v_pk_add_f32 v[16:17], v[16:17], 1.0 op_sel_hi:[1,0]
	s_nop 0
	v_div_scale_f32 v18, s[14:15], v17, v17, 1.0
	v_rcp_f32_e32 v19, v18
	s_nop 0
	v_fma_f32 v75, -v18, v19, 1.0
	v_fmac_f32_e32 v19, v75, v19
	v_div_scale_f32 v75, vcc, 1.0, v17, 1.0
	v_mul_f32_e32 v76, v75, v19
	v_fma_f32 v77, -v18, v76, v75
	v_fmac_f32_e32 v76, v77, v19
	v_fma_f32 v18, -v18, v76, v75
	v_div_fmas_f32 v18, v18, v19, v76
	v_div_fixup_f32 v17, v18, v17, 1.0
	v_div_scale_f32 v18, s[14:15], v16, v16, 1.0
	v_rcp_f32_e32 v19, v18
	s_nop 0
	v_fma_f32 v75, -v18, v19, 1.0
	v_fmac_f32_e32 v19, v75, v19
	v_div_scale_f32 v75, vcc, 1.0, v16, 1.0
	v_mul_f32_e32 v76, v75, v19
	v_fma_f32 v77, -v18, v76, v75
	v_fmac_f32_e32 v76, v77, v19
	v_fma_f32 v18, -v18, v76, v75
	v_div_fmas_f32 v18, v18, v19, v76
	v_div_fixup_f32 v16, v18, v16, 1.0
	v_cvt_pk_bf16_f32 v75, v16, v17
	flat_load_dwordx4 v[16:19], v[70:71] offset:256
	s_waitcnt vmcnt(0) lgkmcnt(0)
; #define P (*launderP(lp))
; DEV float sigm(float x) { return 1.f / (1.f + __expf(-x)); }
; __device__ __forceinline__ void phase_gemm45(PREF P, char* smem, int which) {
;     ...
; #pragma unroll
;         for (int i = 0; i < 4; ++i) {
;           const int row = m0 + wm * 64 + i * 16 + l15;
;     ...
; #pragma unroll
;           for (int j = 0; j < 4; ++j) {
;             const int col = n0 + (j & 1) * 16 + wn * 32 + (j >> 1) * 64 + q * 4;
;             const float4 swc = *(const float4*)(P.swpg + col);
;             part[i][j][0] = pack2(sigm((float)iacc[i][j][0] * shr * swc.x), sigm((float)iacc[i][j][1] * shr * swc.y));
;             part[i][j][1] = pack2(sigm((float)iacc[i][j][2] * shr * swc.z), sigm((float)iacc[i][j][3] * shr * swc.w));
;           }
;         }
	v_mul_f32_e32 v12, v12, v16
	v_mul_f32_e32 v13, v13, v17
	v_mul_f32_e32 v12, 0xbfb8aa3b, v12
	v_mul_f32_e32 v13, 0xbfb8aa3b, v13
	v_exp_f32_e32 v12, v12
	v_exp_f32_e32 v13, v13
	s_nop 0
	v_pk_add_f32 v[12:13], v[12:13], 1.0 op_sel_hi:[1,0]
	s_nop 0
	v_div_scale_f32 v76, s[14:15], v13, v13, 1.0
	v_rcp_f32_e32 v77, v76
	s_nop 0
	v_fma_f32 v79, -v76, v77, 1.0
	v_fmac_f32_e32 v77, v79, v77
	v_div_scale_f32 v79, vcc, 1.0, v13, 1.0
	v_mul_f32_e32 v83, v79, v77
	v_fma_f32 v84, -v76, v83, v79
	v_fmac_f32_e32 v83, v84, v77
	v_fma_f32 v76, -v76, v83, v79
	v_div_fmas_f32 v76, v76, v77, v83
	v_div_fixup_f32 v13, v76, v13, 1.0
	v_div_scale_f32 v76, s[14:15], v12, v12, 1.0
	v_rcp_f32_e32 v77, v76
	s_nop 0
	v_fma_f32 v79, -v76, v77, 1.0
	v_fmac_f32_e32 v77, v79, v77
	v_div_scale_f32 v79, vcc, 1.0, v12, 1.0
	v_mul_f32_e32 v83, v79, v77
	v_fma_f32 v84, -v76, v83, v79
	v_fmac_f32_e32 v83, v84, v77
	v_fma_f32 v76, -v76, v83, v79
	v_div_fmas_f32 v76, v76, v77, v83
	v_div_fixup_f32 v12, v76, v12, 1.0
	v_cvt_pk_bf16_f32 v76, v12, v13
	v_cvt_f32_i32_e32 v12, v14
	v_cvt_f32_i32_e32 v13, v15
	v_mul_f32_e32 v12, v78, v12
	v_mul_f32_e32 v13, v78, v13
	v_mul_f32_e32 v12, v12, v18
	v_mul_f32_e32 v13, v13, v19
	v_mul_f32_e32 v12, 0xbfb8aa3b, v12
	v_mul_f32_e32 v13, 0xbfb8aa3b, v13
	v_exp_f32_e32 v12, v12
	v_exp_f32_e32 v13, v13
	s_nop 0
	v_pk_add_f32 v[12:13], v[12:13], 1.0 op_sel_hi:[1,0]
	s_nop 0
	v_div_scale_f32 v14, s[14:15], v13, v13, 1.0
	v_rcp_f32_e32 v15, v14
	s_nop 0
	v_fma_f32 v77, -v14, v15, 1.0
	v_fmac_f32_e32 v15, v77, v15
	v_div_scale_f32 v77, vcc, 1.0, v13, 1.0
	v_mul_f32_e32 v79, v77, v15
	v_fma_f32 v83, -v14, v79, v77
	v_fmac_f32_e32 v79, v83, v15
	v_fma_f32 v14, -v14, v79, v77
	v_div_fmas_f32 v14, v14, v15, v79
	v_div_fixup_f32 v13, v14, v13, 1.0
	v_div_scale_f32 v14, s[14:15], v12, v12, 1.0
	v_rcp_f32_e32 v15, v14
	s_nop 0
	v_fma_f32 v77, -v14, v15, 1.0
	v_fmac_f32_e32 v15, v77, v15
	v_div_scale_f32 v77, vcc, 1.0, v12, 1.0
	v_mul_f32_e32 v79, v77, v15
	v_fma_f32 v83, -v14, v79, v77
	v_fmac_f32_e32 v79, v83, v15
	v_fma_f32 v14, -v14, v79, v77
	v_div_fmas_f32 v14, v14, v15, v79
	v_div_fixup_f32 v12, v14, v12, 1.0
	v_cvt_pk_bf16_f32 v77, v12, v13
	flat_load_dwordx4 v[12:15], v[70:71] offset:320
	s_waitcnt vmcnt(0) lgkmcnt(0)
	v_mul_f32_e32 v64, v64, v12
	v_mul_f32_e32 v65, v65, v13
	v_mul_f32_e32 v64, 0xbfb8aa3b, v64
	v_mul_f32_e32 v65, 0xbfb8aa3b, v65
	v_exp_f32_e32 v64, v64
	v_exp_f32_e32 v65, v65
	s_nop 0
	v_pk_add_f32 v[64:65], v[64:65], 1.0 op_sel_hi:[1,0]
	s_nop 0
	v_div_scale_f32 v70, s[14:15], v65, v65, 1.0
	v_rcp_f32_e32 v71, v70
	s_nop 0
	v_fma_f32 v79, -v70, v71, 1.0
	v_fmac_f32_e32 v71, v79, v71
	v_div_scale_f32 v79, vcc, 1.0, v65, 1.0
	v_mul_f32_e32 v83, v79, v71
	v_fma_f32 v84, -v70, v83, v79
	v_fmac_f32_e32 v83, v84, v71
	v_fma_f32 v70, -v70, v83, v79
	v_div_fmas_f32 v70, v70, v71, v83
	v_div_fixup_f32 v65, v70, v65, 1.0
	v_div_scale_f32 v70, s[14:15], v64, v64, 1.0
	v_rcp_f32_e32 v71, v70
	s_nop 0
	v_fma_f32 v79, -v70, v71, 1.0
	v_fmac_f32_e32 v71, v79, v71
	v_div_scale_f32 v79, vcc, 1.0, v64, 1.0
	v_mul_f32_e32 v83, v79, v71
	v_fma_f32 v84, -v70, v83, v79
	v_fmac_f32_e32 v83, v84, v71
	v_fma_f32 v70, -v70, v83, v79
	v_div_fmas_f32 v70, v70, v71, v83
	v_div_fixup_f32 v64, v70, v64, 1.0
	v_cvt_pk_bf16_f32 v64, v64, v65
	v_cvt_f32_i32_e32 v65, v66
	v_mul_f32_e32 v65, v78, v65
	v_mul_f32_e32 v65, v65, v14
	v_mul_f32_e32 v65, 0xbfb8aa3b, v65
	v_exp_f32_e32 v66, v65
	v_cvt_f32_i32_e32 v65, v67
	v_mul_f32_e32 v65, v78, v65
	v_mul_f32_e32 v65, v65, v15
	v_mul_f32_e32 v65, 0xbfb8aa3b, v65
	v_exp_f32_e32 v67, v65
	s_nop 0
	v_pk_add_f32 v[66:67], v[66:67], 1.0 op_sel_hi:[1,0]
	s_nop 0
	v_div_scale_f32 v65, s[14:15], v67, v67, 1.0
	v_rcp_f32_e32 v70, v65
	s_nop 0
	v_fma_f32 v71, -v65, v70, 1.0
	v_fmac_f32_e32 v70, v71, v70
	v_div_scale_f32 v71, vcc, 1.0, v67, 1.0
	v_mul_f32_e32 v78, v71, v70
	v_fma_f32 v79, -v65, v78, v71
	v_fmac_f32_e32 v78, v79, v70
	v_fma_f32 v65, -v65, v78, v71
	v_div_fmas_f32 v65, v65, v70, v78
	v_div_fixup_f32 v65, v65, v67, 1.0
	v_div_scale_f32 v67, s[14:15], v66, v66, 1.0
	v_rcp_f32_e32 v70, v67
	s_nop 0
	v_fma_f32 v71, -v67, v70, 1.0
	v_fmac_f32_e32 v70, v71, v70
	v_div_scale_f32 v71, vcc, 1.0, v66, 1.0
	v_mul_f32_e32 v78, v71, v70
	v_fma_f32 v79, -v67, v78, v71
	v_fmac_f32_e32 v78, v79, v70
	v_fma_f32 v67, -v67, v78, v71
	v_div_fmas_f32 v67, v67, v70, v78
	v_div_fixup_f32 v66, v67, v66, 1.0
	v_cvt_pk_bf16_f32 v65, v66, v65
	flat_load_dword v66, v[68:69] offset:64
	s_waitcnt vmcnt(0) lgkmcnt(0)
; #define P (*launderP(lp))
; DEV float sigm(float x) { return 1.f / (1.f + __expf(-x)); }
; __device__ __forceinline__ void phase_gemm45(PREF P, char* smem, int which) {
;     ...
; #pragma unroll
;         for (int i = 0; i < 4; ++i) {
;           const int row = m0 + wm * 64 + i * 16 + l15;
;     ...
; #pragma unroll
;           for (int j = 0; j < 4; ++j) {
;             const int col = n0 + (j & 1) * 16 + wn * 32 + (j >> 1) * 64 + q * 4;
;             const float4 swc = *(const float4*)(P.swpg + col);
;             part[i][j][0] = pack2(sigm((float)iacc[i][j][0] * shr * swc.x), sigm((float)iacc[i][j][1] * shr * swc.y));
;             part[i][j][1] = pack2(sigm((float)iacc[i][j][2] * shr * swc.z), sigm((float)iacc[i][j][3] * shr * swc.w));
;           }
;         }
	v_mul_f32_e32 v60, v66, v60
	v_mul_f32_e32 v61, v66, v61
	v_mul_f32_e32 v60, v24, v60
	v_mul_f32_e32 v61, v25, v61
	v_mul_f32_e32 v60, 0xbfb8aa3b, v60
	v_mul_f32_e32 v61, 0xbfb8aa3b, v61
	v_exp_f32_e32 v60, v60
	v_exp_f32_e32 v61, v61
	v_mul_f32_e32 v56, v66, v56
	v_mul_f32_e32 v57, v66, v57
	v_mul_f32_e32 v56, v28, v56
	v_pk_add_f32 v[60:61], v[60:61], 1.0 op_sel_hi:[1,0]
	v_mul_f32_e32 v57, v29, v57
	v_div_scale_f32 v67, s[14:15], v61, v61, 1.0
	v_rcp_f32_e32 v70, v67
	v_mul_f32_e32 v56, 0xbfb8aa3b, v56
	v_mul_f32_e32 v57, 0xbfb8aa3b, v57
	v_exp_f32_e32 v56, v56
	v_fma_f32 v71, -v67, v70, 1.0
	v_fmac_f32_e32 v70, v71, v70
	v_div_scale_f32 v71, vcc, 1.0, v61, 1.0
	v_mul_f32_e32 v78, v71, v70
	v_fma_f32 v79, -v67, v78, v71
	v_fmac_f32_e32 v78, v79, v70
	v_fma_f32 v67, -v67, v78, v71
	v_div_fmas_f32 v67, v67, v70, v78
	v_div_fixup_f32 v61, v67, v61, 1.0
	v_div_scale_f32 v67, s[14:15], v60, v60, 1.0
	v_rcp_f32_e32 v70, v67
	v_exp_f32_e32 v57, v57
	v_mul_f32_e32 v52, v66, v52
	v_mul_f32_e32 v53, v66, v53
	v_fma_f32 v71, -v67, v70, 1.0
	v_fmac_f32_e32 v70, v71, v70
	v_div_scale_f32 v71, vcc, 1.0, v60, 1.0
	v_mul_f32_e32 v78, v71, v70
	v_fma_f32 v79, -v67, v78, v71
	v_fmac_f32_e32 v78, v79, v70
	v_fma_f32 v67, -v67, v78, v71
	v_div_fmas_f32 v67, v67, v70, v78
	v_div_fixup_f32 v60, v67, v60, 1.0
	v_cvt_pk_bf16_f32 v60, v60, v61
	v_cvt_f32_i32_e32 v61, v62
	v_pk_add_f32 v[56:57], v[56:57], 1.0 op_sel_hi:[1,0]
	v_mul_f32_e32 v52, v16, v52
	v_mul_f32_e32 v53, v17, v53
	v_mul_f32_e32 v61, v66, v61
	v_mul_f32_e32 v61, v26, v61
	v_mul_f32_e32 v61, 0xbfb8aa3b, v61
	v_exp_f32_e32 v62, v61
	v_cvt_f32_i32_e32 v61, v63
	v_mul_f32_e32 v52, 0xbfb8aa3b, v52
	v_mul_f32_e32 v53, 0xbfb8aa3b, v53
	v_exp_f32_e32 v52, v52
	v_mul_f32_e32 v61, v66, v61
	v_mul_f32_e32 v61, v27, v61
	v_mul_f32_e32 v61, 0xbfb8aa3b, v61
	v_exp_f32_e32 v63, v61
	v_exp_f32_e32 v53, v53
	v_mul_f32_e32 v48, v66, v48
	v_mul_f32_e32 v49, v66, v49
	v_pk_add_f32 v[62:63], v[62:63], 1.0 op_sel_hi:[1,0]
	v_pk_add_f32 v[52:53], v[52:53], 1.0 op_sel_hi:[1,0]
	v_div_scale_f32 v61, s[14:15], v63, v63, 1.0
	v_rcp_f32_e32 v67, v61
	v_mul_f32_e32 v48, v12, v48
	v_mul_f32_e32 v49, v13, v49
	v_mul_f32_e32 v48, 0xbfb8aa3b, v48
	v_fma_f32 v70, -v61, v67, 1.0
	v_fmac_f32_e32 v67, v70, v67
	v_div_scale_f32 v70, vcc, 1.0, v63, 1.0
	v_mul_f32_e32 v71, v70, v67
	v_fma_f32 v78, -v61, v71, v70
	v_fmac_f32_e32 v71, v78, v67
	v_fma_f32 v61, -v61, v71, v70
	v_div_fmas_f32 v61, v61, v67, v71
	v_div_fixup_f32 v61, v61, v63, 1.0
	v_div_scale_f32 v63, s[14:15], v62, v62, 1.0
	v_rcp_f32_e32 v67, v63
	v_mul_f32_e32 v49, 0xbfb8aa3b, v49
	v_exp_f32_e32 v48, v48
	v_exp_f32_e32 v49, v49
	v_fma_f32 v70, -v63, v67, 1.0
	v_fmac_f32_e32 v67, v70, v67
	v_div_scale_f32 v70, vcc, 1.0, v62, 1.0
	v_mul_f32_e32 v71, v70, v67
	v_fma_f32 v78, -v63, v71, v70
	v_fmac_f32_e32 v71, v78, v67
	v_fma_f32 v63, -v63, v71, v70
	v_div_fmas_f32 v63, v63, v67, v71
	v_div_fixup_f32 v62, v63, v62, 1.0
	v_cvt_pk_bf16_f32 v61, v62, v61
	v_div_scale_f32 v62, s[14:15], v57, v57, 1.0
	v_rcp_f32_e32 v63, v62
	v_pk_add_f32 v[48:49], v[48:49], 1.0 op_sel_hi:[1,0]
	v_fma_f32 v67, -v62, v63, 1.0
	v_fmac_f32_e32 v63, v67, v63
	v_div_scale_f32 v67, vcc, 1.0, v57, 1.0
	v_mul_f32_e32 v70, v67, v63
	v_fma_f32 v71, -v62, v70, v67
	v_fmac_f32_e32 v70, v71, v63
	v_fma_f32 v62, -v62, v70, v67
	v_div_fmas_f32 v62, v62, v63, v70
	v_div_fixup_f32 v57, v62, v57, 1.0
	v_div_scale_f32 v62, s[14:15], v56, v56, 1.0
	v_rcp_f32_e32 v63, v62
	s_nop 0
	v_fma_f32 v67, -v62, v63, 1.0
	v_fmac_f32_e32 v63, v67, v63
	v_div_scale_f32 v67, vcc, 1.0, v56, 1.0
	v_mul_f32_e32 v70, v67, v63
	v_fma_f32 v71, -v62, v70, v67
	v_fmac_f32_e32 v70, v71, v63
	v_fma_f32 v62, -v62, v70, v67
	v_div_fmas_f32 v62, v62, v63, v70
	v_div_fixup_f32 v56, v62, v56, 1.0
	v_cvt_pk_bf16_f32 v56, v56, v57
	v_cvt_f32_i32_e32 v57, v58
	v_mul_f32_e32 v57, v66, v57
	v_mul_f32_e32 v57, v30, v57
	v_mul_f32_e32 v57, 0xbfb8aa3b, v57
	v_exp_f32_e32 v58, v57
	v_cvt_f32_i32_e32 v57, v59
	v_mul_f32_e32 v57, v66, v57
	v_mul_f32_e32 v57, v31, v57
	v_mul_f32_e32 v57, 0xbfb8aa3b, v57
	v_exp_f32_e32 v59, v57
	s_nop 0
	v_pk_add_f32 v[58:59], v[58:59], 1.0 op_sel_hi:[1,0]
	s_nop 0
	v_div_scale_f32 v57, s[14:15], v59, v59, 1.0
	v_rcp_f32_e32 v62, v57
	s_nop 0
	v_fma_f32 v63, -v57, v62, 1.0
	v_fmac_f32_e32 v62, v63, v62
	v_div_scale_f32 v63, vcc, 1.0, v59, 1.0
	v_mul_f32_e32 v67, v63, v62
	v_fma_f32 v70, -v57, v67, v63
	v_fmac_f32_e32 v67, v70, v62
	v_fma_f32 v57, -v57, v67, v63
	v_div_fmas_f32 v57, v57, v62, v67
	v_div_fixup_f32 v57, v57, v59, 1.0
	v_div_scale_f32 v59, s[14:15], v58, v58, 1.0
	v_rcp_f32_e32 v62, v59
	s_nop 0
	v_fma_f32 v63, -v59, v62, 1.0
	v_fmac_f32_e32 v62, v63, v62
	v_div_scale_f32 v63, vcc, 1.0, v58, 1.0
	v_mul_f32_e32 v67, v63, v62
	v_fma_f32 v70, -v59, v67, v63
	v_fmac_f32_e32 v67, v70, v62
	v_fma_f32 v59, -v59, v67, v63
	v_div_fmas_f32 v59, v59, v62, v67
	v_div_fixup_f32 v58, v59, v58, 1.0
	v_cvt_pk_bf16_f32 v57, v58, v57
	v_div_scale_f32 v58, s[14:15], v53, v53, 1.0
	v_rcp_f32_e32 v59, v58
	s_nop 0
	v_fma_f32 v62, -v58, v59, 1.0
	v_fmac_f32_e32 v59, v62, v59
	v_div_scale_f32 v62, vcc, 1.0, v53, 1.0
	v_mul_f32_e32 v63, v62, v59
	v_fma_f32 v67, -v58, v63, v62
	v_fmac_f32_e32 v63, v67, v59
	v_fma_f32 v58, -v58, v63, v62
	v_div_fmas_f32 v58, v58, v59, v63
	v_div_fixup_f32 v53, v58, v53, 1.0
	v_div_scale_f32 v58, s[14:15], v52, v52, 1.0
	v_rcp_f32_e32 v59, v58
	s_nop 0
	v_fma_f32 v62, -v58, v59, 1.0
	v_fmac_f32_e32 v59, v62, v59
	v_div_scale_f32 v62, vcc, 1.0, v52, 1.0
	v_mul_f32_e32 v63, v62, v59
	v_fma_f32 v67, -v58, v63, v62
	v_fmac_f32_e32 v63, v67, v59
	v_fma_f32 v58, -v58, v63, v62
	v_div_fmas_f32 v58, v58, v59, v63
; #define P (*launderP(lp))
; DEV float sigm(float x) { return 1.f / (1.f + __expf(-x)); }
; __device__ __forceinline__ void phase_gemm45(PREF P, char* smem, int which) {
;     ...
; #pragma unroll
;         for (int i = 0; i < 4; ++i) {
;           const int row = m0 + wm * 64 + i * 16 + l15;
;     ...
; #pragma unroll
;           for (int j = 0; j < 4; ++j) {
;             const int col = n0 + (j & 1) * 16 + wn * 32 + (j >> 1) * 64 + q * 4;
;             const float4 swc = *(const float4*)(P.swpg + col);
;             part[i][j][0] = pack2(sigm((float)iacc[i][j][0] * shr * swc.x), sigm((float)iacc[i][j][1] * shr * swc.y));
;             part[i][j][1] = pack2(sigm((float)iacc[i][j][2] * shr * swc.z), sigm((float)iacc[i][j][3] * shr * swc.w));
;           }
;         }
	v_div_fixup_f32 v52, v58, v52, 1.0
	v_cvt_pk_bf16_f32 v52, v52, v53
	v_cvt_f32_i32_e32 v53, v54
	v_mul_f32_e32 v53, v66, v53
	v_mul_f32_e32 v53, v18, v53
	v_mul_f32_e32 v53, 0xbfb8aa3b, v53
	v_exp_f32_e32 v54, v53
	v_cvt_f32_i32_e32 v53, v55
	v_mul_f32_e32 v53, v66, v53
	v_mul_f32_e32 v53, v19, v53
	v_mul_f32_e32 v53, 0xbfb8aa3b, v53
	v_exp_f32_e32 v55, v53
	s_nop 0
	v_pk_add_f32 v[54:55], v[54:55], 1.0 op_sel_hi:[1,0]
	s_nop 0
	v_div_scale_f32 v53, s[14:15], v55, v55, 1.0
	v_rcp_f32_e32 v58, v53
	s_nop 0
	v_fma_f32 v59, -v53, v58, 1.0
	v_fmac_f32_e32 v58, v59, v58
	v_div_scale_f32 v59, vcc, 1.0, v55, 1.0
	v_mul_f32_e32 v62, v59, v58
	v_fma_f32 v63, -v53, v62, v59
	v_fmac_f32_e32 v62, v63, v58
	v_fma_f32 v53, -v53, v62, v59
	v_div_fmas_f32 v53, v53, v58, v62
	v_div_fixup_f32 v53, v53, v55, 1.0
	v_div_scale_f32 v55, s[14:15], v54, v54, 1.0
	v_rcp_f32_e32 v58, v55
	s_nop 0
	v_fma_f32 v59, -v55, v58, 1.0
	v_fmac_f32_e32 v58, v59, v58
	v_div_scale_f32 v59, vcc, 1.0, v54, 1.0
	v_mul_f32_e32 v62, v59, v58
	v_fma_f32 v63, -v55, v62, v59
	v_fmac_f32_e32 v62, v63, v58
	v_fma_f32 v55, -v55, v62, v59
	v_div_fmas_f32 v55, v55, v58, v62
	v_div_fixup_f32 v54, v55, v54, 1.0
	v_cvt_pk_bf16_f32 v53, v54, v53
	v_div_scale_f32 v54, s[14:15], v49, v49, 1.0
	v_rcp_f32_e32 v55, v54
	s_nop 0
	v_fma_f32 v58, -v54, v55, 1.0
	v_fmac_f32_e32 v55, v58, v55
	v_div_scale_f32 v58, vcc, 1.0, v49, 1.0
	v_mul_f32_e32 v59, v58, v55
	v_fma_f32 v62, -v54, v59, v58
	v_fmac_f32_e32 v59, v62, v55
	v_fma_f32 v54, -v54, v59, v58
	v_div_fmas_f32 v54, v54, v55, v59
	v_div_fixup_f32 v49, v54, v49, 1.0
	v_div_scale_f32 v54, s[14:15], v48, v48, 1.0
	v_rcp_f32_e32 v55, v54
	s_nop 0
	v_fma_f32 v58, -v54, v55, 1.0
	v_fmac_f32_e32 v55, v58, v55
	v_div_scale_f32 v58, vcc, 1.0, v48, 1.0
	v_mul_f32_e32 v59, v58, v55
	v_fma_f32 v62, -v54, v59, v58
	v_fmac_f32_e32 v59, v62, v55
	v_fma_f32 v54, -v54, v59, v58
	v_div_fmas_f32 v54, v54, v55, v59
	v_div_fixup_f32 v48, v54, v48, 1.0
	v_cvt_pk_bf16_f32 v48, v48, v49
	v_cvt_f32_i32_e32 v49, v50
	v_mul_f32_e32 v49, v66, v49
	v_mul_f32_e32 v49, v14, v49
	v_mul_f32_e32 v49, 0xbfb8aa3b, v49
	v_exp_f32_e32 v50, v49
	v_cvt_f32_i32_e32 v49, v51
	v_mul_f32_e32 v49, v66, v49
	v_mul_f32_e32 v49, v15, v49
	v_mul_f32_e32 v49, 0xbfb8aa3b, v49
	v_exp_f32_e32 v51, v49
	s_nop 0
	v_pk_add_f32 v[50:51], v[50:51], 1.0 op_sel_hi:[1,0]
	s_nop 0
	v_div_scale_f32 v49, s[14:15], v51, v51, 1.0
	v_rcp_f32_e32 v54, v49
	s_nop 0
	v_fma_f32 v55, -v49, v54, 1.0
	v_fmac_f32_e32 v54, v55, v54
	v_div_scale_f32 v55, vcc, 1.0, v51, 1.0
	v_mul_f32_e32 v58, v55, v54
	v_fma_f32 v59, -v49, v58, v55
	v_fmac_f32_e32 v58, v59, v54
	v_fma_f32 v49, -v49, v58, v55
	v_div_fmas_f32 v49, v49, v54, v58
	v_div_fixup_f32 v49, v49, v51, 1.0
	v_div_scale_f32 v51, s[14:15], v50, v50, 1.0
	v_rcp_f32_e32 v54, v51
	s_nop 0
	v_fma_f32 v55, -v51, v54, 1.0
	v_fmac_f32_e32 v54, v55, v54
	v_div_scale_f32 v55, vcc, 1.0, v50, 1.0
	v_mul_f32_e32 v58, v55, v54
	v_fma_f32 v59, -v51, v58, v55
	v_fmac_f32_e32 v58, v59, v54
	v_fma_f32 v51, -v51, v58, v55
	v_div_fmas_f32 v51, v51, v54, v58
	v_div_fixup_f32 v50, v51, v50, 1.0
	v_cvt_pk_bf16_f32 v49, v50, v49
	flat_load_dword v50, v[68:69] offset:128
	s_waitcnt vmcnt(0) lgkmcnt(0)
	v_mul_f32_e32 v44, v50, v44
	v_mul_f32_e32 v45, v50, v45
	v_mul_f32_e32 v44, v24, v44
	v_mul_f32_e32 v45, v25, v45
	v_mul_f32_e32 v44, 0xbfb8aa3b, v44
	v_mul_f32_e32 v45, 0xbfb8aa3b, v45
	v_exp_f32_e32 v44, v44
	v_exp_f32_e32 v45, v45
	v_mul_f32_e32 v40, v50, v40
	v_mul_f32_e32 v41, v50, v41
	v_mul_f32_e32 v40, v28, v40
	v_pk_add_f32 v[44:45], v[44:45], 1.0 op_sel_hi:[1,0]
	v_mul_f32_e32 v41, v29, v41
	v_div_scale_f32 v51, s[14:15], v45, v45, 1.0
	v_rcp_f32_e32 v54, v51
	v_mul_f32_e32 v40, 0xbfb8aa3b, v40
	v_mul_f32_e32 v41, 0xbfb8aa3b, v41
	v_exp_f32_e32 v40, v40
	v_fma_f32 v55, -v51, v54, 1.0
	v_fmac_f32_e32 v54, v55, v54
	v_div_scale_f32 v55, vcc, 1.0, v45, 1.0
	v_mul_f32_e32 v58, v55, v54
	v_fma_f32 v59, -v51, v58, v55
	v_fmac_f32_e32 v58, v59, v54
	v_fma_f32 v51, -v51, v58, v55
	v_div_fmas_f32 v51, v51, v54, v58
	v_div_fixup_f32 v45, v51, v45, 1.0
	v_div_scale_f32 v51, s[14:15], v44, v44, 1.0
	v_rcp_f32_e32 v54, v51
	v_exp_f32_e32 v41, v41
	v_mul_f32_e32 v36, v50, v36
	v_mul_f32_e32 v37, v50, v37
	v_fma_f32 v55, -v51, v54, 1.0
	v_fmac_f32_e32 v54, v55, v54
	v_div_scale_f32 v55, vcc, 1.0, v44, 1.0
	v_mul_f32_e32 v58, v55, v54
	v_fma_f32 v59, -v51, v58, v55
	v_fmac_f32_e32 v58, v59, v54
	v_fma_f32 v51, -v51, v58, v55
	v_div_fmas_f32 v51, v51, v54, v58
	v_div_fixup_f32 v44, v51, v44, 1.0
	v_cvt_pk_bf16_f32 v44, v44, v45
	v_cvt_f32_i32_e32 v45, v46
	v_pk_add_f32 v[40:41], v[40:41], 1.0 op_sel_hi:[1,0]
	v_mul_f32_e32 v36, v16, v36
	v_mul_f32_e32 v37, v17, v37
	v_mul_f32_e32 v45, v50, v45
	v_mul_f32_e32 v45, v26, v45
	v_mul_f32_e32 v45, 0xbfb8aa3b, v45
	v_exp_f32_e32 v46, v45
	v_cvt_f32_i32_e32 v45, v47
	v_mul_f32_e32 v36, 0xbfb8aa3b, v36
	v_mul_f32_e32 v37, 0xbfb8aa3b, v37
	v_exp_f32_e32 v36, v36
	v_mul_f32_e32 v45, v50, v45
	v_mul_f32_e32 v45, v27, v45
	v_mul_f32_e32 v45, 0xbfb8aa3b, v45
	v_exp_f32_e32 v47, v45
	v_exp_f32_e32 v37, v37
	v_mul_f32_e32 v32, v50, v32
	v_mul_f32_e32 v33, v50, v33
	v_pk_add_f32 v[46:47], v[46:47], 1.0 op_sel_hi:[1,0]
	v_pk_add_f32 v[36:37], v[36:37], 1.0 op_sel_hi:[1,0]
	v_div_scale_f32 v45, s[14:15], v47, v47, 1.0
	v_rcp_f32_e32 v51, v45
	v_mul_f32_e32 v32, v12, v32
	v_mul_f32_e32 v33, v13, v33
	v_mul_f32_e32 v32, 0xbfb8aa3b, v32
	v_fma_f32 v54, -v45, v51, 1.0
	v_fmac_f32_e32 v51, v54, v51
	v_div_scale_f32 v54, vcc, 1.0, v47, 1.0
	v_mul_f32_e32 v55, v54, v51
	v_fma_f32 v58, -v45, v55, v54
	v_fmac_f32_e32 v55, v58, v51
	v_fma_f32 v45, -v45, v55, v54
; DEV float sigm(float x) { return 1.f / (1.f + __expf(-x)); }
; #define P (*launderP(lp))
; __device__ __forceinline__ void phase_gemm45(PREF P, char* smem, int which) {
;     ...
;         for (int i = 0; i < 4; ++i) {
;           const int row = m0 + wm * 64 + i * 16 + l15;
;     ...
; #pragma unroll
;           for (int j = 0; j < 4; ++j) {
;             const int col = n0 + (j & 1) * 16 + wn * 32 + (j >> 1) * 64 + q * 4;
;             const float4 swc = *(const float4*)(P.swpg + col);
;             part[i][j][0] = pack2(sigm((float)iacc[i][j][0] * shr * swc.x), sigm((float)iacc[i][j][1] * shr * swc.y));
;             part[i][j][1] = pack2(sigm((float)iacc[i][j][2] * shr * swc.z), sigm((float)iacc[i][j][3] * shr * swc.w));
;           }
;         }
	v_div_fmas_f32 v45, v45, v51, v55
	v_div_fixup_f32 v45, v45, v47, 1.0
	v_div_scale_f32 v47, s[14:15], v46, v46, 1.0
	v_rcp_f32_e32 v51, v47
	v_mul_f32_e32 v33, 0xbfb8aa3b, v33
	v_exp_f32_e32 v32, v32
	v_exp_f32_e32 v33, v33
	v_fma_f32 v54, -v47, v51, 1.0
	v_fmac_f32_e32 v51, v54, v51
	v_div_scale_f32 v54, vcc, 1.0, v46, 1.0
	v_mul_f32_e32 v55, v54, v51
	v_fma_f32 v58, -v47, v55, v54
	v_fmac_f32_e32 v55, v58, v51
	v_fma_f32 v47, -v47, v55, v54
	v_div_fmas_f32 v47, v47, v51, v55
	v_div_fixup_f32 v46, v47, v46, 1.0
	v_cvt_pk_bf16_f32 v45, v46, v45
	v_div_scale_f32 v46, s[14:15], v41, v41, 1.0
	v_rcp_f32_e32 v47, v46
	v_pk_add_f32 v[32:33], v[32:33], 1.0 op_sel_hi:[1,0]
	v_fma_f32 v51, -v46, v47, 1.0
	v_fmac_f32_e32 v47, v51, v47
	v_div_scale_f32 v51, vcc, 1.0, v41, 1.0
	v_mul_f32_e32 v54, v51, v47
	v_fma_f32 v55, -v46, v54, v51
	v_fmac_f32_e32 v54, v55, v47
	v_fma_f32 v46, -v46, v54, v51
	v_div_fmas_f32 v46, v46, v47, v54
	v_div_fixup_f32 v41, v46, v41, 1.0
	v_div_scale_f32 v46, s[14:15], v40, v40, 1.0
	v_rcp_f32_e32 v47, v46
	s_nop 0
	v_fma_f32 v51, -v46, v47, 1.0
	v_fmac_f32_e32 v47, v51, v47
	v_div_scale_f32 v51, vcc, 1.0, v40, 1.0
	v_mul_f32_e32 v54, v51, v47
	v_fma_f32 v55, -v46, v54, v51
	v_fmac_f32_e32 v54, v55, v47
	v_fma_f32 v46, -v46, v54, v51
	v_div_fmas_f32 v46, v46, v47, v54
	v_div_fixup_f32 v40, v46, v40, 1.0
	v_cvt_pk_bf16_f32 v40, v40, v41
	v_cvt_f32_i32_e32 v41, v42
	v_mul_f32_e32 v41, v50, v41
	v_mul_f32_e32 v41, v30, v41
	v_mul_f32_e32 v41, 0xbfb8aa3b, v41
	v_exp_f32_e32 v42, v41
	v_cvt_f32_i32_e32 v41, v43
	v_mul_f32_e32 v41, v50, v41
	v_mul_f32_e32 v41, v31, v41
	v_mul_f32_e32 v41, 0xbfb8aa3b, v41
	v_exp_f32_e32 v43, v41
	s_nop 0
	v_pk_add_f32 v[42:43], v[42:43], 1.0 op_sel_hi:[1,0]
	s_nop 0
	v_div_scale_f32 v41, s[14:15], v43, v43, 1.0
	v_rcp_f32_e32 v46, v41
	s_nop 0
	v_fma_f32 v47, -v41, v46, 1.0
	v_fmac_f32_e32 v46, v47, v46
	v_div_scale_f32 v47, vcc, 1.0, v43, 1.0
	v_mul_f32_e32 v51, v47, v46
	v_fma_f32 v54, -v41, v51, v47
	v_fmac_f32_e32 v51, v54, v46
	v_fma_f32 v41, -v41, v51, v47
	v_div_fmas_f32 v41, v41, v46, v51
	v_div_fixup_f32 v41, v41, v43, 1.0
	v_div_scale_f32 v43, s[14:15], v42, v42, 1.0
	v_rcp_f32_e32 v46, v43
	s_nop 0
	v_fma_f32 v47, -v43, v46, 1.0
	v_fmac_f32_e32 v46, v47, v46
	v_div_scale_f32 v47, vcc, 1.0, v42, 1.0
	v_mul_f32_e32 v51, v47, v46
	v_fma_f32 v54, -v43, v51, v47
	v_fmac_f32_e32 v51, v54, v46
	v_fma_f32 v43, -v43, v51, v47
	v_div_fmas_f32 v43, v43, v46, v51
	v_div_fixup_f32 v42, v43, v42, 1.0
	v_cvt_pk_bf16_f32 v41, v42, v41
	v_div_scale_f32 v42, s[14:15], v37, v37, 1.0
	v_rcp_f32_e32 v43, v42
	s_nop 0
	v_fma_f32 v46, -v42, v43, 1.0
	v_fmac_f32_e32 v43, v46, v43
	v_div_scale_f32 v46, vcc, 1.0, v37, 1.0
	v_mul_f32_e32 v47, v46, v43
	v_fma_f32 v51, -v42, v47, v46
	v_fmac_f32_e32 v47, v51, v43
	v_fma_f32 v42, -v42, v47, v46
	v_div_fmas_f32 v42, v42, v43, v47
	v_div_fixup_f32 v37, v42, v37, 1.0
	v_div_scale_f32 v42, s[14:15], v36, v36, 1.0
	v_rcp_f32_e32 v43, v42
	s_nop 0
	v_fma_f32 v46, -v42, v43, 1.0
	v_fmac_f32_e32 v43, v46, v43
	v_div_scale_f32 v46, vcc, 1.0, v36, 1.0
	v_mul_f32_e32 v47, v46, v43
	v_fma_f32 v51, -v42, v47, v46
	v_fmac_f32_e32 v47, v51, v43
	v_fma_f32 v42, -v42, v47, v46
	v_div_fmas_f32 v42, v42, v43, v47
	v_div_fixup_f32 v36, v42, v36, 1.0
	v_cvt_pk_bf16_f32 v36, v36, v37
	v_cvt_f32_i32_e32 v37, v38
	v_mul_f32_e32 v37, v50, v37
	v_mul_f32_e32 v37, v18, v37
	v_mul_f32_e32 v37, 0xbfb8aa3b, v37
	v_exp_f32_e32 v38, v37
	v_cvt_f32_i32_e32 v37, v39
	v_mul_f32_e32 v37, v50, v37
	v_mul_f32_e32 v37, v19, v37
	v_mul_f32_e32 v37, 0xbfb8aa3b, v37
	v_exp_f32_e32 v39, v37
	s_nop 0
	v_pk_add_f32 v[38:39], v[38:39], 1.0 op_sel_hi:[1,0]
	s_nop 0
	v_div_scale_f32 v37, s[14:15], v39, v39, 1.0
	v_rcp_f32_e32 v42, v37
	s_nop 0
	v_fma_f32 v43, -v37, v42, 1.0
	v_fmac_f32_e32 v42, v43, v42
	v_div_scale_f32 v43, vcc, 1.0, v39, 1.0
	v_mul_f32_e32 v46, v43, v42
	v_fma_f32 v47, -v37, v46, v43
	v_fmac_f32_e32 v46, v47, v42
	v_fma_f32 v37, -v37, v46, v43
	v_div_fmas_f32 v37, v37, v42, v46
	v_div_fixup_f32 v37, v37, v39, 1.0
	v_div_scale_f32 v39, s[14:15], v38, v38, 1.0
	v_rcp_f32_e32 v42, v39
	s_nop 0
	v_fma_f32 v43, -v39, v42, 1.0
	v_fmac_f32_e32 v42, v43, v42
	v_div_scale_f32 v43, vcc, 1.0, v38, 1.0
	v_mul_f32_e32 v46, v43, v42
	v_fma_f32 v47, -v39, v46, v43
	v_fmac_f32_e32 v46, v47, v42
	v_fma_f32 v39, -v39, v46, v43
	v_div_fmas_f32 v39, v39, v42, v46
	v_div_fixup_f32 v38, v39, v38, 1.0
	v_cvt_pk_bf16_f32 v37, v38, v37
	v_div_scale_f32 v38, s[14:15], v33, v33, 1.0
	v_rcp_f32_e32 v39, v38
	s_nop 0
	v_fma_f32 v42, -v38, v39, 1.0
	v_fmac_f32_e32 v39, v42, v39
	v_div_scale_f32 v42, vcc, 1.0, v33, 1.0
	v_mul_f32_e32 v43, v42, v39
	v_fma_f32 v46, -v38, v43, v42
	v_fmac_f32_e32 v43, v46, v39
	v_fma_f32 v38, -v38, v43, v42
	v_div_fmas_f32 v38, v38, v39, v43
	v_div_fixup_f32 v33, v38, v33, 1.0
	v_div_scale_f32 v38, s[14:15], v32, v32, 1.0
	v_rcp_f32_e32 v39, v38
	s_nop 0
	v_fma_f32 v42, -v38, v39, 1.0
	v_fmac_f32_e32 v39, v42, v39
	v_div_scale_f32 v42, vcc, 1.0, v32, 1.0
	v_mul_f32_e32 v43, v42, v39
	v_fma_f32 v46, -v38, v43, v42
	v_fmac_f32_e32 v43, v46, v39
	v_fma_f32 v38, -v38, v43, v42
	v_div_fmas_f32 v38, v38, v39, v43
	v_div_fixup_f32 v32, v38, v32, 1.0
	v_cvt_pk_bf16_f32 v32, v32, v33
	v_cvt_f32_i32_e32 v33, v34
	v_mul_f32_e32 v33, v50, v33
	v_mul_f32_e32 v33, v14, v33
	v_mul_f32_e32 v33, 0xbfb8aa3b, v33
	v_exp_f32_e32 v34, v33
	v_cvt_f32_i32_e32 v33, v35
	v_mul_f32_e32 v33, v50, v33
	v_mul_f32_e32 v33, v15, v33
	v_mul_f32_e32 v33, 0xbfb8aa3b, v33
	v_exp_f32_e32 v35, v33
	s_nop 0
	v_pk_add_f32 v[34:35], v[34:35], 1.0 op_sel_hi:[1,0]
	s_nop 0
	v_div_scale_f32 v33, s[14:15], v35, v35, 1.0
	v_rcp_f32_e32 v38, v33
	s_nop 0
	v_fma_f32 v39, -v33, v38, 1.0
	v_fmac_f32_e32 v38, v39, v38
	v_div_scale_f32 v39, vcc, 1.0, v35, 1.0
	v_mul_f32_e32 v42, v39, v38
	v_fma_f32 v43, -v33, v42, v39
	v_fmac_f32_e32 v42, v43, v38
	v_fma_f32 v33, -v33, v42, v39
	v_div_fmas_f32 v33, v33, v38, v42
	v_div_fixup_f32 v33, v33, v35, 1.0
	v_div_scale_f32 v35, s[14:15], v34, v34, 1.0
	v_rcp_f32_e32 v38, v35
	s_nop 0
	v_fma_f32 v39, -v35, v38, 1.0
	v_fmac_f32_e32 v38, v39, v38
	v_div_scale_f32 v39, vcc, 1.0, v34, 1.0
	v_mul_f32_e32 v42, v39, v38
	v_fma_f32 v43, -v35, v42, v39
	v_fmac_f32_e32 v42, v43, v38
	v_fma_f32 v35, -v35, v42, v39
	v_div_fmas_f32 v35, v35, v38, v42
	v_div_fixup_f32 v34, v35, v34, 1.0
	v_cvt_pk_bf16_f32 v33, v34, v33
	flat_load_dword v34, v[68:69] offset:192
	s_waitcnt vmcnt(0) lgkmcnt(0)
; DEV float sigm(float x) { return 1.f / (1.f + __expf(-x)); }
; #define P (*launderP(lp))
; __device__ __forceinline__ void phase_gemm45(PREF P, char* smem, int which) {
;     ...
;         for (int i = 0; i < 4; ++i) {
;           const int row = m0 + wm * 64 + i * 16 + l15;
;     ...
; #pragma unroll
;           for (int j = 0; j < 4; ++j) {
;             const int col = n0 + (j & 1) * 16 + wn * 32 + (j >> 1) * 64 + q * 4;
;             const float4 swc = *(const float4*)(P.swpg + col);
;             part[i][j][0] = pack2(sigm((float)iacc[i][j][0] * shr * swc.x), sigm((float)iacc[i][j][1] * shr * swc.y));
;             part[i][j][1] = pack2(sigm((float)iacc[i][j][2] * shr * swc.z), sigm((float)iacc[i][j][3] * shr * swc.w));
;           }
;         }
	v_mul_f32_e32 v20, v34, v20
	v_mul_f32_e32 v21, v34, v21
	v_mul_f32_e32 v20, v24, v20
	v_mul_f32_e32 v21, v25, v21
	v_mul_f32_e32 v20, 0xbfb8aa3b, v20
	v_mul_f32_e32 v21, 0xbfb8aa3b, v21
	v_exp_f32_e32 v20, v20
	v_exp_f32_e32 v21, v21
	v_mul_f32_e32 v8, v34, v8
	v_mul_f32_e32 v9, v34, v9
	v_mul_f32_e32 v8, v28, v8
	v_pk_add_f32 v[20:21], v[20:21], 1.0 op_sel_hi:[1,0]
	v_mul_f32_e32 v9, v29, v9
	v_div_scale_f32 v24, s[14:15], v21, v21, 1.0
	v_rcp_f32_e32 v25, v24
	v_mul_f32_e32 v8, 0xbfb8aa3b, v8
	v_mul_f32_e32 v9, 0xbfb8aa3b, v9
	v_exp_f32_e32 v8, v8
	v_fma_f32 v35, -v24, v25, 1.0
	v_fmac_f32_e32 v25, v35, v25
	v_div_scale_f32 v35, vcc, 1.0, v21, 1.0
	v_mul_f32_e32 v38, v35, v25
	v_fma_f32 v39, -v24, v38, v35
	v_fmac_f32_e32 v38, v39, v25
	v_fma_f32 v24, -v24, v38, v35
	v_div_fmas_f32 v24, v24, v25, v38
	v_div_fixup_f32 v21, v24, v21, 1.0
	v_div_scale_f32 v24, s[14:15], v20, v20, 1.0
	v_rcp_f32_e32 v25, v24
	v_exp_f32_e32 v9, v9
	v_mul_f32_e32 v4, v34, v4
	v_mul_f32_e32 v5, v34, v5
	v_fma_f32 v35, -v24, v25, 1.0
	v_fmac_f32_e32 v25, v35, v25
	v_div_scale_f32 v35, vcc, 1.0, v20, 1.0
	v_mul_f32_e32 v38, v35, v25
	v_fma_f32 v39, -v24, v38, v35
	v_fmac_f32_e32 v38, v39, v25
	v_fma_f32 v24, -v24, v38, v35
	v_div_fmas_f32 v24, v24, v25, v38
	v_div_fixup_f32 v20, v24, v20, 1.0
	v_cvt_pk_bf16_f32 v20, v20, v21
	v_cvt_f32_i32_e32 v21, v22
	v_pk_add_f32 v[8:9], v[8:9], 1.0 op_sel_hi:[1,0]
	v_mul_f32_e32 v4, v16, v4
	v_mul_f32_e32 v5, v17, v5
	v_mul_f32_e32 v21, v34, v21
	v_mul_f32_e32 v21, v26, v21
	v_mul_f32_e32 v21, 0xbfb8aa3b, v21
	v_exp_f32_e32 v22, v21
	v_cvt_f32_i32_e32 v21, v23
	v_mul_f32_e32 v4, 0xbfb8aa3b, v4
	v_mul_f32_e32 v5, 0xbfb8aa3b, v5
	v_exp_f32_e32 v4, v4
	v_mul_f32_e32 v21, v34, v21
	v_mul_f32_e32 v21, v27, v21
	v_mul_f32_e32 v21, 0xbfb8aa3b, v21
	v_exp_f32_e32 v23, v21
	v_exp_f32_e32 v5, v5
	v_mul_f32_e32 v0, v34, v0
	v_mul_f32_e32 v1, v34, v1
	v_pk_add_f32 v[22:23], v[22:23], 1.0 op_sel_hi:[1,0]
	v_pk_add_f32 v[4:5], v[4:5], 1.0 op_sel_hi:[1,0]
	v_div_scale_f32 v21, s[14:15], v23, v23, 1.0
	v_rcp_f32_e32 v24, v21
	v_mul_f32_e32 v0, v12, v0
	v_mul_f32_e32 v1, v13, v1
	v_mul_f32_e32 v0, 0xbfb8aa3b, v0
	v_fma_f32 v25, -v21, v24, 1.0
	v_fmac_f32_e32 v24, v25, v24
	v_div_scale_f32 v25, vcc, 1.0, v23, 1.0
	v_mul_f32_e32 v26, v25, v24
	v_fma_f32 v27, -v21, v26, v25
	v_fmac_f32_e32 v26, v27, v24
	v_fma_f32 v21, -v21, v26, v25
	v_div_fmas_f32 v21, v21, v24, v26
	v_div_fixup_f32 v21, v21, v23, 1.0
	v_div_scale_f32 v23, s[14:15], v22, v22, 1.0
	v_rcp_f32_e32 v24, v23
	v_mul_f32_e32 v1, 0xbfb8aa3b, v1
	v_exp_f32_e32 v0, v0
	v_exp_f32_e32 v1, v1
	v_fma_f32 v25, -v23, v24, 1.0
	v_fmac_f32_e32 v24, v25, v24
	v_div_scale_f32 v25, vcc, 1.0, v22, 1.0
	v_mul_f32_e32 v26, v25, v24
	v_fma_f32 v27, -v23, v26, v25
	v_fmac_f32_e32 v26, v27, v24
	v_fma_f32 v23, -v23, v26, v25
	v_div_fmas_f32 v23, v23, v24, v26
	v_div_fixup_f32 v22, v23, v22, 1.0
	v_cvt_pk_bf16_f32 v21, v22, v21
	v_div_scale_f32 v22, s[14:15], v9, v9, 1.0
	v_rcp_f32_e32 v23, v22
	v_pk_add_f32 v[0:1], v[0:1], 1.0 op_sel_hi:[1,0]
	v_fma_f32 v24, -v22, v23, 1.0
	v_fmac_f32_e32 v23, v24, v23
	v_div_scale_f32 v24, vcc, 1.0, v9, 1.0
	v_mul_f32_e32 v25, v24, v23
	v_fma_f32 v26, -v22, v25, v24
	v_fmac_f32_e32 v25, v26, v23
	v_fma_f32 v22, -v22, v25, v24
	v_div_fmas_f32 v22, v22, v23, v25
	v_div_fixup_f32 v9, v22, v9, 1.0
	v_div_scale_f32 v22, s[14:15], v8, v8, 1.0
	v_rcp_f32_e32 v23, v22
	s_nop 0
	v_fma_f32 v24, -v22, v23, 1.0
	v_fmac_f32_e32 v23, v24, v23
	v_div_scale_f32 v24, vcc, 1.0, v8, 1.0
	v_mul_f32_e32 v25, v24, v23
	v_fma_f32 v26, -v22, v25, v24
	v_fmac_f32_e32 v25, v26, v23
	v_fma_f32 v22, -v22, v25, v24
	v_div_fmas_f32 v22, v22, v23, v25
	v_div_fixup_f32 v8, v22, v8, 1.0
	v_cvt_pk_bf16_f32 v22, v8, v9
	v_cvt_f32_i32_e32 v8, v10
	v_cvt_f32_i32_e32 v9, v11
	v_mov_b32_e32 v26, v188
	v_mul_f32_e32 v8, v34, v8
	v_mul_f32_e32 v9, v34, v9
	v_mul_f32_e32 v8, v30, v8
	v_mul_f32_e32 v9, v31, v9
	v_mul_f32_e32 v8, 0xbfb8aa3b, v8
	v_mul_f32_e32 v9, 0xbfb8aa3b, v9
	v_exp_f32_e32 v8, v8
	v_exp_f32_e32 v9, v9
	s_nop 0
	v_pk_add_f32 v[8:9], v[8:9], 1.0 op_sel_hi:[1,0]
	s_nop 0
	v_div_scale_f32 v10, s[14:15], v9, v9, 1.0
	v_rcp_f32_e32 v11, v10
	s_nop 0
	v_fma_f32 v23, -v10, v11, 1.0
	v_fmac_f32_e32 v11, v23, v11
	v_div_scale_f32 v23, vcc, 1.0, v9, 1.0
	v_mul_f32_e32 v24, v23, v11
	v_fma_f32 v25, -v10, v24, v23
	v_fmac_f32_e32 v24, v25, v11
	v_fma_f32 v10, -v10, v24, v23
	v_div_fmas_f32 v10, v10, v11, v24
	v_div_fixup_f32 v9, v10, v9, 1.0
	v_div_scale_f32 v10, s[14:15], v8, v8, 1.0
	v_rcp_f32_e32 v11, v10
	s_nop 0
	v_fma_f32 v23, -v10, v11, 1.0
	v_fmac_f32_e32 v11, v23, v11
	v_div_scale_f32 v23, vcc, 1.0, v8, 1.0
	v_mul_f32_e32 v24, v23, v11
	v_fma_f32 v25, -v10, v24, v23
	v_fmac_f32_e32 v24, v25, v11
	v_fma_f32 v10, -v10, v24, v23
	v_div_fmas_f32 v10, v10, v11, v24
	v_div_fixup_f32 v8, v10, v8, 1.0
	v_cvt_pk_bf16_f32 v23, v8, v9
	v_div_scale_f32 v8, s[14:15], v5, v5, 1.0
	v_rcp_f32_e32 v9, v8
	s_nop 0
	v_fma_f32 v10, -v8, v9, 1.0
	v_fmac_f32_e32 v9, v10, v9
	v_div_scale_f32 v10, vcc, 1.0, v5, 1.0
	v_mul_f32_e32 v11, v10, v9
	v_fma_f32 v16, -v8, v11, v10
	v_fmac_f32_e32 v11, v16, v9
	v_fma_f32 v8, -v8, v11, v10
	v_div_fmas_f32 v8, v8, v9, v11
	v_div_fixup_f32 v5, v8, v5, 1.0
	v_div_scale_f32 v8, s[14:15], v4, v4, 1.0
	v_rcp_f32_e32 v9, v8
	s_nop 0
	v_fma_f32 v10, -v8, v9, 1.0
	v_fmac_f32_e32 v9, v10, v9
	v_div_scale_f32 v10, vcc, 1.0, v4, 1.0
	v_mul_f32_e32 v11, v10, v9
	v_fma_f32 v16, -v8, v11, v10
	v_fmac_f32_e32 v11, v16, v9
	v_fma_f32 v8, -v8, v11, v10
	v_div_fmas_f32 v8, v8, v9, v11
	v_div_fixup_f32 v4, v8, v4, 1.0
	v_cvt_pk_bf16_f32 v16, v4, v5
	v_cvt_f32_i32_e32 v4, v6
	v_cvt_f32_i32_e32 v5, v7
; DEV int tid_() { int t = threadIdx.x; asm volatile("" : "+v"(t)); return t; }
; DEV float sigm(float x) { return 1.f / (1.f + __expf(-x)); }
; template <class FragT, class AccT>
; DEV void gemm_core_t(const char* __restrict__ A, size_t lda_bytes, const char* __restrict__ Bt, size_t ldb_bytes, int kbytes,
;                      int m0, int n0, int Sshift, int dl, char* smem, AccT (&acc)[4][4]) {
;   const int tid = tid_(), lane = tid & 63, wid = tid >> 6, wm = wid >> 1, wn = wid & 1;
;   const int l15 = lane & 15, q = lane >> 4;
;   const int srow = lane >> 3, schunk = (lane & 7) ^ (lane >> 3);
;   const char* ap[4];
;   const char* bp[4];
; #pragma unroll
;   for (int u = 0; u < 4; ++u) {
;     int r = (wid * 4 + u) * 8 + srow;
;     int ar = rowmap(m0 + r, Sshift, dl);
;     ap[u] = A + (size_t)ar * lda_bytes + schunk * 16;
;     bp[u] = Bt + (size_t)(n0 + r) * ldb_bytes + schunk * 16;
;   }
; #pragma unroll
;   for (int i = 0; i < 4; ++i)
; #pragma unroll
;     for (int j = 0; j < 4; ++j) acc[i][j] = AccT{0, 0, 0, 0};
;   const int nk = kbytes >> 7;
;   __syncthreads();
; #pragma unroll
;   for (int u = 0; u < 4; ++u) {
;     __builtin_amdgcn_global_load_lds((const unsigned*)ap[u], (unsigned*)(smem + (wid * 4 + u) * 1024 + lane * 16), 16, 0, 0);
;     __builtin_amdgcn_global_load_lds((const unsigned*)bp[u], (unsigned*)(smem + 16384 + (wid * 4 + u) * 1024 + lane * 16), 16, 0, 0);
;   }
;   const unsigned sbase = (unsigned)(unsigned long)((__attribute__((address_space(3))) char*)smem);
;   const unsigned sq0 = (unsigned)((q ^ (l15 & 7)) << 4);
;   const unsigned a0 = sbase + (unsigned)((wm * 64 + l15) * 128) + sq0;
;   const unsigned b0 = sbase + 16384u + (unsigned)((wn * 32 + l15) * 128) + sq0;
;   asm volatile("s_waitcnt vmcnt(0)" ::: "memory");
;   __syncthreads();
; __device__ __forceinline__ void phase_gemm45(PREF P, char* smem, int which) {
;     ...
;             part[i][j][0] = pack2(sigm((float)iacc[i][j][0] * shr * swc.x), sigm((float)iacc[i][j][1] * shr * swc.y));
;             part[i][j][1] = pack2(sigm((float)iacc[i][j][2] * shr * swc.z), sigm((float)iacc[i][j][3] * shr * swc.w));
	v_mul_f32_e32 v4, v34, v4
	v_mul_f32_e32 v5, v34, v5
	v_mul_f32_e32 v4, v18, v4
	v_mul_f32_e32 v5, v19, v5
	v_mul_f32_e32 v4, 0xbfb8aa3b, v4
	v_mul_f32_e32 v5, 0xbfb8aa3b, v5
	v_exp_f32_e32 v4, v4
	v_exp_f32_e32 v5, v5
	s_nop 0
	v_pk_add_f32 v[4:5], v[4:5], 1.0 op_sel_hi:[1,0]
	s_nop 0
	v_div_scale_f32 v6, s[14:15], v5, v5, 1.0
	v_rcp_f32_e32 v7, v6
	s_nop 0
	v_fma_f32 v8, -v6, v7, 1.0
	v_fmac_f32_e32 v7, v8, v7
	v_div_scale_f32 v8, vcc, 1.0, v5, 1.0
	v_mul_f32_e32 v9, v8, v7
	v_fma_f32 v10, -v6, v9, v8
	v_fmac_f32_e32 v9, v10, v7
	v_fma_f32 v6, -v6, v9, v8
	v_div_fmas_f32 v6, v6, v7, v9
	v_div_fixup_f32 v5, v6, v5, 1.0
	v_div_scale_f32 v6, s[14:15], v4, v4, 1.0
	v_rcp_f32_e32 v7, v6
	s_nop 0
	v_fma_f32 v8, -v6, v7, 1.0
	v_fmac_f32_e32 v7, v8, v7
	v_div_scale_f32 v8, vcc, 1.0, v4, 1.0
	v_mul_f32_e32 v9, v8, v7
	v_fma_f32 v10, -v6, v9, v8
	v_fmac_f32_e32 v9, v10, v7
	v_fma_f32 v6, -v6, v9, v8
	v_div_fmas_f32 v6, v6, v7, v9
	v_div_fixup_f32 v4, v6, v4, 1.0
	v_cvt_pk_bf16_f32 v17, v4, v5
	v_div_scale_f32 v4, s[14:15], v1, v1, 1.0
	v_rcp_f32_e32 v5, v4
	s_nop 0
	v_fma_f32 v6, -v4, v5, 1.0
	v_fmac_f32_e32 v5, v6, v5
	v_div_scale_f32 v6, vcc, 1.0, v1, 1.0
	v_mul_f32_e32 v7, v6, v5
	v_fma_f32 v8, -v4, v7, v6
	v_fmac_f32_e32 v7, v8, v5
	v_fma_f32 v4, -v4, v7, v6
	v_div_fmas_f32 v4, v4, v5, v7
	v_div_fixup_f32 v1, v4, v1, 1.0
	v_div_scale_f32 v4, s[14:15], v0, v0, 1.0
	v_rcp_f32_e32 v5, v4
	s_nop 0
	v_fma_f32 v6, -v4, v5, 1.0
	v_fmac_f32_e32 v5, v6, v5
	v_div_scale_f32 v6, vcc, 1.0, v0, 1.0
	v_mul_f32_e32 v7, v6, v5
	v_fma_f32 v8, -v4, v7, v6
	v_fmac_f32_e32 v7, v8, v5
	v_fma_f32 v4, -v4, v7, v6
	v_div_fmas_f32 v4, v4, v5, v7
	v_div_fixup_f32 v0, v4, v0, 1.0
	v_cvt_pk_bf16_f32 v18, v0, v1
	v_cvt_f32_i32_e32 v0, v2
	v_cvt_f32_i32_e32 v1, v3
	v_mul_f32_e32 v0, v34, v0
	v_mul_f32_e32 v1, v34, v1
	v_mul_f32_e32 v0, v14, v0
	v_mul_f32_e32 v1, v15, v1
	v_mul_f32_e32 v0, 0xbfb8aa3b, v0
	v_mul_f32_e32 v1, 0xbfb8aa3b, v1
	v_exp_f32_e32 v0, v0
	v_exp_f32_e32 v1, v1
	s_nop 0
	v_pk_add_f32 v[0:1], v[0:1], 1.0 op_sel_hi:[1,0]
	s_nop 0
	v_div_scale_f32 v2, s[14:15], v1, v1, 1.0
	v_rcp_f32_e32 v3, v2
	s_nop 0
	v_fma_f32 v4, -v2, v3, 1.0
	v_fmac_f32_e32 v3, v4, v3
	v_div_scale_f32 v4, vcc, 1.0, v1, 1.0
	v_mul_f32_e32 v5, v4, v3
	v_fma_f32 v6, -v2, v5, v4
	v_fmac_f32_e32 v5, v6, v3
	v_fma_f32 v2, -v2, v5, v4
	v_div_fmas_f32 v2, v2, v3, v5
	v_div_fixup_f32 v1, v2, v1, 1.0
	v_div_scale_f32 v2, s[14:15], v0, v0, 1.0
	v_rcp_f32_e32 v3, v2
	s_nop 0
	v_fma_f32 v4, -v2, v3, 1.0
	v_fmac_f32_e32 v3, v4, v3
	v_div_scale_f32 v4, vcc, 1.0, v0, 1.0
	v_mul_f32_e32 v5, v4, v3
	v_fma_f32 v6, -v2, v5, v4
	v_fmac_f32_e32 v5, v6, v3
	v_fma_f32 v2, -v2, v5, v4
	v_div_fmas_f32 v2, v2, v3, v5
	v_div_fixup_f32 v0, v2, v0, 1.0
	v_cvt_pk_bf16_f32 v19, v0, v1
	ds_read2_b64 v[0:3], v80 offset0:24 offset1:28
	s_waitcnt lgkmcnt(0)
	v_ashrrev_i32_e32 v28, 6, v26
	v_bfe_u32 v4, v26, 3, 3
	v_lshlrev_b32_e32 v29, 5, v28
	v_bitop3_b32 v5, v4, v26, 7 bitop3:0x78
	v_or_b32_e32 v24, v29, v4
	v_lshlrev_b32_e32 v180, 4, v5
	v_or_b32_e32 v6, 8, v24
	v_or_b32_e32 v10, 16, v24
	v_or_b32_e32 v30, 24, v24
	v_lshl_add_u64 v[12:13], v[2:3], 0, v[180:181]
	v_lshl_add_u64 v[14:15], v[0:1], 0, v[180:181]
	v_add_u32_e32 v0, s17, v24
	v_add_u32_e32 v2, s4, v24
	v_add_u32_e32 v4, s17, v6
	v_add_u32_e32 v8, s17, v10
	v_add_u32_e32 v24, s17, v30
	v_ashrrev_i32_e32 v1, 31, v0
	v_ashrrev_i32_e32 v5, 31, v4
	v_ashrrev_i32_e32 v9, 31, v8
	v_ashrrev_i32_e32 v25, 31, v24
	v_lshlrev_b64 v[0:1], 9, v[0:1]
	v_lshlrev_b64 v[4:5], 9, v[4:5]
	v_lshlrev_b64 v[8:9], 9, v[8:9]
	v_lshlrev_b64 v[24:25], 9, v[24:25]
	v_lshl_add_u64 v[0:1], v[12:13], 0, v[0:1]
	v_lshl_add_u64 v[4:5], v[12:13], 0, v[4:5]
	v_add_u32_e32 v6, s4, v6
	v_lshl_add_u64 v[8:9], v[12:13], 0, v[8:9]
	v_add_u32_e32 v10, s4, v10
	v_lshl_add_u64 v[12:13], v[12:13], 0, v[24:25]
	v_add_u32_e32 v24, s4, v30
	v_ashrrev_i32_e32 v3, 31, v2
	v_ashrrev_i32_e32 v7, 31, v6
	v_ashrrev_i32_e32 v11, 31, v10
	v_ashrrev_i32_e32 v25, 31, v24
	v_lshlrev_b64 v[2:3], 9, v[2:3]
	v_lshlrev_b64 v[6:7], 9, v[6:7]
	v_lshlrev_b64 v[10:11], 9, v[10:11]
	v_lshlrev_b64 v[24:25], 9, v[24:25]
	v_and_b32_e32 v27, 63, v26
	v_lshl_add_u64 v[2:3], v[14:15], 0, v[2:3]
	v_lshl_add_u64 v[6:7], v[14:15], 0, v[6:7]
	v_lshl_add_u64 v[10:11], v[14:15], 0, v[10:11]
	v_lshl_add_u64 v[14:15], v[14:15], 0, v[24:25]
	v_lshlrev_b32_e32 v24, 12, v28
	v_lshl_or_b32 v28, v27, 4, v24
	v_add_u32_e32 v24, 0x4000, v28
	v_readfirstlane_b32 s43, v28
	v_readfirstlane_b32 s36, v24
	v_or_b32_e32 v24, 0x400, v28
	s_mov_b32 m0, s43
	v_readfirstlane_b32 s37, v24
	v_add_u32_e32 v24, 0x4400, v28
	s_barrier
	v_readfirstlane_b32 s38, v24
	v_or_b32_e32 v24, 0x800, v28
	global_load_lds_dwordx4 v[0:1], off
	s_mov_b32 m0, s36
	v_readfirstlane_b32 s39, v24
	v_add_u32_e32 v24, 0x4800, v28
	global_load_lds_dwordx4 v[2:3], off
	s_mov_b32 m0, s37
	v_readfirstlane_b32 s40, v24
	v_or_b32_e32 v24, 0xc00, v28
	global_load_lds_dwordx4 v[4:5], off
	s_mov_b32 m0, s38
	v_readfirstlane_b32 s41, v24
	v_add_u32_e32 v24, 0x4c00, v28
	global_load_lds_dwordx4 v[6:7], off
	s_mov_b32 m0, s39
	v_readfirstlane_b32 s42, v24
	v_lshlrev_b32_e32 v24, 4, v26
	v_and_b32_e32 v25, 15, v26
	global_load_lds_dwordx4 v[8:9], off
	s_mov_b32 m0, s40
	v_bitop3_b32 v27, v27, s31, v24 bitop3:0x48
	v_lshrrev_b32_e32 v24, 1, v26
	global_load_lds_dwordx4 v[10:11], off
	s_mov_b32 m0, s41
	v_and_or_b32 v24, v24, s44, v25
	v_and_or_b32 v25, v29, 32, v25
	v_add_u32_e32 v29, 0x8000, v28
	global_load_lds_dwordx4 v[12:13], off
	s_mov_b32 m0, s42
	v_lshlrev_b32_e32 v26, 7, v24
	v_readfirstlane_b32 s31, v29
	v_add_u32_e32 v29, 0xc000, v28
	global_load_lds_dwordx4 v[14:15], off
	v_or_b32_e32 v24, v27, v26
	v_lshl_or_b32 v34, v25, 7, v27
	v_bitop3_b32 v35, v27, 64, v26 bitop3:0x36
	v_lshl_add_u64 v[26:27], v[0:1], 0, s[46:47]
	s_mov_b32 m0, s31
	v_readfirstlane_b32 s5, v29
	v_add_u32_e32 v29, 0x8400, v28
	s_waitcnt vmcnt(0)
	s_waitcnt vmcnt(0) lgkmcnt(0)
	s_barrier
; DEV f32x4 mma_step(bf16x8 a, bf16x8 b, f32x4 c) { return MFMA(a, b, c); }
; template <class FragT, class AccT>
; DEV void gemm_core_t(const char* __restrict__ A, size_t lda_bytes, const char* __restrict__ Bt, size_t ldb_bytes, int kbytes,
;                      int m0, int n0, int Sshift, int dl, char* smem, AccT (&acc)[4][4]) {
;     ...
;   for (int kt = 0; kt < nk; ++kt) {
;     const unsigned so = (unsigned)(kt & 1) * 32768u;
;     char* nxt = smem + ((kt + 1) & 1) * 32768;
;     if (kt + 1 < nk) {
; #pragma unroll
;       for (int u = 0; u < 4; ++u) {
;         __builtin_amdgcn_global_load_lds((const unsigned*)(ap[u] + (size_t)(kt + 1) * 128), (unsigned*)(nxt + (wid * 4 + u) * 1024 + lane * 16), 16, 0, 0);
;         __builtin_amdgcn_global_load_lds((const unsigned*)(bp[u] + (size_t)(kt + 1) * 128), (unsigned*)(nxt + 16384 + (wid * 4 + u) * 1024 + lane * 16), 16, 0, 0);
;       }
;     }
;     FragT xa[2][4], wb[2][4];
;     asm volatile(
;         "ds_read_b128 %0, %16\n\t"
;         "ds_read_b128 %1, %16 offset:2048\n\t"
;         "ds_read_b128 %2, %16 offset:4096\n\t"
;         "ds_read_b128 %3, %16 offset:6144\n\t"
;         "ds_read_b128 %4, %18\n\t"
;         "ds_read_b128 %5, %18 offset:2048\n\t"
;         "ds_read_b128 %6, %18 offset:8192\n\t"
;         "ds_read_b128 %7, %18 offset:10240\n\t"
;         "ds_read_b128 %8, %17\n\t"
;         "ds_read_b128 %9, %17 offset:2048\n\t"
;         "ds_read_b128 %10, %17 offset:4096\n\t"
;         "ds_read_b128 %11, %17 offset:6144\n\t"
;         "ds_read_b128 %12, %19\n\t"
;         "ds_read_b128 %13, %19 offset:2048\n\t"
;         "ds_read_b128 %14, %19 offset:8192\n\t"
;         "ds_read_b128 %15, %19 offset:10240\n\t"
;         "s_waitcnt lgkmcnt(8)"
;         : "=&v"(xa[0][0]), "=&v"(xa[0][1]), "=&v"(xa[0][2]), "=&v"(xa[0][3]), "=&v"(wb[0][0]), "=&v"(wb[0][1]), "=&v"(wb[0][2]),
;           "=&v"(wb[0][3]), "=&v"(xa[1][0]), "=&v"(xa[1][1]), "=&v"(xa[1][2]), "=&v"(xa[1][3]), "=&v"(wb[1][0]), "=&v"(wb[1][1]),
;           "=&v"(wb[1][2]), "=&v"(wb[1][3])
;         : "v"(a0 + so), "v"((a0 ^ 64u) + so), "v"(b0 + so), "v"((b0 ^ 64u) + so)
;         : "memory");
;     __builtin_amdgcn_s_setprio(1);
; #pragma unroll
;     for (int i = 0; i < 4; ++i)
; #pragma unroll
;       for (int j = 0; j < 4; ++j) acc[i][j] = mma_step(wb[0][j], xa[0][i], acc[i][j]);
;     asm volatile("s_waitcnt lgkmcnt(0)"
	global_load_lds_dwordx4 v[26:27], off
	v_lshl_add_u64 v[26:27], v[2:3], 0, s[46:47]
	s_mov_b32 m0, s5
	v_readfirstlane_b32 s6, v29
	v_add_u32_e32 v29, 0xc400, v28
	global_load_lds_dwordx4 v[26:27], off
	v_lshl_add_u64 v[26:27], v[4:5], 0, s[46:47]
	s_mov_b32 m0, s6
	v_readfirstlane_b32 s14, v29
	v_add_u32_e32 v29, 0x8800, v28
	global_load_lds_dwordx4 v[26:27], off
	v_lshl_add_u64 v[26:27], v[6:7], 0, s[46:47]
	s_mov_b32 m0, s14
	v_readfirstlane_b32 s15, v29
	v_add_u32_e32 v29, 0xc800, v28
	global_load_lds_dwordx4 v[26:27], off
	v_lshl_add_u64 v[26:27], v[8:9], 0, s[46:47]
	s_mov_b32 m0, s15
	v_readfirstlane_b32 s18, v29
	v_add_u32_e32 v29, 0x8c00, v28
	global_load_lds_dwordx4 v[26:27], off
	v_lshl_add_u64 v[26:27], v[10:11], 0, s[46:47]
	s_mov_b32 m0, s18
	v_readfirstlane_b32 s19, v29
	v_add_u32_e32 v28, 0xcc00, v28
	global_load_lds_dwordx4 v[26:27], off
	v_lshl_add_u64 v[26:27], v[12:13], 0, s[46:47]
	s_mov_b32 m0, s19
	v_readfirstlane_b32 s24, v28
	global_load_lds_dwordx4 v[26:27], off
	v_lshl_add_u64 v[26:27], v[14:15], 0, s[46:47]
	s_mov_b32 m0, s24
	v_or_b32_e32 v25, 0x4000, v34
	global_load_lds_dwordx4 v[26:27], off
	v_bitop3_b32 v38, v34, 64, v219 bitop3:0x36
	ds_read_b128 v[26:29], v24
	ds_read_b128 v[66:69], v24 offset:2048
	ds_read_b128 v[84:87], v24 offset:4096
	ds_read_b128 v[88:91], v24 offset:6144
	ds_read_b128 v[92:95], v25
	ds_read_b128 v[96:99], v25 offset:2048
	ds_read_b128 v[100:103], v25 offset:8192
	ds_read_b128 v[104:107], v25 offset:10240
	ds_read_b128 v[108:111], v35
	ds_read_b128 v[112:115], v35 offset:2048
	ds_read_b128 v[116:119], v35 offset:4096
	ds_read_b128 v[120:123], v35 offset:6144
	ds_read_b128 v[124:127], v38
	ds_read_b128 v[128:131], v38 offset:2048
	ds_read_b128 v[132:135], v38 offset:8192
	ds_read_b128 v[136:139], v38 offset:10240
	s_waitcnt lgkmcnt(8)
	s_setprio 1
	v_mfma_f32_16x16x32_bf16 v[140:143], v[92:95], v[26:29], 0
	v_mfma_f32_16x16x32_bf16 v[144:147], v[96:99], v[26:29], 0
	v_mfma_f32_16x16x32_bf16 v[148:151], v[100:103], v[26:29], 0
	v_mfma_f32_16x16x32_bf16 v[26:29], v[104:107], v[26:29], 0
	v_mfma_f32_16x16x32_bf16 v[152:155], v[92:95], v[66:69], 0
	v_mfma_f32_16x16x32_bf16 v[156:159], v[96:99], v[66:69], 0
	v_mfma_f32_16x16x32_bf16 v[160:163], v[100:103], v[66:69], 0
	v_mfma_f32_16x16x32_bf16 v[66:69], v[104:107], v[66:69], 0
	v_mfma_f32_16x16x32_bf16 v[164:167], v[92:95], v[84:87], 0
	v_mfma_f32_16x16x32_bf16 v[168:171], v[96:99], v[84:87], 0
	v_mfma_f32_16x16x32_bf16 v[172:175], v[100:103], v[84:87], 0
	v_mfma_f32_16x16x32_bf16 v[84:87], v[104:107], v[84:87], 0
	v_mfma_f32_16x16x32_bf16 v[92:95], v[92:95], v[88:91], 0
	v_mfma_f32_16x16x32_bf16 v[96:99], v[96:99], v[88:91], 0
	v_mfma_f32_16x16x32_bf16 v[100:103], v[100:103], v[88:91], 0
	v_mfma_f32_16x16x32_bf16 v[88:91], v[104:107], v[88:91], 0
	s_waitcnt lgkmcnt(0)
	s_nop 0
	v_mfma_f32_16x16x32_bf16 v[104:107], v[124:127], v[108:111], v[140:143]
	v_mfma_f32_16x16x32_bf16 v[140:143], v[128:131], v[108:111], v[144:147]
	v_mfma_f32_16x16x32_bf16 v[144:147], v[132:135], v[108:111], v[148:151]
	v_mfma_f32_16x16x32_bf16 v[26:29], v[136:139], v[108:111], v[26:29]
	v_mfma_f32_16x16x32_bf16 v[108:111], v[124:127], v[112:115], v[152:155]
	v_mfma_f32_16x16x32_bf16 v[148:151], v[128:131], v[112:115], v[156:159]
	v_mfma_f32_16x16x32_bf16 v[152:155], v[132:135], v[112:115], v[160:163]
	v_mfma_f32_16x16x32_bf16 v[66:69], v[136:139], v[112:115], v[66:69]
	v_mfma_f32_16x16x32_bf16 v[112:115], v[124:127], v[116:119], v[164:167]
	v_mfma_f32_16x16x32_bf16 v[156:159], v[128:131], v[116:119], v[168:171]
	v_mfma_f32_16x16x32_bf16 v[160:163], v[132:135], v[116:119], v[172:175]
	v_mfma_f32_16x16x32_bf16 v[84:87], v[136:139], v[116:119], v[84:87]
	v_mfma_f32_16x16x32_bf16 v[92:95], v[124:127], v[120:123], v[92:95]
	v_mfma_f32_16x16x32_bf16 v[96:99], v[128:131], v[120:123], v[96:99]
	v_mfma_f32_16x16x32_bf16 v[100:103], v[132:135], v[120:123], v[100:103]
	v_mfma_f32_16x16x32_bf16 v[88:91], v[136:139], v[120:123], v[88:91]
	s_setprio 0
	s_mov_b64 s[48:49], 0x100
	s_mov_b32 m0, s43
	v_lshl_add_u64 v[30:31], v[0:1], 0, s[48:49]
	s_waitcnt vmcnt(0)
	s_waitcnt vmcnt(0) lgkmcnt(0)
	s_barrier
	global_load_lds_dwordx4 v[30:31], off
	v_lshl_add_u64 v[30:31], v[2:3], 0, s[48:49]
	s_mov_b32 m0, s36
	v_add_u32_e32 v39, 0x8000, v24
	global_load_lds_dwordx4 v[30:31], off
	v_lshl_add_u64 v[30:31], v[4:5], 0, s[48:49]
	s_mov_b32 m0, s37
	v_readlane_b32 s36, v251, 55
	global_load_lds_dwordx4 v[30:31], off
	v_lshl_add_u64 v[30:31], v[6:7], 0, s[48:49]
	s_mov_b32 m0, s38
	v_add_u32_e32 v42, 0x8000, v35
	global_load_lds_dwordx4 v[30:31], off
	v_lshl_add_u64 v[30:31], v[8:9], 0, s[48:49]
	s_mov_b32 m0, s39
	v_or_b32_e32 v34, 0xc000, v34
	global_load_lds_dwordx4 v[30:31], off
	v_lshl_add_u64 v[30:31], v[10:11], 0, s[48:49]
	s_mov_b32 m0, s40
	v_bitop3_b32 v43, v25, s36, 64 bitop3:0xde
	global_load_lds_dwordx4 v[30:31], off
	v_lshl_add_u64 v[30:31], v[12:13], 0, s[48:49]
	s_mov_b32 m0, s41
	v_readlane_b32 s37, v251, 56
	global_load_lds_dwordx4 v[30:31], off
	v_lshl_add_u64 v[30:31], v[14:15], 0, s[48:49]
	s_mov_b32 m0, s42
	s_nop 0
	global_load_lds_dwordx4 v[30:31], off
	ds_read_b128 v[116:119], v39
	ds_read_b128 v[120:123], v39 offset:2048
	ds_read_b128 v[124:127], v39 offset:4096
	ds_read_b128 v[128:131], v39 offset:6144
	ds_read_b128 v[132:135], v34
	ds_read_b128 v[136:139], v34 offset:2048
	ds_read_b128 v[164:167], v34 offset:8192
	ds_read_b128 v[168:171], v34 offset:10240
	ds_read_b128 v[172:175], v42
	ds_read_b128 v[184:187], v42 offset:2048
	ds_read_b128 v[222:225], v42 offset:4096
	ds_read_b128 v[226:229], v42 offset:6144
	ds_read_b128 v[230:233], v43
	ds_read_b128 v[234:237], v43 offset:2048
	ds_read_b128 v[238:241], v43 offset:8192
	ds_read_b128 v[242:245], v43 offset:10240
	s_waitcnt lgkmcnt(8)
; DEV f32x4 mma_step(bf16x8 a, bf16x8 b, f32x4 c) { return MFMA(a, b, c); }
; template <class FragT, class AccT>
; DEV void gemm_core_t(const char* __restrict__ A, size_t lda_bytes, const char* __restrict__ Bt, size_t ldb_bytes, int kbytes,
;                      int m0, int n0, int Sshift, int dl, char* smem, AccT (&acc)[4][4]) {
;     ...
;   for (int kt = 0; kt < nk; ++kt) {
;     const unsigned so = (unsigned)(kt & 1) * 32768u;
;     char* nxt = smem + ((kt + 1) & 1) * 32768;
;     if (kt + 1 < nk) {
; #pragma unroll
;       for (int u = 0; u < 4; ++u) {
;         __builtin_amdgcn_global_load_lds((const unsigned*)(ap[u] + (size_t)(kt + 1) * 128), (unsigned*)(nxt + (wid * 4 + u) * 1024 + lane * 16), 16, 0, 0);
;         __builtin_amdgcn_global_load_lds((const unsigned*)(bp[u] + (size_t)(kt + 1) * 128), (unsigned*)(nxt + 16384 + (wid * 4 + u) * 1024 + lane * 16), 16, 0, 0);
;       }
;     }
;     FragT xa[2][4], wb[2][4];
;     asm volatile(
;         "ds_read_b128 %0, %16\n\t"
;         "ds_read_b128 %1, %16 offset:2048\n\t"
;         "ds_read_b128 %2, %16 offset:4096\n\t"
;         "ds_read_b128 %3, %16 offset:6144\n\t"
;         "ds_read_b128 %4, %18\n\t"
;         "ds_read_b128 %5, %18 offset:2048\n\t"
;         "ds_read_b128 %6, %18 offset:8192\n\t"
;         "ds_read_b128 %7, %18 offset:10240\n\t"
;         "ds_read_b128 %8, %17\n\t"
;         "ds_read_b128 %9, %17 offset:2048\n\t"
;         "ds_read_b128 %10, %17 offset:4096\n\t"
;         "ds_read_b128 %11, %17 offset:6144\n\t"
;         "ds_read_b128 %12, %19\n\t"
;         "ds_read_b128 %13, %19 offset:2048\n\t"
;         "ds_read_b128 %14, %19 offset:8192\n\t"
;         "ds_read_b128 %15, %19 offset:10240\n\t"
;         "s_waitcnt lgkmcnt(8)"
;         : "=&v"(xa[0][0]), "=&v"(xa[0][1]), "=&v"(xa[0][2]), "=&v"(xa[0][3]), "=&v"(wb[0][0]), "=&v"(wb[0][1]), "=&v"(wb[0][2]),
;           "=&v"(wb[0][3]), "=&v"(xa[1][0]), "=&v"(xa[1][1]), "=&v"(xa[1][2]), "=&v"(xa[1][3]), "=&v"(wb[1][0]), "=&v"(wb[1][1]),
;           "=&v"(wb[1][2]), "=&v"(wb[1][3])
;         : "v"(a0 + so), "v"((a0 ^ 64u) + so), "v"(b0 + so), "v"((b0 ^ 64u) + so)
;         : "memory");
;     __builtin_amdgcn_s_setprio(1);
; #pragma unroll
;     for (int i = 0; i < 4; ++i)
; #pragma unroll
;       for (int j = 0; j < 4; ++j) acc[i][j] = mma_step(wb[0][j], xa[0][i], acc[i][j]);
;     asm volatile("s_waitcnt lgkmcnt(0)"
	s_setprio 1
	v_mfma_f32_16x16x32_bf16 v[104:107], v[132:135], v[116:119], v[104:107]
	v_mfma_f32_16x16x32_bf16 v[140:143], v[136:139], v[116:119], v[140:143]
	v_mfma_f32_16x16x32_bf16 v[144:147], v[164:167], v[116:119], v[144:147]
	v_mfma_f32_16x16x32_bf16 v[26:29], v[168:171], v[116:119], v[26:29]
	v_mfma_f32_16x16x32_bf16 v[108:111], v[132:135], v[120:123], v[108:111]
	v_mfma_f32_16x16x32_bf16 v[116:119], v[136:139], v[120:123], v[148:151]
	v_mfma_f32_16x16x32_bf16 v[148:151], v[164:167], v[120:123], v[152:155]
	v_mfma_f32_16x16x32_bf16 v[66:69], v[168:171], v[120:123], v[66:69]
	v_mfma_f32_16x16x32_bf16 v[112:115], v[132:135], v[124:127], v[112:115]
	v_mfma_f32_16x16x32_bf16 v[120:123], v[136:139], v[124:127], v[156:159]
	v_mfma_f32_16x16x32_bf16 v[152:155], v[164:167], v[124:127], v[160:163]
	v_mfma_f32_16x16x32_bf16 v[84:87], v[168:171], v[124:127], v[84:87]
	v_mfma_f32_16x16x32_bf16 v[92:95], v[132:135], v[128:131], v[92:95]
	v_mfma_f32_16x16x32_bf16 v[96:99], v[136:139], v[128:131], v[96:99]
	v_mfma_f32_16x16x32_bf16 v[100:103], v[164:167], v[128:131], v[100:103]
	v_mfma_f32_16x16x32_bf16 v[88:91], v[168:171], v[128:131], v[88:91]
	s_waitcnt lgkmcnt(0)
	s_nop 0
	v_mfma_f32_16x16x32_bf16 v[104:107], v[230:233], v[172:175], v[104:107]
	v_mfma_f32_16x16x32_bf16 v[124:127], v[234:237], v[172:175], v[140:143]
	v_mfma_f32_16x16x32_bf16 v[128:131], v[238:241], v[172:175], v[144:147]
	v_mfma_f32_16x16x32_bf16 v[26:29], v[242:245], v[172:175], v[26:29]
	v_mfma_f32_16x16x32_bf16 v[108:111], v[230:233], v[184:187], v[108:111]
	v_mfma_f32_16x16x32_bf16 v[116:119], v[234:237], v[184:187], v[116:119]
	v_mfma_f32_16x16x32_bf16 v[132:135], v[238:241], v[184:187], v[148:151]
	v_mfma_f32_16x16x32_bf16 v[66:69], v[242:245], v[184:187], v[66:69]
	v_mfma_f32_16x16x32_bf16 v[112:115], v[230:233], v[222:225], v[112:115]
	v_mfma_f32_16x16x32_bf16 v[120:123], v[234:237], v[222:225], v[120:123]
	v_mfma_f32_16x16x32_bf16 v[136:139], v[238:241], v[222:225], v[152:155]
	v_mfma_f32_16x16x32_bf16 v[84:87], v[242:245], v[222:225], v[84:87]
	v_mfma_f32_16x16x32_bf16 v[92:95], v[230:233], v[226:229], v[92:95]
	v_mfma_f32_16x16x32_bf16 v[96:99], v[234:237], v[226:229], v[96:99]
	v_mfma_f32_16x16x32_bf16 v[100:103], v[238:241], v[226:229], v[100:103]
	v_mfma_f32_16x16x32_bf16 v[88:91], v[242:245], v[226:229], v[88:91]
	s_setprio 0
	s_mov_b64 s[36:37], 0x180
	s_mov_b32 m0, s31
	v_lshl_add_u64 v[0:1], v[0:1], 0, s[36:37]
	s_waitcnt vmcnt(0)
	s_waitcnt vmcnt(0) lgkmcnt(0)
	s_barrier
	global_load_lds_dwordx4 v[0:1], off
	v_lshl_add_u64 v[0:1], v[2:3], 0, s[36:37]
	s_mov_b32 m0, s5
	s_movk_i32 s31, 0x70
	global_load_lds_dwordx4 v[0:1], off
	v_lshl_add_u64 v[0:1], v[4:5], 0, s[36:37]
	s_mov_b32 m0, s6
	s_nop 0
	global_load_lds_dwordx4 v[0:1], off
	v_lshl_add_u64 v[0:1], v[6:7], 0, s[36:37]
	s_mov_b32 m0, s14
	s_nop 0
	global_load_lds_dwordx4 v[0:1], off
	v_lshl_add_u64 v[0:1], v[8:9], 0, s[36:37]
	s_mov_b32 m0, s15
	s_nop 0
	global_load_lds_dwordx4 v[0:1], off
	v_lshl_add_u64 v[0:1], v[10:11], 0, s[36:37]
	s_mov_b32 m0, s18
	s_nop 0
	global_load_lds_dwordx4 v[0:1], off
	v_lshl_add_u64 v[0:1], v[12:13], 0, s[36:37]
	s_mov_b32 m0, s19
	s_nop 0
	global_load_lds_dwordx4 v[0:1], off
	v_lshl_add_u64 v[0:1], v[14:15], 0, s[36:37]
	s_mov_b32 m0, s24
	s_nop 0
	global_load_lds_dwordx4 v[0:1], off
	ds_read_b128 v[0:3], v24
	ds_read_b128 v[4:7], v24 offset:2048
	ds_read_b128 v[8:11], v24 offset:4096
	ds_read_b128 v[12:15], v24 offset:6144
	ds_read_b128 v[140:143], v25
	ds_read_b128 v[144:147], v25 offset:2048
	ds_read_b128 v[148:151], v25 offset:8192
	ds_read_b128 v[152:155], v25 offset:10240
	ds_read_b128 v[156:159], v35
	ds_read_b128 v[160:163], v35 offset:2048
	ds_read_b128 v[164:167], v35 offset:4096
	ds_read_b128 v[168:171], v35 offset:6144
	ds_read_b128 v[172:175], v38
	ds_read_b128 v[184:187], v38 offset:2048
	ds_read_b128 v[222:225], v38 offset:8192
	ds_read_b128 v[226:229], v38 offset:10240
	s_waitcnt lgkmcnt(8)
	s_setprio 1
	v_mfma_f32_16x16x32_bf16 v[104:107], v[140:143], v[0:3], v[104:107]
	v_mfma_f32_16x16x32_bf16 v[124:127], v[144:147], v[0:3], v[124:127]
	v_mfma_f32_16x16x32_bf16 v[128:131], v[148:151], v[0:3], v[128:131]
	v_mfma_f32_16x16x32_bf16 v[0:3], v[152:155], v[0:3], v[26:29]
	v_mfma_f32_16x16x32_bf16 v[24:27], v[140:143], v[4:7], v[108:111]
	v_mfma_f32_16x16x32_bf16 v[28:31], v[144:147], v[4:7], v[116:119]
	v_mfma_f32_16x16x32_bf16 v[108:111], v[148:151], v[4:7], v[132:135]
	v_mfma_f32_16x16x32_bf16 v[4:7], v[152:155], v[4:7], v[66:69]
	v_mfma_f32_16x16x32_bf16 v[66:69], v[140:143], v[8:11], v[112:115]
	v_mfma_f32_16x16x32_bf16 v[112:115], v[144:147], v[8:11], v[120:123]
	v_mfma_f32_16x16x32_bf16 v[116:119], v[148:151], v[8:11], v[136:139]
	v_mfma_f32_16x16x32_bf16 v[8:11], v[152:155], v[8:11], v[84:87]
	v_mfma_f32_16x16x32_bf16 v[84:87], v[140:143], v[12:15], v[92:95]
	v_mfma_f32_16x16x32_bf16 v[92:95], v[144:147], v[12:15], v[96:99]
	v_mfma_f32_16x16x32_bf16 v[96:99], v[148:151], v[12:15], v[100:103]
	v_mfma_f32_16x16x32_bf16 v[12:15], v[152:155], v[12:15], v[88:91]
	s_waitcnt lgkmcnt(0)
	s_nop 0
	v_mfma_f32_16x16x32_bf16 v[88:91], v[172:175], v[156:159], v[104:107]
	v_mfma_f32_16x16x32_bf16 v[100:103], v[184:187], v[156:159], v[124:127]
	v_mfma_f32_16x16x32_bf16 v[104:107], v[222:225], v[156:159], v[128:131]
	v_mfma_f32_16x16x32_bf16 v[0:3], v[226:229], v[156:159], v[0:3]
	v_mfma_f32_16x16x32_bf16 v[24:27], v[172:175], v[160:163], v[24:27]
	v_mfma_f32_16x16x32_bf16 v[28:31], v[184:187], v[160:163], v[28:31]
	v_mfma_f32_16x16x32_bf16 v[108:111], v[222:225], v[160:163], v[108:111]
	v_mfma_f32_16x16x32_bf16 v[4:7], v[226:229], v[160:163], v[4:7]
	v_mfma_f32_16x16x32_bf16 v[66:69], v[172:175], v[164:167], v[66:69]
	v_mfma_f32_16x16x32_bf16 v[112:115], v[184:187], v[164:167], v[112:115]
	v_mfma_f32_16x16x32_bf16 v[116:119], v[222:225], v[164:167], v[116:119]
	v_mfma_f32_16x16x32_bf16 v[8:11], v[226:229], v[164:167], v[8:11]
	v_mfma_f32_16x16x32_bf16 v[84:87], v[172:175], v[168:171], v[84:87]
	v_mfma_f32_16x16x32_bf16 v[92:95], v[184:187], v[168:171], v[92:95]
	v_mfma_f32_16x16x32_bf16 v[96:99], v[222:225], v[168:171], v[96:99]
	v_mfma_f32_16x16x32_bf16 v[12:15], v[226:229], v[168:171], v[12:15]
	s_setprio 0
	s_waitcnt vmcnt(0)
	s_waitcnt vmcnt(0) lgkmcnt(0)
	s_barrier
; DEV float bflo(unsigned u) { return __uint_as_float(u << 16); }
; DEV float bfhi(unsigned u) { return __uint_as_float(u & 0xffff0000u); }
; DEV f32x4 mma_step(bf16x8 a, bf16x8 b, f32x4 c) { return MFMA(a, b, c); }
; DEV i32x4 mma_step(i32x4 a, i32x4 b, i32x4 c) { return __builtin_amdgcn_mfma_i32_16x16x64_i8(a, b, c, 0, 0, 0); }
; template <class FragT, class AccT>
; DEV void gemm_core_t(const char* __restrict__ A, size_t lda_bytes, const char* __restrict__ Bt, size_t ldb_bytes, int kbytes,
;                      int m0, int n0, int Sshift, int dl, char* smem, AccT (&acc)[4][4]) {
;     ...
;     for (int i = 0; i < 4; ++i)
; #pragma unroll
;       for (int j = 0; j < 4; ++j) acc[i][j] = mma_step(wb[0][j], xa[0][i], acc[i][j]);
;     asm volatile("s_waitcnt lgkmcnt(0)"
;                  : "+v"(xa[1][0]), "+v"(xa[1][1]), "+v"(xa[1][2]), "+v"(xa[1][3]), "+v"(wb[1][0]), "+v"(wb[1][1]), "+v"(wb[1][2]),
;                    "+v"(wb[1][3]), "+v"(acc[0][0]), "+v"(acc[0][1]), "+v"(acc[0][2]), "+v"(acc[0][3]), "+v"(acc[1][0]),
;                    "+v"(acc[1][1]), "+v"(acc[1][2]), "+v"(acc[1][3]), "+v"(acc[2][0]), "+v"(acc[2][1]), "+v"(acc[2][2]),
;                    "+v"(acc[2][3]), "+v"(acc[3][0]), "+v"(acc[3][1]), "+v"(acc[3][2]), "+v"(acc[3][3])
;                  :
;                  : "memory");
; #pragma unroll
;     for (int i = 0; i < 4; ++i)
; #pragma unroll
;       for (int j = 0; j < 4; ++j) acc[i][j] = mma_step(wb[1][j], xa[1][i], acc[i][j]);
;     __builtin_amdgcn_s_setprio(0);
; __device__ __forceinline__ void phase_gemm45(PREF P, char* smem, int which) {
;     ...
; #pragma unroll
;       for (int i = 0; i < 4; ++i)
; #pragma unroll
;         for (int j = 0; j < 4; ++j) {
;           const int row = m0 + wm * 64 + i * 16 + l15, col = n0 + (j & 1) * 16 + wn * 32 + (j >> 1) * 64 + q * 4;
;           f32x4 v;
;           v[0] = bflo(part[i][j][0]) * acc[i][j][0]; v[1] = bfhi(part[i][j][0]) * acc[i][j][1];
;           v[2] = bflo(part[i][j][1]) * acc[i][j][2]; v[3] = bfhi(part[i][j][1]) * acc[i][j][3];
;           acc[i][j] = v;
;         }
	ds_read_b128 v[120:123], v39
	ds_read_b128 v[124:127], v39 offset:2048
	ds_read_b128 v[128:131], v39 offset:4096
	ds_read_b128 v[132:135], v39 offset:6144
	ds_read_b128 v[136:139], v34
	ds_read_b128 v[140:143], v34 offset:2048
	ds_read_b128 v[144:147], v34 offset:8192
	ds_read_b128 v[148:151], v34 offset:10240
	ds_read_b128 v[152:155], v42
	ds_read_b128 v[156:159], v42 offset:2048
	ds_read_b128 v[160:163], v42 offset:4096
	ds_read_b128 v[164:167], v42 offset:6144
	ds_read_b128 v[168:171], v43
	ds_read_b128 v[172:175], v43 offset:2048
	ds_read_b128 v[184:187], v43 offset:8192
	ds_read_b128 v[222:225], v43 offset:10240
	s_waitcnt lgkmcnt(8)
	s_setprio 1
	v_mfma_f32_16x16x32_bf16 v[88:91], v[136:139], v[120:123], v[88:91]
	v_mfma_f32_16x16x32_bf16 v[100:103], v[140:143], v[120:123], v[100:103]
	v_mfma_f32_16x16x32_bf16 v[104:107], v[144:147], v[120:123], v[104:107]
	v_mfma_f32_16x16x32_bf16 v[0:3], v[148:151], v[120:123], v[0:3]
	v_mfma_f32_16x16x32_bf16 v[24:27], v[136:139], v[124:127], v[24:27]
	v_mfma_f32_16x16x32_bf16 v[28:31], v[140:143], v[124:127], v[28:31]
	v_mfma_f32_16x16x32_bf16 v[108:111], v[144:147], v[124:127], v[108:111]
	v_mfma_f32_16x16x32_bf16 v[4:7], v[148:151], v[124:127], v[4:7]
	v_mfma_f32_16x16x32_bf16 v[66:69], v[136:139], v[128:131], v[66:69]
	v_mfma_f32_16x16x32_bf16 v[112:115], v[140:143], v[128:131], v[112:115]
	v_mfma_f32_16x16x32_bf16 v[116:119], v[144:147], v[128:131], v[116:119]
	v_mfma_f32_16x16x32_bf16 v[8:11], v[148:151], v[128:131], v[8:11]
	v_mfma_f32_16x16x32_bf16 v[84:87], v[136:139], v[132:135], v[84:87]
	v_mfma_f32_16x16x32_bf16 v[92:95], v[140:143], v[132:135], v[92:95]
	v_mfma_f32_16x16x32_bf16 v[96:99], v[144:147], v[132:135], v[96:99]
	v_mfma_f32_16x16x32_bf16 v[12:15], v[148:151], v[132:135], v[12:15]
	s_waitcnt lgkmcnt(0)
	s_nop 0
	v_mfma_f32_16x16x32_bf16 v[88:91], v[168:171], v[152:155], v[88:91]
	v_mfma_f32_16x16x32_bf16 v[100:103], v[172:175], v[152:155], v[100:103]
	v_mfma_f32_16x16x32_bf16 v[104:107], v[184:187], v[152:155], v[104:107]
	v_mfma_f32_16x16x32_bf16 v[0:3], v[222:225], v[152:155], v[0:3]
	v_mfma_f32_16x16x32_bf16 v[24:27], v[168:171], v[156:159], v[24:27]
	v_mfma_f32_16x16x32_bf16 v[28:31], v[172:175], v[156:159], v[28:31]
	v_mfma_f32_16x16x32_bf16 v[108:111], v[184:187], v[156:159], v[108:111]
	v_mfma_f32_16x16x32_bf16 v[4:7], v[222:225], v[156:159], v[4:7]
	v_mfma_f32_16x16x32_bf16 v[66:69], v[168:171], v[160:163], v[66:69]
	v_mfma_f32_16x16x32_bf16 v[112:115], v[172:175], v[160:163], v[112:115]
	v_mfma_f32_16x16x32_bf16 v[116:119], v[184:187], v[160:163], v[116:119]
	v_mfma_f32_16x16x32_bf16 v[8:11], v[222:225], v[160:163], v[8:11]
	v_mfma_f32_16x16x32_bf16 v[84:87], v[168:171], v[164:167], v[84:87]
	v_mfma_f32_16x16x32_bf16 v[92:95], v[172:175], v[164:167], v[92:95]
	v_mfma_f32_16x16x32_bf16 v[96:99], v[184:187], v[164:167], v[96:99]
	v_mfma_f32_16x16x32_bf16 v[12:15], v[222:225], v[164:167], v[12:15]
	s_setprio 0
	s_waitcnt vmcnt(0)
	v_lshlrev_b32_e32 v58, 16, v64
	v_and_b32_e32 v59, 0xffff0000, v64
	v_mul_f32_e32 v0, v0, v58
	v_mul_f32_e32 v1, v1, v59
	v_lshlrev_b32_e32 v58, 16, v65
	v_and_b32_e32 v59, 0xffff0000, v65
	v_mul_f32_e32 v2, v2, v58
	v_mul_f32_e32 v3, v3, v59
	v_lshlrev_b32_e32 v58, 16, v60
	v_and_b32_e32 v59, 0xffff0000, v60
	v_mul_f32_e32 v24, v24, v58
	v_mul_f32_e32 v25, v25, v59
	v_lshlrev_b32_e32 v58, 16, v61
	v_and_b32_e32 v59, 0xffff0000, v61
	v_mul_f32_e32 v26, v26, v58
	v_mul_f32_e32 v27, v27, v59
	v_lshlrev_b32_e32 v58, 16, v56
	v_and_b32_e32 v59, 0xffff0000, v56
	v_mul_f32_e32 v28, v28, v58
	v_mul_f32_e32 v29, v29, v59
	v_lshlrev_b32_e32 v58, 16, v48
	v_and_b32_e32 v59, 0xffff0000, v48
	v_lshlrev_b32_e32 v48, 16, v49
	v_and_b32_e32 v49, 0xffff0000, v49
	v_mul_f32_e32 v6, v6, v48
	v_mul_f32_e32 v7, v7, v49
	v_lshlrev_b32_e32 v48, 16, v44
	v_and_b32_e32 v49, 0xffff0000, v44
	v_lshlrev_b32_e32 v34, 16, v72
	v_and_b32_e32 v35, 0xffff0000, v72
	v_lshlrev_b32_e32 v38, 16, v73
	v_and_b32_e32 v39, 0xffff0000, v73
	v_mul_f32_e32 v48, v66, v48
	v_mul_f32_e32 v49, v67, v49
	v_lshlrev_b32_e32 v66, 16, v18
	v_and_b32_e32 v67, 0xffff0000, v18
	v_mul_f32_e32 v34, v88, v34
	v_mul_f32_e32 v35, v89, v35
	v_mul_f32_e32 v38, v90, v38
	v_mul_f32_e32 v39, v91, v39
	v_lshlrev_b32_e32 v44, 16, v45
	v_and_b32_e32 v45, 0xffff0000, v45
	v_mul_f32_e32 v12, v12, v66
	v_mul_f32_e32 v13, v13, v67
	v_lshlrev_b32_e32 v18, 16, v19
	v_and_b32_e32 v19, 0xffff0000, v19
	v_mov_b32_e32 v66, v188
	s_barrier
; DEV int tid_() { int t = threadIdx.x; asm volatile("" : "+v"(t)); return t; }
; DEV float bflo(unsigned u) { return __uint_as_float(u << 16); }
; DEV float bfhi(unsigned u) { return __uint_as_float(u & 0xffff0000u); }
; #define P (*launderP(lp))
; DEV void stage_tile_bf16(char* smem, const f32x4 (&v)[4][4], u16* buf, int ld, int m0, int col0) {
;   const int tid = tid_(), lane = tid & 63, wid = tid >> 6, wm = wid >> 1, wn = wid & 1, l15 = lane & 15, q = lane >> 4;
; #pragma unroll
;   for (int i = 0; i < 4; ++i)
; #pragma unroll
;     for (int j = 0; j < 4; ++j) {
;       const int rl = wm * 64 + i * 16 + l15, cl = (j & 1) * 16 + wn * 32 + (j >> 1) * 64 + q * 4;
;       u32x2 o; o.x = pack2(v[i][j][0], v[i][j][1]); o.y = pack2(v[i][j][2], v[i][j][3]);
;       *(u32x2*)(smem + rl * 272 + cl * 2) = o;
;     }
;   __syncthreads();
; __device__ __forceinline__ void phase_gemm45(PREF P, char* smem, int which) {
;     ...
; #pragma unroll
;       for (int i = 0; i < 4; ++i)
; #pragma unroll
;         for (int j = 0; j < 4; ++j) {
;           const int row = m0 + wm * 64 + i * 16 + l15, col = n0 + (j & 1) * 16 + wn * 32 + (j >> 1) * 64 + q * 4;
;           f32x4 v;
;           v[0] = bflo(part[i][j][0]) * acc[i][j][0]; v[1] = bfhi(part[i][j][0]) * acc[i][j][1];
;           v[2] = bflo(part[i][j][1]) * acc[i][j][2]; v[3] = bfhi(part[i][j][1]) * acc[i][j][3];
;           acc[i][j] = v;
;         }
;       stage_tile_bf16(smem, acc, P.peb, 2048, m0, n0);
	v_lshlrev_b32_e32 v42, 16, v74
	v_and_b32_e32 v43, 0xffff0000, v74
	v_lshlrev_b32_e32 v46, 16, v75
	v_and_b32_e32 v47, 0xffff0000, v75
	v_mul_f32_e32 v44, v68, v44
	v_mul_f32_e32 v45, v69, v45
	v_mul_f32_e32 v14, v14, v18
	v_mul_f32_e32 v15, v15, v19
	ds_read_b64 v[18:19], v80 offset:360
	s_mov_b32 s5, 0xfffffc0
	v_and_b32_e32 v67, 15, v66
	v_lshrrev_b32_e32 v68, 1, v66
	v_cvt_pk_bf16_f32 v34, v34, v35
	v_cvt_pk_bf16_f32 v35, v38, v39
	v_and_b32_e32 v38, 64, v66
	v_mul_f32_e32 v42, v100, v42
	v_mul_f32_e32 v43, v101, v43
	v_mul_f32_e32 v46, v102, v46
	v_mul_f32_e32 v47, v103, v47
	v_lshlrev_b32_e32 v50, 16, v76
	v_and_b32_e32 v51, 0xffff0000, v76
	v_lshlrev_b32_e32 v54, 16, v77
	v_and_b32_e32 v55, 0xffff0000, v77
	v_and_or_b32 v69, v68, s5, v67
	v_and_or_b32 v38, v68, 24, v38
	v_mul_f32_e32 v50, v104, v50
	v_mul_f32_e32 v51, v105, v51
	v_mul_f32_e32 v54, v106, v54
	v_mul_f32_e32 v55, v107, v55
	v_lshlrev_b32_e32 v56, 16, v57
	v_and_b32_e32 v57, 0xffff0000, v57
	v_mad_u64_u32 v[38:39], s[14:15], v69, s11, v[38:39]
	v_cvt_pk_bf16_f32 v42, v42, v43
	v_cvt_pk_bf16_f32 v43, v46, v47
	v_mul_f32_e32 v30, v30, v56
	v_mul_f32_e32 v31, v31, v57
	v_lshlrev_b32_e32 v56, 16, v52
	v_and_b32_e32 v57, 0xffff0000, v52
	v_lshlrev_b32_e32 v52, 16, v53
	v_and_b32_e32 v53, 0xffff0000, v53
	ds_write2_b64 v38, v[34:35], v[42:43] offset1:4
	v_cvt_pk_bf16_f32 v34, v50, v51
	v_cvt_pk_bf16_f32 v35, v54, v55
	v_cvt_pk_bf16_f32 v0, v0, v1
	v_cvt_pk_bf16_f32 v1, v2, v3
	v_mul_f32_e32 v56, v108, v56
	v_mul_f32_e32 v57, v109, v57
	v_mul_f32_e32 v52, v110, v52
	v_mul_f32_e32 v53, v111, v53
	v_mul_f32_e32 v4, v4, v58
	v_mul_f32_e32 v5, v5, v59
	v_lshlrev_b32_e32 v58, 16, v40
	v_and_b32_e32 v59, 0xffff0000, v40
	v_lshlrev_b32_e32 v40, 16, v41
	v_and_b32_e32 v41, 0xffff0000, v41
	ds_write2_b64 v38, v[34:35], v[0:1] offset0:16 offset1:20
	v_cvt_pk_bf16_f32 v0, v24, v25
	v_cvt_pk_bf16_f32 v1, v26, v27
	v_cvt_pk_bf16_f32 v2, v28, v29
	v_cvt_pk_bf16_f32 v3, v30, v31
	v_add_u32_e32 v24, 0x1000, v38
	v_mul_f32_e32 v58, v112, v58
	v_mul_f32_e32 v59, v113, v59
	v_mul_f32_e32 v40, v114, v40
	v_mul_f32_e32 v41, v115, v41
	v_lshlrev_b32_e32 v60, 16, v36
	v_and_b32_e32 v61, 0xffff0000, v36
	v_lshlrev_b32_e32 v36, 16, v37
	v_and_b32_e32 v37, 0xffff0000, v37
	v_lshlrev_b32_e32 v62, 16, v32
	v_and_b32_e32 v63, 0xffff0000, v32
	v_lshlrev_b32_e32 v32, 16, v33
	v_and_b32_e32 v33, 0xffff0000, v33
	ds_write2_b64 v24, v[0:1], v[2:3] offset0:32 offset1:36
	v_cvt_pk_bf16_f32 v0, v56, v57
	v_cvt_pk_bf16_f32 v1, v52, v53
	v_cvt_pk_bf16_f32 v2, v4, v5
	v_cvt_pk_bf16_f32 v3, v6, v7
	v_mul_f32_e32 v60, v116, v60
	v_mul_f32_e32 v61, v117, v61
	v_mul_f32_e32 v36, v118, v36
	v_mul_f32_e32 v37, v119, v37
	v_mul_f32_e32 v8, v8, v62
	v_mul_f32_e32 v9, v9, v63
	v_mul_f32_e32 v10, v10, v32
	v_mul_f32_e32 v11, v11, v33
	v_lshlrev_b32_e32 v32, 16, v20
	v_and_b32_e32 v33, 0xffff0000, v20
	v_lshlrev_b32_e32 v20, 16, v21
	v_and_b32_e32 v21, 0xffff0000, v21
	v_lshlrev_b32_e32 v62, 16, v22
	v_and_b32_e32 v63, 0xffff0000, v22
	v_lshlrev_b32_e32 v22, 16, v23
	v_and_b32_e32 v23, 0xffff0000, v23
	ds_write2_b64 v24, v[0:1], v[2:3] offset0:48 offset1:52
	v_cvt_pk_bf16_f32 v0, v48, v49
	v_cvt_pk_bf16_f32 v1, v44, v45
	v_cvt_pk_bf16_f32 v2, v58, v59
	v_cvt_pk_bf16_f32 v3, v40, v41
	v_add_u32_e32 v4, 0x2000, v38
	v_mul_f32_e32 v32, v84, v32
	v_mul_f32_e32 v33, v85, v33
	v_mul_f32_e32 v20, v86, v20
	v_mul_f32_e32 v21, v87, v21
	v_mul_f32_e32 v62, v92, v62
	v_mul_f32_e32 v63, v93, v63
	v_mul_f32_e32 v22, v94, v22
	v_mul_f32_e32 v23, v95, v23
	v_lshlrev_b32_e32 v64, 16, v16
	v_and_b32_e32 v65, 0xffff0000, v16
	v_lshlrev_b32_e32 v16, 16, v17
	v_and_b32_e32 v17, 0xffff0000, v17
	ds_write2_b64 v4, v[0:1], v[2:3] offset0:64 offset1:68
	v_cvt_pk_bf16_f32 v0, v60, v61
	v_cvt_pk_bf16_f32 v1, v36, v37
	v_cvt_pk_bf16_f32 v2, v8, v9
	v_cvt_pk_bf16_f32 v3, v10, v11
	v_mul_f32_e32 v64, v96, v64
	v_mul_f32_e32 v65, v97, v65
	v_mul_f32_e32 v16, v98, v16
	v_mul_f32_e32 v17, v99, v17
	ds_write2_b64 v4, v[0:1], v[2:3] offset0:80 offset1:84
	v_cvt_pk_bf16_f32 v0, v32, v33
	v_cvt_pk_bf16_f32 v1, v20, v21
	v_cvt_pk_bf16_f32 v2, v62, v63
	v_cvt_pk_bf16_f32 v3, v22, v23
	v_add_u32_e32 v4, 0x3000, v38
	ds_write2_b64 v4, v[0:1], v[2:3] offset0:96 offset1:100
	v_cvt_pk_bf16_f32 v0, v64, v65
	v_cvt_pk_bf16_f32 v1, v16, v17
	v_cvt_pk_bf16_f32 v2, v12, v13
	v_cvt_pk_bf16_f32 v3, v14, v15
	s_ashr_i32 s5, s4, 31
	ds_write2_b64 v4, v[0:1], v[2:3] offset0:112 offset1:116
	v_lshlrev_b32_e32 v180, 4, v67
	s_waitcnt lgkmcnt(8)
	v_lshl_add_u64 v[0:1], s[4:5], 1, v[18:19]
	v_ashrrev_i32_e32 v6, 4, v66
	v_lshl_add_u64 v[4:5], v[0:1], 0, v[180:181]
	v_mad_u64_u32 v[0:1], s[4:5], v6, s11, v[180:181]
	s_waitcnt lgkmcnt(0)
	s_barrier
; DEV int bid_() { int t = blockIdx.x; asm volatile("" : "+s"(t)); return t; }
; DEV int gdim_() { int t = gridDim.x; asm volatile("" : "+s"(t)); return t; }
; DEV void stage_tile_bf16(char* smem, const f32x4 (&v)[4][4], u16* buf, int ld, int m0, int col0) {
;     ...
; #pragma unroll
;   for (int k = 0; k < 8; ++k) {
;     const int chunk = tid + 256 * k, rl = chunk >> 4, c16 = chunk & 15;
;     u32x4 d = *(const u32x4*)(smem + rl * 272 + c16 * 16);
;     *(u32x4*)(buf + (size_t)(m0 + rl) * ld + col0 + c16 * 8) = d;
;   }
; __device__ __forceinline__ void phase_gemm45(PREF P, char* smem, int which) {
;     ...
;   for (int t = bid_(); t < 64 * 16; t += gdim_()) {
	ds_read_b128 v[0:3], v0
	v_add_u32_e32 v6, s17, v6
	v_ashrrev_i32_e32 v7, 31, v6
	v_lshlrev_b64 v[6:7], 12, v[6:7]
	v_lshl_add_u64 v[6:7], v[4:5], 0, v[6:7]
	s_waitcnt lgkmcnt(0)
	flat_store_dwordx4 v[6:7], v[0:3]
	s_nop 1
	v_add_u32_e32 v0, 0x100, v66
	v_ashrrev_i32_e32 v6, 4, v0
	v_mad_u64_u32 v[0:1], s[4:5], v6, s11, v[180:181]
	ds_read_b128 v[0:3], v0
	v_add_u32_e32 v6, s17, v6
	v_ashrrev_i32_e32 v7, 31, v6
	v_lshlrev_b64 v[6:7], 12, v[6:7]
	v_lshl_add_u64 v[6:7], v[4:5], 0, v[6:7]
	s_waitcnt lgkmcnt(0)
	flat_store_dwordx4 v[6:7], v[0:3]
	s_nop 1
	v_add_u32_e32 v0, 0x200, v66
	v_ashrrev_i32_e32 v6, 4, v0
	v_mad_u64_u32 v[0:1], s[4:5], v6, s11, v[180:181]
	ds_read_b128 v[0:3], v0
	v_add_u32_e32 v6, s17, v6
	v_ashrrev_i32_e32 v7, 31, v6
	v_lshlrev_b64 v[6:7], 12, v[6:7]
	v_lshl_add_u64 v[6:7], v[4:5], 0, v[6:7]
	s_waitcnt lgkmcnt(0)
	flat_store_dwordx4 v[6:7], v[0:3]
	s_nop 1
	v_add_u32_e32 v0, 0x300, v66
	v_ashrrev_i32_e32 v6, 4, v0
	v_mad_u64_u32 v[0:1], s[4:5], v6, s11, v[180:181]
	ds_read_b128 v[0:3], v0
	v_add_u32_e32 v6, s17, v6
	v_ashrrev_i32_e32 v7, 31, v6
	v_lshlrev_b64 v[6:7], 12, v[6:7]
	v_lshl_add_u64 v[6:7], v[4:5], 0, v[6:7]
	s_waitcnt lgkmcnt(0)
	flat_store_dwordx4 v[6:7], v[0:3]
	s_nop 1
	v_add_u32_e32 v0, 0x400, v66
	v_ashrrev_i32_e32 v6, 4, v0
	v_mad_u64_u32 v[0:1], s[4:5], v6, s11, v[180:181]
	ds_read_b128 v[0:3], v0
	v_add_u32_e32 v6, s17, v6
	v_ashrrev_i32_e32 v7, 31, v6
	v_lshlrev_b64 v[6:7], 12, v[6:7]
	v_lshl_add_u64 v[6:7], v[4:5], 0, v[6:7]
	s_waitcnt lgkmcnt(0)
	flat_store_dwordx4 v[6:7], v[0:3]
	s_nop 1
	v_add_u32_e32 v0, 0x500, v66
	v_ashrrev_i32_e32 v6, 4, v0
	v_mad_u64_u32 v[0:1], s[4:5], v6, s11, v[180:181]
	ds_read_b128 v[0:3], v0
	v_add_u32_e32 v6, s17, v6
	v_ashrrev_i32_e32 v7, 31, v6
	v_lshlrev_b64 v[6:7], 12, v[6:7]
	v_lshl_add_u64 v[6:7], v[4:5], 0, v[6:7]
	s_waitcnt lgkmcnt(0)
	flat_store_dwordx4 v[6:7], v[0:3]
	s_nop 1
	v_add_u32_e32 v0, 0x600, v66
	v_ashrrev_i32_e32 v6, 4, v0
	v_mad_u64_u32 v[0:1], s[4:5], v6, s11, v[180:181]
	ds_read_b128 v[0:3], v0
	v_add_u32_e32 v6, s17, v6
	v_ashrrev_i32_e32 v7, 31, v6
	v_lshlrev_b64 v[6:7], 12, v[6:7]
	v_lshl_add_u64 v[6:7], v[4:5], 0, v[6:7]
	s_waitcnt lgkmcnt(0)
	flat_store_dwordx4 v[6:7], v[0:3]
	s_nop 1
	v_add_u32_e32 v0, 0x700, v66
	v_ashrrev_i32_e32 v6, 4, v0
	v_mad_u64_u32 v[0:1], s[4:5], v6, s11, v[180:181]
	ds_read_b128 v[0:3], v0
	v_add_u32_e32 v6, s17, v6
	v_ashrrev_i32_e32 v7, 31, v6
	v_lshlrev_b64 v[6:7], 12, v[6:7]
	v_lshl_add_u64 v[4:5], v[4:5], 0, v[6:7]
	v_readlane_b32 s4, v251, 6
	s_waitcnt lgkmcnt(0)
	flat_store_dwordx4 v[4:5], v[0:3]
	s_add_i32 s16, s4, s16
	s_cmpk_gt_i32 s16, 0x3ff
	v_readlane_b32 s5, v251, 7
	s_cbranch_scc0 .LBB0_623
	s_branch .LBB0_616

; #define P (*launderP(lp))
; __device__ __forceinline__ void phase_peer_gather(PREF P, int slab, int tbeg, int tend) {
;     ...
;     {
;       const float corr = 128.f * csum;
;       float hv[16], pv[16];
; #pragma unroll
;       for (int hf = 0; hf < 2; ++hf) {
;         ld16bf(hrow + hf * 1024, hv);
;         ld16bf(P.peb + (size_t)t * 2048 + lane * 16 + hf * 1024, pv);
; #pragma unroll
;         for (int e = 0; e < 16; ++e) acc[hf * 16 + e] = acc[hf * 16 + e] - corr + DN_ALPHA * hv[e] + pv[e];
;       }
;     }
;     float s = 0.f;
; #pragma unroll
;     for (int e = 0; e < 32; ++e) s += acc[e];
;     const float mu = wsum(s) * (1.f / 2048.f);
.LBB0_692:
	ds_read_b64 v[2:3], v53 offset:360
	v_mul_f32_e32 v18, 0x43000000, v55
	v_sub_f32_e32 v20, v134, v18
	v_sub_f32_e32 v21, v135, v18
	v_sub_f32_e32 v22, v132, v18
	v_sub_f32_e32 v23, v133, v18
	v_sub_f32_e32 v24, v130, v18
	v_sub_f32_e32 v25, v131, v18
	s_waitcnt lgkmcnt(0)
	v_lshl_add_u64 v[2:3], v[0:1], 1, v[2:3]
	v_lshl_add_u64 v[14:15], v[2:3], 0, v[180:181]
	flat_load_dwordx4 v[2:5], v[14:15]
	flat_load_dwordx4 v[6:9], v[14:15] offset:16
	flat_load_dwordx4 v[10:13], v[14:15] offset:2048
	s_nop 0
	flat_load_dwordx4 v[14:17], v[14:15] offset:2064
	v_sub_f32_e32 v26, v128, v18
	v_sub_f32_e32 v27, v129, v18
	v_sub_f32_e32 v28, v126, v18
	v_sub_f32_e32 v29, v127, v18
	v_sub_f32_e32 v30, v124, v18
	v_sub_f32_e32 v31, v125, v18
	v_sub_f32_e32 v32, v122, v18
	v_sub_f32_e32 v33, v123, v18
	v_sub_f32_e32 v34, v120, v18
	v_sub_f32_e32 v35, v121, v18
	v_sub_f32_e32 v36, v118, v18
	v_sub_f32_e32 v37, v119, v18
	v_sub_f32_e32 v38, v116, v18
	v_sub_f32_e32 v39, v117, v18
	v_sub_f32_e32 v40, v114, v18
	v_sub_f32_e32 v41, v115, v18
	v_sub_f32_e32 v42, v112, v18
	v_sub_f32_e32 v43, v113, v18
	v_sub_f32_e32 v44, v110, v18
	v_sub_f32_e32 v45, v111, v18
	v_sub_f32_e32 v46, v108, v18
	v_sub_f32_e32 v47, v109, v18
	v_sub_f32_e32 v100, v106, v18
	v_sub_f32_e32 v101, v107, v18
	v_sub_f32_e32 v19, v137, v18
	v_sub_f32_e32 v18, v136, v18
	v_fmac_f32_e32 v20, s28, v68
	v_fmac_f32_e32 v21, s28, v69
	v_fma_f32 v68, v76, s28, v28
	v_fma_f32 v69, v77, s28, v29
	v_fma_f32 v76, v98, s28, v18
	v_fma_f32 v77, v99, s28, v19
	v_fmac_f32_e32 v24, s28, v72
	v_fmac_f32_e32 v25, s28, v73
	v_fma_f32 v72, v80, s28, v32
	v_fma_f32 v73, v81, s28, v33
	v_fmac_f32_e32 v34, s28, v82
	v_fmac_f32_e32 v35, s28, v83
	v_fmac_f32_e32 v22, s28, v70
	v_fmac_f32_e32 v23, s28, v71
	v_fma_f32 v70, v78, s28, v30
	v_fma_f32 v71, v79, s28, v31
	v_fmac_f32_e32 v26, s28, v74
	v_fmac_f32_e32 v27, s28, v75
	v_fmac_f32_e32 v36, s28, v84
	v_fmac_f32_e32 v37, s28, v85
	v_fmac_f32_e32 v44, s28, v92
	v_fmac_f32_e32 v45, s28, v93
	v_fmac_f32_e32 v46, s28, v94
	v_fmac_f32_e32 v47, s28, v95
	v_fmac_f32_e32 v38, s28, v86
	v_fmac_f32_e32 v39, s28, v87
	v_fmac_f32_e32 v40, s28, v88
	v_fmac_f32_e32 v41, s28, v89
	v_fmac_f32_e32 v42, s28, v90
	v_fmac_f32_e32 v43, s28, v91
	v_fma_f32 v74, v96, s28, v100
	v_fma_f32 v75, v97, s28, v101
	v_lshlrev_b32_e32 v180, 2, v54
	s_mov_b32 s6, 0x800000
	v_mov_b32_e32 v61, v181
	v_mov_b32_e32 v63, v181
	v_mov_b32_e32 v65, v181
	v_mov_b32_e32 v67, v181
	v_readlane_b32 s14, v251, 6
	v_readlane_b32 s15, v251, 7
	s_waitcnt vmcnt(0) lgkmcnt(0)
	v_lshlrev_b32_e32 v18, 16, v2
	v_and_b32_e32 v19, 0xffff0000, v2
	v_lshlrev_b32_e32 v80, 16, v8
	v_and_b32_e32 v81, 0xffff0000, v8
	v_lshlrev_b32_e32 v8, 16, v9
	v_and_b32_e32 v9, 0xffff0000, v9
	v_add_f32_e32 v32, v20, v18
	v_add_f32_e32 v33, v21, v19
	v_lshlrev_b32_e32 v2, 16, v3
	v_and_b32_e32 v3, 0xffff0000, v3
	v_add_f32_e32 v18, v34, v8
	v_add_f32_e32 v19, v35, v9
	v_add_f32_e32 v34, 0, v32
	v_add_f32_e32 v30, v22, v2
	v_add_f32_e32 v31, v23, v3
	v_add_f32_e32 v34, v33, v34
	v_lshlrev_b32_e32 v28, 16, v4
	v_and_b32_e32 v29, 0xffff0000, v4
	v_add_f32_e32 v34, v30, v34
	v_add_f32_e32 v28, v24, v28
	v_add_f32_e32 v29, v25, v29
	v_add_f32_e32 v34, v31, v34
	v_lshlrev_b32_e32 v4, 16, v5
	v_and_b32_e32 v5, 0xffff0000, v5
	v_add_f32_e32 v34, v28, v34
	v_add_f32_e32 v26, v26, v4
	v_add_f32_e32 v27, v27, v5
	v_add_f32_e32 v34, v29, v34
	v_lshlrev_b32_e32 v78, 16, v6
	v_and_b32_e32 v79, 0xffff0000, v6
	v_add_f32_e32 v34, v26, v34
	v_add_f32_e32 v24, v68, v78
	v_add_f32_e32 v25, v69, v79
	v_add_f32_e32 v34, v27, v34
	v_lshlrev_b32_e32 v6, 16, v7
	v_and_b32_e32 v7, 0xffff0000, v7
	v_add_f32_e32 v34, v24, v34
	v_add_f32_e32 v22, v70, v6
	v_add_f32_e32 v23, v71, v7
	v_add_f32_e32 v34, v25, v34
	v_add_f32_e32 v34, v22, v34
	v_add_f32_e32 v20, v72, v80
	v_add_f32_e32 v21, v73, v81
	v_add_f32_e32 v34, v23, v34
	v_add_f32_e32 v34, v20, v34
	v_add_f32_e32 v34, v21, v34
	v_lshlrev_b32_e32 v82, 16, v10
	v_and_b32_e32 v83, 0xffff0000, v10
	v_add_f32_e32 v34, v18, v34
	v_lshlrev_b32_e32 v92, 16, v16
	v_and_b32_e32 v93, 0xffff0000, v16
	v_lshlrev_b32_e32 v94, 16, v17
	v_and_b32_e32 v95, 0xffff0000, v17
	v_add_f32_e32 v16, v36, v82
	v_add_f32_e32 v17, v37, v83
	v_add_f32_e32 v34, v19, v34
	v_lshlrev_b32_e32 v10, 16, v11
	v_and_b32_e32 v11, 0xffff0000, v11
	v_add_f32_e32 v34, v16, v34
	v_lshlrev_b32_e32 v88, 16, v14
	v_and_b32_e32 v89, 0xffff0000, v14
	v_lshlrev_b32_e32 v90, 16, v15
	v_and_b32_e32 v91, 0xffff0000, v15
	v_add_f32_e32 v14, v38, v10
	v_add_f32_e32 v15, v39, v11
	v_add_f32_e32 v34, v17, v34
	v_lshlrev_b32_e32 v84, 16, v12
	v_and_b32_e32 v85, 0xffff0000, v12
	v_add_f32_e32 v34, v14, v34
	v_lshlrev_b32_e32 v86, 16, v13
	v_and_b32_e32 v87, 0xffff0000, v13
	v_add_f32_e32 v12, v40, v84
	v_add_f32_e32 v13, v41, v85
	v_add_f32_e32 v34, v15, v34
	v_add_f32_e32 v34, v12, v34
	v_add_f32_e32 v10, v42, v86
	v_add_f32_e32 v11, v43, v87
	v_add_f32_e32 v34, v13, v34
	v_add_f32_e32 v34, v10, v34
	v_add_f32_e32 v8, v44, v88
	v_add_f32_e32 v9, v45, v89
	v_add_f32_e32 v34, v11, v34
	v_add_f32_e32 v34, v8, v34
	v_add_f32_e32 v6, v46, v90
	v_add_f32_e32 v7, v47, v91
	v_add_f32_e32 v34, v9, v34
	v_add_f32_e32 v34, v6, v34
	v_add_f32_e32 v4, v74, v92
	v_add_f32_e32 v5, v75, v93
	v_add_f32_e32 v34, v7, v34
	v_add_f32_e32 v34, v4, v34
	v_add_f32_e32 v2, v76, v94
	v_add_f32_e32 v3, v77, v95
	v_add_f32_e32 v34, v5, v34
	v_add_f32_e32 v34, v2, v34
	v_add_f32_e32 v34, v3, v34
	ds_bpermute_b32 v35, v138, v34
	s_waitcnt lgkmcnt(0)
	v_add_f32_e32 v34, v34, v35
	ds_bpermute_b32 v35, v139, v34
	s_waitcnt lgkmcnt(0)
	v_add_f32_e32 v34, v34, v35
	ds_bpermute_b32 v35, v140, v34
	s_waitcnt lgkmcnt(0)
; __device__ __forceinline__ void phase_peer_gather(PREF P, int slab, int tbeg, int tend) {
;     ...
;     float s = 0.f;
; #pragma unroll
;     for (int e = 0; e < 32; ++e) s += acc[e];
;     const float mu = wsum(s) * (1.f / 2048.f);
;     float vs = 0.f;
; #pragma unroll
;     for (int e = 0; e < 32; ++e) { float d = acc[e] - mu; vs += d * d; }
;     const float rs = rsqrtf(wsum(vs) * (1.f / 2048.f) + LN_EPS);
	v_add_f32_e32 v34, v34, v35
	ds_bpermute_b32 v35, v141, v34
	s_waitcnt lgkmcnt(0)
	v_add_f32_e32 v38, v34, v35
	ds_bpermute_b32 v39, v142, v38
	ds_read2_b64 v[34:37], v53 offset0:18 offset1:19
	s_waitcnt lgkmcnt(1)
	v_add_f32_e32 v42, v38, v39
	ds_bpermute_b32 v43, v143, v42
	s_waitcnt lgkmcnt(1)
	v_lshl_add_u64 v[34:35], v[34:35], 0, v[180:181]
	v_lshl_add_u64 v[38:39], v[36:37], 0, v[180:181]
	flat_load_dwordx4 v[34:37], v[34:35]
	s_nop 0
	flat_load_dwordx4 v[38:41], v[38:39]
	s_waitcnt lgkmcnt(0)
	v_add_f32_e32 v42, v42, v43
	v_mul_f32_e32 v42, 0x3a000000, v42
	v_sub_f32_e32 v32, v32, v42
	v_sub_f32_e32 v33, v33, v42
	v_sub_f32_e32 v30, v30, v42
	v_sub_f32_e32 v31, v31, v42
	v_mul_f32_e32 v44, v32, v32
	v_mul_f32_e32 v45, v33, v33
	v_mul_f32_e32 v46, v30, v30
	v_mul_f32_e32 v47, v31, v31
	v_add_f32_e32 v44, v44, v45
	v_sub_f32_e32 v28, v28, v42
	v_sub_f32_e32 v29, v29, v42
	v_add_f32_e32 v44, v46, v44
	v_mul_f32_e32 v68, v28, v28
	v_mul_f32_e32 v69, v29, v29
	v_add_f32_e32 v44, v47, v44
	v_sub_f32_e32 v26, v26, v42
	v_sub_f32_e32 v27, v27, v42
	v_add_f32_e32 v44, v68, v44
	v_mul_f32_e32 v70, v26, v26
	v_mul_f32_e32 v71, v27, v27
	v_add_f32_e32 v44, v69, v44
	v_sub_f32_e32 v24, v24, v42
	v_sub_f32_e32 v25, v25, v42
	v_add_f32_e32 v44, v70, v44
	v_mul_f32_e32 v72, v24, v24
	v_mul_f32_e32 v73, v25, v25
	v_add_f32_e32 v44, v71, v44
	v_sub_f32_e32 v22, v22, v42
	v_sub_f32_e32 v23, v23, v42
	v_add_f32_e32 v44, v72, v44
	v_mul_f32_e32 v74, v22, v22
	v_mul_f32_e32 v75, v23, v23
	v_add_f32_e32 v44, v73, v44
	v_sub_f32_e32 v20, v20, v42
	v_sub_f32_e32 v21, v21, v42
	v_add_f32_e32 v44, v74, v44
	v_mul_f32_e32 v76, v20, v20
	v_mul_f32_e32 v77, v21, v21
	v_add_f32_e32 v44, v75, v44
	v_sub_f32_e32 v18, v18, v42
	v_sub_f32_e32 v19, v19, v42
	v_add_f32_e32 v44, v76, v44
	v_mul_f32_e32 v78, v18, v18
	v_mul_f32_e32 v79, v19, v19
	v_add_f32_e32 v44, v77, v44
	v_sub_f32_e32 v16, v16, v42
	v_sub_f32_e32 v17, v17, v42
	v_add_f32_e32 v44, v78, v44
	v_mul_f32_e32 v80, v16, v16
	v_mul_f32_e32 v81, v17, v17
	v_add_f32_e32 v44, v79, v44
	v_sub_f32_e32 v14, v14, v42
	v_sub_f32_e32 v15, v15, v42
	v_add_f32_e32 v44, v80, v44
	v_mul_f32_e32 v82, v14, v14
	v_mul_f32_e32 v83, v15, v15
	v_add_f32_e32 v44, v81, v44
	v_sub_f32_e32 v12, v12, v42
	v_sub_f32_e32 v13, v13, v42
	v_add_f32_e32 v44, v82, v44
	v_mul_f32_e32 v84, v12, v12
	v_mul_f32_e32 v85, v13, v13
	v_add_f32_e32 v44, v83, v44
	v_sub_f32_e32 v10, v10, v42
	v_sub_f32_e32 v11, v11, v42
	v_add_f32_e32 v44, v84, v44
	v_mul_f32_e32 v86, v10, v10
	v_mul_f32_e32 v87, v11, v11
	v_add_f32_e32 v44, v85, v44
	v_sub_f32_e32 v8, v8, v42
	v_sub_f32_e32 v9, v9, v42
	v_add_f32_e32 v44, v86, v44
	v_mul_f32_e32 v88, v8, v8
	v_mul_f32_e32 v89, v9, v9
	v_add_f32_e32 v44, v87, v44
	v_sub_f32_e32 v90, v6, v42
	v_sub_f32_e32 v91, v7, v42
	v_add_f32_e32 v44, v88, v44
	v_mul_f32_e32 v6, v90, v90
	v_mul_f32_e32 v7, v91, v91
	v_add_f32_e32 v44, v89, v44
	v_sub_f32_e32 v92, v4, v42
	v_sub_f32_e32 v93, v5, v42
	v_add_f32_e32 v6, v6, v44
	v_mul_f32_e32 v4, v92, v92
	v_mul_f32_e32 v5, v93, v93
	v_add_f32_e32 v6, v7, v6
	v_sub_f32_e32 v43, v3, v42
	v_sub_f32_e32 v42, v2, v42
	v_add_f32_e32 v4, v4, v6
	v_mul_f32_e32 v2, v42, v42
	v_mul_f32_e32 v3, v43, v43
	v_add_f32_e32 v4, v5, v4
	v_add_f32_e32 v2, v2, v4
	v_add_f32_e32 v2, v3, v2
	ds_bpermute_b32 v3, v138, v2
	v_lshl_add_u64 v[44:45], v[0:1], 2, v[50:51]
	v_lshl_add_u64 v[46:47], v[44:45], 0, v[180:181]
	s_waitcnt lgkmcnt(0)
	v_add_f32_e32 v2, v2, v3
	ds_bpermute_b32 v3, v139, v2
	s_waitcnt lgkmcnt(0)
	v_add_f32_e32 v2, v2, v3
	ds_bpermute_b32 v3, v140, v2
	s_waitcnt lgkmcnt(0)
	v_add_f32_e32 v2, v2, v3
	ds_bpermute_b32 v3, v141, v2
	s_waitcnt lgkmcnt(0)
	v_add_f32_e32 v2, v2, v3
	ds_bpermute_b32 v3, v142, v2
	s_waitcnt lgkmcnt(0)
	v_add_f32_e32 v2, v2, v3
	ds_bpermute_b32 v3, v143, v2
	s_waitcnt lgkmcnt(0)
	v_add_f32_e32 v2, v2, v3
	v_fmamk_f32 v2, v2, 0x3a000000, v191
	v_mul_f32_e32 v3, 0x4b800000, v2
	v_cmp_gt_f32_e32 vcc, s6, v2
	s_mov_b32 s6, s14
	s_nop 0
	v_cndmask_b32_e32 v2, v2, v3, vcc
	v_rsq_f32_e32 v2, v2
	s_nop 0
	v_mul_f32_e32 v0, 0x45800000, v2
	v_cndmask_b32_e32 v68, v2, v0, vcc
	v_mul_f32_e32 v0, v32, v68
	v_mul_f32_e32 v1, v33, v68
	v_mul_f32_e32 v2, v30, v68
	v_mul_f32_e32 v3, v31, v68
	s_waitcnt vmcnt(0)
; #define P (*launderP(lp))
; __device__ __forceinline__ void phase_peer_gather(PREF P, int slab, int tbeg, int tend) {
;     ...
;     float* orow = outs + (size_t)t * 2048;
; #pragma unroll
;     for (int hf = 0; hf < 2; ++hf)
; #pragma unroll
;       for (int c4 = 0; c4 < 4; ++c4) {
;         const int c = hf * 1024 + lane * 16 + c4 * 4;
;         float4 g = *(const float4*)(P.ln2_g + c), b = *(const float4*)(P.ln2_b + c);
;         float4 o;
;         o.x = (acc[hf * 16 + c4 * 4 + 0] - mu) * rs * g.x + b.x;
;         o.y = (acc[hf * 16 + c4 * 4 + 1] - mu) * rs * g.y + b.y;
;         o.z = (acc[hf * 16 + c4 * 4 + 2] - mu) * rs * g.z + b.z;
;         o.w = (acc[hf * 16 + c4 * 4 + 3] - mu) * rs * g.w + b.w;
;         *(float4*)(orow + c) = o;
;       }
;   }
	v_fma_f32 v0, v34, v0, v38
	v_fma_f32 v1, v35, v1, v39
	v_fma_f32 v2, v36, v2, v40
	v_fma_f32 v3, v37, v3, v41
	flat_store_dwordx4 v[46:47], v[0:3]
	ds_read2_b64 v[0:3], v53 offset0:18 offset1:19
	v_mul_f32_e32 v28, v28, v68
	v_mul_f32_e32 v29, v29, v68
	v_mul_f32_e32 v26, v26, v68
	v_mul_f32_e32 v27, v27, v68
	v_mul_f32_e32 v24, v24, v68
	v_mul_f32_e32 v25, v25, v68
	v_mul_f32_e32 v22, v22, v68
	v_mul_f32_e32 v23, v23, v68
	s_waitcnt lgkmcnt(0)
	v_lshl_add_u64 v[0:1], v[0:1], 0, v[180:181]
	v_lshl_add_u64 v[4:5], v[2:3], 0, v[180:181]
	flat_load_dwordx4 v[0:3], v[0:1] offset:16
	s_nop 0
	flat_load_dwordx4 v[4:7], v[4:5] offset:16
	v_mul_f32_e32 v20, v20, v68
	v_mul_f32_e32 v21, v21, v68
	v_mul_f32_e32 v18, v18, v68
	v_mul_f32_e32 v19, v19, v68
	v_mul_f32_e32 v16, v16, v68
	v_mul_f32_e32 v17, v17, v68
	v_mul_f32_e32 v14, v14, v68
	v_mul_f32_e32 v15, v15, v68
	v_mul_f32_e32 v12, v12, v68
	v_mul_f32_e32 v13, v13, v68
	v_mul_f32_e32 v10, v10, v68
	v_mul_f32_e32 v11, v11, v68
	v_mul_f32_e32 v8, v8, v68
	v_mul_f32_e32 v9, v9, v68
	s_waitcnt vmcnt(0) lgkmcnt(0)
	v_fma_f32 v0, v0, v28, v4
	v_fma_f32 v1, v1, v29, v5
	v_fma_f32 v2, v2, v26, v6
	v_fma_f32 v3, v3, v27, v7
	flat_store_dwordx4 v[46:47], v[0:3] offset:16
	ds_read2_b64 v[0:3], v53 offset0:18 offset1:19
	s_waitcnt lgkmcnt(0)
	v_lshl_add_u64 v[4:5], v[2:3], 0, v[180:181]
	v_lshl_add_u64 v[0:1], v[0:1], 0, v[180:181]
	flat_load_dwordx4 v[0:3], v[0:1] offset:32
	s_nop 0
	flat_load_dwordx4 v[4:7], v[4:5] offset:32
	s_waitcnt vmcnt(0) lgkmcnt(0)
	v_fma_f32 v0, v0, v24, v4
	v_fma_f32 v1, v1, v25, v5
	v_fma_f32 v2, v2, v22, v6
	v_fma_f32 v3, v3, v23, v7
	flat_store_dwordx4 v[46:47], v[0:3] offset:32
	ds_read2_b64 v[0:3], v53 offset0:18 offset1:19
	s_waitcnt lgkmcnt(0)
	v_lshl_add_u64 v[4:5], v[2:3], 0, v[180:181]
	v_lshl_add_u64 v[0:1], v[0:1], 0, v[180:181]
	flat_load_dwordx4 v[0:3], v[0:1] offset:48
	s_nop 0
	flat_load_dwordx4 v[4:7], v[4:5] offset:48
	s_waitcnt vmcnt(0) lgkmcnt(0)
	v_fma_f32 v0, v0, v20, v4
	v_fma_f32 v1, v1, v21, v5
	v_fma_f32 v2, v2, v18, v6
	v_fma_f32 v3, v3, v19, v7
	flat_store_dwordx4 v[46:47], v[0:3] offset:48
	ds_read2_b64 v[0:3], v53 offset0:18 offset1:19
	v_lshl_add_u64 v[18:19], v[44:45], 0, v[60:61]
	s_waitcnt lgkmcnt(0)
	v_lshl_add_u64 v[0:1], v[0:1], 0, v[60:61]
	v_lshl_add_u64 v[4:5], v[2:3], 0, v[60:61]
	flat_load_dwordx4 v[0:3], v[0:1]
	s_nop 0
	flat_load_dwordx4 v[4:7], v[4:5]
	s_waitcnt vmcnt(0) lgkmcnt(0)
	v_fma_f32 v0, v0, v16, v4
	v_fma_f32 v1, v1, v17, v5
	v_fma_f32 v2, v2, v14, v6
	v_fma_f32 v3, v3, v15, v7
	flat_store_dwordx4 v[18:19], v[0:3]
	ds_read2_b64 v[0:3], v53 offset0:18 offset1:19
	v_lshl_add_u64 v[14:15], v[44:45], 0, v[62:63]
	s_waitcnt lgkmcnt(0)
	v_lshl_add_u64 v[0:1], v[0:1], 0, v[62:63]
	v_lshl_add_u64 v[4:5], v[2:3], 0, v[62:63]
	flat_load_dwordx4 v[0:3], v[0:1]
	s_nop 0
	flat_load_dwordx4 v[4:7], v[4:5]
	s_waitcnt vmcnt(0) lgkmcnt(0)
	v_fma_f32 v0, v0, v12, v4
	v_fma_f32 v1, v1, v13, v5
	v_fma_f32 v2, v2, v10, v6
	v_fma_f32 v3, v3, v11, v7
	flat_store_dwordx4 v[14:15], v[0:3]
	ds_read2_b64 v[0:3], v53 offset0:18 offset1:19
	v_mul_f32_e32 v12, v90, v68
	v_mul_f32_e32 v13, v91, v68
	v_lshl_add_u64 v[10:11], v[44:45], 0, v[64:65]
	s_waitcnt lgkmcnt(0)
	v_lshl_add_u64 v[0:1], v[0:1], 0, v[64:65]
	v_lshl_add_u64 v[4:5], v[2:3], 0, v[64:65]
	flat_load_dwordx4 v[0:3], v[0:1]
	s_nop 0
	flat_load_dwordx4 v[4:7], v[4:5]
	s_waitcnt vmcnt(0) lgkmcnt(0)
	v_fma_f32 v0, v8, v0, v4
	v_fma_f32 v1, v9, v1, v5
	v_fma_f32 v2, v12, v2, v6
	v_fma_f32 v3, v13, v3, v7
	flat_store_dwordx4 v[10:11], v[0:3]
	ds_read2_b64 v[0:3], v53 offset0:18 offset1:19
	v_mul_f32_e32 v10, v92, v68
	v_mul_f32_e32 v11, v93, v68
	v_mul_f32_e32 v12, v42, v68
	v_mul_f32_e32 v13, v43, v68
	v_lshl_add_u64 v[8:9], v[44:45], 0, v[66:67]
	s_waitcnt lgkmcnt(0)
	v_lshl_add_u64 v[0:1], v[0:1], 0, v[66:67]
	v_lshl_add_u64 v[4:5], v[2:3], 0, v[66:67]
	flat_load_dwordx4 v[0:3], v[0:1]
	s_nop 0
	flat_load_dwordx4 v[4:7], v[4:5]
	s_waitcnt vmcnt(0) lgkmcnt(0)
	v_fma_f32 v0, v10, v0, v4
	v_fma_f32 v1, v11, v1, v5
	v_fma_f32 v2, v12, v2, v6
	v_fma_f32 v3, v13, v3, v7
	flat_store_dwordx4 v[8:9], v[0:3]
	s_nop 0
	v_lshl_add_u32 v48, s6, 2, v48
	v_cmp_le_i32_e32 vcc, s24, v48
	s_or_b64 s[38:39], vcc, s[38:39]
	s_andn2_b64 exec, exec, s[38:39]
	s_cbranch_execz .LBB0_714

; DEV f32x4 mma_step(bf16x8 a, bf16x8 b, f32x4 c) { return MFMA(a, b, c); }
; template <class FragT, class AccT>
; DEV void gemm_core_t(const char* __restrict__ A, size_t lda_bytes, const char* __restrict__ Bt, size_t ldb_bytes, int kbytes,
;                      int m0, int n0, int Sshift, int dl, char* smem, AccT (&acc)[4][4]) {
;     ...
;   for (int kt = 0; kt < nk; ++kt) {
;     const unsigned so = (unsigned)(kt & 1) * 32768u;
;     char* nxt = smem + ((kt + 1) & 1) * 32768;
;     if (kt + 1 < nk) {
; #pragma unroll
;       for (int u = 0; u < 4; ++u) {
;         __builtin_amdgcn_global_load_lds((const unsigned*)(ap[u] + (size_t)(kt + 1) * 128), (unsigned*)(nxt + (wid * 4 + u) * 1024 + lane * 16), 16, 0, 0);
;         __builtin_amdgcn_global_load_lds((const unsigned*)(bp[u] + (size_t)(kt + 1) * 128), (unsigned*)(nxt + 16384 + (wid * 4 + u) * 1024 + lane * 16), 16, 0, 0);
;       }
;     }
;     FragT xa[2][4], wb[2][4];
;     asm volatile(
;         "ds_read_b128 %0, %16\n\t"
;         "ds_read_b128 %1, %16 offset:2048\n\t"
;         "ds_read_b128 %2, %16 offset:4096\n\t"
;         "ds_read_b128 %3, %16 offset:6144\n\t"
;         "ds_read_b128 %4, %18\n\t"
;         "ds_read_b128 %5, %18 offset:2048\n\t"
;         "ds_read_b128 %6, %18 offset:8192\n\t"
;         "ds_read_b128 %7, %18 offset:10240\n\t"
;         "ds_read_b128 %8, %17\n\t"
;         "ds_read_b128 %9, %17 offset:2048\n\t"
;         "ds_read_b128 %10, %17 offset:4096\n\t"
;         "ds_read_b128 %11, %17 offset:6144\n\t"
;         "ds_read_b128 %12, %19\n\t"
;         "ds_read_b128 %13, %19 offset:2048\n\t"
;         "ds_read_b128 %14, %19 offset:8192\n\t"
;         "ds_read_b128 %15, %19 offset:10240\n\t"
;         "s_waitcnt lgkmcnt(8)"
;         : "=&v"(xa[0][0]), "=&v"(xa[0][1]), "=&v"(xa[0][2]), "=&v"(xa[0][3]), "=&v"(wb[0][0]), "=&v"(wb[0][1]), "=&v"(wb[0][2]),
;           "=&v"(wb[0][3]), "=&v"(xa[1][0]), "=&v"(xa[1][1]), "=&v"(xa[1][2]), "=&v"(xa[1][3]), "=&v"(wb[1][0]), "=&v"(wb[1][1]),
;           "=&v"(wb[1][2]), "=&v"(wb[1][3])
;         : "v"(a0 + so), "v"((a0 ^ 64u) + so), "v"(b0 + so), "v"((b0 ^ 64u) + so)
;         : "memory");
;     __builtin_amdgcn_s_setprio(1);
; #pragma unroll
;     for (int i = 0; i < 4; ++i)
; #pragma unroll
;       for (int j = 0; j < 4; ++j) acc[i][j] = mma_step(wb[0][j], xa[0][i], acc[i][j]);
;     asm volatile("s_waitcnt lgkmcnt(0)"
.LBB0_734:
	s_add_i32 s37, s19, 0xffff8000
	s_and_b32 s37, s37, 0x8000
	v_add_u32_e32 v92, s37, v84
	v_add_u32_e32 v93, s37, v87
	v_or_b32_e32 v99, s37, v85
	v_or_b32_e32 v160, s37, v86
	s_and_b32 s37, s19, 0x8000
	s_add_i32 s37, s37, s62
	s_mov_b32 m0, s37
	ds_read_b128 v[88:91], v92
	global_load_lds_dwordx4 v82, s[64:65]
	ds_read_b128 v[100:103], v92 offset:2048
	s_add_i32 m0, s37, 0x4000
	ds_read_b128 v[104:107], v92 offset:4096
	global_load_lds_dwordx4 v76, s[66:67]
	ds_read_b128 v[108:111], v92 offset:6144
	s_add_i32 m0, s37, 0x400
	ds_read_b128 v[112:115], v99
	global_load_lds_dwordx4 v74, s[64:65]
	ds_read_b128 v[116:119], v99 offset:2048
	s_add_i32 m0, s37, 0x4400
	ds_read_b128 v[120:123], v99 offset:8192
	global_load_lds_dwordx4 v72, s[66:67]
	ds_read_b128 v[124:127], v99 offset:10240
	ds_read_b128 v[128:131], v93
	ds_read_b128 v[132:135], v93 offset:2048
	ds_read_b128 v[136:139], v93 offset:4096
	ds_read_b128 v[140:143], v93 offset:6144
	ds_read_b128 v[144:147], v160
	ds_read_b128 v[148:151], v160 offset:2048
	ds_read_b128 v[152:155], v160 offset:8192
	ds_read_b128 v[156:159], v160 offset:10240
	s_waitcnt lgkmcnt(8)
	s_setprio 1
	v_mfma_i32_16x16x64_i8 v[60:63], v[112:115], v[88:91], v[60:63]
	v_mfma_i32_16x16x64_i8 v[56:59], v[116:119], v[88:91], v[56:59]
	s_add_i32 m0, s37, 0x800
	v_mfma_i32_16x16x64_i8 v[52:55], v[120:123], v[88:91], v[52:55]
	global_load_lds_dwordx4 v70, s[64:65]
	v_mfma_i32_16x16x64_i8 v[48:51], v[124:127], v[88:91], v[48:51]
	v_mfma_i32_16x16x64_i8 v[44:47], v[112:115], v[100:103], v[44:47]
	v_mfma_i32_16x16x64_i8 v[40:43], v[116:119], v[100:103], v[40:43]
	s_add_i32 m0, s37, 0x4800
	v_mfma_i32_16x16x64_i8 v[36:39], v[120:123], v[100:103], v[36:39]
	global_load_lds_dwordx4 v68, s[66:67]
	v_mfma_i32_16x16x64_i8 v[32:35], v[124:127], v[100:103], v[32:35]
	v_mfma_i32_16x16x64_i8 v[28:31], v[112:115], v[104:107], v[28:31]
	v_mfma_i32_16x16x64_i8 v[24:27], v[116:119], v[104:107], v[24:27]
	s_add_i32 m0, s37, 0xc00
	v_mfma_i32_16x16x64_i8 v[20:23], v[120:123], v[104:107], v[20:23]
	global_load_lds_dwordx4 v66, s[64:65]
	v_mfma_i32_16x16x64_i8 v[16:19], v[124:127], v[104:107], v[16:19]
	v_mfma_i32_16x16x64_i8 v[12:15], v[112:115], v[108:111], v[12:15]
	v_mfma_i32_16x16x64_i8 v[8:11], v[116:119], v[108:111], v[8:11]
	s_add_i32 m0, s37, 0x4c00
	v_mfma_i32_16x16x64_i8 v[4:7], v[120:123], v[108:111], v[4:7]
	global_load_lds_dwordx4 v64, s[66:67]
	v_mfma_i32_16x16x64_i8 v[0:3], v[124:127], v[108:111], v[0:3]
	s_waitcnt lgkmcnt(0)
	s_nop 0
	v_mfma_i32_16x16x64_i8 v[60:63], v[144:147], v[128:131], v[60:63]
	v_mfma_i32_16x16x64_i8 v[56:59], v[148:151], v[128:131], v[56:59]
	v_mfma_i32_16x16x64_i8 v[52:55], v[152:155], v[128:131], v[52:55]
	v_mfma_i32_16x16x64_i8 v[48:51], v[156:159], v[128:131], v[48:51]
	v_mfma_i32_16x16x64_i8 v[44:47], v[144:147], v[132:135], v[44:47]
	v_mfma_i32_16x16x64_i8 v[40:43], v[148:151], v[132:135], v[40:43]
	v_mfma_i32_16x16x64_i8 v[36:39], v[152:155], v[132:135], v[36:39]
	v_mfma_i32_16x16x64_i8 v[32:35], v[156:159], v[132:135], v[32:35]
	v_mfma_i32_16x16x64_i8 v[28:31], v[144:147], v[136:139], v[28:31]
	v_mfma_i32_16x16x64_i8 v[24:27], v[148:151], v[136:139], v[24:27]
	v_mfma_i32_16x16x64_i8 v[20:23], v[152:155], v[136:139], v[20:23]
	v_mfma_i32_16x16x64_i8 v[16:19], v[156:159], v[136:139], v[16:19]
	v_mfma_i32_16x16x64_i8 v[12:15], v[144:147], v[140:143], v[12:15]
	v_mfma_i32_16x16x64_i8 v[8:11], v[148:151], v[140:143], v[8:11]
	v_mfma_i32_16x16x64_i8 v[4:7], v[152:155], v[140:143], v[4:7]
	v_mfma_i32_16x16x64_i8 v[0:3], v[156:159], v[140:143], v[0:3]
	s_setprio 0
	s_waitcnt vmcnt(0)
	s_add_u32 s44, s44, 0x80
	s_addc_u32 s45, s45, 0
	s_add_u32 s64, s64, 0x80
	s_addc_u32 s65, s65, 0
	s_add_u32 s66, s66, 0x80
	s_addc_u32 s67, s67, 0
	s_add_i32 s19, s19, 0x8000
	s_cmpk_lg_i32 s44, 0x780
	s_waitcnt vmcnt(0) lgkmcnt(0)
	s_barrier
	s_cbranch_scc1 .LBB0_734
	v_add_u32_e32 v76, 0x8000, v84
	v_add_u32_e32 v77, 0x8000, v87
	v_or_b32_e32 v81, 0x8000, v85
	v_or_b32_e32 v99, 0x8000, v86
	ds_read_b128 v[64:67], v76
	ds_read_b128 v[68:71], v76 offset:2048
	ds_read_b128 v[72:75], v76 offset:4096
	ds_read_b128 v[82:85], v76 offset:6144
	ds_read_b128 v[86:89], v81
	ds_read_b128 v[90:93], v81 offset:2048
	ds_read_b128 v[100:103], v81 offset:8192
	ds_read_b128 v[104:107], v81 offset:10240
	ds_read_b128 v[108:111], v77
	ds_read_b128 v[112:115], v77 offset:2048
	ds_read_b128 v[116:119], v77 offset:4096
	ds_read_b128 v[120:123], v77 offset:6144
	ds_read_b128 v[124:127], v99
	ds_read_b128 v[128:131], v99 offset:2048
	ds_read_b128 v[132:135], v99 offset:8192
	ds_read_b128 v[136:139], v99 offset:10240
	s_waitcnt lgkmcnt(8)
	s_setprio 1
	v_mfma_i32_16x16x64_i8 v[60:63], v[86:89], v[64:67], v[60:63]
	v_mfma_i32_16x16x64_i8 v[56:59], v[90:93], v[64:67], v[56:59]
	v_mfma_i32_16x16x64_i8 v[52:55], v[100:103], v[64:67], v[52:55]
	v_mfma_i32_16x16x64_i8 v[48:51], v[104:107], v[64:67], v[48:51]
	v_mfma_i32_16x16x64_i8 v[64:67], v[86:89], v[68:71], v[44:47]
	v_mfma_i32_16x16x64_i8 v[40:43], v[90:93], v[68:71], v[40:43]
	v_mfma_i32_16x16x64_i8 v[36:39], v[100:103], v[68:71], v[36:39]
	v_mfma_i32_16x16x64_i8 v[32:35], v[104:107], v[68:71], v[32:35]
	v_mfma_i32_16x16x64_i8 v[68:71], v[86:89], v[72:75], v[28:31]
	v_mfma_i32_16x16x64_i8 v[24:27], v[90:93], v[72:75], v[24:27]
	v_mfma_i32_16x16x64_i8 v[20:23], v[100:103], v[72:75], v[20:23]
	v_mfma_i32_16x16x64_i8 v[16:19], v[104:107], v[72:75], v[16:19]
	v_mfma_i32_16x16x64_i8 v[74:77], v[86:89], v[82:85], v[12:15]
	v_mfma_i32_16x16x64_i8 v[8:11], v[90:93], v[82:85], v[8:11]
	v_mfma_i32_16x16x64_i8 v[86:89], v[100:103], v[82:85], v[4:7]
	v_mfma_i32_16x16x64_i8 v[82:85], v[104:107], v[82:85], v[0:3]
	s_waitcnt lgkmcnt(0)
	s_nop 0
	v_mfma_i32_16x16x64_i8 v[56:59], v[128:131], v[108:111], v[56:59]
	v_mfma_i32_16x16x64_i8 v[140:143], v[132:135], v[108:111], v[52:55]
	v_mfma_i32_16x16x64_i8 v[46:49], v[136:139], v[108:111], v[48:51]
	v_mfma_i32_16x16x64_i8 v[52:55], v[124:127], v[112:115], v[64:67]
	v_mfma_i32_16x16x64_i8 v[40:43], v[128:131], v[112:115], v[40:43]
	v_mfma_i32_16x16x64_i8 v[36:39], v[132:135], v[112:115], v[36:39]
	v_mfma_i32_16x16x64_i8 v[30:33], v[136:139], v[112:115], v[32:35]
	v_mfma_i32_16x16x64_i8 v[24:27], v[128:131], v[116:119], v[24:27]
	v_mfma_i32_16x16x64_i8 v[20:23], v[132:135], v[116:119], v[20:23]
	v_mfma_i32_16x16x64_i8 v[14:17], v[136:139], v[116:119], v[16:19]
	v_mfma_i32_16x16x64_i8 v[4:7], v[124:127], v[120:123], v[74:77]
	v_mfma_i32_16x16x64_i8 v[0:3], v[128:131], v[120:123], v[8:11]
	v_mfma_i32_16x16x64_i8 v[8:11], v[136:139], v[120:123], v[82:85]
	v_mfma_i32_16x16x64_i8 v[102:105], v[124:127], v[108:111], v[60:63]
	v_mfma_i32_16x16x64_i8 v[70:73], v[124:127], v[116:119], v[68:71]
	v_mfma_i32_16x16x64_i8 v[62:65], v[132:135], v[120:123], v[86:89]
	s_setprio 0
	s_waitcnt vmcnt(0)
	s_barrier
; #define P (*launderP(lp))
; __device__ __forceinline__ void phase_gemm1(PREF P, int slab, char* smem) {
;     ...
; #pragma unroll
;       for (int i = 0; i < 4; ++i) {
;         const float sxr = P.sx[rowmap(m0 + wm * 64 + i * 16 + l15, Sshift, dl)];
; #pragma unroll
;         for (int j = 0; j < 4; ++j) {
;           const float4 swc = *(const float4*)(P.sw + n0 + (j & 1) * 16 + wn * 32 + (j >> 1) * 64 + q * 4);
;           acc[i][j][0] = (float)iacc[i][j][0] * sxr * swc.x; acc[i][j][1] = (float)iacc[i][j][1] * sxr * swc.y;
;           acc[i][j][2] = (float)iacc[i][j][2] * sxr * swc.z; acc[i][j][3] = (float)iacc[i][j][3] * sxr * swc.w;
;         }
;       }
	s_nop 0
	ds_read2_b64 v[84:87], v79 offset0:52 offset1:53
	v_add_u32_e32 v28, s36, v94
	v_mov_b32_e32 v29, s51
	v_and_b32_e32 v101, s51, v28
	v_bitop3_b32 v19, v28, s18, v29 bitop3:0x80
	v_lshrrev_b32_e32 v18, s17, v101
	v_and_b32_e32 v34, s50, v28
	v_lshlrev_b32_e32 v19, s6, v19
	v_add3_u32 v18, v18, v34, v19
	v_ashrrev_i32_e32 v19, 31, v18
	s_waitcnt lgkmcnt(0)
	v_lshl_add_u64 v[18:19], v[18:19], 2, v[84:85]
	flat_load_dword v82, v[18:19]
	v_or_b32_e32 v18, 16, v28
	v_bitop3_b32 v100, v28, s51, 16 bitop3:0xc8
	v_bitop3_b32 v18, v18, s18, v29 bitop3:0x80
	s_ashr_i32 s41, s40, 31
	v_lshrrev_b32_e32 v19, s17, v100
	v_lshlrev_b32_e32 v18, s6, v18
	v_lshl_add_u64 v[12:13], s[40:41], 2, v[86:87]
	v_mov_b32_e32 v81, v181
	v_add3_u32 v18, v19, v34, v18
	v_lshl_add_u64 v[12:13], v[12:13], 0, v[80:81]
	v_ashrrev_i32_e32 v19, 31, v18
	v_lshlrev_b32_e32 v180, 2, v78
	v_lshl_add_u64 v[18:19], v[18:19], 2, v[84:85]
	v_lshl_add_u64 v[12:13], v[12:13], 0, v[180:181]
	flat_load_dword v114, v[18:19]
	flat_load_dwordx4 v[106:109], v[12:13]
	flat_load_dwordx4 v[110:113], v[12:13] offset:256
	flat_load_dwordx4 v[74:77], v[12:13] offset:64
	flat_load_dwordx4 v[66:69], v[12:13] offset:320
	v_or_b32_e32 v12, 32, v28
	v_bitop3_b32 v99, v28, s51, 32 bitop3:0xc8
	v_bitop3_b32 v12, v12, s18, v29 bitop3:0x80
	v_lshrrev_b32_e32 v13, s17, v99
	v_lshlrev_b32_e32 v12, s6, v12
	v_add3_u32 v12, v13, v34, v12
	v_ashrrev_i32_e32 v13, 31, v12
	v_lshl_add_u64 v[12:13], v[12:13], 2, v[84:85]
	flat_load_dword v116, v[12:13]
	v_or_b32_e32 v12, 48, v28
	v_bitop3_b32 v81, v28, s51, 48 bitop3:0xc8
	v_bitop3_b32 v12, v12, s18, v29 bitop3:0x80
	v_lshrrev_b32_e32 v18, s17, v81
	v_lshlrev_b32_e32 v12, s6, v12
	v_add3_u32 v18, v18, v34, v12
	v_ashrrev_i32_e32 v19, 31, v18
	v_lshl_add_u64 v[18:19], v[18:19], 2, v[84:85]
	flat_load_dword v118, v[18:19]
	v_cvt_f32_i32_e32 v19, v143
	v_cvt_f32_i32_e32 v18, v105
	v_cvt_f32_i32_e32 v29, v48
	v_cvt_f32_i32_e32 v28, v58
	v_cvt_f32_i32_e32 v13, v142
	v_cvt_f32_i32_e32 v12, v104
	v_cvt_f32_i32_e32 v35, v49
	v_cvt_f32_i32_e32 v34, v59
	v_cvt_f32_i32_e32 v49, v32
	v_cvt_f32_i32_e32 v33, v33
	v_cvt_f32_i32_e32 v32, v43
	v_cvt_f32_i32_e32 v59, v22
	v_cvt_f32_i32_e32 v58, v72
	v_cvt_f32_i32_e32 v45, v38
	v_cvt_f32_i32_e32 v44, v54
	v_cvt_f32_i32_e32 v38, v55
	v_cvt_f32_i32_e32 v48, v42
	v_cvt_f32_i32_e32 v5, v5
	v_cvt_f32_i32_e32 v4, v4
	v_cvt_f32_i32_e32 v25, v25
	v_cvt_f32_i32_e32 v24, v24
	v_cvt_f32_i32_e32 v15, v15
	v_cvt_f32_i32_e32 v14, v14
	v_cvt_f32_i32_e32 v31, v31
	v_cvt_f32_i32_e32 v30, v30
	v_cvt_f32_i32_e32 v1, v1
	v_cvt_f32_i32_e32 v0, v0
	v_cvt_f32_i32_e32 v39, v39
	v_cvt_f32_i32_e32 v11, v11
	s_andn2_b64 vcc, exec, s[14:15]
	s_waitcnt vmcnt(0) lgkmcnt(0)
	v_mul_f32_e32 v18, v82, v18
	v_mul_f32_e32 v19, v82, v19
	v_mul_f32_e32 v28, v82, v28
	v_mul_f32_e32 v29, v82, v29
	v_mul_f32_e32 v12, v82, v12
	v_mul_f32_e32 v13, v82, v13
	v_mul_f32_e32 v34, v82, v34
	v_mul_f32_e32 v35, v82, v35
	v_mov_b32_e32 v84, v108
	v_mov_b32_e32 v85, v112
	v_mov_b32_e32 v112, v109
	v_mov_b32_e32 v104, v76
	v_mov_b32_e32 v105, v68
	v_mul_f32_e32 v54, v18, v112
	v_mul_f32_e32 v55, v19, v113
	v_cvt_f32_i32_e32 v19, v23
	v_cvt_f32_i32_e32 v18, v73
	v_mul_f32_e32 v42, v28, v104
	v_mul_f32_e32 v43, v29, v105
	v_cvt_f32_i32_e32 v29, v16
	v_cvt_f32_i32_e32 v28, v26
	v_mov_b32_e32 v68, v77
	v_mul_f32_e32 v88, v12, v84
	v_mul_f32_e32 v89, v13, v85
	v_mul_f32_e32 v12, v114, v32
	v_mul_f32_e32 v13, v114, v33
	v_mul_f32_e32 v50, v34, v68
	v_mul_f32_e32 v51, v35, v69
	v_mul_f32_e32 v34, v68, v12
	v_mul_f32_e32 v35, v69, v13
	v_mul_f32_e32 v12, v116, v58
	v_mul_f32_e32 v13, v116, v59
	v_mul_f32_e32 v86, v84, v12
	v_mul_f32_e32 v87, v85, v13
	v_mul_f32_e32 v12, v116, v18
	v_mul_f32_e32 v13, v116, v19
	v_mul_f32_e32 v22, v112, v12
	v_mul_f32_e32 v23, v113, v13
	v_mul_f32_e32 v12, v116, v28
	v_mul_f32_e32 v13, v116, v29
	v_mul_f32_e32 v76, v104, v12
	v_mul_f32_e32 v77, v105, v13
	v_cvt_f32_i32_e32 v13, v17
	v_cvt_f32_i32_e32 v12, v27
	v_cvt_f32_i32_e32 v17, v103
	v_cvt_f32_i32_e32 v16, v102
	v_cvt_f32_i32_e32 v27, v141
	v_cvt_f32_i32_e32 v26, v140
	v_cvt_f32_i32_e32 v29, v37
	v_cvt_f32_i32_e32 v28, v36
	v_mul_f32_e32 v12, v116, v12
	v_mul_f32_e32 v13, v116, v13
	v_mul_f32_e32 v18, v68, v12
	v_mul_f32_e32 v19, v69, v13
	v_mul_f32_e32 v12, v82, v16
	v_mul_f32_e32 v13, v82, v17
	v_mul_f32_e32 v16, v82, v26
	v_mul_f32_e32 v17, v82, v27
	v_cvt_f32_i32_e32 v27, v53
	v_cvt_f32_i32_e32 v26, v52
	v_mul_f32_e32 v52, v16, v110
	v_mul_f32_e32 v53, v17, v111
	v_mul_f32_e32 v16, v114, v28
	v_mul_f32_e32 v17, v114, v29
	v_mul_f32_e32 v36, v110, v16
	v_mul_f32_e32 v37, v111, v17
	v_cvt_f32_i32_e32 v17, v21
	v_cvt_f32_i32_e32 v16, v20
	v_mul_f32_e32 v44, v114, v44
	v_mul_f32_e32 v45, v114, v45
	v_mul_f32_e32 v60, v106, v12
	v_mul_f32_e32 v61, v107, v13
	v_mul_f32_e32 v12, v114, v26
	v_mul_f32_e32 v13, v114, v27
	v_mul_f32_e32 v92, v84, v44
	v_mul_f32_e32 v93, v85, v45
	v_mul_f32_e32 v44, v106, v12
	v_mul_f32_e32 v45, v107, v13
	v_cvt_f32_i32_e32 v13, v71
	v_cvt_f32_i32_e32 v12, v70
	v_mul_f32_e32 v16, v116, v16
	v_mul_f32_e32 v17, v116, v17
	v_mul_f32_e32 v20, v110, v16
	v_mul_f32_e32 v21, v111, v17
	v_cvt_f32_i32_e32 v17, v63
	v_cvt_f32_i32_e32 v16, v62
	v_cvt_f32_i32_e32 v27, v64
	v_cvt_f32_i32_e32 v26, v6
	v_mul_f32_e32 v12, v116, v12
	v_mul_f32_e32 v13, v116, v13
	v_mul_f32_e32 v4, v118, v4
	v_mul_f32_e32 v5, v118, v5
	v_mul_f32_e32 v28, v106, v12
	v_mul_f32_e32 v29, v107, v13
	v_mul_f32_e32 v12, v106, v4
	v_mul_f32_e32 v13, v107, v5
	v_mul_f32_e32 v4, v118, v16
	v_mul_f32_e32 v5, v118, v17
	v_mul_f32_e32 v16, v118, v26
	v_mul_f32_e32 v17, v118, v27
	v_mul_f32_e32 v84, v84, v16
; #define P (*launderP(lp))
; __device__ __forceinline__ void phase_gemm1(PREF P, int slab, char* smem) {
;     ...
; #pragma unroll
;       for (int i = 0; i < 4; ++i) {
;         const float sxr = P.sx[rowmap(m0 + wm * 64 + i * 16 + l15, Sshift, dl)];
; #pragma unroll
;         for (int j = 0; j < 4; ++j) {
;           const float4 swc = *(const float4*)(P.sw + n0 + (j & 1) * 16 + wn * 32 + (j >> 1) * 64 + q * 4);
;           acc[i][j][0] = (float)iacc[i][j][0] * sxr * swc.x; acc[i][j][1] = (float)iacc[i][j][1] * sxr * swc.y;
;           acc[i][j][2] = (float)iacc[i][j][2] * sxr * swc.z; acc[i][j][3] = (float)iacc[i][j][3] * sxr * swc.w;
;         }
;       }
;     }
;     if (region <= 1) {
; #pragma unroll
;       for (int i = 0; i < 4; ++i) {
;         const int row = m0 + wm * 64 + i * 16 + l15;
;         const float s = (float)(row & ((1 << Sshift) - 1));
; #pragma unroll
;         for (int jj = 0; jj < 2; ++jj)
; #pragma unroll
;           for (int r = 0; r < 4; ++r) {
;             const int d = jj * 16 + wn * 32 + q * 4 + r;
;             float fr = __builtin_amdgcn_fractf(s * P.ropec[d]);
;             float cs = __builtin_amdgcn_cosf(fr), sn = __builtin_amdgcn_sinf(fr);
;             float t1 = acc[i][jj][r], t2 = acc[i][jj + 2][r];
;             float o1 = t1 * cs - t2 * sn, o2 = t1 * sn + t2 * cs;
;             if (region == 1) { o1 *= QK_SCALE; o2 *= QK_SCALE; }
;             acc[i][jj][r] = o1;
;             acc[i][jj + 2][r] = o2;
;           }
	v_mul_f32_e32 v85, v85, v17
	v_cvt_f32_i32_e32 v17, v65
	v_cvt_f32_i32_e32 v16, v7
	v_cvt_f32_i32_e32 v27, v57
	v_cvt_f32_i32_e32 v26, v56
	v_cvt_f32_i32_e32 v33, v47
	v_cvt_f32_i32_e32 v32, v46
	v_mul_f32_e32 v6, v118, v16
	v_mul_f32_e32 v7, v118, v17
	v_mul_f32_e32 v16, v82, v26
	v_mul_f32_e32 v17, v82, v27
	v_mul_f32_e32 v56, v16, v74
	v_mul_f32_e32 v57, v17, v75
	v_mul_f32_e32 v26, v82, v32
	v_mul_f32_e32 v27, v82, v33
	v_cvt_f32_i32_e32 v33, v41
	v_cvt_f32_i32_e32 v32, v40
	v_mul_f32_e32 v48, v114, v48
	v_mul_f32_e32 v49, v114, v49
	v_mul_f32_e32 v14, v116, v14
	v_mul_f32_e32 v15, v116, v15
	v_mul_f32_e32 v90, v104, v48
	v_mul_f32_e32 v91, v105, v49
	v_mul_f32_e32 v16, v114, v32
	v_mul_f32_e32 v17, v114, v33
	v_mul_f32_e32 v40, v74, v16
	v_mul_f32_e32 v41, v75, v17
	v_mul_f32_e32 v16, v116, v24
	v_mul_f32_e32 v17, v116, v25
	v_mul_f32_e32 v48, v26, v66
	v_mul_f32_e32 v49, v27, v67
	v_mul_f32_e32 v26, v114, v30
	v_mul_f32_e32 v27, v114, v31
	v_mul_f32_e32 v24, v74, v16
	v_mul_f32_e32 v25, v75, v17
	v_mul_f32_e32 v16, v66, v14
	v_mul_f32_e32 v17, v67, v15
	v_cvt_f32_i32_e32 v15, v10
	v_cvt_f32_i32_e32 v14, v2
	v_mul_f32_e32 v32, v66, v26
	v_mul_f32_e32 v33, v67, v27
	v_cvt_f32_i32_e32 v27, v9
	v_cvt_f32_i32_e32 v26, v8
	v_cvt_f32_i32_e32 v10, v3
	v_mul_f32_e32 v0, v118, v0
	v_mul_f32_e32 v1, v118, v1
	v_mul_f32_e32 v2, v118, v14
	v_mul_f32_e32 v3, v118, v15
	v_mul_f32_e32 v38, v114, v38
	v_mul_f32_e32 v39, v114, v39
	v_mul_f32_e32 v8, v74, v0
	v_mul_f32_e32 v9, v75, v1
	v_mul_f32_e32 v0, v118, v26
	v_mul_f32_e32 v1, v118, v27
	v_mul_f32_e32 v82, v104, v2
	v_mul_f32_e32 v83, v105, v3
	v_mul_f32_e32 v2, v118, v10
	v_mul_f32_e32 v3, v118, v11
	v_mul_f32_e32 v38, v112, v38
	v_mul_f32_e32 v39, v113, v39
	v_mul_f32_e32 v4, v110, v4
	v_mul_f32_e32 v5, v111, v5
	v_mul_f32_e32 v6, v112, v6
	v_mul_f32_e32 v7, v113, v7
	v_mul_f32_e32 v0, v66, v0
	v_mul_f32_e32 v1, v67, v1
	v_mul_f32_e32 v2, v68, v2
	v_mul_f32_e32 v3, v69, v3
	s_cbranch_vccnz .LBB0_737
	ds_read2_b32 v[10:11], v96 offset0:134 offset1:135
	v_cvt_f32_u32_e32 v26, v101
	v_mov_b32_e32 v30, v60
	v_mov_b32_e32 v31, v52
	v_mov_b32_e32 v46, v61
	s_waitcnt lgkmcnt(0)
	v_mul_f32_e32 v14, v10, v26
	v_fract_f32_e32 v15, v14
	v_cos_f32_e32 v14, v15
	v_sin_f32_e32 v15, v15
	v_mov_b32_e32 v47, v53
	v_mul_f32_e32 v30, v30, v14
	v_mul_f32_e32 v31, v31, v15
	s_nop 0
	v_sub_f32_e32 v27, v30, v31
	v_mul_f32_e32 v30, 0x3db504f3, v27
	v_cndmask_b32_e64 v62, v27, v30, s[42:43]
	v_mul_f32_e32 v27, v11, v26
	v_fract_f32_e32 v27, v27
	v_cos_f32_e32 v30, v27
	v_sin_f32_e32 v31, v27
	s_nop 0
	v_mul_f32_e32 v46, v46, v30
	v_mul_f32_e32 v47, v47, v31
	s_nop 0
	v_sub_f32_e32 v27, v46, v47
	v_mov_b32_e32 v46, v15
	v_mov_b32_e32 v15, v30
	v_mov_b32_e32 v47, v31
	v_mul_f32_e32 v14, v52, v14
	v_mul_f32_e32 v15, v53, v15
	v_mul_f32_e32 v63, 0x3db504f3, v27
	v_fmac_f32_e32 v14, v60, v46
	v_fmac_f32_e32 v15, v61, v47
	v_cndmask_b32_e64 v63, v27, v63, s[42:43]
	v_mul_f32_e32 v30, s12, v14
	v_mul_f32_e32 v31, s12, v15
	v_mov_b32_e32 v52, v57
	v_cndmask_b32_e64 v59, v15, v31, s[42:43]
	v_cndmask_b32_e64 v58, v14, v30, s[42:43]
	ds_read2_b32 v[14:15], v96 offset0:136 offset1:137
	v_mov_b32_e32 v53, v49
	s_waitcnt lgkmcnt(0)
	v_mul_f32_e32 v27, v14, v26
	v_fract_f32_e32 v27, v27
	v_cos_f32_e32 v30, v27
	v_sin_f32_e32 v31, v27
	s_nop 0
	v_mul_f32_e32 v46, v88, v30
	v_mul_f32_e32 v47, v89, v31
	s_nop 0
	v_sub_f32_e32 v27, v46, v47
	v_mov_b32_e32 v46, v31
	v_mov_b32_e32 v47, v30
	v_mul_f32_e32 v30, v88, v46
	v_mul_f32_e32 v31, v89, v47
	ds_read2_b32 v[88:89], v96 offset0:150 offset1:151
	v_add_f32_e32 v30, v30, v31
	v_mul_f32_e32 v31, 0x3db504f3, v27
	v_cndmask_b32_e64 v64, v27, v31, s[42:43]
	v_mul_f32_e32 v27, v15, v26
	v_mul_f32_e32 v46, 0x3db504f3, v30
	v_fract_f32_e32 v27, v27
	v_cndmask_b32_e64 v60, v30, v46, s[42:43]
	v_cos_f32_e32 v30, v27
	v_sin_f32_e32 v31, v27
	s_nop 0
	v_mul_f32_e32 v46, v54, v30
	v_mul_f32_e32 v47, v55, v31
	s_nop 0
	v_sub_f32_e32 v27, v46, v47
	v_mov_b32_e32 v46, v31
	v_mov_b32_e32 v47, v30
	v_mul_f32_e32 v30, v54, v46
	v_mul_f32_e32 v31, v55, v47
	v_mov_b32_e32 v47, v48
	v_add_f32_e32 v30, v30, v31
	v_mul_f32_e32 v31, 0x3db504f3, v27
	v_cndmask_b32_e64 v65, v27, v31, s[42:43]
	s_waitcnt lgkmcnt(0)
	v_mul_f32_e32 v27, v88, v26
	v_mul_f32_e32 v46, 0x3db504f3, v30
	v_fract_f32_e32 v27, v27
	v_cndmask_b32_e64 v61, v30, v46, s[42:43]
	v_cos_f32_e32 v30, v27
	v_sin_f32_e32 v31, v27
	v_mov_b32_e32 v46, v56
	v_mul_f32_e32 v46, v46, v30
	v_mul_f32_e32 v47, v47, v31
	s_nop 0
	v_sub_f32_e32 v27, v46, v47
	v_mul_f32_e32 v46, 0x3db504f3, v27
	v_cndmask_b32_e64 v66, v27, v46, s[42:43]
	v_mul_f32_e32 v27, v89, v26
	v_fract_f32_e32 v27, v27
	v_cos_f32_e32 v46, v27
	v_sin_f32_e32 v47, v27
	s_nop 0
	v_mul_f32_e32 v52, v52, v46
	v_mul_f32_e32 v53, v53, v47
	s_nop 0
	v_sub_f32_e32 v27, v52, v53
	v_mov_b32_e32 v52, v31
	v_mov_b32_e32 v31, v46
	v_mov_b32_e32 v53, v47
	v_mul_f32_e32 v30, v48, v30
	v_mul_f32_e32 v31, v49, v31
	v_mul_f32_e32 v54, 0x3db504f3, v27
	v_fmac_f32_e32 v30, v56, v52
	v_fmac_f32_e32 v31, v57, v53
	ds_read2_b32 v[56:57], v96 offset0:152 offset1:153
	v_cndmask_b32_e64 v67, v27, v54, s[42:43]
	v_mul_f32_e32 v46, s12, v30
	v_mul_f32_e32 v47, s12, v31
	s_waitcnt lgkmcnt(0)
; #define P (*launderP(lp))
; __device__ __forceinline__ void phase_gemm1(PREF P, int slab, char* smem) {
;     ...
;     if (region <= 1) {
; #pragma unroll
;       for (int i = 0; i < 4; ++i) {
;         const int row = m0 + wm * 64 + i * 16 + l15;
;         const float s = (float)(row & ((1 << Sshift) - 1));
; #pragma unroll
;         for (int jj = 0; jj < 2; ++jj)
; #pragma unroll
;           for (int r = 0; r < 4; ++r) {
;             const int d = jj * 16 + wn * 32 + q * 4 + r;
;             float fr = __builtin_amdgcn_fractf(s * P.ropec[d]);
;             float cs = __builtin_amdgcn_cosf(fr), sn = __builtin_amdgcn_sinf(fr);
;             float t1 = acc[i][jj][r], t2 = acc[i][jj + 2][r];
;             float o1 = t1 * cs - t2 * sn, o2 = t1 * sn + t2 * cs;
;             if (region == 1) { o1 *= QK_SCALE; o2 *= QK_SCALE; }
;             acc[i][jj][r] = o1;
;             acc[i][jj + 2][r] = o2;
;           }
;       }
	v_mul_f32_e32 v27, v56, v26
	v_fract_f32_e32 v27, v27
	v_cndmask_b32_e64 v53, v31, v47, s[42:43]
	v_cndmask_b32_e64 v52, v30, v46, s[42:43]
	v_cos_f32_e32 v30, v27
	v_sin_f32_e32 v31, v27
	v_mul_f32_e32 v26, v57, v26
	v_mul_f32_e32 v46, v42, v30
	v_mul_f32_e32 v47, v43, v31
	s_nop 0
	v_sub_f32_e32 v27, v46, v47
	v_mov_b32_e32 v46, v31
	v_mov_b32_e32 v47, v30
	v_mul_f32_e32 v30, v42, v46
	v_mul_f32_e32 v31, v43, v47
	v_mov_b32_e32 v43, v37
	v_add_f32_e32 v30, v30, v31
	v_mul_f32_e32 v31, 0x3db504f3, v27
	v_cndmask_b32_e64 v68, v27, v31, s[42:43]
	v_fract_f32_e32 v27, v26
	v_cos_f32_e32 v26, v27
	v_sin_f32_e32 v27, v27
	v_mul_f32_e32 v42, 0x3db504f3, v30
	v_cndmask_b32_e64 v54, v30, v42, s[42:43]
	v_mul_f32_e32 v30, v50, v26
	v_mul_f32_e32 v31, v51, v27
	s_nop 0
	v_sub_f32_e32 v42, v30, v31
	v_mov_b32_e32 v30, v27
	v_mov_b32_e32 v31, v26
	v_mul_f32_e32 v26, v50, v30
	v_mul_f32_e32 v27, v51, v31
	v_cvt_f32_u32_e32 v50, v100
	v_add_f32_e32 v26, v26, v27
	v_mul_f32_e32 v30, 0x3db504f3, v26
	v_mul_f32_e32 v27, 0x3db504f3, v42
	v_cndmask_b32_e64 v55, v26, v30, s[42:43]
	v_mul_f32_e32 v26, v10, v50
	v_cndmask_b32_e64 v69, v42, v27, s[42:43]
	v_fract_f32_e32 v27, v26
	v_cos_f32_e32 v26, v27
	v_sin_f32_e32 v27, v27
	v_mov_b32_e32 v30, v44
	v_mov_b32_e32 v31, v36
	v_mov_b32_e32 v42, v45
	v_mul_f32_e32 v30, v30, v26
	v_mul_f32_e32 v31, v31, v27
	s_nop 0
	v_sub_f32_e32 v30, v30, v31
	v_mul_f32_e32 v31, 0x3db504f3, v30
	v_cndmask_b32_e64 v46, v30, v31, s[42:43]
	v_mul_f32_e32 v30, v11, v50
	v_fract_f32_e32 v31, v30
	v_cos_f32_e32 v30, v31
	v_sin_f32_e32 v31, v31
	s_nop 0
	v_mul_f32_e32 v42, v42, v30
	v_mul_f32_e32 v43, v43, v31
	s_nop 0
	v_sub_f32_e32 v47, v42, v43
	v_mov_b32_e32 v42, v27
	v_mov_b32_e32 v27, v30
	v_mov_b32_e32 v43, v31
	v_mul_f32_e32 v26, v36, v26
	v_mul_f32_e32 v27, v37, v27
	v_mul_f32_e32 v48, 0x3db504f3, v47
	v_fmac_f32_e32 v26, v44, v42
	v_fmac_f32_e32 v27, v45, v43
	v_cndmask_b32_e64 v47, v47, v48, s[42:43]
	v_mul_f32_e32 v30, s12, v26
	v_mul_f32_e32 v31, s12, v27
	v_mov_b32_e32 v37, v33
	v_cndmask_b32_e64 v42, v26, v30, s[42:43]
	v_mul_f32_e32 v26, v14, v50
	v_cndmask_b32_e64 v43, v27, v31, s[42:43]
	v_fract_f32_e32 v27, v26
	v_cos_f32_e32 v26, v27
	v_sin_f32_e32 v27, v27
	s_nop 0
	v_mul_f32_e32 v30, v92, v26
	v_mul_f32_e32 v31, v93, v27
	s_nop 0
	v_sub_f32_e32 v36, v30, v31
	v_mov_b32_e32 v30, v27
	v_mov_b32_e32 v31, v26
	v_mul_f32_e32 v26, v92, v30
	v_mul_f32_e32 v27, v93, v31
	s_nop 0
	v_add_f32_e32 v26, v26, v27
	v_mul_f32_e32 v30, 0x3db504f3, v26
	v_mul_f32_e32 v27, 0x3db504f3, v36
	v_cndmask_b32_e64 v44, v26, v30, s[42:43]
	v_mul_f32_e32 v26, v15, v50
	v_cndmask_b32_e64 v48, v36, v27, s[42:43]
	v_fract_f32_e32 v27, v26
	v_cos_f32_e32 v26, v27
	v_sin_f32_e32 v27, v27
	s_nop 0
	v_mul_f32_e32 v30, v38, v26
	v_mul_f32_e32 v31, v39, v27
	s_nop 0
	v_sub_f32_e32 v36, v30, v31
	v_mov_b32_e32 v30, v27
	v_mov_b32_e32 v31, v26
	v_mul_f32_e32 v26, v38, v30
	v_mul_f32_e32 v27, v39, v31
	v_mov_b32_e32 v31, v32
	v_add_f32_e32 v26, v26, v27
	v_mul_f32_e32 v30, 0x3db504f3, v26
	v_mul_f32_e32 v27, 0x3db504f3, v36
	v_cndmask_b32_e64 v45, v26, v30, s[42:43]
	v_mul_f32_e32 v26, v88, v50
	v_cndmask_b32_e64 v49, v36, v27, s[42:43]
	v_fract_f32_e32 v27, v26
	v_cos_f32_e32 v26, v27
	v_sin_f32_e32 v27, v27
	v_mov_b32_e32 v30, v40
	v_mov_b32_e32 v36, v41
	v_mul_f32_e32 v30, v30, v26
	v_mul_f32_e32 v31, v31, v27
	s_nop 0
	v_sub_f32_e32 v30, v30, v31
	v_mul_f32_e32 v31, 0x3db504f3, v30
	v_cndmask_b32_e64 v70, v30, v31, s[42:43]
	v_mul_f32_e32 v30, v89, v50
	v_fract_f32_e32 v31, v30
	v_cos_f32_e32 v30, v31
	v_sin_f32_e32 v31, v31
	s_nop 0
	v_mul_f32_e32 v36, v36, v30
	v_mul_f32_e32 v37, v37, v31
	s_nop 0
	v_sub_f32_e32 v38, v36, v37
	v_mov_b32_e32 v36, v27
	v_mov_b32_e32 v27, v30
	v_mov_b32_e32 v37, v31
	v_mul_f32_e32 v26, v32, v26
	v_mul_f32_e32 v27, v33, v27
	v_mul_f32_e32 v39, 0x3db504f3, v38
	v_fmac_f32_e32 v26, v40, v36
	v_fmac_f32_e32 v27, v41, v37
	v_cndmask_b32_e64 v71, v38, v39, s[42:43]
	v_mul_f32_e32 v30, s12, v26
	v_mul_f32_e32 v31, s12, v27
	v_cvt_f32_u32_e32 v40, v99
	v_cndmask_b32_e64 v36, v26, v30, s[42:43]
	v_mul_f32_e32 v26, v56, v50
	v_cndmask_b32_e64 v37, v27, v31, s[42:43]
	v_fract_f32_e32 v27, v26
	v_cos_f32_e32 v26, v27
	v_sin_f32_e32 v27, v27
	s_nop 0
	v_mul_f32_e32 v30, v90, v26
	v_mul_f32_e32 v31, v91, v27
	s_nop 0
	v_sub_f32_e32 v32, v30, v31
	v_mov_b32_e32 v30, v27
	v_mov_b32_e32 v31, v26
	v_mul_f32_e32 v26, v90, v30
	v_mul_f32_e32 v27, v91, v31
	s_nop 0
	v_add_f32_e32 v26, v26, v27
	v_mul_f32_e32 v30, 0x3db504f3, v26
	v_mul_f32_e32 v27, 0x3db504f3, v32
	v_cndmask_b32_e64 v38, v26, v30, s[42:43]
	v_mul_f32_e32 v26, v57, v50
	v_cndmask_b32_e64 v72, v32, v27, s[42:43]
	v_fract_f32_e32 v27, v26
	v_cos_f32_e32 v26, v27
	v_sin_f32_e32 v27, v27
	s_nop 0
	v_mul_f32_e32 v30, v34, v26
	v_mul_f32_e32 v31, v35, v27
	s_nop 0
	v_sub_f32_e32 v32, v30, v31
	v_mov_b32_e32 v30, v27
	v_mov_b32_e32 v31, v26
	v_mul_f32_e32 v26, v34, v30
	v_mul_f32_e32 v27, v35, v31
	v_mov_b32_e32 v31, v20
	v_add_f32_e32 v26, v26, v27
	v_mul_f32_e32 v30, 0x3db504f3, v26
	v_mul_f32_e32 v27, 0x3db504f3, v32
	v_cndmask_b32_e64 v39, v26, v30, s[42:43]
	v_mul_f32_e32 v26, v10, v40
	v_cndmask_b32_e64 v73, v32, v27, s[42:43]
	v_fract_f32_e32 v27, v26
	v_cos_f32_e32 v26, v27
	v_sin_f32_e32 v27, v27
	v_mov_b32_e32 v30, v28
	v_mov_b32_e32 v34, v29
	v_mov_b32_e32 v35, v21
	v_mul_f32_e32 v30, v30, v26
	v_mul_f32_e32 v31, v31, v27
	s_nop 0
	v_sub_f32_e32 v30, v30, v31
	v_mul_f32_e32 v31, 0x3db504f3, v30
	v_cndmask_b32_e64 v30, v30, v31, s[42:43]
	v_mul_f32_e32 v31, v11, v40
	v_fract_f32_e32 v31, v31
	v_cos_f32_e32 v32, v31
	v_sin_f32_e32 v33, v31
	s_nop 0
	v_mul_f32_e32 v34, v34, v32
; #define P (*launderP(lp))
; __device__ __forceinline__ void phase_gemm1(PREF P, int slab, char* smem) {
;     ...
;     if (region <= 1) {
; #pragma unroll
;       for (int i = 0; i < 4; ++i) {
;         const int row = m0 + wm * 64 + i * 16 + l15;
;         const float s = (float)(row & ((1 << Sshift) - 1));
; #pragma unroll
;         for (int jj = 0; jj < 2; ++jj)
; #pragma unroll
;           for (int r = 0; r < 4; ++r) {
;             const int d = jj * 16 + wn * 32 + q * 4 + r;
;             float fr = __builtin_amdgcn_fractf(s * P.ropec[d]);
;             float cs = __builtin_amdgcn_cosf(fr), sn = __builtin_amdgcn_sinf(fr);
;             float t1 = acc[i][jj][r], t2 = acc[i][jj + 2][r];
;             float o1 = t1 * cs - t2 * sn, o2 = t1 * sn + t2 * cs;
;             if (region == 1) { o1 *= QK_SCALE; o2 *= QK_SCALE; }
;             acc[i][jj][r] = o1;
;             acc[i][jj + 2][r] = o2;
;           }
;       }
	v_mul_f32_e32 v35, v35, v33
	s_nop 0
	v_sub_f32_e32 v31, v34, v35
	v_mov_b32_e32 v34, v27
	v_mov_b32_e32 v27, v32
	v_mov_b32_e32 v35, v33
	v_mul_f32_e32 v20, v20, v26
	v_mul_f32_e32 v21, v21, v27
	v_mul_f32_e32 v41, 0x3db504f3, v31
	v_fmac_f32_e32 v20, v28, v34
	v_fmac_f32_e32 v21, v29, v35
	v_cndmask_b32_e64 v31, v31, v41, s[42:43]
	v_mul_f32_e32 v26, s12, v20
	v_mul_f32_e32 v27, s12, v21
	s_nop 0
	v_cndmask_b32_e64 v26, v20, v26, s[42:43]
	v_mul_f32_e32 v20, v14, v40
	v_cndmask_b32_e64 v27, v21, v27, s[42:43]
	v_fract_f32_e32 v21, v20
	v_cos_f32_e32 v20, v21
	v_sin_f32_e32 v21, v21
	s_nop 0
	v_mul_f32_e32 v28, v86, v20
	v_mul_f32_e32 v29, v87, v21
	s_nop 0
	v_sub_f32_e32 v32, v28, v29
	v_mov_b32_e32 v28, v21
	v_mov_b32_e32 v29, v20
	v_mul_f32_e32 v20, v86, v28
	v_mul_f32_e32 v21, v87, v29
	s_nop 0
	v_add_f32_e32 v20, v20, v21
	v_mul_f32_e32 v28, 0x3db504f3, v20
	v_mul_f32_e32 v21, 0x3db504f3, v32
	v_cndmask_b32_e64 v28, v20, v28, s[42:43]
	v_mul_f32_e32 v20, v15, v40
	v_cndmask_b32_e64 v32, v32, v21, s[42:43]
	v_fract_f32_e32 v21, v20
	v_cos_f32_e32 v20, v21
	v_sin_f32_e32 v21, v21
	s_nop 0
	v_mul_f32_e32 v34, v22, v20
	v_mul_f32_e32 v35, v23, v21
	s_nop 0
	v_sub_f32_e32 v33, v34, v35
	v_mov_b32_e32 v34, v21
	v_mov_b32_e32 v35, v20
	v_mul_f32_e32 v20, v22, v34
	v_mul_f32_e32 v21, v23, v35
	v_mov_b32_e32 v23, v16
	v_add_f32_e32 v20, v20, v21
	v_mul_f32_e32 v22, 0x3db504f3, v20
	v_mul_f32_e32 v21, 0x3db504f3, v33
	v_cndmask_b32_e64 v29, v20, v22, s[42:43]
	v_mul_f32_e32 v20, v88, v40
	v_cndmask_b32_e64 v33, v33, v21, s[42:43]
	v_fract_f32_e32 v21, v20
	v_cos_f32_e32 v20, v21
	v_sin_f32_e32 v21, v21
	v_mov_b32_e32 v22, v24
	v_mov_b32_e32 v34, v25
	v_mov_b32_e32 v35, v17
	v_mul_f32_e32 v22, v22, v20
	v_mul_f32_e32 v23, v23, v21
	s_nop 0
	v_sub_f32_e32 v22, v22, v23
	v_mul_f32_e32 v23, 0x3db504f3, v22
	v_cndmask_b32_e64 v74, v22, v23, s[42:43]
	v_mul_f32_e32 v22, v89, v40
	v_fract_f32_e32 v23, v22
	v_cos_f32_e32 v22, v23
	v_sin_f32_e32 v23, v23
	s_nop 0
	v_mul_f32_e32 v34, v34, v22
	v_mul_f32_e32 v35, v35, v23
	s_nop 0
	v_sub_f32_e32 v41, v34, v35
	v_mov_b32_e32 v34, v21
	v_mov_b32_e32 v21, v22
	v_mov_b32_e32 v35, v23
	v_mul_f32_e32 v16, v16, v20
	v_mul_f32_e32 v17, v17, v21
	v_mul_f32_e32 v50, 0x3db504f3, v41
	v_fmac_f32_e32 v16, v24, v34
	v_fmac_f32_e32 v17, v25, v35
	v_cndmask_b32_e64 v75, v41, v50, s[42:43]
	v_mul_f32_e32 v20, s12, v16
	v_mul_f32_e32 v21, s12, v17
	s_nop 0
	v_cndmask_b32_e64 v20, v16, v20, s[42:43]
	v_mul_f32_e32 v16, v56, v40
	v_cndmask_b32_e64 v21, v17, v21, s[42:43]
	v_fract_f32_e32 v17, v16
	v_cos_f32_e32 v16, v17
	v_sin_f32_e32 v17, v17
	s_nop 0
	v_mul_f32_e32 v22, v76, v16
	v_mul_f32_e32 v23, v77, v17
	s_nop 0
	v_sub_f32_e32 v24, v22, v23
	v_mov_b32_e32 v22, v17
	v_mov_b32_e32 v23, v16
	v_mul_f32_e32 v16, v76, v22
	v_mul_f32_e32 v17, v77, v23
	s_nop 0
	v_add_f32_e32 v16, v16, v17
	v_mul_f32_e32 v22, 0x3db504f3, v16
	v_mul_f32_e32 v17, 0x3db504f3, v24
	v_cndmask_b32_e64 v22, v16, v22, s[42:43]
	v_mul_f32_e32 v16, v57, v40
	v_cndmask_b32_e64 v76, v24, v17, s[42:43]
	v_fract_f32_e32 v17, v16
	v_cos_f32_e32 v16, v17
	v_sin_f32_e32 v17, v17
	s_nop 0
	v_mul_f32_e32 v24, v18, v16
	v_mul_f32_e32 v25, v19, v17
	s_nop 0
	v_sub_f32_e32 v34, v24, v25
	v_mov_b32_e32 v24, v17
	v_mov_b32_e32 v25, v16
	v_mul_f32_e32 v16, v18, v24
	v_mul_f32_e32 v17, v19, v25
	v_mov_b32_e32 v24, v13
	v_add_f32_e32 v16, v16, v17
	v_mul_f32_e32 v17, 0x3db504f3, v34
	v_cndmask_b32_e64 v77, v34, v17, s[42:43]
	v_cvt_f32_u32_e32 v34, v81
	v_mul_f32_e32 v18, 0x3db504f3, v16
	v_cndmask_b32_e64 v23, v16, v18, s[42:43]
	v_mov_b32_e32 v16, v12
	v_mul_f32_e32 v10, v10, v34
	v_fract_f32_e32 v10, v10
	v_cos_f32_e32 v18, v10
	v_sin_f32_e32 v19, v10
	v_mov_b32_e32 v17, v4
	v_mov_b32_e32 v25, v5
	v_mul_f32_e32 v16, v16, v18
	v_mul_f32_e32 v17, v17, v19
	s_nop 0
	v_sub_f32_e32 v10, v16, v17
	v_mul_f32_e32 v16, 0x3db504f3, v10
	v_cndmask_b32_e64 v16, v10, v16, s[42:43]
	v_mul_f32_e32 v10, v11, v34
	v_fract_f32_e32 v11, v10
	v_cos_f32_e32 v10, v11
	v_sin_f32_e32 v11, v11
	s_nop 0
	v_mul_f32_e32 v24, v24, v10
	v_mul_f32_e32 v25, v25, v11
	s_nop 0
	v_sub_f32_e32 v17, v24, v25
	v_mov_b32_e32 v24, v19
	v_mov_b32_e32 v19, v10
	v_mov_b32_e32 v25, v11
	v_mul_f32_e32 v4, v4, v18
	v_mul_f32_e32 v5, v5, v19
	v_mul_f32_e32 v35, 0x3db504f3, v17
; #define P (*launderP(lp))
; __device__ __forceinline__ void phase_gemm1(PREF P, int slab, char* smem) {
;     ...
;     if (region <= 1) {
; #pragma unroll
;       for (int i = 0; i < 4; ++i) {
;         const int row = m0 + wm * 64 + i * 16 + l15;
;         const float s = (float)(row & ((1 << Sshift) - 1));
; #pragma unroll
;         for (int jj = 0; jj < 2; ++jj)
; #pragma unroll
;           for (int r = 0; r < 4; ++r) {
;             const int d = jj * 16 + wn * 32 + q * 4 + r;
;             float fr = __builtin_amdgcn_fractf(s * P.ropec[d]);
;             float cs = __builtin_amdgcn_cosf(fr), sn = __builtin_amdgcn_sinf(fr);
;             float t1 = acc[i][jj][r], t2 = acc[i][jj + 2][r];
;             float o1 = t1 * cs - t2 * sn, o2 = t1 * sn + t2 * cs;
;             if (region == 1) { o1 *= QK_SCALE; o2 *= QK_SCALE; }
;             acc[i][jj][r] = o1;
;             acc[i][jj + 2][r] = o2;
;           }
;       }
;     }
	v_fmac_f32_e32 v4, v12, v24
	v_fmac_f32_e32 v5, v13, v25
	v_cndmask_b32_e64 v17, v17, v35, s[42:43]
	v_mul_f32_e32 v10, s12, v4
	v_mul_f32_e32 v11, s12, v5
	s_nop 0
	v_cndmask_b32_e64 v10, v4, v10, s[42:43]
	v_mul_f32_e32 v4, v14, v34
	v_cndmask_b32_e64 v11, v5, v11, s[42:43]
	v_fract_f32_e32 v5, v4
	v_cos_f32_e32 v4, v5
	v_sin_f32_e32 v5, v5
	s_nop 0
	v_mul_f32_e32 v12, v84, v4
	v_mul_f32_e32 v13, v85, v5
	s_nop 0
	v_sub_f32_e32 v14, v12, v13
	v_mov_b32_e32 v12, v5
	v_mov_b32_e32 v13, v4
	v_mul_f32_e32 v4, v84, v12
	v_mul_f32_e32 v5, v85, v13
	s_nop 0
	v_add_f32_e32 v4, v4, v5
	v_mul_f32_e32 v12, 0x3db504f3, v4
	v_mul_f32_e32 v5, 0x3db504f3, v14
	v_cndmask_b32_e64 v12, v4, v12, s[42:43]
	v_mul_f32_e32 v4, v15, v34
	v_cndmask_b32_e64 v18, v14, v5, s[42:43]
	v_fract_f32_e32 v5, v4
	v_cos_f32_e32 v4, v5
	v_sin_f32_e32 v5, v5
	s_nop 0
	v_mul_f32_e32 v14, v6, v4
	v_mul_f32_e32 v15, v7, v5
	s_nop 0
	v_sub_f32_e32 v19, v14, v15
	v_mov_b32_e32 v14, v5
	v_mov_b32_e32 v15, v4
	v_mul_f32_e32 v4, v6, v14
	v_mul_f32_e32 v5, v7, v15
	v_mov_b32_e32 v7, v0
	v_add_f32_e32 v4, v4, v5
	v_mul_f32_e32 v6, 0x3db504f3, v4
	v_mul_f32_e32 v5, 0x3db504f3, v19
	v_cndmask_b32_e64 v13, v4, v6, s[42:43]
	v_mul_f32_e32 v4, v88, v34
	v_cndmask_b32_e64 v19, v19, v5, s[42:43]
	v_fract_f32_e32 v5, v4
	v_cos_f32_e32 v4, v5
	v_sin_f32_e32 v5, v5
	v_mov_b32_e32 v6, v8
	v_mov_b32_e32 v14, v9
	v_mov_b32_e32 v15, v1
	v_mul_f32_e32 v6, v6, v4
	v_mul_f32_e32 v7, v7, v5
	s_nop 0
	v_sub_f32_e32 v6, v6, v7
	v_mul_f32_e32 v7, 0x3db504f3, v6
	v_cndmask_b32_e64 v84, v6, v7, s[42:43]
	v_mul_f32_e32 v6, v89, v34
	v_fract_f32_e32 v7, v6
	v_cos_f32_e32 v6, v7
	v_sin_f32_e32 v7, v7
	s_nop 0
	v_mul_f32_e32 v14, v14, v6
	v_mul_f32_e32 v15, v15, v7
	s_nop 0
	v_sub_f32_e32 v24, v14, v15
	v_mov_b32_e32 v14, v5
	v_mov_b32_e32 v5, v6
	v_mov_b32_e32 v15, v7
	v_mul_f32_e32 v0, v0, v4
	v_mul_f32_e32 v1, v1, v5
	v_mul_f32_e32 v25, 0x3db504f3, v24
	v_fmac_f32_e32 v0, v8, v14
	v_fmac_f32_e32 v1, v9, v15
	v_cndmask_b32_e64 v85, v24, v25, s[42:43]
	v_mul_f32_e32 v4, s12, v0
	v_mul_f32_e32 v5, s12, v1
	s_nop 0
	v_cndmask_b32_e64 v4, v0, v4, s[42:43]
	v_mul_f32_e32 v0, v56, v34
	v_cndmask_b32_e64 v5, v1, v5, s[42:43]
	v_fract_f32_e32 v1, v0
	v_cos_f32_e32 v0, v1
	v_sin_f32_e32 v1, v1
	s_nop 0
	v_mul_f32_e32 v6, v82, v0
	v_mul_f32_e32 v7, v83, v1
	s_nop 0
	v_sub_f32_e32 v8, v6, v7
	v_mov_b32_e32 v6, v1
	v_mov_b32_e32 v7, v0
	v_mul_f32_e32 v0, v82, v6
	v_mul_f32_e32 v1, v83, v7
	s_nop 0
	v_add_f32_e32 v0, v0, v1
	v_mul_f32_e32 v6, 0x3db504f3, v0
	v_mul_f32_e32 v1, 0x3db504f3, v8
	v_cndmask_b32_e64 v6, v0, v6, s[42:43]
	v_mul_f32_e32 v0, v57, v34
	v_cndmask_b32_e64 v86, v8, v1, s[42:43]
	v_fract_f32_e32 v1, v0
	v_cos_f32_e32 v0, v1
	v_sin_f32_e32 v1, v1
	s_nop 0
	v_mul_f32_e32 v8, v2, v0
	v_mul_f32_e32 v9, v3, v1
	s_nop 0
	v_sub_f32_e32 v14, v8, v9
	v_mov_b32_e32 v8, v1
	v_mov_b32_e32 v9, v0
	v_mul_f32_e32 v0, v2, v8
	v_mul_f32_e32 v1, v3, v9
	s_nop 0
	v_add_f32_e32 v0, v0, v1
	v_mul_f32_e32 v1, 0x3db504f3, v14
	v_mul_f32_e32 v2, 0x3db504f3, v0
	v_cndmask_b32_e64 v7, v0, v2, s[42:43]
	v_cndmask_b32_e64 v87, v14, v1, s[42:43]
	v_mov_b64_e32 v[0:1], v[4:5]
	v_mov_b64_e32 v[2:3], v[6:7]
	v_mov_b64_e32 v[4:5], v[10:11]
	v_mov_b64_e32 v[6:7], v[12:13]
	v_mov_b64_e32 v[12:13], v[16:17]
	v_mov_b64_e32 v[14:15], v[18:19]
	v_mov_b64_e32 v[16:17], v[20:21]
	v_mov_b64_e32 v[18:19], v[22:23]
	v_mov_b64_e32 v[20:21], v[26:27]
	v_mov_b64_e32 v[22:23], v[28:29]
	v_mov_b64_e32 v[28:29], v[30:31]
	v_mov_b64_e32 v[30:31], v[32:33]
	v_mov_b64_e32 v[32:33], v[36:37]
	v_mov_b64_e32 v[34:35], v[38:39]
	v_mov_b64_e32 v[36:37], v[42:43]
	v_mov_b64_e32 v[38:39], v[44:45]
	v_mov_b64_e32 v[44:45], v[46:47]
	v_mov_b64_e32 v[46:47], v[48:49]
	v_mov_b64_e32 v[48:49], v[52:53]
	v_mov_b64_e32 v[50:51], v[54:55]
	v_mov_b64_e32 v[52:53], v[58:59]
	v_mov_b64_e32 v[8:9], v[84:85]
	v_mov_b64_e32 v[24:25], v[74:75]
	v_mov_b64_e32 v[40:41], v[70:71]
	v_mov_b64_e32 v[54:55], v[60:61]
	v_mov_b64_e32 v[56:57], v[66:67]
	v_mov_b64_e32 v[60:61], v[62:63]
	v_mov_b64_e32 v[10:11], v[86:87]
	v_mov_b64_e32 v[26:27], v[76:77]
	v_mov_b64_e32 v[42:43], v[72:73]
	v_mov_b64_e32 v[58:59], v[68:69]
	v_mov_b64_e32 v[62:63], v[64:65]
	s_cmp_lt_i32 s16, 3
	s_mov_b64 s[14:15], -1
	s_cbranch_scc1 .LBB0_751
	s_branch .LBB0_738

; __device__ __forceinline__ void phase_gemm1(PREF P, int slab, char* smem) {
;     ...
;     if (region == 4) {
; #pragma unroll
;       for (int i = 0; i < 4; ++i)
; #pragma unroll
;         for (int j = 0; j < 4; ++j) acc[i][j] = acc[i][j] * QK_SCALE;
;     }
.LBB0_759:
	s_andn2_b64 vcc, exec, s[48:49]
	s_cbranch_vccnz .LBB0_761
	v_mul_f32_e32 v62, s12, v62
	v_mul_f32_e32 v63, s12, v63
	v_mul_f32_e32 v60, s12, v60
	v_mul_f32_e32 v61, s12, v61
	v_mul_f32_e32 v58, s12, v58
	v_mul_f32_e32 v59, s12, v59
	v_mul_f32_e32 v56, s12, v56
	v_mul_f32_e32 v57, s12, v57
	v_mul_f32_e32 v54, s12, v54
	v_mul_f32_e32 v55, s12, v55
	v_mul_f32_e32 v52, s12, v52
	v_mul_f32_e32 v53, s12, v53
	v_mul_f32_e32 v50, s12, v50
	v_mul_f32_e32 v51, s12, v51
	v_mul_f32_e32 v48, s12, v48
	v_mul_f32_e32 v49, s12, v49
	v_mul_f32_e32 v46, s12, v46
	v_mul_f32_e32 v47, s12, v47
	v_mul_f32_e32 v44, s12, v44
	v_mul_f32_e32 v45, s12, v45
	v_mul_f32_e32 v42, s12, v42
	v_mul_f32_e32 v43, s12, v43
	v_mul_f32_e32 v40, s12, v40
	v_mul_f32_e32 v41, s12, v41
	v_mul_f32_e32 v38, s12, v38
	v_mul_f32_e32 v39, s12, v39
	v_mul_f32_e32 v36, s12, v36
	v_mul_f32_e32 v37, s12, v37
	v_mul_f32_e32 v34, s12, v34
	v_mul_f32_e32 v35, s12, v35
	v_mul_f32_e32 v32, s12, v32
	v_mul_f32_e32 v33, s12, v33
	v_mul_f32_e32 v30, s12, v30
	v_mul_f32_e32 v31, s12, v31
	v_mul_f32_e32 v28, s12, v28
	v_mul_f32_e32 v29, s12, v29
	v_mul_f32_e32 v26, s12, v26
	v_mul_f32_e32 v27, s12, v27
	v_mul_f32_e32 v24, s12, v24
	v_mul_f32_e32 v25, s12, v25
	v_mul_f32_e32 v22, s12, v22
	v_mul_f32_e32 v23, s12, v23
	v_mul_f32_e32 v20, s12, v20
	v_mul_f32_e32 v21, s12, v21
	v_mul_f32_e32 v18, s12, v18
	v_mul_f32_e32 v19, s12, v19
	v_mul_f32_e32 v16, s12, v16
	v_mul_f32_e32 v17, s12, v17
	v_mul_f32_e32 v14, s12, v14
	v_mul_f32_e32 v15, s12, v15
	v_mul_f32_e32 v12, s12, v12
	v_mul_f32_e32 v13, s12, v13
	v_mul_f32_e32 v10, s12, v10
	v_mul_f32_e32 v11, s12, v11
	v_mul_f32_e32 v8, s12, v8
	v_mul_f32_e32 v9, s12, v9
	v_mul_f32_e32 v6, s12, v6
	v_mul_f32_e32 v7, s12, v7
	v_mul_f32_e32 v4, s12, v4
	v_mul_f32_e32 v5, s12, v5
	v_mul_f32_e32 v2, s12, v2
	v_mul_f32_e32 v3, s12, v3
	v_mul_f32_e32 v0, s12, v0
	v_mul_f32_e32 v1, s12, v1
